# gemm1 epilogues: hipcc's packed f32 VALU ops split into scalar halves (bit-identical); prologue weight transposes: both 16-load batches of an item issued before the first LDS writes; rest as v74
# baseline (speedup 1.0000x reference)
; template <bool REMAP> __device__ __forceinline__ void p0_transpose_item(const float* W, int K, int N, bf16r* WT, LAS float* scr, int item, int lane) {
;     ...
; #pragma unroll 8
;     for (int i = 0; i < 32; ++i) { const int kk = 2 * i + (lane >> 5); scr[kk * 33 + (lane & 31)] = W[(size_t)(k0 + kk) * N + n0 + (lane & 31)]; }
.LBB0_11:
	s_lshl_b32 s38, s34, 1
	s_lshl_b32 s39, s36, 1
	v_or_b32_e32 v11, s38, v1
	v_or_b32_e32 v13, s39, v2
	s_add_i32 s41, s39, 4
	s_add_i32 s40, s38, 4
	s_add_i32 s42, s38, 8
	s_add_i32 s43, s39, 8
	s_add_i32 s44, s38, 12
	s_add_i32 s46, s38, 16
	s_add_i32 s48, s38, 20
	s_add_i32 s50, s38, 24
	s_add_i32 s38, s38, 28
	v_add_lshl_u32 v8, v11, s35, 10
	v_add_lshl_u32 v24, v13, s33, 10
	v_or_b32_e32 v43, s41, v2
	s_add_i32 s45, s39, 12
	v_or_b32_e32 v42, s40, v1
	v_or_b32_e32 v44, s42, v1
	v_or_b32_e32 v45, s43, v2
	v_or_b32_e32 v46, s44, v1
	v_or_b32_e32 v48, s46, v1
	v_or_b32_e32 v50, s48, v1
	v_or_b32_e32 v52, s50, v1
	v_or_b32_e32 v55, s38, v1
	v_or_b32_e32 v22, v3, v8
	v_or_b32_e32 v8, v12, v24
	v_add_lshl_u32 v26, v43, s33, 10
	v_mov_b32_e32 v23, v9
	s_add_i32 s47, s39, 16
	v_or_b32_e32 v47, s45, v2
	v_add_lshl_u32 v24, v42, s35, 10
	v_add_lshl_u32 v28, v44, s35, 10
	v_add_lshl_u32 v58, v45, s33, 10
	v_add_lshl_u32 v30, v46, s35, 10
	v_add_lshl_u32 v32, v48, s35, 10
	v_add_lshl_u32 v34, v50, s35, 10
	v_add_lshl_u32 v36, v52, s35, 10
	v_add_lshl_u32 v40, v55, s35, 10
	v_lshl_add_u64 v[38:39], v[8:9], 2, s[14:15]
	v_or_b32_e32 v8, v12, v26
	v_mov_b32_e32 v25, v9
	s_add_i32 s49, s39, 20
	v_or_b32_e32 v49, s47, v2
	v_add_lshl_u32 v59, v47, s33, 10
	v_lshl_add_u64 v[22:23], v[22:23], 2, s[14:15]
	v_or_b32_e32 v24, v3, v24
	v_or_b32_e32 v26, v3, v28
	v_or_b32_e32 v28, v3, v30
	v_or_b32_e32 v30, v3, v32
	v_or_b32_e32 v32, v3, v34
	v_or_b32_e32 v34, v3, v36
	v_or_b32_e32 v36, v3, v40
	v_lshl_add_u64 v[40:41], v[8:9], 2, s[14:15]
	v_or_b32_e32 v8, v12, v58
	s_add_i32 s51, s39, 24
	v_or_b32_e32 v51, s49, v2
	v_add_lshl_u32 v60, v49, s33, 10
	v_lshl_add_u64 v[24:25], v[24:25], 2, s[14:15]
	global_load_dword v58, v[38:39], off
	global_load_dword v64, v[22:23], off
	global_load_dword v65, v[40:41], off
	global_load_dword v66, v[24:25], off
	v_lshl_add_u64 v[22:23], v[8:9], 2, s[14:15]
	v_or_b32_e32 v8, v12, v59
	v_mov_b32_e32 v27, v9
	v_mov_b32_e32 v29, v9
	s_add_i32 s39, s39, 28
	v_or_b32_e32 v53, s51, v2
	v_add_lshl_u32 v61, v51, s33, 10
	v_lshl_add_u64 v[24:25], v[8:9], 2, s[14:15]
	v_or_b32_e32 v8, v12, v60
	v_or_b32_e32 v57, s39, v2
	v_add_lshl_u32 v62, v53, s33, 10
	v_lshl_add_u64 v[26:27], v[26:27], 2, s[14:15]
	v_lshl_add_u64 v[28:29], v[28:29], 2, s[14:15]
	global_load_dword v59, v[22:23], off
	global_load_dword v60, v[26:27], off
	global_load_dword v67, v[24:25], off
	global_load_dword v68, v[28:29], off
	v_lshl_add_u64 v[22:23], v[8:9], 2, s[14:15]
	v_or_b32_e32 v8, v12, v61
	v_mov_b32_e32 v31, v9
	v_mov_b32_e32 v33, v9
	v_add_lshl_u32 v63, v57, s33, 10
	v_lshl_add_u64 v[24:25], v[8:9], 2, s[14:15]
	v_or_b32_e32 v8, v12, v62
	v_mov_b32_e32 v35, v9
	v_mov_b32_e32 v37, v9
	v_lshl_add_u64 v[30:31], v[30:31], 2, s[14:15]
	v_lshl_add_u64 v[32:33], v[32:33], 2, s[14:15]
	global_load_dword v61, v[22:23], off
	global_load_dword v62, v[30:31], off
	global_load_dword v69, v[24:25], off
	global_load_dword v70, v[32:33], off
	v_lshl_add_u64 v[22:23], v[8:9], 2, s[14:15]
	v_or_b32_e32 v8, v12, v63
	v_lshl_add_u64 v[34:35], v[34:35], 2, s[14:15]
	v_lshl_add_u64 v[36:37], v[36:37], 2, s[14:15]
	v_lshl_add_u64 v[24:25], v[8:9], 2, s[14:15]
	global_load_dword v8, v[22:23], off
	global_load_dword v63, v[34:35], off
	global_load_dword v71, v[24:25], off
	global_load_dword v72, v[36:37], off
	s_add_i32 s36, s36, 16
	s_add_i32 s34, s34, 16
	s_add_i32 s37, s37, -16
	v_mad_u64_u32 v[22:23], s[38:39], v13, s19, v[6:7]
	s_cmp_lg_u32 s37, 0
	v_mad_u64_u32 v[24:25], s[38:39], v11, s19, v[6:7]
	v_mad_u64_u32 v[26:27], s[38:39], v43, s19, v[6:7]
	v_mad_u64_u32 v[28:29], s[38:39], v42, s19, v[6:7]
	v_mad_u64_u32 v[30:31], s[38:39], v45, s19, v[6:7]
	v_mad_u64_u32 v[32:33], s[38:39], v44, s19, v[6:7]
	v_mad_u64_u32 v[34:35], s[38:39], v47, s19, v[6:7]
	v_mad_u64_u32 v[36:37], s[38:39], v46, s19, v[6:7]
	v_mad_u64_u32 v[38:39], s[38:39], v49, s19, v[6:7]
	v_mad_u64_u32 v[40:41], s[38:39], v48, s19, v[6:7]
	v_mad_u64_u32 v[42:43], s[38:39], v51, s19, v[6:7]
	v_mad_u64_u32 v[44:45], s[38:39], v50, s19, v[6:7]
	v_mad_u64_u32 v[46:47], s[38:39], v53, s19, v[6:7]
	v_mad_u64_u32 v[48:49], s[38:39], v52, s19, v[6:7]
	v_mad_u64_u32 v[50:51], s[38:39], v57, s19, v[6:7]
	v_mad_u64_u32 v[52:53], s[38:39], v55, s19, v[6:7]
	v_mov_b32_e32 v109, v9
	s_lshl_b32 s38, s34, 1
	s_lshl_b32 s39, s36, 1
	v_or_b32_e32 v111, s38, v1
	v_or_b32_e32 v113, s39, v2
	s_add_i32 s41, s39, 4
	s_add_i32 s40, s38, 4
	s_add_i32 s42, s38, 8
	s_add_i32 s43, s39, 8
	s_add_i32 s44, s38, 12
	s_add_i32 s46, s38, 16
	s_add_i32 s48, s38, 20
	s_add_i32 s50, s38, 24
	s_add_i32 s38, s38, 28
	v_add_lshl_u32 v108, v111, s35, 10
	v_add_lshl_u32 v124, v113, s33, 10
	v_or_b32_e32 v143, s41, v2
	s_add_i32 s45, s39, 12
	v_or_b32_e32 v142, s40, v1
	v_or_b32_e32 v144, s42, v1
	v_or_b32_e32 v145, s43, v2
	v_or_b32_e32 v146, s44, v1
	v_or_b32_e32 v148, s46, v1
	v_or_b32_e32 v150, s48, v1
	v_or_b32_e32 v152, s50, v1
	v_or_b32_e32 v155, s38, v1
	v_or_b32_e32 v122, v3, v108
	v_or_b32_e32 v108, v12, v124
	v_add_lshl_u32 v126, v143, s33, 10
	v_mov_b32_e32 v123, v109
	s_add_i32 s47, s39, 16
	v_or_b32_e32 v147, s45, v2
	v_add_lshl_u32 v124, v142, s35, 10
	v_add_lshl_u32 v128, v144, s35, 10
	v_add_lshl_u32 v158, v145, s33, 10
	v_add_lshl_u32 v130, v146, s35, 10
	v_add_lshl_u32 v132, v148, s35, 10
	v_add_lshl_u32 v134, v150, s35, 10
	v_add_lshl_u32 v136, v152, s35, 10
	v_add_lshl_u32 v140, v155, s35, 10
	v_lshl_add_u64 v[138:139], v[108:109], 2, s[14:15]
	v_or_b32_e32 v108, v12, v126
	v_mov_b32_e32 v125, v109
	s_add_i32 s49, s39, 20
	v_or_b32_e32 v149, s47, v2
	v_add_lshl_u32 v159, v147, s33, 10
	v_lshl_add_u64 v[122:123], v[122:123], 2, s[14:15]
; #define LDS_WAIT() asm volatile("s_waitcnt lgkmcnt(0)" ::: "memory")
; template <bool REMAP> __device__ __forceinline__ void p0_transpose_item(const float* W, int K, int N, bf16r* WT, LAS float* scr, int item, int lane) {
;     ...
; #pragma unroll 8
;     for (int i = 0; i < 32; ++i) { const int kk = 2 * i + (lane >> 5); scr[kk * 33 + (lane & 31)] = W[(size_t)(k0 + kk) * N + n0 + (lane & 31)]; }
;     LDS_WAIT(); asm volatile("" ::: "memory");
	v_or_b32_e32 v124, v3, v124
	v_or_b32_e32 v126, v3, v128
	v_or_b32_e32 v128, v3, v130
	v_or_b32_e32 v130, v3, v132
	v_or_b32_e32 v132, v3, v134
	v_or_b32_e32 v134, v3, v136
	v_or_b32_e32 v136, v3, v140
	v_lshl_add_u64 v[140:141], v[108:109], 2, s[14:15]
	v_or_b32_e32 v108, v12, v158
	s_add_i32 s51, s39, 24
	v_or_b32_e32 v151, s49, v2
	v_add_lshl_u32 v160, v149, s33, 10
	v_lshl_add_u64 v[124:125], v[124:125], 2, s[14:15]
	global_load_dword v158, v[138:139], off
	global_load_dword v164, v[122:123], off
	global_load_dword v165, v[140:141], off
	global_load_dword v166, v[124:125], off
	v_lshl_add_u64 v[122:123], v[108:109], 2, s[14:15]
	v_or_b32_e32 v108, v12, v159
	v_mov_b32_e32 v127, v109
	v_mov_b32_e32 v129, v109
	s_add_i32 s39, s39, 28
	v_or_b32_e32 v153, s51, v2
	v_add_lshl_u32 v161, v151, s33, 10
	v_lshl_add_u64 v[124:125], v[108:109], 2, s[14:15]
	v_or_b32_e32 v108, v12, v160
	v_or_b32_e32 v157, s39, v2
	v_add_lshl_u32 v162, v153, s33, 10
	v_lshl_add_u64 v[126:127], v[126:127], 2, s[14:15]
	v_lshl_add_u64 v[128:129], v[128:129], 2, s[14:15]
	global_load_dword v159, v[122:123], off
	global_load_dword v160, v[126:127], off
	global_load_dword v167, v[124:125], off
	global_load_dword v168, v[128:129], off
	v_lshl_add_u64 v[122:123], v[108:109], 2, s[14:15]
	v_or_b32_e32 v108, v12, v161
	v_mov_b32_e32 v131, v109
	v_mov_b32_e32 v133, v109
	v_add_lshl_u32 v163, v157, s33, 10
	v_lshl_add_u64 v[124:125], v[108:109], 2, s[14:15]
	v_or_b32_e32 v108, v12, v162
	v_mov_b32_e32 v135, v109
	v_mov_b32_e32 v137, v109
	v_lshl_add_u64 v[130:131], v[130:131], 2, s[14:15]
	v_lshl_add_u64 v[132:133], v[132:133], 2, s[14:15]
	global_load_dword v161, v[122:123], off
	global_load_dword v162, v[130:131], off
	global_load_dword v169, v[124:125], off
	global_load_dword v170, v[132:133], off
	v_lshl_add_u64 v[122:123], v[108:109], 2, s[14:15]
	v_or_b32_e32 v108, v12, v163
	v_lshl_add_u64 v[134:135], v[134:135], 2, s[14:15]
	v_lshl_add_u64 v[136:137], v[136:137], 2, s[14:15]
	v_lshl_add_u64 v[124:125], v[108:109], 2, s[14:15]
	global_load_dword v108, v[122:123], off
	global_load_dword v163, v[134:135], off
	global_load_dword v171, v[124:125], off
	global_load_dword v172, v[136:137], off
	s_add_i32 s36, s36, 16
	s_add_i32 s34, s34, 16
	s_add_i32 s37, s37, -16
	v_mad_u64_u32 v[122:123], s[38:39], v113, s19, v[6:7]
	s_cmp_lg_u32 s37, 0
	v_mad_u64_u32 v[124:125], s[38:39], v111, s19, v[6:7]
	v_mad_u64_u32 v[126:127], s[38:39], v143, s19, v[6:7]
	v_mad_u64_u32 v[128:129], s[38:39], v142, s19, v[6:7]
	v_mad_u64_u32 v[130:131], s[38:39], v145, s19, v[6:7]
	v_mad_u64_u32 v[132:133], s[38:39], v144, s19, v[6:7]
	v_mad_u64_u32 v[134:135], s[38:39], v147, s19, v[6:7]
	v_mad_u64_u32 v[136:137], s[38:39], v146, s19, v[6:7]
	v_mad_u64_u32 v[138:139], s[38:39], v149, s19, v[6:7]
	v_mad_u64_u32 v[140:141], s[38:39], v148, s19, v[6:7]
	v_mad_u64_u32 v[142:143], s[38:39], v151, s19, v[6:7]
	v_mad_u64_u32 v[144:145], s[38:39], v150, s19, v[6:7]
	v_mad_u64_u32 v[146:147], s[38:39], v153, s19, v[6:7]
	v_mad_u64_u32 v[148:149], s[38:39], v152, s19, v[6:7]
	v_mad_u64_u32 v[150:151], s[38:39], v157, s19, v[6:7]
	v_mad_u64_u32 v[152:153], s[38:39], v155, s19, v[6:7]
	s_waitcnt vmcnt(31)
	ds_write_b32 v22, v58
	s_waitcnt vmcnt(30)
	ds_write_b32 v24, v64
	s_waitcnt vmcnt(29)
	ds_write_b32 v26, v65
	s_waitcnt vmcnt(28)
	ds_write_b32 v28, v66
	s_waitcnt vmcnt(27)
	ds_write_b32 v30, v59
	s_waitcnt vmcnt(26)
	ds_write_b32 v32, v60
	s_waitcnt vmcnt(25)
	ds_write_b32 v34, v67
	s_waitcnt vmcnt(24)
	ds_write_b32 v36, v68
	s_waitcnt vmcnt(23)
	ds_write_b32 v38, v61
	s_waitcnt vmcnt(22)
	ds_write_b32 v40, v62
	s_waitcnt vmcnt(21)
	ds_write_b32 v42, v69
	s_waitcnt vmcnt(20)
	ds_write_b32 v44, v70
	s_waitcnt vmcnt(19)
	ds_write_b32 v46, v8
	s_waitcnt vmcnt(18)
	ds_write_b32 v48, v63
	s_waitcnt vmcnt(17)
	ds_write_b32 v50, v71
	s_waitcnt vmcnt(16)
	ds_write_b32 v52, v72
	s_waitcnt vmcnt(15)
	ds_write_b32 v122, v158
	s_waitcnt vmcnt(14)
	ds_write_b32 v124, v164
	s_waitcnt vmcnt(13)
	ds_write_b32 v126, v165
	s_waitcnt vmcnt(12)
	ds_write_b32 v128, v166
	s_waitcnt vmcnt(11)
	ds_write_b32 v130, v159
	s_waitcnt vmcnt(10)
	ds_write_b32 v132, v160
	s_waitcnt vmcnt(9)
	ds_write_b32 v134, v167
	s_waitcnt vmcnt(8)
	ds_write_b32 v136, v168
	s_waitcnt vmcnt(7)
	ds_write_b32 v138, v161
	s_waitcnt vmcnt(6)
	ds_write_b32 v140, v162
	s_waitcnt vmcnt(5)
	ds_write_b32 v142, v169
	s_waitcnt vmcnt(4)
	ds_write_b32 v144, v170
	s_waitcnt vmcnt(3)
	ds_write_b32 v146, v108
	s_waitcnt vmcnt(2)
	ds_write_b32 v148, v163
	s_waitcnt vmcnt(1)
	ds_write_b32 v150, v171
	s_waitcnt vmcnt(0)
	ds_write_b32 v152, v172
	s_waitcnt lgkmcnt(0)
; #define LAS __attribute__((address_space(3)))
; __device__ __forceinline__ unsigned pk2(float lo, float hi) { return f2bf(lo) | (f2bf(hi) << 16); }
; #define LDS_WAIT() asm volatile("s_waitcnt lgkmcnt(0)" ::: "memory")
; template <bool REMAP> __device__ __forceinline__ void p0_transpose_item(const float* W, int K, int N, bf16r* WT, LAS float* scr, int item, int lane) {
;     ...
;     const int c = lane & 7;
; #pragma unroll
;     for (int j = 0; j < 4; ++j) { const int n = (lane >> 3) + 8 * j; const LAS float* s = scr + (8 * c) * 33 + n;
;         v4u o; o.x = pk2(s[0 * 33], s[1 * 33]); o.y = pk2(s[2 * 33], s[3 * 33]); o.z = pk2(s[4 * 33], s[5 * 33]); o.w = pk2(s[6 * 33], s[7 * 33]);
;         const int rn = slot ? (16 * ((n >> 2) & 1) + 4 * (n >> 3) + (n & 3)) : n;
;         *(v4u*)(WT + (size_t)(r0 + rn) * K + k0 + 8 * c) = o; }
;     LDS_WAIT(); asm volatile("" ::: "memory");
	ds_read2_b32 v[12:13], v14 offset1:8
	ds_read2_b32 v[28:29], v14 offset0:33 offset1:41
	ds_read2_b32 v[30:31], v14 offset0:66 offset1:74
	ds_read2_b32 v[32:33], v14 offset0:99 offset1:107
	ds_read2_b32 v[34:35], v14 offset0:132 offset1:140
	s_waitcnt lgkmcnt(4)
	v_bfe_u32 v3, v12, 16, 1
	v_add3_u32 v3, v12, v3, s22
	s_waitcnt lgkmcnt(3)
	v_bfe_u32 v8, v28, 16, 1
	v_lshrrev_b32_e32 v3, 16, v3
	v_add3_u32 v8, v28, v8, s22
	ds_read2_b32 v[36:37], v14 offset0:165 offset1:173
	v_and_or_b32 v22, v8, s23, v3
	s_waitcnt lgkmcnt(3)
	v_bfe_u32 v3, v30, 16, 1
	v_add3_u32 v3, v30, v3, s22
	s_waitcnt lgkmcnt(2)
	v_bfe_u32 v8, v32, 16, 1
	ds_read2_b32 v[38:39], v14 offset0:198 offset1:206
	v_lshrrev_b32_e32 v3, 16, v3
	v_add3_u32 v8, v32, v8, s22
	ds_read2_b32 v[40:41], v14 offset0:231 offset1:239
	v_and_or_b32 v23, v8, s23, v3
	s_waitcnt lgkmcnt(3)
	v_bfe_u32 v3, v34, 16, 1
	v_add3_u32 v3, v34, v3, s22
	s_waitcnt lgkmcnt(2)
	v_bfe_u32 v8, v36, 16, 1
	s_lshl_b64 s[12:13], s[12:13], 1
	v_lshrrev_b32_e32 v3, 16, v3
	v_add3_u32 v8, v36, v8, s22
	s_add_u32 s12, s17, s12
	v_and_or_b32 v24, v8, s23, v3
	s_waitcnt lgkmcnt(1)
	v_bfe_u32 v3, v38, 16, 1
	s_addc_u32 s13, s18, s13
	s_lshl_b32 s14, s33, 1
	v_add3_u32 v3, v38, v3, s22
	s_waitcnt lgkmcnt(0)
	v_bfe_u32 v8, v40, 16, 1
	s_add_u32 s12, s12, s14
	v_lshrrev_b32_e32 v3, 16, v3
	v_add3_u32 v8, v40, v8, s22
	s_addc_u32 s13, s13, 0
	v_mov_b32_e32 v11, v9
	v_and_or_b32 v25, v8, s23, v3
	v_or_b32_e32 v3, s11, v7
	v_lshl_add_u64 v[26:27], s[12:13], 0, v[10:11]
	v_lshlrev_b32_e32 v8, 11, v3
	v_bfe_u32 v3, v13, 16, 1
	v_lshl_add_u64 v[42:43], v[26:27], 0, v[8:9]
	v_add3_u32 v3, v13, v3, s22
	v_bfe_u32 v8, v29, 16, 1
	v_lshrrev_b32_e32 v3, 16, v3
	v_add3_u32 v8, v29, v8, s22
	global_store_dwordx4 v[42:43], v[22:25], off
	ds_read2_b32 v[12:13], v14 offset0:16 offset1:24
	s_nop 0
	v_and_or_b32 v22, v8, s23, v3
	v_bfe_u32 v3, v31, 16, 1
	v_add3_u32 v3, v31, v3, s22
	v_bfe_u32 v8, v33, 16, 1
	v_lshrrev_b32_e32 v3, 16, v3
	v_add3_u32 v8, v33, v8, s22
	v_and_or_b32 v23, v8, s23, v3
	v_bfe_u32 v3, v35, 16, 1
	v_add3_u32 v3, v35, v3, s22
	v_bfe_u32 v8, v37, 16, 1
	v_lshrrev_b32_e32 v3, 16, v3
	v_add3_u32 v8, v37, v8, s22
	v_and_or_b32 v24, v8, s23, v3
	v_bfe_u32 v3, v39, 16, 1
	v_add3_u32 v3, v39, v3, s22
	v_bfe_u32 v8, v41, 16, 1
	v_lshrrev_b32_e32 v3, 16, v3
	v_add3_u32 v8, v41, v8, s22
	v_and_or_b32 v25, v8, s23, v3
	v_or_b32_e32 v3, s11, v15
	v_lshlrev_b32_e32 v8, 11, v3
	v_lshl_add_u64 v[28:29], v[26:27], 0, v[8:9]
	global_store_dwordx4 v[28:29], v[22:25], off
	ds_read2_b32 v[28:29], v14 offset0:49 offset1:57
	ds_read2_b32 v[30:31], v14 offset0:82 offset1:90
	ds_read2_b32 v[32:33], v14 offset0:115 offset1:123
	s_waitcnt lgkmcnt(3)
	v_bfe_u32 v3, v12, 16, 1
	v_add3_u32 v3, v12, v3, s22
	s_waitcnt lgkmcnt(2)
	v_bfe_u32 v8, v28, 16, 1
	ds_read2_b32 v[34:35], v14 offset0:148 offset1:156
	v_lshrrev_b32_e32 v3, 16, v3
	v_add3_u32 v8, v28, v8, s22
	ds_read2_b32 v[36:37], v14 offset0:181 offset1:189
	v_and_or_b32 v22, v8, s23, v3
	s_waitcnt lgkmcnt(3)
	v_bfe_u32 v3, v30, 16, 1
	v_add3_u32 v3, v30, v3, s22
	s_waitcnt lgkmcnt(2)
	v_bfe_u32 v8, v32, 16, 1
	ds_read2_b32 v[38:39], v14 offset0:214 offset1:222
	v_lshrrev_b32_e32 v3, 16, v3
	v_add3_u32 v8, v32, v8, s22
	ds_read2_b32 v[40:41], v14 offset0:247 offset1:255
	v_and_or_b32 v23, v8, s23, v3
	s_waitcnt lgkmcnt(3)
	v_bfe_u32 v3, v34, 16, 1
	v_add3_u32 v3, v34, v3, s22
	s_waitcnt lgkmcnt(2)
	v_bfe_u32 v8, v36, 16, 1
	v_lshrrev_b32_e32 v3, 16, v3
	v_add3_u32 v8, v36, v8, s22
	v_and_or_b32 v24, v8, s23, v3
	s_waitcnt lgkmcnt(1)
	v_bfe_u32 v3, v38, 16, 1
	v_add3_u32 v3, v38, v3, s22
	s_waitcnt lgkmcnt(0)
	v_bfe_u32 v8, v40, 16, 1
	v_lshrrev_b32_e32 v3, 16, v3
	v_add3_u32 v8, v40, v8, s22
	v_and_or_b32 v25, v8, s23, v3
	v_or_b32_e32 v3, s11, v16
	v_lshlrev_b32_e32 v8, 11, v3
	v_bfe_u32 v3, v13, 16, 1
	v_lshl_add_u64 v[42:43], v[26:27], 0, v[8:9]
	v_add3_u32 v3, v13, v3, s22
	v_bfe_u32 v8, v29, 16, 1
	v_lshrrev_b32_e32 v3, 16, v3
	v_add3_u32 v8, v29, v8, s22
	global_store_dwordx4 v[42:43], v[22:25], off
	s_nop 1
	v_and_or_b32 v22, v8, s23, v3
	v_bfe_u32 v3, v31, 16, 1
	v_add3_u32 v3, v31, v3, s22
	v_bfe_u32 v8, v33, 16, 1
	v_lshrrev_b32_e32 v3, 16, v3
	v_add3_u32 v8, v33, v8, s22
	v_and_or_b32 v23, v8, s23, v3
	v_bfe_u32 v3, v35, 16, 1
	v_add3_u32 v3, v35, v3, s22
	v_bfe_u32 v8, v37, 16, 1
	v_lshrrev_b32_e32 v3, 16, v3
	v_add3_u32 v8, v37, v8, s22
	v_and_or_b32 v24, v8, s23, v3
	v_bfe_u32 v3, v39, 16, 1
	v_add3_u32 v3, v39, v3, s22
	v_bfe_u32 v8, v41, 16, 1
	v_lshrrev_b32_e32 v3, 16, v3
	v_add3_u32 v8, v41, v8, s22
	v_and_or_b32 v25, v8, s23, v3
	v_or_b32_e32 v3, s11, v17
	v_lshlrev_b32_e32 v8, 11, v3
	v_lshl_add_u64 v[12:13], v[26:27], 0, v[8:9]
	global_store_dwordx4 v[12:13], v[22:25], off
	s_waitcnt lgkmcnt(0)
	s_branch .LBB0_8

; template <bool REMAP> __device__ __forceinline__ void p0_transpose_item(const float* W, int K, int N, bf16r* WT, LAS float* scr, int item, int lane) {
;     ...
; #pragma unroll 8
;     for (int i = 0; i < 32; ++i) { const int kk = 2 * i + (lane >> 5); scr[kk * 33 + (lane & 31)] = W[(size_t)(k0 + kk) * N + n0 + (lane & 31)]; }
.LBB0_29:
	s_lshl_b32 s35, s15, 1
	s_lshl_b32 s36, s33, 1
	v_or_b32_e32 v3, s35, v1
	v_or_b32_e32 v8, s36, v2
	s_add_i32 s37, s35, 4
	s_add_i32 s38, s36, 4
	s_add_i32 s39, s35, 8
	s_add_i32 s40, s36, 8
	s_add_i32 s41, s35, 12
	s_add_i32 s42, s36, 12
	s_add_i32 s43, s35, 16
	s_add_i32 s44, s36, 16
	s_add_i32 s45, s35, 20
	s_add_i32 s46, s36, 20
	s_add_i32 s47, s35, 24
	s_add_i32 s48, s36, 24
	s_add_i32 s35, s35, 28
	s_add_i32 s36, s36, 28
	v_add_u32_e32 v11, s13, v3
	v_add_u32_e32 v22, s14, v8
	v_or_b32_e32 v55, s37, v1
	v_or_b32_e32 v57, s38, v2
	v_or_b32_e32 v58, s39, v1
	v_or_b32_e32 v59, s40, v2
	v_or_b32_e32 v60, s41, v1
	v_or_b32_e32 v61, s42, v2
	v_or_b32_e32 v62, s43, v1
	v_or_b32_e32 v63, s44, v2
	v_or_b32_e32 v64, s45, v1
	v_or_b32_e32 v65, s46, v2
	v_or_b32_e32 v66, s47, v1
	v_or_b32_e32 v67, s48, v2
	v_or_b32_e32 v68, s35, v1
	v_or_b32_e32 v69, s36, v2
	v_mul_lo_u32 v22, v22, s30
	v_mul_lo_u32 v24, v11, s30
	v_add_u32_e32 v11, s13, v55
	v_add_u32_e32 v26, s14, v57
	v_add_u32_e32 v27, s13, v58
	v_add_u32_e32 v29, s14, v59
	v_add_u32_e32 v31, s13, v60
	v_add_u32_e32 v33, s14, v61
	v_add_u32_e32 v35, s13, v62
	v_add_u32_e32 v37, s14, v63
	v_add_u32_e32 v39, s13, v64
	v_add_u32_e32 v41, s14, v65
	v_add_u32_e32 v43, s13, v66
	v_add_u32_e32 v45, s14, v67
	v_add_u32_e32 v47, s13, v68
	v_add_u32_e32 v49, s14, v69
	v_ashrrev_i32_e32 v23, 31, v22
	v_mul_lo_u32 v26, v26, s30
	v_mul_lo_u32 v28, v11, s30
	v_mul_lo_u32 v30, v29, s30
	v_mul_lo_u32 v32, v27, s30
	v_mul_lo_u32 v34, v33, s30
	v_mul_lo_u32 v36, v31, s30
	v_mul_lo_u32 v38, v37, s30
	v_mul_lo_u32 v40, v35, s30
	v_mul_lo_u32 v42, v41, s30
	v_mul_lo_u32 v44, v39, s30
	v_mul_lo_u32 v46, v45, s30
	v_mul_lo_u32 v48, v43, s30
	v_mul_lo_u32 v50, v49, s30
	v_mul_lo_u32 v52, v47, s30
	v_ashrrev_i32_e32 v25, 31, v24
	v_lshl_add_u64 v[22:23], v[12:13], 0, v[22:23]
	v_ashrrev_i32_e32 v29, 31, v28
	v_ashrrev_i32_e32 v27, 31, v26
	v_ashrrev_i32_e32 v33, 31, v32
	v_ashrrev_i32_e32 v31, 31, v30
	v_ashrrev_i32_e32 v37, 31, v36
	v_ashrrev_i32_e32 v35, 31, v34
	v_ashrrev_i32_e32 v41, 31, v40
	v_ashrrev_i32_e32 v39, 31, v38
	v_ashrrev_i32_e32 v45, 31, v44
	v_ashrrev_i32_e32 v43, 31, v42
	v_ashrrev_i32_e32 v49, 31, v48
	v_ashrrev_i32_e32 v47, 31, v46
	v_ashrrev_i32_e32 v53, 31, v52
	v_ashrrev_i32_e32 v51, 31, v50
	v_lshl_add_u64 v[24:25], v[12:13], 0, v[24:25]
	v_lshl_add_u64 v[26:27], v[12:13], 0, v[26:27]
	v_lshl_add_u64 v[28:29], v[12:13], 0, v[28:29]
	v_lshl_add_u64 v[30:31], v[12:13], 0, v[30:31]
	v_lshl_add_u64 v[32:33], v[12:13], 0, v[32:33]
	v_lshl_add_u64 v[34:35], v[12:13], 0, v[34:35]
	v_lshl_add_u64 v[36:37], v[12:13], 0, v[36:37]
	v_lshl_add_u64 v[38:39], v[12:13], 0, v[38:39]
	v_lshl_add_u64 v[40:41], v[12:13], 0, v[40:41]
	v_lshl_add_u64 v[42:43], v[12:13], 0, v[42:43]
	v_lshl_add_u64 v[44:45], v[12:13], 0, v[44:45]
	v_lshl_add_u64 v[46:47], v[12:13], 0, v[46:47]
	v_lshl_add_u64 v[48:49], v[12:13], 0, v[48:49]
	v_lshl_add_u64 v[50:51], v[12:13], 0, v[50:51]
	v_lshl_add_u64 v[52:53], v[12:13], 0, v[52:53]
	global_load_dword v11, v[22:23], off
	global_load_dword v70, v[24:25], off
	global_load_dword v71, v[26:27], off
	global_load_dword v72, v[28:29], off
	global_load_dword v73, v[30:31], off
	global_load_dword v74, v[32:33], off
	global_load_dword v75, v[34:35], off
	global_load_dword v76, v[36:37], off
	global_load_dword v77, v[38:39], off
	global_load_dword v78, v[40:41], off
	global_load_dword v79, v[42:43], off
	global_load_dword v80, v[44:45], off
	global_load_dword v81, v[46:47], off
	global_load_dword v82, v[48:49], off
	global_load_dword v83, v[50:51], off
	global_load_dword v84, v[52:53], off
	s_add_i32 s33, s33, 16
	s_add_i32 s15, s15, 16
	s_add_i32 s34, s34, -16
	v_mad_u64_u32 v[22:23], s[36:37], v8, s19, v[6:7]
	s_cmp_lg_u32 s34, 0
	v_mad_u64_u32 v[24:25], s[36:37], v3, s19, v[6:7]
	v_mad_u64_u32 v[26:27], s[36:37], v57, s19, v[6:7]
	v_mad_u64_u32 v[28:29], s[36:37], v55, s19, v[6:7]
	v_mad_u64_u32 v[30:31], s[36:37], v59, s19, v[6:7]
	v_mad_u64_u32 v[32:33], s[36:37], v58, s19, v[6:7]
	v_mad_u64_u32 v[34:35], s[36:37], v61, s19, v[6:7]
	v_mad_u64_u32 v[36:37], s[36:37], v60, s19, v[6:7]
	v_mad_u64_u32 v[38:39], s[36:37], v63, s19, v[6:7]
	v_mad_u64_u32 v[40:41], s[36:37], v62, s19, v[6:7]
	v_mad_u64_u32 v[42:43], s[36:37], v65, s19, v[6:7]
	v_mad_u64_u32 v[44:45], s[36:37], v64, s19, v[6:7]
	v_mad_u64_u32 v[46:47], s[36:37], v67, s19, v[6:7]
	v_mad_u64_u32 v[48:49], s[36:37], v66, s19, v[6:7]
	v_mad_u64_u32 v[50:51], s[36:37], v69, s19, v[6:7]
	v_mad_u64_u32 v[52:53], s[36:37], v68, s19, v[6:7]
	s_lshl_b32 s35, s15, 1
	s_lshl_b32 s36, s33, 1
	v_or_b32_e32 v103, s35, v1
	v_or_b32_e32 v108, s36, v2
	s_add_i32 s37, s35, 4
	s_add_i32 s38, s36, 4
	s_add_i32 s39, s35, 8
	s_add_i32 s40, s36, 8
	s_add_i32 s41, s35, 12
	s_add_i32 s42, s36, 12
	s_add_i32 s43, s35, 16
	s_add_i32 s44, s36, 16
	s_add_i32 s45, s35, 20
	s_add_i32 s46, s36, 20
	s_add_i32 s47, s35, 24
	s_add_i32 s48, s36, 24
	s_add_i32 s35, s35, 28
	s_add_i32 s36, s36, 28
	v_add_u32_e32 v111, s13, v103
	v_add_u32_e32 v122, s14, v108
	v_or_b32_e32 v155, s37, v1
	v_or_b32_e32 v157, s38, v2
	v_or_b32_e32 v158, s39, v1
	v_or_b32_e32 v159, s40, v2
	v_or_b32_e32 v160, s41, v1
	v_or_b32_e32 v161, s42, v2
	v_or_b32_e32 v162, s43, v1
	v_or_b32_e32 v163, s44, v2
	v_or_b32_e32 v164, s45, v1
	v_or_b32_e32 v165, s46, v2
	v_or_b32_e32 v166, s47, v1
	v_or_b32_e32 v167, s48, v2
	v_or_b32_e32 v168, s35, v1
	v_or_b32_e32 v169, s36, v2
	v_mul_lo_u32 v122, v122, s30
	v_mul_lo_u32 v124, v111, s30
	v_add_u32_e32 v111, s13, v155
	v_add_u32_e32 v126, s14, v157
	v_add_u32_e32 v127, s13, v158
	v_add_u32_e32 v129, s14, v159
	v_add_u32_e32 v131, s13, v160
; #define LDS_WAIT() asm volatile("s_waitcnt lgkmcnt(0)" ::: "memory")
; template <bool REMAP> __device__ __forceinline__ void p0_transpose_item(const float* W, int K, int N, bf16r* WT, LAS float* scr, int item, int lane) {
;     ...
; #pragma unroll 8
;     for (int i = 0; i < 32; ++i) { const int kk = 2 * i + (lane >> 5); scr[kk * 33 + (lane & 31)] = W[(size_t)(k0 + kk) * N + n0 + (lane & 31)]; }
;     LDS_WAIT(); asm volatile("" ::: "memory");
	v_add_u32_e32 v133, s14, v161
	v_add_u32_e32 v135, s13, v162
	v_add_u32_e32 v137, s14, v163
	v_add_u32_e32 v139, s13, v164
	v_add_u32_e32 v141, s14, v165
	v_add_u32_e32 v143, s13, v166
	v_add_u32_e32 v145, s14, v167
	v_add_u32_e32 v147, s13, v168
	v_add_u32_e32 v149, s14, v169
	v_ashrrev_i32_e32 v123, 31, v122
	v_mul_lo_u32 v126, v126, s30
	v_mul_lo_u32 v128, v111, s30
	v_mul_lo_u32 v130, v129, s30
	v_mul_lo_u32 v132, v127, s30
	v_mul_lo_u32 v134, v133, s30
	v_mul_lo_u32 v136, v131, s30
	v_mul_lo_u32 v138, v137, s30
	v_mul_lo_u32 v140, v135, s30
	v_mul_lo_u32 v142, v141, s30
	v_mul_lo_u32 v144, v139, s30
	v_mul_lo_u32 v146, v145, s30
	v_mul_lo_u32 v148, v143, s30
	v_mul_lo_u32 v150, v149, s30
	v_mul_lo_u32 v152, v147, s30
	v_ashrrev_i32_e32 v125, 31, v124
	v_lshl_add_u64 v[122:123], v[12:13], 0, v[122:123]
	v_ashrrev_i32_e32 v129, 31, v128
	v_ashrrev_i32_e32 v127, 31, v126
	v_ashrrev_i32_e32 v133, 31, v132
	v_ashrrev_i32_e32 v131, 31, v130
	v_ashrrev_i32_e32 v137, 31, v136
	v_ashrrev_i32_e32 v135, 31, v134
	v_ashrrev_i32_e32 v141, 31, v140
	v_ashrrev_i32_e32 v139, 31, v138
	v_ashrrev_i32_e32 v145, 31, v144
	v_ashrrev_i32_e32 v143, 31, v142
	v_ashrrev_i32_e32 v149, 31, v148
	v_ashrrev_i32_e32 v147, 31, v146
	v_ashrrev_i32_e32 v153, 31, v152
	v_ashrrev_i32_e32 v151, 31, v150
	v_lshl_add_u64 v[124:125], v[12:13], 0, v[124:125]
	v_lshl_add_u64 v[126:127], v[12:13], 0, v[126:127]
	v_lshl_add_u64 v[128:129], v[12:13], 0, v[128:129]
	v_lshl_add_u64 v[130:131], v[12:13], 0, v[130:131]
	v_lshl_add_u64 v[132:133], v[12:13], 0, v[132:133]
	v_lshl_add_u64 v[134:135], v[12:13], 0, v[134:135]
	v_lshl_add_u64 v[136:137], v[12:13], 0, v[136:137]
	v_lshl_add_u64 v[138:139], v[12:13], 0, v[138:139]
	v_lshl_add_u64 v[140:141], v[12:13], 0, v[140:141]
	v_lshl_add_u64 v[142:143], v[12:13], 0, v[142:143]
	v_lshl_add_u64 v[144:145], v[12:13], 0, v[144:145]
	v_lshl_add_u64 v[146:147], v[12:13], 0, v[146:147]
	v_lshl_add_u64 v[148:149], v[12:13], 0, v[148:149]
	v_lshl_add_u64 v[150:151], v[12:13], 0, v[150:151]
	v_lshl_add_u64 v[152:153], v[12:13], 0, v[152:153]
	global_load_dword v111, v[122:123], off
	global_load_dword v170, v[124:125], off
	global_load_dword v171, v[126:127], off
	global_load_dword v172, v[128:129], off
	global_load_dword v173, v[130:131], off
	global_load_dword v174, v[132:133], off
	global_load_dword v175, v[134:135], off
	global_load_dword v176, v[136:137], off
	global_load_dword v177, v[138:139], off
	global_load_dword v178, v[140:141], off
	global_load_dword v179, v[142:143], off
	global_load_dword v180, v[144:145], off
	global_load_dword v181, v[146:147], off
	global_load_dword v182, v[148:149], off
	global_load_dword v183, v[150:151], off
	global_load_dword v184, v[152:153], off
	s_add_i32 s33, s33, 16
	s_add_i32 s15, s15, 16
	s_add_i32 s34, s34, -16
	v_mad_u64_u32 v[122:123], s[36:37], v108, s19, v[6:7]
	s_cmp_lg_u32 s34, 0
	v_mad_u64_u32 v[124:125], s[36:37], v103, s19, v[6:7]
	v_mad_u64_u32 v[126:127], s[36:37], v157, s19, v[6:7]
	v_mad_u64_u32 v[128:129], s[36:37], v155, s19, v[6:7]
	v_mad_u64_u32 v[130:131], s[36:37], v159, s19, v[6:7]
	v_mad_u64_u32 v[132:133], s[36:37], v158, s19, v[6:7]
	v_mad_u64_u32 v[134:135], s[36:37], v161, s19, v[6:7]
	v_mad_u64_u32 v[136:137], s[36:37], v160, s19, v[6:7]
	v_mad_u64_u32 v[138:139], s[36:37], v163, s19, v[6:7]
	v_mad_u64_u32 v[140:141], s[36:37], v162, s19, v[6:7]
	v_mad_u64_u32 v[142:143], s[36:37], v165, s19, v[6:7]
	v_mad_u64_u32 v[144:145], s[36:37], v164, s19, v[6:7]
	v_mad_u64_u32 v[146:147], s[36:37], v167, s19, v[6:7]
	v_mad_u64_u32 v[148:149], s[36:37], v166, s19, v[6:7]
	v_mad_u64_u32 v[150:151], s[36:37], v169, s19, v[6:7]
	v_mad_u64_u32 v[152:153], s[36:37], v168, s19, v[6:7]
	s_waitcnt vmcnt(31)
	ds_write_b32 v22, v11
	s_waitcnt vmcnt(30)
	ds_write_b32 v24, v70
	s_waitcnt vmcnt(29)
	ds_write_b32 v26, v71
	s_waitcnt vmcnt(28)
	ds_write_b32 v28, v72
	s_waitcnt vmcnt(27)
	ds_write_b32 v30, v73
	s_waitcnt vmcnt(26)
	ds_write_b32 v32, v74
	s_waitcnt vmcnt(25)
	ds_write_b32 v34, v75
	s_waitcnt vmcnt(24)
	ds_write_b32 v36, v76
	s_waitcnt vmcnt(23)
	ds_write_b32 v38, v77
	s_waitcnt vmcnt(22)
	ds_write_b32 v40, v78
	s_waitcnt vmcnt(21)
	ds_write_b32 v42, v79
	s_waitcnt vmcnt(20)
	ds_write_b32 v44, v80
	s_waitcnt vmcnt(19)
	ds_write_b32 v46, v81
	s_waitcnt vmcnt(18)
	ds_write_b32 v48, v82
	s_waitcnt vmcnt(17)
	ds_write_b32 v50, v83
	s_waitcnt vmcnt(16)
	ds_write_b32 v52, v84
	s_waitcnt vmcnt(15)
	ds_write_b32 v122, v111
	s_waitcnt vmcnt(14)
	ds_write_b32 v124, v170
	s_waitcnt vmcnt(13)
	ds_write_b32 v126, v171
	s_waitcnt vmcnt(12)
	ds_write_b32 v128, v172
	s_waitcnt vmcnt(11)
	ds_write_b32 v130, v173
	s_waitcnt vmcnt(10)
	ds_write_b32 v132, v174
	s_waitcnt vmcnt(9)
	ds_write_b32 v134, v175
	s_waitcnt vmcnt(8)
	ds_write_b32 v136, v176
	s_waitcnt vmcnt(7)
	ds_write_b32 v138, v177
	s_waitcnt vmcnt(6)
	ds_write_b32 v140, v178
	s_waitcnt vmcnt(5)
	ds_write_b32 v142, v179
	s_waitcnt vmcnt(4)
	ds_write_b32 v144, v180
	s_waitcnt vmcnt(3)
	ds_write_b32 v146, v181
	s_waitcnt vmcnt(2)
	ds_write_b32 v148, v182
	s_waitcnt vmcnt(1)
	ds_write_b32 v150, v183
	s_waitcnt vmcnt(0)
	ds_write_b32 v152, v184
	s_waitcnt lgkmcnt(0)
; #define LAS __attribute__((address_space(3)))
; __device__ __forceinline__ unsigned pk2(float lo, float hi) { return f2bf(lo) | (f2bf(hi) << 16); }
; #define LDS_WAIT() asm volatile("s_waitcnt lgkmcnt(0)" ::: "memory")
; __host__ __device__ __forceinline__ int win_l2p(int l) { return (int)((0xd951ecb8a746032ULL >> (4 * l)) & 15); }
; template <bool REMAP> __device__ __forceinline__ void p0_transpose_item(const float* W, int K, int N, bf16r* WT, LAS float* scr, int item, int lane) {
;     const int nblk = N / 32, kb = item / nblk, nb = item % nblk, k0 = 64 * kb, n0 = 32 * nb, rl = REMAP ? win_row_remap(n0) : n0, r0 = REMAP ? 256 * win_l2p(rl >> 8) + (rl & 255) : n0;
;     const bool slot = REMAP && win_block_plain(n0);
; #pragma unroll 8
;     for (int i = 0; i < 32; ++i) { const int kk = 2 * i + (lane >> 5); scr[kk * 33 + (lane & 31)] = W[(size_t)(k0 + kk) * N + n0 + (lane & 31)]; }
;     LDS_WAIT(); asm volatile("" ::: "memory");
;     const int c = lane & 7;
; #pragma unroll
;     for (int j = 0; j < 4; ++j) { const int n = (lane >> 3) + 8 * j; const LAS float* s = scr + (8 * c) * 33 + n;
;         v4u o; o.x = pk2(s[0 * 33], s[1 * 33]); o.y = pk2(s[2 * 33], s[3 * 33]); o.z = pk2(s[4 * 33], s[5 * 33]); o.w = pk2(s[6 * 33], s[7 * 33]);
;         const int rn = slot ? (16 * ((n >> 2) & 1) + 4 * (n >> 3) + (n & 3)) : n;
;         *(v4u*)(WT + (size_t)(r0 + rn) * K + k0 + 8 * c) = o; }
;     LDS_WAIT(); asm volatile("" ::: "memory");
	s_mul_hi_i32 s13, s10, 0x780000
	s_mul_i32 s10, s10, 0x780000
	ds_read2_b32 v[12:13], v14 offset1:8
	s_add_u32 s33, s20, s10
	ds_read2_b32 v[28:29], v14 offset0:33 offset1:41
	s_addc_u32 s38, s21, s13
	s_add_i32 s10, s12, 0xfffff700
	s_cmp_lt_u32 s10, 0xfffffe00
	ds_read2_b32 v[30:31], v14 offset0:66 offset1:74
	s_cselect_b64 s[12:13], -1, 0
	s_and_b32 s10, s11, 0xfff0
	ds_read2_b32 v[32:33], v14 offset0:99 offset1:107
	s_cmp_lg_u32 s10, 32
	s_waitcnt lgkmcnt(3)
	v_bfe_u32 v3, v12, 16, 1
	s_cselect_b64 s[34:35], -1, 0
	s_ashr_i32 s10, s31, 6
	v_add3_u32 v3, v12, v3, s22
	s_waitcnt lgkmcnt(2)
	v_bfe_u32 v8, v28, 16, 1
	ds_read2_b32 v[34:35], v14 offset0:132 offset1:140
	s_and_b32 s10, s10, -4
	v_lshrrev_b32_e32 v3, 16, v3
	v_add3_u32 v8, v28, v8, s22
	ds_read2_b32 v[36:37], v14 offset0:165 offset1:173
	s_lshr_b64 s[36:37], s[8:9], s10
	v_and_or_b32 v22, v8, s23, v3
	s_waitcnt lgkmcnt(3)
	v_bfe_u32 v3, v30, 16, 1
	s_lshl_b32 s10, s36, 8
	v_add3_u32 v3, v30, v3, s22
	s_waitcnt lgkmcnt(2)
	v_bfe_u32 v8, v32, 16, 1
	ds_read2_b32 v[38:39], v14 offset0:198 offset1:206
	s_and_b32 s10, s10, 0xf00
	s_and_b32 s15, s31, 0xff
	v_lshrrev_b32_e32 v3, 16, v3
	v_add3_u32 v8, v32, v8, s22
	ds_read2_b32 v[40:41], v14 offset0:231 offset1:239
	s_or_b32 s31, s10, s15
	v_and_or_b32 v23, v8, s23, v3
	s_waitcnt lgkmcnt(3)
	v_bfe_u32 v3, v34, 16, 1
	s_cmp_gt_i32 s11, 11
	v_add3_u32 v3, v34, v3, s22
	s_waitcnt lgkmcnt(2)
	v_bfe_u32 v8, v36, 16, 1
	s_cselect_b64 s[10:11], -1, 0
	v_lshrrev_b32_e32 v3, 16, v3
	v_add3_u32 v8, v36, v8, s22
	s_and_b64 s[10:11], s[10:11], s[34:35]
	s_ashr_i32 s15, s14, 31
	v_and_or_b32 v24, v8, s23, v3
	s_waitcnt lgkmcnt(1)
	v_bfe_u32 v3, v38, 16, 1
	s_and_b64 vcc, s[10:11], s[12:13]
	s_lshl_b64 s[10:11], s[14:15], 1
	v_add3_u32 v3, v38, v3, s22
	s_waitcnt lgkmcnt(0)
	v_bfe_u32 v8, v40, 16, 1
	s_add_u32 s10, s33, s10
	v_lshrrev_b32_e32 v3, 16, v3
	v_add3_u32 v8, v40, v8, s22
	s_addc_u32 s11, s38, s11
	v_mov_b32_e32 v11, v9
	v_and_or_b32 v25, v8, s23, v3
	v_cndmask_b32_e32 v3, v7, v18, vcc
	v_lshl_add_u64 v[26:27], s[10:11], 0, v[10:11]
	v_add_lshl_u32 v8, s31, v3, 11
	v_bfe_u32 v3, v13, 16, 1
	v_lshl_add_u64 v[42:43], v[26:27], 0, v[8:9]
	v_add3_u32 v3, v13, v3, s22
	v_bfe_u32 v8, v29, 16, 1
	v_lshrrev_b32_e32 v3, 16, v3
	v_add3_u32 v8, v29, v8, s22
	global_store_dwordx4 v[42:43], v[22:25], off
	ds_read2_b32 v[12:13], v14 offset0:16 offset1:24
	s_nop 0
	v_and_or_b32 v22, v8, s23, v3
	v_bfe_u32 v3, v31, 16, 1
	v_add3_u32 v3, v31, v3, s22
	v_bfe_u32 v8, v33, 16, 1
	v_lshrrev_b32_e32 v3, 16, v3
	v_add3_u32 v8, v33, v8, s22
	v_and_or_b32 v23, v8, s23, v3
	v_bfe_u32 v3, v35, 16, 1
	v_add3_u32 v3, v35, v3, s22
	v_bfe_u32 v8, v37, 16, 1
	v_lshrrev_b32_e32 v3, 16, v3
	v_add3_u32 v8, v37, v8, s22
	v_and_or_b32 v24, v8, s23, v3
	v_bfe_u32 v3, v39, 16, 1
	v_add3_u32 v3, v39, v3, s22
	v_bfe_u32 v8, v41, 16, 1
	v_lshrrev_b32_e32 v3, 16, v3
	v_add3_u32 v8, v41, v8, s22
	v_and_or_b32 v25, v8, s23, v3
	v_cndmask_b32_e32 v3, v15, v19, vcc
	v_add_lshl_u32 v8, s31, v3, 11
	v_lshl_add_u64 v[28:29], v[26:27], 0, v[8:9]
	global_store_dwordx4 v[28:29], v[22:25], off
	ds_read2_b32 v[28:29], v14 offset0:49 offset1:57
	ds_read2_b32 v[30:31], v14 offset0:82 offset1:90
	ds_read2_b32 v[32:33], v14 offset0:115 offset1:123
	s_waitcnt lgkmcnt(3)
	v_bfe_u32 v3, v12, 16, 1
	v_add3_u32 v3, v12, v3, s22
	s_waitcnt lgkmcnt(2)
	v_bfe_u32 v8, v28, 16, 1
	ds_read2_b32 v[34:35], v14 offset0:148 offset1:156
	v_lshrrev_b32_e32 v3, 16, v3
	v_add3_u32 v8, v28, v8, s22
	ds_read2_b32 v[36:37], v14 offset0:181 offset1:189
	v_and_or_b32 v22, v8, s23, v3
	s_waitcnt lgkmcnt(3)
	v_bfe_u32 v3, v30, 16, 1
	v_add3_u32 v3, v30, v3, s22
	s_waitcnt lgkmcnt(2)
	v_bfe_u32 v8, v32, 16, 1
	ds_read2_b32 v[38:39], v14 offset0:214 offset1:222
	v_lshrrev_b32_e32 v3, 16, v3
	v_add3_u32 v8, v32, v8, s22
	ds_read2_b32 v[40:41], v14 offset0:247 offset1:255
	v_and_or_b32 v23, v8, s23, v3
	s_waitcnt lgkmcnt(3)
	v_bfe_u32 v3, v34, 16, 1
	v_add3_u32 v3, v34, v3, s22
	s_waitcnt lgkmcnt(2)
	v_bfe_u32 v8, v36, 16, 1
	v_lshrrev_b32_e32 v3, 16, v3
	v_add3_u32 v8, v36, v8, s22
	v_and_or_b32 v24, v8, s23, v3
	s_waitcnt lgkmcnt(1)
	v_bfe_u32 v3, v38, 16, 1
	v_add3_u32 v3, v38, v3, s22
	s_waitcnt lgkmcnt(0)
	v_bfe_u32 v8, v40, 16, 1
	v_lshrrev_b32_e32 v3, 16, v3
	v_add3_u32 v8, v40, v8, s22
	v_and_or_b32 v25, v8, s23, v3
	v_cndmask_b32_e32 v3, v16, v20, vcc
	v_add_lshl_u32 v8, s31, v3, 11
	v_bfe_u32 v3, v13, 16, 1
	v_lshl_add_u64 v[42:43], v[26:27], 0, v[8:9]
	v_add3_u32 v3, v13, v3, s22
	v_bfe_u32 v8, v29, 16, 1
	v_lshrrev_b32_e32 v3, 16, v3
	v_add3_u32 v8, v29, v8, s22
	global_store_dwordx4 v[42:43], v[22:25], off
	s_nop 1
	v_and_or_b32 v22, v8, s23, v3
	v_bfe_u32 v3, v31, 16, 1
	v_add3_u32 v3, v31, v3, s22
	v_bfe_u32 v8, v33, 16, 1
	v_lshrrev_b32_e32 v3, 16, v3
	v_add3_u32 v8, v33, v8, s22
	v_and_or_b32 v23, v8, s23, v3
	v_bfe_u32 v3, v35, 16, 1
	v_add3_u32 v3, v35, v3, s22
	v_bfe_u32 v8, v37, 16, 1
	v_lshrrev_b32_e32 v3, 16, v3
	v_add3_u32 v8, v37, v8, s22
	v_and_or_b32 v24, v8, s23, v3
	v_bfe_u32 v3, v39, 16, 1
	v_add3_u32 v3, v39, v3, s22
	v_bfe_u32 v8, v41, 16, 1
	v_lshrrev_b32_e32 v3, 16, v3
	v_add3_u32 v8, v41, v8, s22
	v_and_or_b32 v25, v8, s23, v3
	v_cndmask_b32_e32 v3, v17, v21, vcc
	v_add_lshl_u32 v8, s31, v3, 11
	v_lshl_add_u64 v[12:13], v[26:27], 0, v[8:9]
	global_store_dwordx4 v[12:13], v[22:25], off
	s_waitcnt lgkmcnt(0)
	s_branch .LBB0_8

;     __device__ __forceinline__ void sub32(const pg8::f32x4 (&acc)[2][2][4][2], int row0, int wc, int fq, bf16r* dst, const float* gain, float scale, const float2* tseq) const {
;         const pg8::f32x4 g1 = *(const pg8::f32x4*)(gain + 4 * fq), g2 = *(const pg8::f32x4*)(gain + 16 + 4 * fq);
; #pragma unroll
;         for (int ai = 0; ai < 2; ++ai) {
;             pg8::f32x4 cs[4][2];
; #pragma unroll
;             for (int m = 0; m < 4; ++m) { const float2* tab = tseq + ((row0 + ai * 128 + m * 16) & (SEQ - 1)) * 16 + 4 * fq; cs[m][0] = *(const pg8::f32x4*)tab; cs[m][1] = *(const pg8::f32x4*)(tab + 2); }
;             asm volatile("" ::: "memory");
; #pragma unroll
;             for (int m = 0; m < 4; ++m) { const int row = row0 + ai * 128 + m * 16;
;                 const pg8::f32x4 cs01 = cs[m][0], cs23 = cs[m][1];
;                 const float c0 = cs01[0], s0 = cs01[1], c1 = cs01[2], s1 = cs01[3], c2 = cs23[0], s2 = cs23[1], c3 = cs23[2], s3 = cs23[3];
; #pragma unroll
;                 for (int bj = 0; bj < 2; ++bj) { const pg8::f32x4 a = acc[ai][bj][m][0], b = acc[ai][bj][m][1];
;                     float ss = ((a[0] * a[0] + a[1] * a[1]) + (a[2] * a[2] + a[3] * a[3])) + ((b[0] * b[0] + b[1] * b[1]) + (b[2] * b[2] + b[3] * b[3]));
;                     ss += __shfl_xor(ss, 16); ss += __shfl_xor(ss, 32);
;                     const float rs = rsqrtf(ss * (1.f / 32.f) + EPS) * scale;
;                     const pg8::f32x4 x1 = a * g1 * rs, x2 = b * g2 * rs;
;                     store_pair16(dst + (size_t)row * 256 + (4 * bj + wc) * 32, fq, pk4(x1[0] * c0 - x2[0] * s0, x1[1] * c1 - x2[1] * s1, x1[2] * c2 - x2[2] * s2, x1[3] * c3 - x2[3] * s3),
;                                  pk4(x2[0] * c0 + x1[0] * s0, x2[1] * c1 + x1[1] * s1, x2[2] * c2 + x1[2] * s2, x2[3] * c3 + x1[3] * s3));
;                     } } }
;     }
;     __device__ __forceinline__ void operator()(const pg8::f32x4 (&acc)[2][2][4][2], const pg8::Unit& u, int wr, int wc, int fr, int fq) const {
;         constexpr float L2E = 1.4426950408889634f;
;         const int row0 = u.pm * 256 + wr * 64 + fr, pn = win_p2l(u.pn);
;         const KParams P = fresh_params(); unsigned char* ws = P->ws;
;         bf16r* PROJ = (bf16r*)(ws + WS_PROJ); bf16r* QA = (bf16r*)(ws + WS_QA); bf16r* KA = (bf16r*)(ws + WS_KA); bf16r* QC = (bf16r*)(ws + WS_QC); bf16r* KC = (bf16r*)(ws + WS_KC);
.LBB0_233:
	v_readlane_b32 s64, v248, 3
	v_readlane_b32 s65, v248, 4
	s_mov_b32 s14, 0x53c410b2
	s_load_dwordx2 s[62:63], s[64:65], 0xd8
	s_lshl_b32 s2, s2, 2
	s_mov_b32 s15, 0xae986d7
	s_lshl_b32 s1, s3, 8
	s_lshr_b64 s[2:3], s[14:15], s2
	s_add_i32 s1, s1, s86
	s_and_b32 s35, s2, 15
	v_or_b32_e32 v210, s1, v183
	s_mov_b64 s[70:71], -1
	s_mov_b64 s[66:67], 0
	s_cmp_lt_i32 s35, 7
	s_mov_b64 s[68:69], 0
	s_cbranch_scc1 .LBB0_239
	s_waitcnt lgkmcnt(0)
	s_add_u32 s70, s62, 0x100000
	s_addc_u32 s71, s63, 0
	s_cmp_gt_i32 s35, 7
	s_cbranch_scc0 .LBB0_242
	s_cmp_eq_u32 s35, 8
	s_mov_b64 s[68:69], -1
	s_cbranch_scc0 .LBB0_237
	s_load_dwordx2 s[2:3], s[64:65], 0x98
	s_lshl_b64 s[14:15], s[58:59], 2
	v_lshlrev_b32_e32 v0, 2, v184
	v_and_b32_e32 v170, 64, v225
	v_add_u32_e32 v170, 64, v170
	s_waitcnt lgkmcnt(0)
	s_add_u32 s2, s2, s14
	s_addc_u32 s3, s3, s15
	global_load_dwordx4 v[134:137], v0, s[2:3]
	global_load_dwordx4 v[130:133], v0, s[2:3] offset:64
	v_lshlrev_b32_e32 v0, 3, v184
	v_lshl_add_u64 v[172:173], s[70:71], 0, v[0:1]
	v_lshlrev_b32_e32 v0, 1, v186
	v_lshl_add_u64 v[138:139], s[62:63], 0, v[0:1]
	v_lshlrev_b32_e32 v0, 7, v210
	s_mov_b64 s[2:3], 0x18800000
	v_and_b32_e32 v0, 0x7e780, v0
	v_lshl_add_u64 v[174:175], v[138:139], 0, s[2:3]
	v_lshl_add_u64 v[138:139], v[172:173], 0, v[0:1]
	global_load_dwordx4 v[162:165], v[138:139], off offset:16
	global_load_dwordx4 v[166:169], v[138:139], off
	global_load_dwordx4 v[154:157], v[138:139], off offset:2064
	global_load_dwordx4 v[158:161], v[138:139], off offset:2048
	v_add_co_u32_e32 v142, vcc, s75, v138
	v_xor_b32_e32 v0, 16, v225
	s_nop 0
	v_addc_co_u32_e32 v143, vcc, 0, v139, vcc
	v_cmp_lt_i32_e32 vcc, v0, v170
	v_mov_b32_e32 v214, v127
	v_mov_b32_e32 v215, v123
	v_cndmask_b32_e32 v0, v225, v0, vcc
	v_mov_b32_e32 v212, v126
	v_mov_b32_e32 v213, v122
	v_mul_f32_e32 v214, v214, v214
	v_mul_f32_e32 v215, v215, v215
	v_mov_b32_e32 v216, v129
	v_mov_b32_e32 v217, v125
	v_lshlrev_b32_e32 v176, 2, v0
	v_xor_b32_e32 v0, 32, v225
	v_fma_f32 v212, v212, v212, v214
	v_fma_f32 v213, v213, v213, v215
	v_mov_b32_e32 v214, v128
	v_mov_b32_e32 v215, v124
	v_mul_f32_e32 v216, v216, v216
	v_mul_f32_e32 v217, v217, v217
	v_cmp_lt_i32_e32 vcc, v0, v170
	v_fma_f32 v214, v214, v214, v216
	v_fma_f32 v215, v215, v215, v217
	v_ashrrev_i32_e32 v211, 31, v210
	v_cndmask_b32_e32 v0, v225, v0, vcc
	v_add_f32_e32 v212, v212, v214
	v_add_f32_e32 v213, v213, v215
	v_lshlrev_b32_e32 v177, 2, v0
	v_add_f32_e32 v0, v212, v213
	v_lshlrev_b64 v[170:171], 9, v[210:211]
	ds_bpermute_b32 v211, v176, v0
	s_mov_b64 s[2:3], 0x1000
	v_lshl_add_u64 v[140:141], v[138:139], 0, s[2:3]
	s_mov_b64 s[2:3], 0x1800
	v_lshl_add_u64 v[138:139], v[138:139], 0, s[2:3]
	s_waitcnt lgkmcnt(0)
	v_add_f32_e32 v0, v0, v211
	ds_bpermute_b32 v211, v177, v0
	global_load_dwordx4 v[150:153], v[142:143], off
	global_load_dwordx4 v[146:149], v[140:141], off offset:16
	s_nop 0
	global_load_dwordx4 v[142:145], v[142:143], off offset:2048
	s_nop 0
	global_load_dwordx4 v[138:141], v[138:139], off offset:16
	v_lshl_add_u64 v[170:171], v[174:175], 0, v[170:171]
	s_waitcnt lgkmcnt(0)
	v_add_f32_e32 v0, v0, v211
	v_fmamk_f32 v0, v0, 0x3d000000, v219
	v_cmp_gt_f32_e32 vcc, s25, v0
	v_mul_f32_e32 v211, 0x4b800000, v0
	s_lshl_b32 s20, s87, 1
	v_cndmask_b32_e32 v0, v0, v211, vcc
	v_rsq_f32_e32 v0, v0
	v_lshl_add_u64 v[170:171], v[170:171], 0, s[20:21]
	v_lshlrev_b32_e32 v189, 4, v210
	s_mov_b32 s2, 0x10000
	v_mul_f32_e32 v211, 0x45800000, v0
	v_cndmask_b32_e32 v0, v0, v211, vcc
	s_mov_b64 s[68:69], 0
	s_waitcnt vmcnt(0)
	v_mul_f32_e32 v212, v128, v136
	v_mul_f32_e32 v213, v129, v137
	v_mul_f32_e32 v214, v126, v134
	v_mul_f32_e32 v215, v127, v135
	v_mul_f32_e32 v228, v122, v130
	v_mul_f32_e32 v229, v123, v131
	v_mul_f32_e32 v216, v212, v0
	v_mul_f32_e32 v217, v213, v0
	v_mul_f32_e32 v214, v214, v0
	v_mul_f32_e32 v215, v215, v0
	v_mul_f32_e32 v212, v124, v132
	v_mul_f32_e32 v213, v125, v133
	v_mul_f32_e32 v228, v228, v0
	v_mul_f32_e32 v229, v229, v0
	v_mul_f32_e32 v230, v212, v0
	v_mul_f32_e32 v231, v213, v0
	v_mov_b32_e32 v212, v214
	v_mov_b32_e32 v213, v228
	v_mul_f32_e32 v212, v166, v212
	v_mul_f32_e32 v213, v167, v213
	v_mov_b32_e32 v233, v214
	v_sub_f32_e32 v0, v212, v213
	v_mov_b32_e32 v212, v215
	v_mov_b32_e32 v213, v229
	v_mul_f32_e32 v212, v168, v212
	v_mul_f32_e32 v213, v169, v213
	v_mov_b32_e32 v214, v229
	v_sub_f32_e32 v211, v212, v213
	v_mov_b32_e32 v212, v216
	v_mov_b32_e32 v213, v230
	v_mul_f32_e32 v212, v162, v212
	v_mul_f32_e32 v213, v163, v213
	v_mul_f32_e32 v214, v168, v214
	v_mul_f32_e32 v215, v169, v215
	v_sub_f32_e32 v227, v212, v213
	v_mov_b32_e32 v212, v217
	v_mov_b32_e32 v213, v231
	v_mul_f32_e32 v212, v164, v212
	v_mul_f32_e32 v213, v165, v213
	v_mov_b32_e32 v232, v228
	v_sub_f32_e32 v213, v212, v213
	v_cvt_pk_bf16_f32 v212, v0, v211
	v_add_f32_e32 v211, v214, v215
	v_mov_b32_e32 v214, v230
	v_mov_b32_e32 v215, v216
	v_mul_f32_e32 v214, v162, v214
	v_mul_f32_e32 v215, v163, v215
	v_mov_b32_e32 v216, v231
	v_cvt_pk_bf16_f32 v213, v227, v213
	v_add_f32_e32 v227, v214, v215
	v_mul_f32_e32 v214, v164, v216
	v_mul_f32_e32 v215, v165, v217
	v_mul_f32_e32 v232, v166, v232
	v_mul_f32_e32 v233, v167, v233
	v_add_f32_e32 v215, v214, v215
	v_add_f32_e32 v0, v232, v233
	v_cvt_pk_bf16_f32 v214, v0, v211
	v_cvt_pk_bf16_f32 v215, v227, v215
	v_mov_b32_e32 v216, v121
	v_permlane16_swap_b32_e32 v212, v214
	v_permlane16_swap_b32_e32 v213, v215
	global_store_dwordx4 v[170:171], v[212:215], off
	v_mov_b32_e32 v217, v117
	v_mul_f32_e32 v216, v216, v216
	v_mul_f32_e32 v217, v217, v217
	v_mov_b32_e32 v214, v119
	v_mov_b32_e32 v215, v115
	v_mov_b32_e32 v212, v118
	v_mov_b32_e32 v213, v114
	v_mul_f32_e32 v214, v214, v214
	v_mul_f32_e32 v215, v215, v215
	v_mul_f32_e32 v228, v114, v130
	v_mul_f32_e32 v229, v115, v131
	v_fma_f32 v212, v212, v212, v214
	v_fma_f32 v213, v213, v213, v215
	v_mov_b32_e32 v214, v120
	v_mov_b32_e32 v215, v116
	v_fma_f32 v214, v214, v214, v216
	v_fma_f32 v215, v215, v215, v217
	s_nop 0
	v_add_f32_e32 v212, v212, v214
	v_add_f32_e32 v213, v213, v215
	v_mul_f32_e32 v214, v118, v134
	v_mul_f32_e32 v215, v119, v135
	v_add_f32_e32 v0, v212, v213
	ds_bpermute_b32 v211, v176, v0
	v_mul_f32_e32 v212, v120, v136
	v_mul_f32_e32 v213, v121, v137
	s_waitcnt lgkmcnt(0)
;     __device__ __forceinline__ static v2u pk4(float a, float b, float c, float d) { v2u o; o.x = pg8::cvt_pk_bf16(a, b); o.y = pg8::cvt_pk_bf16(c, d); return o; }
;     __device__ __forceinline__ void sub32(const pg8::f32x4 (&acc)[2][2][4][2], int row0, int wc, int fq, bf16r* dst, const float* gain, float scale, const float2* tseq) const {
;         const pg8::f32x4 g1 = *(const pg8::f32x4*)(gain + 4 * fq), g2 = *(const pg8::f32x4*)(gain + 16 + 4 * fq);
; #pragma unroll
;         for (int ai = 0; ai < 2; ++ai) {
;             pg8::f32x4 cs[4][2];
; #pragma unroll
;             for (int m = 0; m < 4; ++m) { const float2* tab = tseq + ((row0 + ai * 128 + m * 16) & (SEQ - 1)) * 16 + 4 * fq; cs[m][0] = *(const pg8::f32x4*)tab; cs[m][1] = *(const pg8::f32x4*)(tab + 2); }
;             asm volatile("" ::: "memory");
; #pragma unroll
;             for (int m = 0; m < 4; ++m) { const int row = row0 + ai * 128 + m * 16;
;                 const pg8::f32x4 cs01 = cs[m][0], cs23 = cs[m][1];
;                 const float c0 = cs01[0], s0 = cs01[1], c1 = cs01[2], s1 = cs01[3], c2 = cs23[0], s2 = cs23[1], c3 = cs23[2], s3 = cs23[3];
; #pragma unroll
;                 for (int bj = 0; bj < 2; ++bj) { const pg8::f32x4 a = acc[ai][bj][m][0], b = acc[ai][bj][m][1];
;                     float ss = ((a[0] * a[0] + a[1] * a[1]) + (a[2] * a[2] + a[3] * a[3])) + ((b[0] * b[0] + b[1] * b[1]) + (b[2] * b[2] + b[3] * b[3]));
;                     ss += __shfl_xor(ss, 16); ss += __shfl_xor(ss, 32);
;                     const float rs = rsqrtf(ss * (1.f / 32.f) + EPS) * scale;
;                     const pg8::f32x4 x1 = a * g1 * rs, x2 = b * g2 * rs;
;                     store_pair16(dst + (size_t)row * 256 + (4 * bj + wc) * 32, fq, pk4(x1[0] * c0 - x2[0] * s0, x1[1] * c1 - x2[1] * s1, x1[2] * c2 - x2[2] * s2, x1[3] * c3 - x2[3] * s3),
;                                  pk4(x2[0] * c0 + x1[0] * s0, x2[1] * c1 + x1[1] * s1, x2[2] * c2 + x1[2] * s2, x2[3] * c3 + x1[3] * s3));
;                     } } }
;     }
	v_add_f32_e32 v0, v0, v211
	ds_bpermute_b32 v211, v177, v0
	s_waitcnt lgkmcnt(0)
	v_add_f32_e32 v0, v0, v211
	v_fmamk_f32 v0, v0, 0x3d000000, v219
	v_cmp_gt_f32_e32 vcc, s25, v0
	v_mul_f32_e32 v211, 0x4b800000, v0
	s_nop 0
	v_cndmask_b32_e32 v0, v0, v211, vcc
	v_rsq_f32_e32 v0, v0
	s_nop 0
	v_mul_f32_e32 v211, 0x45800000, v0
	v_cndmask_b32_e32 v0, v0, v211, vcc
	v_mul_f32_e32 v216, v212, v0
	v_mul_f32_e32 v217, v213, v0
	v_mul_f32_e32 v214, v214, v0
	v_mul_f32_e32 v215, v215, v0
	v_mul_f32_e32 v212, v116, v132
	v_mul_f32_e32 v213, v117, v133
	v_mul_f32_e32 v228, v228, v0
	v_mul_f32_e32 v229, v229, v0
	v_mul_f32_e32 v230, v212, v0
	v_mul_f32_e32 v231, v213, v0
	v_mov_b32_e32 v212, v214
	v_mov_b32_e32 v213, v228
	v_mul_f32_e32 v212, v166, v212
	v_mul_f32_e32 v213, v167, v213
	v_mov_b32_e32 v232, v228
	v_sub_f32_e32 v0, v212, v213
	v_mov_b32_e32 v212, v215
	v_mov_b32_e32 v213, v229
	v_mul_f32_e32 v212, v168, v212
	v_mul_f32_e32 v213, v169, v213
	v_mov_b32_e32 v233, v214
	v_sub_f32_e32 v211, v212, v213
	v_mov_b32_e32 v212, v216
	v_mov_b32_e32 v213, v230
	v_mul_f32_e32 v212, v162, v212
	v_mul_f32_e32 v213, v163, v213
	v_mul_f32_e32 v166, v166, v232
	v_mul_f32_e32 v167, v167, v233
	v_sub_f32_e32 v227, v212, v213
	v_mov_b32_e32 v212, v217
	v_mov_b32_e32 v213, v231
	v_mul_f32_e32 v212, v164, v212
	v_mul_f32_e32 v213, v165, v213
	v_mov_b32_e32 v214, v229
	v_sub_f32_e32 v213, v212, v213
	v_cvt_pk_bf16_f32 v212, v0, v211
	v_add_f32_e32 v0, v166, v167
	v_mul_f32_e32 v166, v168, v214
	v_mul_f32_e32 v167, v169, v215
	v_cvt_pk_bf16_f32 v213, v227, v213
	v_mov_b32_e32 v169, v93
	v_add_f32_e32 v168, v166, v167
	v_mov_b32_e32 v166, v230
	v_mov_b32_e32 v167, v216
	v_mul_f32_e32 v162, v162, v166
	v_mul_f32_e32 v163, v163, v167
	v_mov_b32_e32 v216, v231
	v_add_f32_e32 v166, v162, v163
	v_mul_f32_e32 v162, v164, v216
	v_mul_f32_e32 v163, v165, v217
	v_cvt_pk_bf16_f32 v214, v0, v168
	v_mov_b32_e32 v164, v95
	v_add_f32_e32 v162, v162, v163
	v_cvt_pk_bf16_f32 v215, v166, v162
	v_or_b32_e32 v162, 16, v210
	v_ashrrev_i32_e32 v163, 31, v162
	v_lshlrev_b64 v[162:163], 9, v[162:163]
	v_mov_b32_e32 v165, v91
	v_lshl_add_u64 v[166:167], v[174:175], 0, v[162:163]
	v_mov_b32_e32 v162, v94
	v_mov_b32_e32 v163, v90
	v_mul_f32_e32 v164, v164, v164
	v_mul_f32_e32 v165, v165, v165
	v_mov_b32_e32 v168, v97
	v_fma_f32 v162, v162, v162, v164
	v_fma_f32 v163, v163, v163, v165
	v_mov_b32_e32 v164, v96
	v_mov_b32_e32 v165, v92
	v_mul_f32_e32 v168, v168, v168
	v_mul_f32_e32 v169, v169, v169
	v_permlane16_swap_b32_e32 v212, v214
	v_fma_f32 v164, v164, v164, v168
	v_fma_f32 v165, v165, v165, v169
	v_permlane16_swap_b32_e32 v213, v215
	v_add_f32_e32 v162, v162, v164
	v_add_f32_e32 v163, v163, v165
	global_store_dwordx4 v[170:171], v[212:215], off offset:256
	v_add_f32_e32 v0, v162, v163
	ds_bpermute_b32 v162, v176, v0
	v_mul_f32_e32 v164, v94, v134
	v_mul_f32_e32 v165, v95, v135
	v_mul_f32_e32 v212, v90, v130
	v_mul_f32_e32 v213, v91, v131
	v_lshl_add_u64 v[166:167], v[166:167], 0, s[20:21]
	s_waitcnt lgkmcnt(0)
	v_add_f32_e32 v0, v0, v162
	ds_bpermute_b32 v162, v177, v0
	s_waitcnt lgkmcnt(0)
	v_add_f32_e32 v0, v0, v162
	v_fmamk_f32 v0, v0, 0x3d000000, v219
	v_cmp_gt_f32_e32 vcc, s25, v0
	v_mul_f32_e32 v162, 0x4b800000, v0
	s_nop 0
	v_cndmask_b32_e32 v0, v0, v162, vcc
	v_rsq_f32_e32 v0, v0
	s_nop 0
	v_mul_f32_e32 v162, 0x45800000, v0
	v_cndmask_b32_e32 v0, v0, v162, vcc
	v_mul_f32_e32 v162, v96, v136
	v_mul_f32_e32 v163, v97, v137
	v_mul_f32_e32 v164, v164, v0
	v_mul_f32_e32 v165, v165, v0
	v_mul_f32_e32 v168, v162, v0
	v_mul_f32_e32 v169, v163, v0
	v_mul_f32_e32 v162, v92, v132
	v_mul_f32_e32 v163, v93, v133
	v_mul_f32_e32 v212, v212, v0
	v_mul_f32_e32 v213, v213, v0
	v_mul_f32_e32 v214, v162, v0
	v_mul_f32_e32 v215, v163, v0
	v_mov_b32_e32 v162, v164
	v_mov_b32_e32 v163, v212
	v_mul_f32_e32 v162, v158, v162
	v_mul_f32_e32 v163, v159, v163
	v_mov_b32_e32 v217, v164
	v_sub_f32_e32 v0, v162, v163
	v_mov_b32_e32 v162, v165
	v_mov_b32_e32 v163, v213
	v_mul_f32_e32 v162, v160, v162
	v_mul_f32_e32 v163, v161, v163
	v_mov_b32_e32 v164, v213
	v_sub_f32_e32 v211, v162, v163
	v_mov_b32_e32 v162, v168
	v_mov_b32_e32 v163, v214
	v_mul_f32_e32 v162, v154, v162
	v_mul_f32_e32 v163, v155, v163
	v_mul_f32_e32 v164, v160, v164
	v_mul_f32_e32 v165, v161, v165
	v_sub_f32_e32 v216, v162, v163
	v_mov_b32_e32 v162, v169
	v_mov_b32_e32 v163, v215
	v_mul_f32_e32 v162, v156, v162
	v_mul_f32_e32 v163, v157, v163
	s_nop 0
	v_sub_f32_e32 v163, v162, v163
	v_cvt_pk_bf16_f32 v162, v0, v211
	v_add_f32_e32 v211, v164, v165
	v_mov_b32_e32 v164, v214
	v_mov_b32_e32 v165, v168
	v_mul_f32_e32 v164, v154, v164
	v_mul_f32_e32 v165, v155, v165
	v_mov_b32_e32 v168, v215
	v_cvt_pk_bf16_f32 v163, v216, v163
	v_mov_b32_e32 v216, v212
	v_add_f32_e32 v212, v164, v165
	v_mul_f32_e32 v164, v156, v168
	v_mul_f32_e32 v165, v157, v169
	v_mul_f32_e32 v216, v158, v216
	v_mul_f32_e32 v217, v159, v217
	v_add_f32_e32 v165, v164, v165
	v_add_f32_e32 v0, v216, v217
	v_cvt_pk_bf16_f32 v164, v0, v211
	v_cvt_pk_bf16_f32 v165, v212, v165
	v_mov_b32_e32 v168, v89
	v_permlane16_swap_b32_e32 v162, v164
	v_permlane16_swap_b32_e32 v163, v165
	global_store_dwordx4 v[166:167], v[162:165], off
	v_mov_b32_e32 v169, v85
	v_mul_f32_e32 v168, v168, v168
	v_mul_f32_e32 v169, v169, v169
	v_mov_b32_e32 v164, v87
	v_mov_b32_e32 v165, v83
	v_mov_b32_e32 v162, v86
	v_mov_b32_e32 v163, v82
	v_mul_f32_e32 v164, v164, v164
	v_mul_f32_e32 v165, v165, v165
	v_mul_f32_e32 v212, v82, v130
	v_mul_f32_e32 v213, v83, v131
	v_fma_f32 v162, v162, v162, v164
	v_fma_f32 v163, v163, v163, v165
	v_mov_b32_e32 v164, v88
	v_mov_b32_e32 v165, v84
	v_fma_f32 v164, v164, v164, v168
	v_fma_f32 v165, v165, v165, v169
	s_nop 0
	v_add_f32_e32 v162, v162, v164
	v_add_f32_e32 v163, v163, v165
	v_mul_f32_e32 v164, v86, v134
	v_mul_f32_e32 v165, v87, v135
	v_add_f32_e32 v0, v162, v163
	ds_bpermute_b32 v162, v176, v0
	s_waitcnt lgkmcnt(0)
;     __device__ __forceinline__ static v2u pk4(float a, float b, float c, float d) { v2u o; o.x = pg8::cvt_pk_bf16(a, b); o.y = pg8::cvt_pk_bf16(c, d); return o; }
;     __device__ __forceinline__ void sub32(const pg8::f32x4 (&acc)[2][2][4][2], int row0, int wc, int fq, bf16r* dst, const float* gain, float scale, const float2* tseq) const {
;         const pg8::f32x4 g1 = *(const pg8::f32x4*)(gain + 4 * fq), g2 = *(const pg8::f32x4*)(gain + 16 + 4 * fq);
; #pragma unroll
;         for (int ai = 0; ai < 2; ++ai) {
;             pg8::f32x4 cs[4][2];
; #pragma unroll
;             for (int m = 0; m < 4; ++m) { const float2* tab = tseq + ((row0 + ai * 128 + m * 16) & (SEQ - 1)) * 16 + 4 * fq; cs[m][0] = *(const pg8::f32x4*)tab; cs[m][1] = *(const pg8::f32x4*)(tab + 2); }
;             asm volatile("" ::: "memory");
; #pragma unroll
;             for (int m = 0; m < 4; ++m) { const int row = row0 + ai * 128 + m * 16;
;                 const pg8::f32x4 cs01 = cs[m][0], cs23 = cs[m][1];
;                 const float c0 = cs01[0], s0 = cs01[1], c1 = cs01[2], s1 = cs01[3], c2 = cs23[0], s2 = cs23[1], c3 = cs23[2], s3 = cs23[3];
; #pragma unroll
;                 for (int bj = 0; bj < 2; ++bj) { const pg8::f32x4 a = acc[ai][bj][m][0], b = acc[ai][bj][m][1];
;                     float ss = ((a[0] * a[0] + a[1] * a[1]) + (a[2] * a[2] + a[3] * a[3])) + ((b[0] * b[0] + b[1] * b[1]) + (b[2] * b[2] + b[3] * b[3]));
;                     ss += __shfl_xor(ss, 16); ss += __shfl_xor(ss, 32);
;                     const float rs = rsqrtf(ss * (1.f / 32.f) + EPS) * scale;
;                     const pg8::f32x4 x1 = a * g1 * rs, x2 = b * g2 * rs;
;                     store_pair16(dst + (size_t)row * 256 + (4 * bj + wc) * 32, fq, pk4(x1[0] * c0 - x2[0] * s0, x1[1] * c1 - x2[1] * s1, x1[2] * c2 - x2[2] * s2, x1[3] * c3 - x2[3] * s3),
;                                  pk4(x2[0] * c0 + x1[0] * s0, x2[1] * c1 + x1[1] * s1, x2[2] * c2 + x1[2] * s2, x2[3] * c3 + x1[3] * s3));
;                     } } }
;     }
	v_add_f32_e32 v0, v0, v162
	ds_bpermute_b32 v162, v177, v0
	s_waitcnt lgkmcnt(0)
	v_add_f32_e32 v0, v0, v162
	v_fmamk_f32 v0, v0, 0x3d000000, v219
	v_cmp_gt_f32_e32 vcc, s25, v0
	v_mul_f32_e32 v162, 0x4b800000, v0
	s_nop 0
	v_cndmask_b32_e32 v0, v0, v162, vcc
	v_rsq_f32_e32 v0, v0
	s_nop 0
	v_mul_f32_e32 v162, 0x45800000, v0
	v_cndmask_b32_e32 v0, v0, v162, vcc
	v_mul_f32_e32 v162, v88, v136
	v_mul_f32_e32 v163, v89, v137
	v_mul_f32_e32 v164, v164, v0
	v_mul_f32_e32 v165, v165, v0
	v_mul_f32_e32 v168, v162, v0
	v_mul_f32_e32 v169, v163, v0
	v_mul_f32_e32 v162, v84, v132
	v_mul_f32_e32 v163, v85, v133
	v_mul_f32_e32 v212, v212, v0
	v_mul_f32_e32 v213, v213, v0
	v_mul_f32_e32 v214, v162, v0
	v_mul_f32_e32 v215, v163, v0
	v_mov_b32_e32 v162, v164
	v_mov_b32_e32 v163, v212
	v_mul_f32_e32 v162, v158, v162
	v_mul_f32_e32 v163, v159, v163
	v_mov_b32_e32 v217, v164
	v_sub_f32_e32 v0, v162, v163
	v_mov_b32_e32 v162, v165
	v_mov_b32_e32 v163, v213
	v_mul_f32_e32 v162, v160, v162
	v_mul_f32_e32 v163, v161, v163
	v_mov_b32_e32 v164, v213
	v_sub_f32_e32 v211, v162, v163
	v_mov_b32_e32 v162, v168
	v_mov_b32_e32 v163, v214
	v_mul_f32_e32 v162, v154, v162
	v_mul_f32_e32 v163, v155, v163
	v_mov_b32_e32 v213, v109
	v_sub_f32_e32 v216, v162, v163
	v_mov_b32_e32 v162, v169
	v_mov_b32_e32 v163, v215
	v_mul_f32_e32 v162, v156, v162
	v_mul_f32_e32 v163, v157, v163
	s_nop 0
	v_sub_f32_e32 v163, v162, v163
	v_cvt_pk_bf16_f32 v162, v0, v211
	v_cvt_pk_bf16_f32 v163, v216, v163
	v_mov_b32_e32 v216, v212
	v_mul_f32_e32 v158, v158, v216
	v_mul_f32_e32 v159, v159, v217
	v_mov_b32_e32 v212, v113
	v_add_f32_e32 v0, v158, v159
	v_mul_f32_e32 v158, v160, v164
	v_mul_f32_e32 v159, v161, v165
	v_mov_b32_e32 v161, v61
	v_add_f32_e32 v160, v158, v159
	v_mov_b32_e32 v158, v214
	v_mov_b32_e32 v159, v168
	v_mul_f32_e32 v154, v154, v158
	v_mul_f32_e32 v155, v155, v159
	v_mov_b32_e32 v168, v215
	v_add_f32_e32 v158, v154, v155
	v_mul_f32_e32 v154, v156, v168
	v_mul_f32_e32 v155, v157, v169
	v_cvt_pk_bf16_f32 v164, v0, v160
	v_mov_b32_e32 v156, v63
	v_add_f32_e32 v154, v154, v155
	v_cvt_pk_bf16_f32 v165, v158, v154
	v_or_b32_e32 v154, 32, v210
	v_ashrrev_i32_e32 v155, 31, v154
	v_lshlrev_b64 v[154:155], 9, v[154:155]
	v_mov_b32_e32 v157, v59
	v_lshl_add_u64 v[158:159], v[174:175], 0, v[154:155]
	v_mov_b32_e32 v154, v62
	v_mov_b32_e32 v155, v58
	v_mul_f32_e32 v156, v156, v156
	v_mul_f32_e32 v157, v157, v157
	v_mov_b32_e32 v160, v65
	v_fma_f32 v154, v154, v154, v156
	v_fma_f32 v155, v155, v155, v157
	v_mov_b32_e32 v156, v64
	v_mov_b32_e32 v157, v60
	v_mul_f32_e32 v160, v160, v160
	v_mul_f32_e32 v161, v161, v161
	v_permlane16_swap_b32_e32 v162, v164
	v_fma_f32 v156, v156, v156, v160
	v_fma_f32 v157, v157, v157, v161
	v_permlane16_swap_b32_e32 v163, v165
	v_add_f32_e32 v154, v154, v156
	v_add_f32_e32 v155, v155, v157
	global_store_dwordx4 v[166:167], v[162:165], off offset:256
	v_add_f32_e32 v0, v154, v155
	ds_bpermute_b32 v154, v176, v0
	v_mul_f32_e32 v156, v62, v134
	v_mul_f32_e32 v157, v63, v135
	v_mul_f32_e32 v162, v58, v130
	v_mul_f32_e32 v163, v59, v131
	v_lshl_add_u64 v[158:159], v[158:159], 0, s[20:21]
	v_mul_f32_e32 v212, v212, v212
	v_mul_f32_e32 v213, v213, v213
	s_waitcnt lgkmcnt(0)
	v_add_f32_e32 v0, v0, v154
	ds_bpermute_b32 v154, v177, v0
	v_mul_f32_e32 v214, v106, v130
	v_mul_f32_e32 v215, v107, v131
	s_waitcnt lgkmcnt(0)
	v_add_f32_e32 v0, v0, v154
	v_fmamk_f32 v0, v0, 0x3d000000, v219
	v_cmp_gt_f32_e32 vcc, s25, v0
	v_mul_f32_e32 v154, 0x4b800000, v0
	s_nop 0
	v_cndmask_b32_e32 v0, v0, v154, vcc
	v_rsq_f32_e32 v0, v0
	s_nop 0
	v_mul_f32_e32 v154, 0x45800000, v0
	v_cndmask_b32_e32 v0, v0, v154, vcc
	v_mul_f32_e32 v154, v64, v136
	v_mul_f32_e32 v155, v65, v137
	v_mul_f32_e32 v156, v156, v0
	v_mul_f32_e32 v157, v157, v0
	v_mul_f32_e32 v160, v154, v0
	v_mul_f32_e32 v161, v155, v0
	v_mul_f32_e32 v154, v60, v132
	v_mul_f32_e32 v155, v61, v133
	v_mul_f32_e32 v162, v162, v0
	v_mul_f32_e32 v163, v163, v0
	v_mul_f32_e32 v164, v154, v0
	v_mul_f32_e32 v165, v155, v0
	v_mov_b32_e32 v154, v156
	v_mov_b32_e32 v155, v162
	v_mul_f32_e32 v154, v150, v154
	v_mul_f32_e32 v155, v151, v155
	s_nop 0
	v_sub_f32_e32 v0, v154, v155
	v_mov_b32_e32 v154, v157
	v_mov_b32_e32 v155, v163
	v_mul_f32_e32 v154, v152, v154
	v_mul_f32_e32 v155, v153, v155
	s_nop 0
	v_sub_f32_e32 v166, v154, v155
	v_mov_b32_e32 v154, v160
	v_mov_b32_e32 v155, v164
	v_mul_f32_e32 v154, v146, v154
	v_mul_f32_e32 v155, v147, v155
	s_nop 0
	v_sub_f32_e32 v167, v154, v155
	v_mov_b32_e32 v154, v161
	v_mov_b32_e32 v155, v165
	v_mul_f32_e32 v154, v148, v154
	v_mul_f32_e32 v155, v149, v155
	s_nop 0
	v_sub_f32_e32 v155, v154, v155
	v_cvt_pk_bf16_f32 v154, v0, v166
	v_cvt_pk_bf16_f32 v155, v167, v155
	v_mov_b32_e32 v167, v156
	v_mov_b32_e32 v156, v163
	v_mul_f32_e32 v156, v152, v156
	v_mul_f32_e32 v157, v153, v157
	v_mov_b32_e32 v166, v162
	v_add_f32_e32 v162, v156, v157
	v_mov_b32_e32 v156, v164
	v_mov_b32_e32 v157, v160
	v_mul_f32_e32 v156, v146, v156
	v_mul_f32_e32 v157, v147, v157
	v_mov_b32_e32 v160, v165
	v_add_f32_e32 v163, v156, v157
	v_mul_f32_e32 v156, v148, v160
	v_mul_f32_e32 v157, v149, v161
	v_mul_f32_e32 v166, v150, v166
	v_mul_f32_e32 v167, v151, v167
	v_add_f32_e32 v157, v156, v157
	v_add_f32_e32 v0, v166, v167
	v_cvt_pk_bf16_f32 v156, v0, v162
	v_cvt_pk_bf16_f32 v157, v163, v157
	v_mov_b32_e32 v160, v57
	v_permlane16_swap_b32_e32 v154, v156
	v_permlane16_swap_b32_e32 v155, v157
	global_store_dwordx4 v[158:159], v[154:157], off
	v_mov_b32_e32 v161, v53
	v_mul_f32_e32 v160, v160, v160
	v_mul_f32_e32 v161, v161, v161
	v_mov_b32_e32 v156, v55
	v_mov_b32_e32 v157, v51
	v_mov_b32_e32 v154, v54
	v_mov_b32_e32 v155, v50
	v_mul_f32_e32 v156, v156, v156
	v_mul_f32_e32 v157, v157, v157
	v_mul_f32_e32 v162, v50, v130
	v_mul_f32_e32 v163, v51, v131
	v_fma_f32 v154, v154, v154, v156
	v_fma_f32 v155, v155, v155, v157
	v_mov_b32_e32 v156, v56
	v_mov_b32_e32 v157, v52
	v_fma_f32 v156, v156, v156, v160
	v_fma_f32 v157, v157, v157, v161
	s_nop 0
	v_add_f32_e32 v154, v154, v156
	v_add_f32_e32 v155, v155, v157
	v_mul_f32_e32 v156, v54, v134
	v_mul_f32_e32 v157, v55, v135
	v_add_f32_e32 v0, v154, v155
	ds_bpermute_b32 v154, v176, v0
	s_waitcnt lgkmcnt(0)
;     __device__ __forceinline__ static v2u pk4(float a, float b, float c, float d) { v2u o; o.x = pg8::cvt_pk_bf16(a, b); o.y = pg8::cvt_pk_bf16(c, d); return o; }
;     __device__ __forceinline__ void sub32(const pg8::f32x4 (&acc)[2][2][4][2], int row0, int wc, int fq, bf16r* dst, const float* gain, float scale, const float2* tseq) const {
;         const pg8::f32x4 g1 = *(const pg8::f32x4*)(gain + 4 * fq), g2 = *(const pg8::f32x4*)(gain + 16 + 4 * fq);
; #pragma unroll
;         for (int ai = 0; ai < 2; ++ai) {
;             pg8::f32x4 cs[4][2];
; #pragma unroll
;             for (int m = 0; m < 4; ++m) { const float2* tab = tseq + ((row0 + ai * 128 + m * 16) & (SEQ - 1)) * 16 + 4 * fq; cs[m][0] = *(const pg8::f32x4*)tab; cs[m][1] = *(const pg8::f32x4*)(tab + 2); }
;             asm volatile("" ::: "memory");
; #pragma unroll
;             for (int m = 0; m < 4; ++m) { const int row = row0 + ai * 128 + m * 16;
;                 const pg8::f32x4 cs01 = cs[m][0], cs23 = cs[m][1];
;                 const float c0 = cs01[0], s0 = cs01[1], c1 = cs01[2], s1 = cs01[3], c2 = cs23[0], s2 = cs23[1], c3 = cs23[2], s3 = cs23[3];
; #pragma unroll
;                 for (int bj = 0; bj < 2; ++bj) { const pg8::f32x4 a = acc[ai][bj][m][0], b = acc[ai][bj][m][1];
;                     float ss = ((a[0] * a[0] + a[1] * a[1]) + (a[2] * a[2] + a[3] * a[3])) + ((b[0] * b[0] + b[1] * b[1]) + (b[2] * b[2] + b[3] * b[3]));
;                     ss += __shfl_xor(ss, 16); ss += __shfl_xor(ss, 32);
;                     const float rs = rsqrtf(ss * (1.f / 32.f) + EPS) * scale;
;                     const pg8::f32x4 x1 = a * g1 * rs, x2 = b * g2 * rs;
;                     store_pair16(dst + (size_t)row * 256 + (4 * bj + wc) * 32, fq, pk4(x1[0] * c0 - x2[0] * s0, x1[1] * c1 - x2[1] * s1, x1[2] * c2 - x2[2] * s2, x1[3] * c3 - x2[3] * s3),
;                                  pk4(x2[0] * c0 + x1[0] * s0, x2[1] * c1 + x1[1] * s1, x2[2] * c2 + x1[2] * s2, x2[3] * c3 + x1[3] * s3));
;                     } } }
;     }
	v_add_f32_e32 v0, v0, v154
	ds_bpermute_b32 v154, v177, v0
	s_waitcnt lgkmcnt(0)
	v_add_f32_e32 v0, v0, v154
	v_fmamk_f32 v0, v0, 0x3d000000, v219
	v_cmp_gt_f32_e32 vcc, s25, v0
	v_mul_f32_e32 v154, 0x4b800000, v0
	s_nop 0
	v_cndmask_b32_e32 v0, v0, v154, vcc
	v_rsq_f32_e32 v0, v0
	s_nop 0
	v_mul_f32_e32 v154, 0x45800000, v0
	v_cndmask_b32_e32 v0, v0, v154, vcc
	v_mul_f32_e32 v154, v56, v136
	v_mul_f32_e32 v155, v57, v137
	v_mul_f32_e32 v156, v156, v0
	v_mul_f32_e32 v157, v157, v0
	v_mul_f32_e32 v160, v154, v0
	v_mul_f32_e32 v161, v155, v0
	v_mul_f32_e32 v154, v52, v132
	v_mul_f32_e32 v155, v53, v133
	v_mul_f32_e32 v162, v162, v0
	v_mul_f32_e32 v163, v163, v0
	v_mul_f32_e32 v164, v154, v0
	v_mul_f32_e32 v165, v155, v0
	v_mov_b32_e32 v154, v156
	v_mov_b32_e32 v155, v162
	v_mul_f32_e32 v154, v150, v154
	v_mul_f32_e32 v155, v151, v155
	s_nop 0
	v_sub_f32_e32 v0, v154, v155
	v_mov_b32_e32 v154, v157
	v_mov_b32_e32 v155, v163
	v_mul_f32_e32 v154, v152, v154
	v_mul_f32_e32 v155, v153, v155
	s_nop 0
	v_sub_f32_e32 v166, v154, v155
	v_mov_b32_e32 v154, v160
	v_mov_b32_e32 v155, v164
	v_mul_f32_e32 v154, v146, v154
	v_mul_f32_e32 v155, v147, v155
	s_nop 0
	v_sub_f32_e32 v167, v154, v155
	v_mov_b32_e32 v154, v161
	v_mov_b32_e32 v155, v165
	v_mul_f32_e32 v154, v148, v154
	v_mul_f32_e32 v155, v149, v155
	s_nop 0
	v_sub_f32_e32 v155, v154, v155
	v_cvt_pk_bf16_f32 v154, v0, v166
	v_cvt_pk_bf16_f32 v155, v167, v155
	v_mov_b32_e32 v166, v162
	v_mov_b32_e32 v167, v156
	v_mul_f32_e32 v150, v150, v166
	v_mul_f32_e32 v151, v151, v167
	v_mov_b32_e32 v156, v163
	v_add_f32_e32 v0, v150, v151
	v_mul_f32_e32 v150, v152, v156
	v_mul_f32_e32 v151, v153, v157
	v_mov_b32_e32 v153, v29
	v_add_f32_e32 v152, v150, v151
	v_mov_b32_e32 v150, v164
	v_mov_b32_e32 v151, v160
	v_mul_f32_e32 v146, v146, v150
	v_mul_f32_e32 v147, v147, v151
	v_mov_b32_e32 v160, v165
	v_add_f32_e32 v150, v146, v147
	v_mul_f32_e32 v146, v148, v160
	v_mul_f32_e32 v147, v149, v161
	v_cvt_pk_bf16_f32 v156, v0, v152
	v_mov_b32_e32 v148, v31
	v_add_f32_e32 v146, v146, v147
	v_cvt_pk_bf16_f32 v157, v150, v146
	v_or_b32_e32 v146, 48, v210
	v_ashrrev_i32_e32 v147, 31, v146
	v_lshlrev_b64 v[146:147], 9, v[146:147]
	v_mov_b32_e32 v149, v27
	v_lshl_add_u64 v[150:151], v[174:175], 0, v[146:147]
	v_mov_b32_e32 v146, v30
	v_mov_b32_e32 v147, v26
	v_mul_f32_e32 v148, v148, v148
	v_mul_f32_e32 v149, v149, v149
	v_mov_b32_e32 v152, v33
	v_fma_f32 v146, v146, v146, v148
	v_fma_f32 v147, v147, v147, v149
	v_mov_b32_e32 v148, v32
	v_mov_b32_e32 v149, v28
	v_mul_f32_e32 v152, v152, v152
	v_mul_f32_e32 v153, v153, v153
	v_permlane16_swap_b32_e32 v154, v156
	v_fma_f32 v148, v148, v148, v152
	v_fma_f32 v149, v149, v149, v153
	v_permlane16_swap_b32_e32 v155, v157
	v_add_f32_e32 v146, v146, v148
	v_add_f32_e32 v147, v147, v149
	global_store_dwordx4 v[158:159], v[154:157], off offset:256
	v_add_f32_e32 v0, v146, v147
	ds_bpermute_b32 v146, v176, v0
	v_mul_f32_e32 v148, v30, v134
	v_mul_f32_e32 v149, v31, v135
	v_mul_f32_e32 v154, v26, v130
	v_mul_f32_e32 v155, v27, v131
	v_lshl_add_u64 v[150:151], v[150:151], 0, s[20:21]
	v_mov_b32_e32 v174, v111
	s_waitcnt lgkmcnt(0)
	v_add_f32_e32 v0, v0, v146
	ds_bpermute_b32 v146, v177, v0
	v_mov_b32_e32 v175, v107
	v_mul_f32_e32 v174, v174, v174
	v_mul_f32_e32 v175, v175, v175
	s_waitcnt lgkmcnt(0)
	v_add_f32_e32 v0, v0, v146
	v_fmamk_f32 v0, v0, 0x3d000000, v219
	v_cmp_gt_f32_e32 vcc, s25, v0
	v_mul_f32_e32 v146, 0x4b800000, v0
	s_nop 0
	v_cndmask_b32_e32 v0, v0, v146, vcc
	v_rsq_f32_e32 v0, v0
	s_nop 0
	v_mul_f32_e32 v146, 0x45800000, v0
	v_cndmask_b32_e32 v0, v0, v146, vcc
	v_mul_f32_e32 v146, v32, v136
	v_mul_f32_e32 v147, v33, v137
	v_mul_f32_e32 v148, v148, v0
	v_mul_f32_e32 v149, v149, v0
	v_mul_f32_e32 v152, v146, v0
	v_mul_f32_e32 v153, v147, v0
	v_mul_f32_e32 v146, v28, v132
	v_mul_f32_e32 v147, v29, v133
	v_mul_f32_e32 v154, v154, v0
	v_mul_f32_e32 v155, v155, v0
	v_mul_f32_e32 v156, v146, v0
	v_mul_f32_e32 v157, v147, v0
	v_mov_b32_e32 v146, v148
	v_mov_b32_e32 v147, v154
	v_mul_f32_e32 v146, v142, v146
	v_mul_f32_e32 v147, v143, v147
	s_nop 0
	v_sub_f32_e32 v0, v146, v147
	v_mov_b32_e32 v146, v149
	v_mov_b32_e32 v147, v155
	v_mul_f32_e32 v146, v144, v146
	v_mul_f32_e32 v147, v145, v147
	s_nop 0
	v_sub_f32_e32 v158, v146, v147
	v_mov_b32_e32 v146, v152
	v_mov_b32_e32 v147, v156
	v_mul_f32_e32 v146, v138, v146
	v_mul_f32_e32 v147, v139, v147
	s_nop 0
	v_sub_f32_e32 v159, v146, v147
	v_mov_b32_e32 v146, v153
	v_mov_b32_e32 v147, v157
	v_mul_f32_e32 v146, v140, v146
	v_mul_f32_e32 v147, v141, v147
	s_nop 0
	v_sub_f32_e32 v147, v146, v147
	v_cvt_pk_bf16_f32 v146, v0, v158
	v_cvt_pk_bf16_f32 v147, v159, v147
	v_mov_b32_e32 v159, v148
	v_mov_b32_e32 v148, v155
	v_mul_f32_e32 v148, v144, v148
	v_mul_f32_e32 v149, v145, v149
	v_mov_b32_e32 v158, v154
	v_add_f32_e32 v154, v148, v149
	v_mov_b32_e32 v148, v156
	v_mov_b32_e32 v149, v152
	v_mul_f32_e32 v148, v138, v148
	v_mul_f32_e32 v149, v139, v149
	v_mov_b32_e32 v152, v157
	v_add_f32_e32 v155, v148, v149
	v_mul_f32_e32 v148, v140, v152
	v_mul_f32_e32 v149, v141, v153
	v_mul_f32_e32 v158, v142, v158
	v_mul_f32_e32 v159, v143, v159
	v_add_f32_e32 v149, v148, v149
	v_add_f32_e32 v0, v158, v159
	v_cvt_pk_bf16_f32 v148, v0, v154
	v_cvt_pk_bf16_f32 v149, v155, v149
	v_mov_b32_e32 v152, v25
	v_permlane16_swap_b32_e32 v146, v148
	v_permlane16_swap_b32_e32 v147, v149
	global_store_dwordx4 v[150:151], v[146:149], off
	v_mov_b32_e32 v153, v21
	v_mul_f32_e32 v152, v152, v152
	v_mul_f32_e32 v153, v153, v153
	v_mov_b32_e32 v148, v23
	v_mov_b32_e32 v149, v19
	v_mov_b32_e32 v146, v22
	v_mov_b32_e32 v147, v18
	v_mul_f32_e32 v148, v148, v148
	v_mul_f32_e32 v149, v149, v149
	v_mul_f32_e32 v154, v18, v130
	v_mul_f32_e32 v155, v19, v131
	v_fma_f32 v146, v146, v146, v148
	v_fma_f32 v147, v147, v147, v149
	v_mov_b32_e32 v148, v24
	v_mov_b32_e32 v149, v20
	v_fma_f32 v148, v148, v148, v152
	v_fma_f32 v149, v149, v149, v153
	s_nop 0
	v_add_f32_e32 v146, v146, v148
	v_add_f32_e32 v147, v147, v149
	v_mul_f32_e32 v148, v22, v134
	v_mul_f32_e32 v149, v23, v135
	v_add_f32_e32 v0, v146, v147
	ds_bpermute_b32 v146, v176, v0
	s_waitcnt lgkmcnt(0)
;     __device__ __forceinline__ static v2u pk4(float a, float b, float c, float d) { v2u o; o.x = pg8::cvt_pk_bf16(a, b); o.y = pg8::cvt_pk_bf16(c, d); return o; }
;     __device__ __forceinline__ void sub32(const pg8::f32x4 (&acc)[2][2][4][2], int row0, int wc, int fq, bf16r* dst, const float* gain, float scale, const float2* tseq) const {
;         const pg8::f32x4 g1 = *(const pg8::f32x4*)(gain + 4 * fq), g2 = *(const pg8::f32x4*)(gain + 16 + 4 * fq);
; #pragma unroll
;         for (int ai = 0; ai < 2; ++ai) {
;             pg8::f32x4 cs[4][2];
; #pragma unroll
;             for (int m = 0; m < 4; ++m) { const float2* tab = tseq + ((row0 + ai * 128 + m * 16) & (SEQ - 1)) * 16 + 4 * fq; cs[m][0] = *(const pg8::f32x4*)tab; cs[m][1] = *(const pg8::f32x4*)(tab + 2); }
;             asm volatile("" ::: "memory");
; #pragma unroll
;             for (int m = 0; m < 4; ++m) { const int row = row0 + ai * 128 + m * 16;
;                 const pg8::f32x4 cs01 = cs[m][0], cs23 = cs[m][1];
;                 const float c0 = cs01[0], s0 = cs01[1], c1 = cs01[2], s1 = cs01[3], c2 = cs23[0], s2 = cs23[1], c3 = cs23[2], s3 = cs23[3];
; #pragma unroll
;                 for (int bj = 0; bj < 2; ++bj) { const pg8::f32x4 a = acc[ai][bj][m][0], b = acc[ai][bj][m][1];
;                     float ss = ((a[0] * a[0] + a[1] * a[1]) + (a[2] * a[2] + a[3] * a[3])) + ((b[0] * b[0] + b[1] * b[1]) + (b[2] * b[2] + b[3] * b[3]));
;                     ss += __shfl_xor(ss, 16); ss += __shfl_xor(ss, 32);
;                     const float rs = rsqrtf(ss * (1.f / 32.f) + EPS) * scale;
;                     const pg8::f32x4 x1 = a * g1 * rs, x2 = b * g2 * rs;
;                     store_pair16(dst + (size_t)row * 256 + (4 * bj + wc) * 32, fq, pk4(x1[0] * c0 - x2[0] * s0, x1[1] * c1 - x2[1] * s1, x1[2] * c2 - x2[2] * s2, x1[3] * c3 - x2[3] * s3),
;                                  pk4(x2[0] * c0 + x1[0] * s0, x2[1] * c1 + x1[1] * s1, x2[2] * c2 + x1[2] * s2, x2[3] * c3 + x1[3] * s3));
;                     } } }
;     }
	v_add_f32_e32 v0, v0, v146
	ds_bpermute_b32 v146, v177, v0
	s_waitcnt lgkmcnt(0)
	v_add_f32_e32 v0, v0, v146
	v_fmamk_f32 v0, v0, 0x3d000000, v219
	v_cmp_gt_f32_e32 vcc, s25, v0
	v_mul_f32_e32 v146, 0x4b800000, v0
	s_nop 0
	v_cndmask_b32_e32 v0, v0, v146, vcc
	v_rsq_f32_e32 v0, v0
	s_nop 0
	v_mul_f32_e32 v146, 0x45800000, v0
	v_cndmask_b32_e32 v0, v0, v146, vcc
	v_mul_f32_e32 v146, v24, v136
	v_mul_f32_e32 v147, v25, v137
	v_mul_f32_e32 v148, v148, v0
	v_mul_f32_e32 v149, v149, v0
	v_mul_f32_e32 v152, v146, v0
	v_mul_f32_e32 v153, v147, v0
	v_mul_f32_e32 v146, v20, v132
	v_mul_f32_e32 v147, v21, v133
	v_mul_f32_e32 v154, v154, v0
	v_mul_f32_e32 v155, v155, v0
	v_mul_f32_e32 v156, v146, v0
	v_mul_f32_e32 v157, v147, v0
	v_mov_b32_e32 v146, v148
	v_mov_b32_e32 v147, v154
	v_mul_f32_e32 v146, v142, v146
	v_mul_f32_e32 v147, v143, v147
	s_nop 0
	v_sub_f32_e32 v0, v146, v147
	v_mov_b32_e32 v146, v149
	v_mov_b32_e32 v147, v155
	v_mul_f32_e32 v146, v144, v146
	v_mul_f32_e32 v147, v145, v147
	s_nop 0
	v_sub_f32_e32 v158, v146, v147
	v_mov_b32_e32 v146, v152
	v_mov_b32_e32 v147, v156
	v_mul_f32_e32 v146, v138, v146
	v_mul_f32_e32 v147, v139, v147
	s_nop 0
	v_sub_f32_e32 v159, v146, v147
	v_mov_b32_e32 v146, v153
	v_mov_b32_e32 v147, v157
	v_mul_f32_e32 v146, v140, v146
	v_mul_f32_e32 v147, v141, v147
	s_nop 0
	v_sub_f32_e32 v147, v146, v147
	v_cvt_pk_bf16_f32 v146, v0, v158
	v_cvt_pk_bf16_f32 v147, v159, v147
	v_mov_b32_e32 v158, v154
	v_mov_b32_e32 v159, v148
	v_mul_f32_e32 v142, v142, v158
	v_mul_f32_e32 v143, v143, v159
	v_mov_b32_e32 v148, v155
	v_add_f32_e32 v0, v142, v143
	v_mul_f32_e32 v142, v144, v148
	v_mul_f32_e32 v143, v145, v149
	s_nop 0
	v_add_f32_e32 v144, v142, v143
	v_mov_b32_e32 v142, v156
	v_mov_b32_e32 v143, v152
	v_mul_f32_e32 v138, v138, v142
	v_mul_f32_e32 v139, v139, v143
	v_mov_b32_e32 v152, v157
	v_add_f32_e32 v142, v138, v139
	v_mul_f32_e32 v138, v140, v152
	v_mul_f32_e32 v139, v141, v153
	v_cvt_pk_bf16_f32 v148, v0, v144
	v_add_u32_e32 v0, 0x800, v189
	v_add_f32_e32 v138, v138, v139
	v_cvt_pk_bf16_f32 v149, v142, v138
	v_and_b32_e32 v0, 0xfcf0, v0
	v_permlane16_swap_b32_e32 v146, v148
	v_permlane16_swap_b32_e32 v147, v149
	v_lshlrev_b32_e32 v0, 3, v0
	global_store_dwordx4 v[150:151], v[146:149], off offset:256
	v_lshl_add_u64 v[138:139], v[172:173], 0, v[0:1]
	global_load_dwordx4 v[162:165], v[138:139], off offset:16
	global_load_dwordx4 v[166:169], v[138:139], off
	v_add_u32_e32 v0, 0x900, v189
	v_and_b32_e32 v0, 0xfdf0, v0
	v_lshlrev_b32_e32 v0, 3, v0
	v_lshl_add_u64 v[138:139], v[172:173], 0, v[0:1]
	v_add_u32_e32 v0, 0xa00, v189
	v_and_b32_e32 v0, 0xfef0, v0
	v_lshlrev_b32_e32 v0, 3, v0
	global_load_dwordx4 v[154:157], v[138:139], off offset:16
	global_load_dwordx4 v[158:161], v[138:139], off
	v_lshl_add_u64 v[138:139], v[172:173], 0, v[0:1]
	v_add_u32_e32 v0, 0xb00, v189
	v_and_b32_e32 v0, 0xfff0, v0
	v_lshlrev_b32_e32 v0, 3, v0
	v_lshl_add_u64 v[142:143], v[172:173], 0, v[0:1]
	v_mov_b32_e32 v172, v110
	v_mov_b32_e32 v173, v106
	v_fma_f32 v172, v172, v172, v174
	v_fma_f32 v173, v173, v173, v175
	v_mov_b32_e32 v174, v112
	v_mov_b32_e32 v175, v108
	v_fma_f32 v174, v174, v174, v212
	v_fma_f32 v175, v175, v175, v213
	global_load_dwordx4 v[146:149], v[138:139], off offset:16
	global_load_dwordx4 v[150:153], v[138:139], off
	v_add_f32_e32 v172, v172, v174
	v_add_f32_e32 v173, v173, v175
	v_mul_f32_e32 v174, v110, v134
	v_mul_f32_e32 v175, v111, v135
	v_add_f32_e32 v0, v172, v173
	ds_bpermute_b32 v172, v176, v0
	global_load_dwordx4 v[138:141], v[142:143], off offset:16
	s_nop 0
	global_load_dwordx4 v[142:145], v[142:143], off
	s_waitcnt lgkmcnt(0)
	v_add_f32_e32 v0, v0, v172
	ds_bpermute_b32 v172, v177, v0
	s_waitcnt lgkmcnt(0)
	v_add_f32_e32 v0, v0, v172
	v_fmamk_f32 v0, v0, 0x3d000000, v219
	v_cmp_gt_f32_e32 vcc, s25, v0
	v_mul_f32_e32 v172, 0x4b800000, v0
	s_nop 0
	v_cndmask_b32_e32 v0, v0, v172, vcc
	v_rsq_f32_e32 v0, v0
	s_nop 0
	v_mul_f32_e32 v172, 0x45800000, v0
	v_cndmask_b32_e32 v0, v0, v172, vcc
	v_mul_f32_e32 v172, v112, v136
	v_mul_f32_e32 v173, v113, v137
	v_mul_f32_e32 v174, v174, v0
	v_mul_f32_e32 v175, v175, v0
	v_mul_f32_e32 v212, v172, v0
	v_mul_f32_e32 v213, v173, v0
	v_mul_f32_e32 v172, v108, v132
	v_mul_f32_e32 v173, v109, v133
	v_mul_f32_e32 v214, v214, v0
	v_mul_f32_e32 v215, v215, v0
	v_mul_f32_e32 v216, v172, v0
	v_mul_f32_e32 v217, v173, v0
	v_mov_b32_e32 v172, v174
	v_mov_b32_e32 v173, v214
	v_mov_b32_e32 v229, v174
	v_mov_b32_e32 v174, v215
	v_mov_b32_e32 v228, v214
	v_add_co_u32_e32 v214, vcc, s2, v170
	s_mov_b64 s[2:3], 0x12000
	s_waitcnt vmcnt(6)
	v_mul_f32_e32 v172, v166, v172
	v_mul_f32_e32 v173, v167, v173
	s_nop 0
	v_sub_f32_e32 v0, v172, v173
	v_mov_b32_e32 v172, v175
	v_mov_b32_e32 v173, v215
	v_mul_f32_e32 v172, v168, v172
	v_mul_f32_e32 v173, v169, v173
	v_mul_f32_e32 v174, v168, v174
	v_mul_f32_e32 v175, v169, v175
	v_sub_f32_e32 v189, v172, v173
	v_mov_b32_e32 v172, v212
	v_mov_b32_e32 v173, v216
	v_mul_f32_e32 v172, v162, v172
	v_mul_f32_e32 v173, v163, v173
	v_mul_f32_e32 v228, v166, v228
	v_mul_f32_e32 v229, v167, v229
	v_sub_f32_e32 v211, v172, v173
	v_mov_b32_e32 v172, v213
	v_mov_b32_e32 v173, v217
	v_mul_f32_e32 v172, v164, v172
	v_mul_f32_e32 v173, v165, v173
	v_addc_co_u32_e32 v215, vcc, 0, v171, vcc
	v_sub_f32_e32 v173, v172, v173
	v_cvt_pk_bf16_f32 v172, v0, v189
	v_add_f32_e32 v189, v174, v175
	v_mov_b32_e32 v174, v216
	v_mov_b32_e32 v175, v212
	v_mul_f32_e32 v174, v162, v174
	v_mul_f32_e32 v175, v163, v175
	v_mov_b32_e32 v212, v217
	v_cvt_pk_bf16_f32 v173, v211, v173
	v_add_f32_e32 v211, v174, v175
	v_mul_f32_e32 v174, v164, v212
	v_mul_f32_e32 v175, v165, v213
	v_add_f32_e32 v0, v228, v229
	v_add_f32_e32 v175, v174, v175
	v_cvt_pk_bf16_f32 v174, v0, v189
	v_cvt_pk_bf16_f32 v175, v211, v175
	v_mul_f32_e32 v216, v98, v130
	v_mul_f32_e32 v217, v99, v131
	v_permlane16_swap_b32_e32 v172, v174
	v_permlane16_swap_b32_e32 v173, v175
	global_store_dwordx4 v[214:215], v[172:175], off
	v_mov_b32_e32 v214, v105
	v_mov_b32_e32 v215, v101
	v_mov_b32_e32 v174, v103
	v_mov_b32_e32 v175, v99
	v_mov_b32_e32 v172, v102
	v_mov_b32_e32 v173, v98
	v_mul_f32_e32 v174, v174, v174
	v_mul_f32_e32 v175, v175, v175
	v_mul_f32_e32 v214, v214, v214
	v_mul_f32_e32 v215, v215, v215
	v_fma_f32 v172, v172, v172, v174
	v_fma_f32 v173, v173, v173, v175
	v_mov_b32_e32 v174, v104
	v_mov_b32_e32 v175, v100
	v_fma_f32 v174, v174, v174, v214
	v_fma_f32 v175, v175, v175, v215
	v_lshl_add_u64 v[212:213], v[170:171], 0, s[92:93]
	v_add_f32_e32 v172, v172, v174
	v_add_f32_e32 v173, v173, v175
	v_mul_f32_e32 v174, v102, v134
	v_mul_f32_e32 v175, v103, v135
	v_add_f32_e32 v0, v172, v173
	ds_bpermute_b32 v172, v176, v0
	s_waitcnt lgkmcnt(0)
;     __device__ __forceinline__ static v2u pk4(float a, float b, float c, float d) { v2u o; o.x = pg8::cvt_pk_bf16(a, b); o.y = pg8::cvt_pk_bf16(c, d); return o; }
;     __device__ __forceinline__ void sub32(const pg8::f32x4 (&acc)[2][2][4][2], int row0, int wc, int fq, bf16r* dst, const float* gain, float scale, const float2* tseq) const {
;         const pg8::f32x4 g1 = *(const pg8::f32x4*)(gain + 4 * fq), g2 = *(const pg8::f32x4*)(gain + 16 + 4 * fq);
; #pragma unroll
;         for (int ai = 0; ai < 2; ++ai) {
;             pg8::f32x4 cs[4][2];
; #pragma unroll
;             for (int m = 0; m < 4; ++m) { const float2* tab = tseq + ((row0 + ai * 128 + m * 16) & (SEQ - 1)) * 16 + 4 * fq; cs[m][0] = *(const pg8::f32x4*)tab; cs[m][1] = *(const pg8::f32x4*)(tab + 2); }
;             asm volatile("" ::: "memory");
; #pragma unroll
;             for (int m = 0; m < 4; ++m) { const int row = row0 + ai * 128 + m * 16;
;                 const pg8::f32x4 cs01 = cs[m][0], cs23 = cs[m][1];
;                 const float c0 = cs01[0], s0 = cs01[1], c1 = cs01[2], s1 = cs01[3], c2 = cs23[0], s2 = cs23[1], c3 = cs23[2], s3 = cs23[3];
; #pragma unroll
;                 for (int bj = 0; bj < 2; ++bj) { const pg8::f32x4 a = acc[ai][bj][m][0], b = acc[ai][bj][m][1];
;                     float ss = ((a[0] * a[0] + a[1] * a[1]) + (a[2] * a[2] + a[3] * a[3])) + ((b[0] * b[0] + b[1] * b[1]) + (b[2] * b[2] + b[3] * b[3]));
;                     ss += __shfl_xor(ss, 16); ss += __shfl_xor(ss, 32);
;                     const float rs = rsqrtf(ss * (1.f / 32.f) + EPS) * scale;
;                     const pg8::f32x4 x1 = a * g1 * rs, x2 = b * g2 * rs;
;                     store_pair16(dst + (size_t)row * 256 + (4 * bj + wc) * 32, fq, pk4(x1[0] * c0 - x2[0] * s0, x1[1] * c1 - x2[1] * s1, x1[2] * c2 - x2[2] * s2, x1[3] * c3 - x2[3] * s3),
;                                  pk4(x2[0] * c0 + x1[0] * s0, x2[1] * c1 + x1[1] * s1, x2[2] * c2 + x1[2] * s2, x2[3] * c3 + x1[3] * s3));
;                     } } }
;     }
	v_add_f32_e32 v0, v0, v172
	ds_bpermute_b32 v172, v177, v0
	s_waitcnt lgkmcnt(0)
	v_add_f32_e32 v0, v0, v172
	v_fmamk_f32 v0, v0, 0x3d000000, v219
	v_cmp_gt_f32_e32 vcc, s25, v0
	v_mul_f32_e32 v172, 0x4b800000, v0
	s_nop 0
	v_cndmask_b32_e32 v0, v0, v172, vcc
	v_rsq_f32_e32 v0, v0
	s_nop 0
	v_mul_f32_e32 v172, 0x45800000, v0
	v_cndmask_b32_e32 v0, v0, v172, vcc
	v_mul_f32_e32 v172, v104, v136
	v_mul_f32_e32 v173, v105, v137
	v_mul_f32_e32 v174, v174, v0
	v_mul_f32_e32 v175, v175, v0
	v_mul_f32_e32 v214, v172, v0
	v_mul_f32_e32 v215, v173, v0
	v_mul_f32_e32 v172, v100, v132
	v_mul_f32_e32 v173, v101, v133
	v_mul_f32_e32 v216, v216, v0
	v_mul_f32_e32 v217, v217, v0
	v_mul_f32_e32 v228, v172, v0
	v_mul_f32_e32 v229, v173, v0
	v_mov_b32_e32 v172, v174
	v_mov_b32_e32 v173, v216
	v_mul_f32_e32 v172, v166, v172
	v_mul_f32_e32 v173, v167, v173
	v_mov_b32_e32 v230, v216
	v_sub_f32_e32 v0, v172, v173
	v_mov_b32_e32 v172, v175
	v_mov_b32_e32 v173, v217
	v_mul_f32_e32 v172, v168, v172
	v_mul_f32_e32 v173, v169, v173
	v_mov_b32_e32 v231, v174
	v_sub_f32_e32 v189, v172, v173
	v_mov_b32_e32 v172, v214
	v_mov_b32_e32 v173, v228
	v_mul_f32_e32 v172, v162, v172
	v_mul_f32_e32 v173, v163, v173
	v_mul_f32_e32 v166, v166, v230
	v_mul_f32_e32 v167, v167, v231
	v_sub_f32_e32 v211, v172, v173
	v_mov_b32_e32 v172, v215
	v_mov_b32_e32 v173, v229
	v_mul_f32_e32 v172, v164, v172
	v_mul_f32_e32 v173, v165, v173
	v_mov_b32_e32 v174, v217
	v_sub_f32_e32 v173, v172, v173
	v_cvt_pk_bf16_f32 v172, v0, v189
	v_add_f32_e32 v0, v166, v167
	v_mul_f32_e32 v166, v168, v174
	v_mul_f32_e32 v167, v169, v175
	v_cvt_pk_bf16_f32 v173, v211, v173
	s_nop 0
	v_add_f32_e32 v168, v166, v167
	v_mov_b32_e32 v166, v228
	v_mov_b32_e32 v167, v214
	v_mul_f32_e32 v162, v162, v166
	v_mul_f32_e32 v163, v163, v167
	v_mov_b32_e32 v214, v229
	v_add_f32_e32 v166, v162, v163
	v_mul_f32_e32 v162, v164, v214
	v_mul_f32_e32 v163, v165, v215
	v_mov_b32_e32 v164, v79
	v_add_f32_e32 v162, v162, v163
	v_mov_b32_e32 v165, v75
	v_cvt_pk_bf16_f32 v174, v0, v168
	v_cvt_pk_bf16_f32 v175, v166, v162
	v_mov_b32_e32 v162, v78
	v_mov_b32_e32 v163, v74
	v_mul_f32_e32 v164, v164, v164
	v_mul_f32_e32 v165, v165, v165
	v_mov_b32_e32 v166, v81
	v_mov_b32_e32 v167, v77
	v_fma_f32 v162, v162, v162, v164
	v_fma_f32 v163, v163, v163, v165
	v_mov_b32_e32 v164, v80
	v_mov_b32_e32 v165, v76
	v_mul_f32_e32 v166, v166, v166
	v_mul_f32_e32 v167, v167, v167
	v_mul_f32_e32 v168, v74, v130
	v_mul_f32_e32 v169, v75, v131
	v_fma_f32 v164, v164, v164, v166
	v_fma_f32 v165, v165, v165, v167
	v_permlane16_swap_b32_e32 v172, v174
	v_add_f32_e32 v162, v162, v164
	v_add_f32_e32 v163, v163, v165
	v_mul_f32_e32 v164, v78, v134
	v_mul_f32_e32 v165, v79, v135
	v_add_f32_e32 v0, v162, v163
	ds_bpermute_b32 v162, v176, v0
	v_permlane16_swap_b32_e32 v173, v175
	global_store_dwordx4 v[212:213], v[172:175], off offset:256
	s_waitcnt lgkmcnt(0)
	v_add_f32_e32 v0, v0, v162
	ds_bpermute_b32 v162, v177, v0
	s_waitcnt lgkmcnt(0)
	v_add_f32_e32 v0, v0, v162
	v_fmamk_f32 v0, v0, 0x3d000000, v219
	v_cmp_gt_f32_e32 vcc, s25, v0
	v_mul_f32_e32 v162, 0x4b800000, v0
	s_nop 0
	v_cndmask_b32_e32 v0, v0, v162, vcc
	v_rsq_f32_e32 v0, v0
	s_nop 0
	v_mul_f32_e32 v162, 0x45800000, v0
	v_cndmask_b32_e32 v0, v0, v162, vcc
	v_mul_f32_e32 v162, v80, v136
	v_mul_f32_e32 v163, v81, v137
	v_mul_f32_e32 v164, v164, v0
	v_mul_f32_e32 v165, v165, v0
	v_mul_f32_e32 v166, v162, v0
	v_mul_f32_e32 v167, v163, v0
	v_mul_f32_e32 v162, v76, v132
	v_mul_f32_e32 v163, v77, v133
	v_mul_f32_e32 v168, v168, v0
	v_mul_f32_e32 v169, v169, v0
	v_mul_f32_e32 v172, v162, v0
	v_mul_f32_e32 v173, v163, v0
	v_mov_b32_e32 v162, v164
	v_mov_b32_e32 v163, v168
	s_waitcnt vmcnt(6)
	v_mul_f32_e32 v162, v158, v162
	v_mul_f32_e32 v163, v159, v163
	s_nop 0
	v_sub_f32_e32 v0, v162, v163
	v_mov_b32_e32 v162, v165
	v_mov_b32_e32 v163, v169
	v_mul_f32_e32 v162, v160, v162
	v_mul_f32_e32 v163, v161, v163
	s_nop 0
	v_sub_f32_e32 v174, v162, v163
	v_mov_b32_e32 v162, v166
	v_mov_b32_e32 v163, v172
	v_mul_f32_e32 v162, v154, v162
	v_mul_f32_e32 v163, v155, v163
	s_nop 0
	v_sub_f32_e32 v175, v162, v163
	v_mov_b32_e32 v162, v167
	v_mov_b32_e32 v163, v173
	v_mul_f32_e32 v162, v156, v162
	v_mul_f32_e32 v163, v157, v163
	s_nop 0
	v_sub_f32_e32 v163, v162, v163
	v_cvt_pk_bf16_f32 v162, v0, v174
	v_cvt_pk_bf16_f32 v163, v175, v163
	v_mov_b32_e32 v175, v164
	v_mov_b32_e32 v164, v169
	v_mul_f32_e32 v164, v160, v164
	v_mul_f32_e32 v165, v161, v165
	v_mov_b32_e32 v174, v168
	v_add_f32_e32 v168, v164, v165
	v_mov_b32_e32 v164, v172
	v_mov_b32_e32 v165, v166
	v_mul_f32_e32 v164, v154, v164
	v_mul_f32_e32 v165, v155, v165
	v_mov_b32_e32 v166, v173
	v_add_f32_e32 v169, v164, v165
	v_mul_f32_e32 v164, v156, v166
	v_mul_f32_e32 v165, v157, v167
	v_mul_f32_e32 v174, v158, v174
	v_mul_f32_e32 v175, v159, v175
	v_add_f32_e32 v165, v164, v165
	v_lshl_add_u64 v[166:167], v[170:171], 0, s[2:3]
	s_mov_b32 s2, 0x12000
	v_add_f32_e32 v0, v174, v175
	v_cvt_pk_bf16_f32 v164, v0, v168
	v_cvt_pk_bf16_f32 v165, v169, v165
	v_add_co_u32_e32 v168, vcc, s2, v170
	v_permlane16_swap_b32_e32 v162, v164
	v_permlane16_swap_b32_e32 v163, v165
	v_addc_co_u32_e32 v169, vcc, 0, v171, vcc
	global_store_dwordx4 v[168:169], v[162:165], off
	v_mov_b32_e32 v168, v73
	v_mov_b32_e32 v169, v69
	v_mov_b32_e32 v164, v71
	v_mov_b32_e32 v165, v67
	v_mov_b32_e32 v162, v70
	v_mov_b32_e32 v163, v66
	v_mul_f32_e32 v164, v164, v164
	v_mul_f32_e32 v165, v165, v165
	v_mul_f32_e32 v168, v168, v168
	v_mul_f32_e32 v169, v169, v169
	v_fma_f32 v162, v162, v162, v164
	v_fma_f32 v163, v163, v163, v165
	v_mov_b32_e32 v164, v72
	v_mov_b32_e32 v165, v68
	v_fma_f32 v164, v164, v164, v168
	v_fma_f32 v165, v165, v165, v169
	v_mul_f32_e32 v172, v66, v130
	v_mul_f32_e32 v173, v67, v131
	v_add_f32_e32 v162, v162, v164
	v_add_f32_e32 v163, v163, v165
	v_mul_f32_e32 v164, v70, v134
	v_mul_f32_e32 v165, v71, v135
	v_add_f32_e32 v0, v162, v163
	ds_bpermute_b32 v162, v176, v0
	s_mov_b64 s[2:3], 0x14000
	s_waitcnt lgkmcnt(0)
;     __device__ __forceinline__ static v2u pk4(float a, float b, float c, float d) { v2u o; o.x = pg8::cvt_pk_bf16(a, b); o.y = pg8::cvt_pk_bf16(c, d); return o; }
;     __device__ __forceinline__ void sub32(const pg8::f32x4 (&acc)[2][2][4][2], int row0, int wc, int fq, bf16r* dst, const float* gain, float scale, const float2* tseq) const {
;         const pg8::f32x4 g1 = *(const pg8::f32x4*)(gain + 4 * fq), g2 = *(const pg8::f32x4*)(gain + 16 + 4 * fq);
; #pragma unroll
;         for (int ai = 0; ai < 2; ++ai) {
;             pg8::f32x4 cs[4][2];
; #pragma unroll
;             for (int m = 0; m < 4; ++m) { const float2* tab = tseq + ((row0 + ai * 128 + m * 16) & (SEQ - 1)) * 16 + 4 * fq; cs[m][0] = *(const pg8::f32x4*)tab; cs[m][1] = *(const pg8::f32x4*)(tab + 2); }
;             asm volatile("" ::: "memory");
; #pragma unroll
;             for (int m = 0; m < 4; ++m) { const int row = row0 + ai * 128 + m * 16;
;                 const pg8::f32x4 cs01 = cs[m][0], cs23 = cs[m][1];
;                 const float c0 = cs01[0], s0 = cs01[1], c1 = cs01[2], s1 = cs01[3], c2 = cs23[0], s2 = cs23[1], c3 = cs23[2], s3 = cs23[3];
; #pragma unroll
;                 for (int bj = 0; bj < 2; ++bj) { const pg8::f32x4 a = acc[ai][bj][m][0], b = acc[ai][bj][m][1];
;                     float ss = ((a[0] * a[0] + a[1] * a[1]) + (a[2] * a[2] + a[3] * a[3])) + ((b[0] * b[0] + b[1] * b[1]) + (b[2] * b[2] + b[3] * b[3]));
;                     ss += __shfl_xor(ss, 16); ss += __shfl_xor(ss, 32);
;                     const float rs = rsqrtf(ss * (1.f / 32.f) + EPS) * scale;
;                     const pg8::f32x4 x1 = a * g1 * rs, x2 = b * g2 * rs;
;                     store_pair16(dst + (size_t)row * 256 + (4 * bj + wc) * 32, fq, pk4(x1[0] * c0 - x2[0] * s0, x1[1] * c1 - x2[1] * s1, x1[2] * c2 - x2[2] * s2, x1[3] * c3 - x2[3] * s3),
;                                  pk4(x2[0] * c0 + x1[0] * s0, x2[1] * c1 + x1[1] * s1, x2[2] * c2 + x1[2] * s2, x2[3] * c3 + x1[3] * s3));
;                     } } }
;     }
	v_add_f32_e32 v0, v0, v162
	ds_bpermute_b32 v162, v177, v0
	s_waitcnt lgkmcnt(0)
	v_add_f32_e32 v0, v0, v162
	v_fmamk_f32 v0, v0, 0x3d000000, v219
	v_cmp_gt_f32_e32 vcc, s25, v0
	v_mul_f32_e32 v162, 0x4b800000, v0
	s_nop 0
	v_cndmask_b32_e32 v0, v0, v162, vcc
	v_rsq_f32_e32 v0, v0
	s_nop 0
	v_mul_f32_e32 v162, 0x45800000, v0
	v_cndmask_b32_e32 v0, v0, v162, vcc
	v_mul_f32_e32 v162, v72, v136
	v_mul_f32_e32 v163, v73, v137
	v_mul_f32_e32 v164, v164, v0
	v_mul_f32_e32 v165, v165, v0
	v_mul_f32_e32 v168, v162, v0
	v_mul_f32_e32 v169, v163, v0
	v_mul_f32_e32 v162, v68, v132
	v_mul_f32_e32 v163, v69, v133
	v_mul_f32_e32 v172, v172, v0
	v_mul_f32_e32 v173, v173, v0
	v_mul_f32_e32 v174, v162, v0
	v_mul_f32_e32 v175, v163, v0
	v_mov_b32_e32 v162, v164
	v_mov_b32_e32 v163, v172
	v_mul_f32_e32 v162, v158, v162
	v_mul_f32_e32 v163, v159, v163
	v_mov_b32_e32 v212, v172
	v_sub_f32_e32 v0, v162, v163
	v_mov_b32_e32 v162, v165
	v_mov_b32_e32 v163, v173
	v_mul_f32_e32 v162, v160, v162
	v_mul_f32_e32 v163, v161, v163
	v_mov_b32_e32 v213, v164
	v_sub_f32_e32 v189, v162, v163
	v_mov_b32_e32 v162, v168
	v_mov_b32_e32 v163, v174
	v_mul_f32_e32 v162, v154, v162
	v_mul_f32_e32 v163, v155, v163
	v_mul_f32_e32 v158, v158, v212
	v_mul_f32_e32 v159, v159, v213
	v_sub_f32_e32 v211, v162, v163
	v_mov_b32_e32 v162, v169
	v_mov_b32_e32 v163, v175
	v_mul_f32_e32 v162, v156, v162
	v_mul_f32_e32 v163, v157, v163
	v_mov_b32_e32 v164, v173
	v_sub_f32_e32 v163, v162, v163
	v_cvt_pk_bf16_f32 v162, v0, v189
	v_add_f32_e32 v0, v158, v159
	v_mul_f32_e32 v158, v160, v164
	v_mul_f32_e32 v159, v161, v165
	v_cvt_pk_bf16_f32 v163, v211, v163
	s_nop 0
	v_add_f32_e32 v160, v158, v159
	v_mov_b32_e32 v158, v174
	v_mov_b32_e32 v159, v168
	v_mul_f32_e32 v154, v154, v158
	v_mul_f32_e32 v155, v155, v159
	v_mov_b32_e32 v168, v175
	v_add_f32_e32 v158, v154, v155
	v_mul_f32_e32 v154, v156, v168
	v_mul_f32_e32 v155, v157, v169
	v_mov_b32_e32 v156, v47
	v_add_f32_e32 v154, v154, v155
	v_mov_b32_e32 v157, v43
	v_cvt_pk_bf16_f32 v164, v0, v160
	v_cvt_pk_bf16_f32 v165, v158, v154
	v_mov_b32_e32 v154, v46
	v_mov_b32_e32 v155, v42
	v_mul_f32_e32 v156, v156, v156
	v_mul_f32_e32 v157, v157, v157
	v_mov_b32_e32 v158, v49
	v_mov_b32_e32 v159, v45
	v_fma_f32 v154, v154, v154, v156
	v_fma_f32 v155, v155, v155, v157
	v_mov_b32_e32 v156, v48
	v_mov_b32_e32 v157, v44
	v_mul_f32_e32 v158, v158, v158
	v_mul_f32_e32 v159, v159, v159
	v_mul_f32_e32 v160, v42, v130
	v_mul_f32_e32 v161, v43, v131
	v_fma_f32 v156, v156, v156, v158
	v_fma_f32 v157, v157, v157, v159
	v_permlane16_swap_b32_e32 v162, v164
	v_add_f32_e32 v154, v154, v156
	v_add_f32_e32 v155, v155, v157
	v_mul_f32_e32 v156, v46, v134
	v_mul_f32_e32 v157, v47, v135
	v_add_f32_e32 v0, v154, v155
	ds_bpermute_b32 v154, v176, v0
	v_permlane16_swap_b32_e32 v163, v165
	global_store_dwordx4 v[166:167], v[162:165], off offset:256
	s_waitcnt lgkmcnt(0)
	v_add_f32_e32 v0, v0, v154
	ds_bpermute_b32 v154, v177, v0
	s_waitcnt lgkmcnt(0)
	v_add_f32_e32 v0, v0, v154
	v_fmamk_f32 v0, v0, 0x3d000000, v219
	v_cmp_gt_f32_e32 vcc, s25, v0
	v_mul_f32_e32 v154, 0x4b800000, v0
	s_nop 0
	v_cndmask_b32_e32 v0, v0, v154, vcc
	v_rsq_f32_e32 v0, v0
	s_nop 0
	v_mul_f32_e32 v154, 0x45800000, v0
	v_cndmask_b32_e32 v0, v0, v154, vcc
	v_mul_f32_e32 v154, v48, v136
	v_mul_f32_e32 v155, v49, v137
	v_mul_f32_e32 v156, v156, v0
	v_mul_f32_e32 v157, v157, v0
	v_mul_f32_e32 v158, v154, v0
	v_mul_f32_e32 v159, v155, v0
	v_mul_f32_e32 v154, v44, v132
	v_mul_f32_e32 v155, v45, v133
	v_mul_f32_e32 v160, v160, v0
	v_mul_f32_e32 v161, v161, v0
	v_mul_f32_e32 v162, v154, v0
	v_mul_f32_e32 v163, v155, v0
	v_mov_b32_e32 v154, v156
	v_mov_b32_e32 v155, v160
	s_waitcnt vmcnt(6)
	v_mul_f32_e32 v154, v150, v154
	v_mul_f32_e32 v155, v151, v155
	s_nop 0
	v_sub_f32_e32 v0, v154, v155
	v_mov_b32_e32 v154, v157
	v_mov_b32_e32 v155, v161
	v_mul_f32_e32 v154, v152, v154
	v_mul_f32_e32 v155, v153, v155
	s_nop 0
	v_sub_f32_e32 v164, v154, v155
	v_mov_b32_e32 v154, v158
	v_mov_b32_e32 v155, v162
	v_mul_f32_e32 v154, v146, v154
	v_mul_f32_e32 v155, v147, v155
	s_nop 0
	v_sub_f32_e32 v165, v154, v155
	v_mov_b32_e32 v154, v159
	v_mov_b32_e32 v155, v163
	v_mul_f32_e32 v154, v148, v154
	v_mul_f32_e32 v155, v149, v155
	s_nop 0
	v_sub_f32_e32 v155, v154, v155
	v_cvt_pk_bf16_f32 v154, v0, v164
	v_cvt_pk_bf16_f32 v155, v165, v155
	v_mov_b32_e32 v165, v156
	v_mov_b32_e32 v156, v161
	v_mul_f32_e32 v156, v152, v156
	v_mul_f32_e32 v157, v153, v157
	v_mov_b32_e32 v164, v160
	v_add_f32_e32 v160, v156, v157
	v_mov_b32_e32 v156, v162
	v_mov_b32_e32 v157, v158
	v_mul_f32_e32 v156, v146, v156
	v_mul_f32_e32 v157, v147, v157
	v_mov_b32_e32 v158, v163
	v_add_f32_e32 v161, v156, v157
	v_mul_f32_e32 v156, v148, v158
	v_mul_f32_e32 v157, v149, v159
	v_mul_f32_e32 v164, v150, v164
	v_mul_f32_e32 v165, v151, v165
	v_add_f32_e32 v157, v156, v157
	v_lshl_add_u64 v[158:159], v[170:171], 0, s[2:3]
	s_mov_b32 s2, 0x14000
	v_add_f32_e32 v0, v164, v165
	v_cvt_pk_bf16_f32 v156, v0, v160
	v_cvt_pk_bf16_f32 v157, v161, v157
	v_add_co_u32_e32 v160, vcc, s2, v170
	v_permlane16_swap_b32_e32 v154, v156
	v_permlane16_swap_b32_e32 v155, v157
	v_addc_co_u32_e32 v161, vcc, 0, v171, vcc
	global_store_dwordx4 v[160:161], v[154:157], off
	v_mov_b32_e32 v160, v41
	v_mov_b32_e32 v161, v37
	v_mov_b32_e32 v156, v39
	v_mov_b32_e32 v157, v35
	v_mov_b32_e32 v154, v38
	v_mov_b32_e32 v155, v34
	v_mul_f32_e32 v156, v156, v156
	v_mul_f32_e32 v157, v157, v157
	v_mul_f32_e32 v160, v160, v160
	v_mul_f32_e32 v161, v161, v161
	v_fma_f32 v154, v154, v154, v156
	v_fma_f32 v155, v155, v155, v157
	v_mov_b32_e32 v156, v40
	v_mov_b32_e32 v157, v36
	v_fma_f32 v156, v156, v156, v160
	v_fma_f32 v157, v157, v157, v161
	v_mul_f32_e32 v162, v34, v130
	v_mul_f32_e32 v163, v35, v131
	v_add_f32_e32 v154, v154, v156
	v_add_f32_e32 v155, v155, v157
	v_mul_f32_e32 v156, v38, v134
	v_mul_f32_e32 v157, v39, v135
	v_add_f32_e32 v0, v154, v155
	ds_bpermute_b32 v154, v176, v0
	s_mov_b64 s[2:3], 0x16000
	s_waitcnt lgkmcnt(0)
;     __device__ __forceinline__ static v2u pk4(float a, float b, float c, float d) { v2u o; o.x = pg8::cvt_pk_bf16(a, b); o.y = pg8::cvt_pk_bf16(c, d); return o; }
;     __device__ __forceinline__ void sub32(const pg8::f32x4 (&acc)[2][2][4][2], int row0, int wc, int fq, bf16r* dst, const float* gain, float scale, const float2* tseq) const {
;         const pg8::f32x4 g1 = *(const pg8::f32x4*)(gain + 4 * fq), g2 = *(const pg8::f32x4*)(gain + 16 + 4 * fq);
; #pragma unroll
;         for (int ai = 0; ai < 2; ++ai) {
;             pg8::f32x4 cs[4][2];
; #pragma unroll
;             for (int m = 0; m < 4; ++m) { const float2* tab = tseq + ((row0 + ai * 128 + m * 16) & (SEQ - 1)) * 16 + 4 * fq; cs[m][0] = *(const pg8::f32x4*)tab; cs[m][1] = *(const pg8::f32x4*)(tab + 2); }
;             asm volatile("" ::: "memory");
; #pragma unroll
;             for (int m = 0; m < 4; ++m) { const int row = row0 + ai * 128 + m * 16;
;                 const pg8::f32x4 cs01 = cs[m][0], cs23 = cs[m][1];
;                 const float c0 = cs01[0], s0 = cs01[1], c1 = cs01[2], s1 = cs01[3], c2 = cs23[0], s2 = cs23[1], c3 = cs23[2], s3 = cs23[3];
; #pragma unroll
;                 for (int bj = 0; bj < 2; ++bj) { const pg8::f32x4 a = acc[ai][bj][m][0], b = acc[ai][bj][m][1];
;                     float ss = ((a[0] * a[0] + a[1] * a[1]) + (a[2] * a[2] + a[3] * a[3])) + ((b[0] * b[0] + b[1] * b[1]) + (b[2] * b[2] + b[3] * b[3]));
;                     ss += __shfl_xor(ss, 16); ss += __shfl_xor(ss, 32);
;                     const float rs = rsqrtf(ss * (1.f / 32.f) + EPS) * scale;
;                     const pg8::f32x4 x1 = a * g1 * rs, x2 = b * g2 * rs;
;                     store_pair16(dst + (size_t)row * 256 + (4 * bj + wc) * 32, fq, pk4(x1[0] * c0 - x2[0] * s0, x1[1] * c1 - x2[1] * s1, x1[2] * c2 - x2[2] * s2, x1[3] * c3 - x2[3] * s3),
;                                  pk4(x2[0] * c0 + x1[0] * s0, x2[1] * c1 + x1[1] * s1, x2[2] * c2 + x1[2] * s2, x2[3] * c3 + x1[3] * s3));
;                     } } }
;     }
	v_add_f32_e32 v0, v0, v154
	ds_bpermute_b32 v154, v177, v0
	s_waitcnt lgkmcnt(0)
	v_add_f32_e32 v0, v0, v154
	v_fmamk_f32 v0, v0, 0x3d000000, v219
	v_cmp_gt_f32_e32 vcc, s25, v0
	v_mul_f32_e32 v154, 0x4b800000, v0
	s_nop 0
	v_cndmask_b32_e32 v0, v0, v154, vcc
	v_rsq_f32_e32 v0, v0
	s_nop 0
	v_mul_f32_e32 v154, 0x45800000, v0
	v_cndmask_b32_e32 v0, v0, v154, vcc
	v_mul_f32_e32 v154, v40, v136
	v_mul_f32_e32 v155, v41, v137
	v_mul_f32_e32 v156, v156, v0
	v_mul_f32_e32 v157, v157, v0
	v_mul_f32_e32 v160, v154, v0
	v_mul_f32_e32 v161, v155, v0
	v_mul_f32_e32 v154, v36, v132
	v_mul_f32_e32 v155, v37, v133
	v_mul_f32_e32 v162, v162, v0
	v_mul_f32_e32 v163, v163, v0
	v_mul_f32_e32 v164, v154, v0
	v_mul_f32_e32 v165, v155, v0
	v_mov_b32_e32 v154, v156
	v_mov_b32_e32 v155, v162
	v_mul_f32_e32 v154, v150, v154
	v_mul_f32_e32 v155, v151, v155
	s_nop 0
	v_sub_f32_e32 v0, v154, v155
	v_mov_b32_e32 v154, v157
	v_mov_b32_e32 v155, v163
	v_mul_f32_e32 v154, v152, v154
	v_mul_f32_e32 v155, v153, v155
	s_nop 0
	v_sub_f32_e32 v166, v154, v155
	v_mov_b32_e32 v154, v160
	v_mov_b32_e32 v155, v164
	v_mul_f32_e32 v154, v146, v154
	v_mul_f32_e32 v155, v147, v155
	s_nop 0
	v_sub_f32_e32 v167, v154, v155
	v_mov_b32_e32 v154, v161
	v_mov_b32_e32 v155, v165
	v_mul_f32_e32 v154, v148, v154
	v_mul_f32_e32 v155, v149, v155
	s_nop 0
	v_sub_f32_e32 v155, v154, v155
	v_cvt_pk_bf16_f32 v154, v0, v166
	v_cvt_pk_bf16_f32 v155, v167, v155
	v_mov_b32_e32 v166, v162
	v_mov_b32_e32 v167, v156
	v_mul_f32_e32 v150, v150, v166
	v_mul_f32_e32 v151, v151, v167
	v_mov_b32_e32 v156, v163
	v_add_f32_e32 v0, v150, v151
	v_mul_f32_e32 v150, v152, v156
	v_mul_f32_e32 v151, v153, v157
	s_nop 0
	v_add_f32_e32 v152, v150, v151
	v_mov_b32_e32 v150, v164
	v_mov_b32_e32 v151, v160
	v_mul_f32_e32 v146, v146, v150
	v_mul_f32_e32 v147, v147, v151
	v_mov_b32_e32 v160, v165
	v_add_f32_e32 v150, v146, v147
	v_mul_f32_e32 v146, v148, v160
	v_mul_f32_e32 v147, v149, v161
	v_mov_b32_e32 v148, v15
	v_add_f32_e32 v146, v146, v147
	v_mov_b32_e32 v149, v11
	v_cvt_pk_bf16_f32 v156, v0, v152
	v_cvt_pk_bf16_f32 v157, v150, v146
	v_mov_b32_e32 v146, v14
	v_mov_b32_e32 v147, v10
	v_mul_f32_e32 v148, v148, v148
	v_mul_f32_e32 v149, v149, v149
	v_mov_b32_e32 v150, v17
	v_mov_b32_e32 v151, v13
	v_fma_f32 v146, v146, v146, v148
	v_fma_f32 v147, v147, v147, v149
	v_mov_b32_e32 v148, v16
	v_mov_b32_e32 v149, v12
	v_mul_f32_e32 v150, v150, v150
	v_mul_f32_e32 v151, v151, v151
	v_mul_f32_e32 v152, v10, v130
	v_mul_f32_e32 v153, v11, v131
	v_fma_f32 v148, v148, v148, v150
	v_fma_f32 v149, v149, v149, v151
	v_permlane16_swap_b32_e32 v154, v156
	v_add_f32_e32 v146, v146, v148
	v_add_f32_e32 v147, v147, v149
	v_mul_f32_e32 v148, v14, v134
	v_mul_f32_e32 v149, v15, v135
	v_add_f32_e32 v0, v146, v147
	ds_bpermute_b32 v146, v176, v0
	v_permlane16_swap_b32_e32 v155, v157
	global_store_dwordx4 v[158:159], v[154:157], off offset:256
	v_mul_f32_e32 v134, v6, v134
	v_mul_f32_e32 v135, v7, v135
	s_waitcnt lgkmcnt(0)
	v_add_f32_e32 v0, v0, v146
	ds_bpermute_b32 v146, v177, v0
	v_mul_f32_e32 v130, v2, v130
	v_mul_f32_e32 v131, v3, v131
	s_waitcnt lgkmcnt(0)
	v_add_f32_e32 v0, v0, v146
	v_fmamk_f32 v0, v0, 0x3d000000, v219
	v_cmp_gt_f32_e32 vcc, s25, v0
	v_mul_f32_e32 v146, 0x4b800000, v0
	s_nop 0
	v_cndmask_b32_e32 v0, v0, v146, vcc
	v_rsq_f32_e32 v0, v0
	s_nop 0
	v_mul_f32_e32 v146, 0x45800000, v0
	v_cndmask_b32_e32 v0, v0, v146, vcc
	v_mul_f32_e32 v146, v16, v136
	v_mul_f32_e32 v147, v17, v137
	v_mul_f32_e32 v148, v148, v0
	v_mul_f32_e32 v149, v149, v0
	v_mul_f32_e32 v150, v146, v0
	v_mul_f32_e32 v151, v147, v0
	v_mul_f32_e32 v146, v12, v132
	v_mul_f32_e32 v147, v13, v133
	v_mul_f32_e32 v152, v152, v0
	v_mul_f32_e32 v153, v153, v0
	v_mul_f32_e32 v154, v146, v0
	v_mul_f32_e32 v155, v147, v0
	v_mov_b32_e32 v146, v148
	v_mov_b32_e32 v147, v152
	s_waitcnt vmcnt(6)
;     __device__ __forceinline__ static v2u pk4(float a, float b, float c, float d) { v2u o; o.x = pg8::cvt_pk_bf16(a, b); o.y = pg8::cvt_pk_bf16(c, d); return o; }
;     __device__ __forceinline__ void sub32(const pg8::f32x4 (&acc)[2][2][4][2], int row0, int wc, int fq, bf16r* dst, const float* gain, float scale, const float2* tseq) const {
;     ...
;             for (int m = 0; m < 4; ++m) { const int row = row0 + ai * 128 + m * 16;
;                 const pg8::f32x4 cs01 = cs[m][0], cs23 = cs[m][1];
;                 const float c0 = cs01[0], s0 = cs01[1], c1 = cs01[2], s1 = cs01[3], c2 = cs23[0], s2 = cs23[1], c3 = cs23[2], s3 = cs23[3];
; #pragma unroll
;                 for (int bj = 0; bj < 2; ++bj) { const pg8::f32x4 a = acc[ai][bj][m][0], b = acc[ai][bj][m][1];
;                     float ss = ((a[0] * a[0] + a[1] * a[1]) + (a[2] * a[2] + a[3] * a[3])) + ((b[0] * b[0] + b[1] * b[1]) + (b[2] * b[2] + b[3] * b[3]));
;                     ss += __shfl_xor(ss, 16); ss += __shfl_xor(ss, 32);
;                     const float rs = rsqrtf(ss * (1.f / 32.f) + EPS) * scale;
;                     const pg8::f32x4 x1 = a * g1 * rs, x2 = b * g2 * rs;
;                     store_pair16(dst + (size_t)row * 256 + (4 * bj + wc) * 32, fq, pk4(x1[0] * c0 - x2[0] * s0, x1[1] * c1 - x2[1] * s1, x1[2] * c2 - x2[2] * s2, x1[3] * c3 - x2[3] * s3),
;                                  pk4(x2[0] * c0 + x1[0] * s0, x2[1] * c1 + x1[1] * s1, x2[2] * c2 + x1[2] * s2, x2[3] * c3 + x1[3] * s3));
;                     } } }
	v_mul_f32_e32 v146, v142, v146
	v_mul_f32_e32 v147, v143, v147
	v_mul_f32_e32 v136, v8, v136
	v_mul_f32_e32 v137, v9, v137
	v_sub_f32_e32 v0, v146, v147
	v_mov_b32_e32 v146, v149
	v_mov_b32_e32 v147, v153
	v_mul_f32_e32 v146, v144, v146
	v_mul_f32_e32 v147, v145, v147
	v_mul_f32_e32 v132, v4, v132
	v_mul_f32_e32 v133, v5, v133
	v_sub_f32_e32 v156, v146, v147
	v_mov_b32_e32 v146, v150
	v_mov_b32_e32 v147, v154
	v_mul_f32_e32 v146, v138, v146
	v_mul_f32_e32 v147, v139, v147
	s_nop 0
	v_sub_f32_e32 v157, v146, v147
	v_mov_b32_e32 v146, v151
	v_mov_b32_e32 v147, v155
	v_mul_f32_e32 v146, v140, v146
	v_mul_f32_e32 v147, v141, v147
	s_nop 0
	v_sub_f32_e32 v147, v146, v147
	v_cvt_pk_bf16_f32 v146, v0, v156
	v_cvt_pk_bf16_f32 v147, v157, v147
	v_mov_b32_e32 v157, v148
	v_mov_b32_e32 v148, v153
	v_mul_f32_e32 v148, v144, v148
	v_mul_f32_e32 v149, v145, v149
	v_mov_b32_e32 v156, v152
	v_add_f32_e32 v152, v148, v149
	v_mov_b32_e32 v148, v154
	v_mov_b32_e32 v149, v150
	v_mul_f32_e32 v148, v138, v148
	v_mul_f32_e32 v149, v139, v149
	v_mov_b32_e32 v150, v155
	v_add_f32_e32 v153, v148, v149
	v_mul_f32_e32 v148, v140, v150
	v_mul_f32_e32 v149, v141, v151
	v_mul_f32_e32 v156, v142, v156
	v_mul_f32_e32 v157, v143, v157
	v_add_f32_e32 v149, v148, v149
	v_lshl_add_u64 v[150:151], v[170:171], 0, s[2:3]
	s_mov_b32 s2, 0x16000
	v_add_f32_e32 v0, v156, v157
	v_cvt_pk_bf16_f32 v148, v0, v152
	v_cvt_pk_bf16_f32 v149, v153, v149
	v_add_co_u32_e32 v152, vcc, s2, v170
	v_permlane16_swap_b32_e32 v146, v148
	v_permlane16_swap_b32_e32 v147, v149
	v_addc_co_u32_e32 v153, vcc, 0, v171, vcc
	global_store_dwordx4 v[152:153], v[146:149], off
	v_mov_b32_e32 v152, v9
	v_mov_b32_e32 v153, v5
	v_mov_b32_e32 v148, v7
	v_mov_b32_e32 v149, v3
	v_mov_b32_e32 v146, v6
	v_mov_b32_e32 v147, v2
	v_mul_f32_e32 v148, v148, v148
	v_mul_f32_e32 v149, v149, v149
	v_mul_f32_e32 v152, v152, v152
	v_mul_f32_e32 v153, v153, v153
	v_fma_f32 v146, v146, v146, v148
	v_fma_f32 v147, v147, v147, v149
	v_mov_b32_e32 v148, v8
	v_mov_b32_e32 v149, v4
	v_fma_f32 v148, v148, v148, v152
	v_fma_f32 v149, v149, v149, v153
	s_nop 0
	v_add_f32_e32 v146, v146, v148
	v_add_f32_e32 v147, v147, v149
	s_nop 0
	v_add_f32_e32 v0, v146, v147
	ds_bpermute_b32 v146, v176, v0
	s_waitcnt lgkmcnt(0)
	v_add_f32_e32 v0, v0, v146
	ds_bpermute_b32 v146, v177, v0
	s_waitcnt lgkmcnt(0)
	v_add_f32_e32 v0, v0, v146
	v_fmamk_f32 v0, v0, 0x3d000000, v219
	v_cmp_gt_f32_e32 vcc, s25, v0
	v_mul_f32_e32 v146, 0x4b800000, v0
	s_nop 0
	v_cndmask_b32_e32 v0, v0, v146, vcc
	v_rsq_f32_e32 v0, v0
	s_nop 0
	v_mul_f32_e32 v146, 0x45800000, v0
	v_cndmask_b32_e32 v0, v0, v146, vcc
	v_mul_f32_e32 v134, v134, v0
	v_mul_f32_e32 v135, v135, v0
	v_mul_f32_e32 v146, v130, v0
	v_mul_f32_e32 v147, v131, v0
	v_mov_b32_e32 v130, v134
	v_mov_b32_e32 v131, v146
	v_mul_f32_e32 v130, v142, v130
	v_mul_f32_e32 v131, v143, v131
	v_mul_f32_e32 v136, v136, v0
	v_mul_f32_e32 v137, v137, v0
	v_mul_f32_e32 v132, v132, v0
	v_mul_f32_e32 v133, v133, v0
	v_sub_f32_e32 v0, v130, v131
	v_mov_b32_e32 v130, v135
	v_mov_b32_e32 v131, v147
	v_mul_f32_e32 v130, v144, v130
	v_mul_f32_e32 v131, v145, v131
	s_nop 0
	v_sub_f32_e32 v148, v130, v131
	v_mov_b32_e32 v130, v136
	v_mov_b32_e32 v131, v132
	v_mul_f32_e32 v130, v138, v130
	v_mul_f32_e32 v131, v139, v131
	s_nop 0
	v_sub_f32_e32 v149, v130, v131
	v_mov_b32_e32 v130, v137
	v_mov_b32_e32 v131, v133
	v_mul_f32_e32 v130, v140, v130
	v_mul_f32_e32 v131, v141, v131
	s_nop 0
	v_sub_f32_e32 v131, v130, v131
	v_cvt_pk_bf16_f32 v130, v0, v148
	v_cvt_pk_bf16_f32 v131, v149, v131
	v_mov_b32_e32 v148, v146
	v_mov_b32_e32 v149, v134
	v_mov_b32_e32 v134, v147
	v_mul_f32_e32 v142, v142, v148
	v_mul_f32_e32 v143, v143, v149
	v_mul_f32_e32 v134, v144, v134
	v_mul_f32_e32 v135, v145, v135
	v_add_f32_e32 v0, v142, v143
	v_add_f32_e32 v142, v134, v135
	v_mov_b32_e32 v135, v136
	v_mov_b32_e32 v136, v133
	v_mov_b32_e32 v134, v132
	v_mul_f32_e32 v132, v140, v136
	v_mul_f32_e32 v133, v141, v137
	v_mul_f32_e32 v134, v138, v134
	v_mul_f32_e32 v135, v139, v135
	v_add_f32_e32 v133, v132, v133
	v_add_f32_e32 v134, v134, v135
	v_cvt_pk_bf16_f32 v132, v0, v142
	v_cvt_pk_bf16_f32 v133, v134, v133
	s_nop 0
	v_permlane16_swap_b32_e32 v130, v132
	v_permlane16_swap_b32_e32 v131, v133
	global_store_dwordx4 v[150:151], v[130:133], off offset:256

;     __device__ __forceinline__ static v2u pk4(float a, float b, float c, float d) { v2u o; o.x = pg8::cvt_pk_bf16(a, b); o.y = pg8::cvt_pk_bf16(c, d); return o; }
;     __device__ __forceinline__ void sub32(const pg8::f32x4 (&acc)[2][2][4][2], int row0, int wc, int fq, bf16r* dst, const float* gain, float scale, const float2* tseq) const {
;         const pg8::f32x4 g1 = *(const pg8::f32x4*)(gain + 4 * fq), g2 = *(const pg8::f32x4*)(gain + 16 + 4 * fq);
; #pragma unroll
;         for (int ai = 0; ai < 2; ++ai) {
;             pg8::f32x4 cs[4][2];
; #pragma unroll
;             for (int m = 0; m < 4; ++m) { const float2* tab = tseq + ((row0 + ai * 128 + m * 16) & (SEQ - 1)) * 16 + 4 * fq; cs[m][0] = *(const pg8::f32x4*)tab; cs[m][1] = *(const pg8::f32x4*)(tab + 2); }
;             asm volatile("" ::: "memory");
; #pragma unroll
;             for (int m = 0; m < 4; ++m) { const int row = row0 + ai * 128 + m * 16;
;                 const pg8::f32x4 cs01 = cs[m][0], cs23 = cs[m][1];
;                 const float c0 = cs01[0], s0 = cs01[1], c1 = cs01[2], s1 = cs01[3], c2 = cs23[0], s2 = cs23[1], c3 = cs23[2], s3 = cs23[3];
; #pragma unroll
;                 for (int bj = 0; bj < 2; ++bj) { const pg8::f32x4 a = acc[ai][bj][m][0], b = acc[ai][bj][m][1];
;                     float ss = ((a[0] * a[0] + a[1] * a[1]) + (a[2] * a[2] + a[3] * a[3])) + ((b[0] * b[0] + b[1] * b[1]) + (b[2] * b[2] + b[3] * b[3]));
;                     ss += __shfl_xor(ss, 16); ss += __shfl_xor(ss, 32);
;                     const float rs = rsqrtf(ss * (1.f / 32.f) + EPS) * scale;
;                     const pg8::f32x4 x1 = a * g1 * rs, x2 = b * g2 * rs;
;                     store_pair16(dst + (size_t)row * 256 + (4 * bj + wc) * 32, fq, pk4(x1[0] * c0 - x2[0] * s0, x1[1] * c1 - x2[1] * s1, x1[2] * c2 - x2[2] * s2, x1[3] * c3 - x2[3] * s3),
;                                  pk4(x2[0] * c0 + x1[0] * s0, x2[1] * c1 + x1[1] * s1, x2[2] * c2 + x1[2] * s2, x2[3] * c3 + x1[3] * s3));
;                     } } }
.LBB0_242:
	s_cbranch_execz .LBB0_238
	s_load_dwordx2 s[2:3], s[64:65], 0x90
	s_lshl_b64 s[14:15], s[58:59], 2
	v_lshlrev_b32_e32 v0, 2, v184
	v_and_b32_e32 v170, 64, v225
	v_add_u32_e32 v170, 64, v170
	s_waitcnt lgkmcnt(0)
	s_add_u32 s2, s2, s14
	s_addc_u32 s3, s3, s15
	global_load_dwordx4 v[134:137], v0, s[2:3]
	global_load_dwordx4 v[130:133], v0, s[2:3] offset:64
	v_lshlrev_b32_e32 v0, 3, v184
	v_lshl_add_u64 v[172:173], s[70:71], 0, v[0:1]
	v_lshlrev_b32_e32 v0, 1, v186
	v_lshl_add_u64 v[138:139], s[62:63], 0, v[0:1]
	v_lshlrev_b32_e32 v0, 7, v210
	s_mov_b64 s[2:3], 0x16800000
	v_and_b32_e32 v0, 0x7e780, v0
	v_lshl_add_u64 v[174:175], v[138:139], 0, s[2:3]
	v_lshl_add_u64 v[138:139], v[172:173], 0, v[0:1]
	global_load_dwordx4 v[162:165], v[138:139], off offset:16
	global_load_dwordx4 v[166:169], v[138:139], off
	global_load_dwordx4 v[154:157], v[138:139], off offset:2064
	global_load_dwordx4 v[158:161], v[138:139], off offset:2048
	v_add_co_u32_e32 v142, vcc, s75, v138
	v_xor_b32_e32 v0, 16, v225
	s_nop 0
	v_addc_co_u32_e32 v143, vcc, 0, v139, vcc
	v_cmp_lt_i32_e32 vcc, v0, v170
	v_mov_b32_e32 v214, v127
	v_mov_b32_e32 v215, v123
	v_cndmask_b32_e32 v0, v225, v0, vcc
	v_mov_b32_e32 v212, v126
	v_mov_b32_e32 v213, v122
	v_mul_f32_e32 v214, v214, v214
	v_mul_f32_e32 v215, v215, v215
	v_mov_b32_e32 v216, v129
	v_mov_b32_e32 v217, v125
	v_lshlrev_b32_e32 v176, 2, v0
	v_xor_b32_e32 v0, 32, v225
	v_fma_f32 v212, v212, v212, v214
	v_fma_f32 v213, v213, v213, v215
	v_mov_b32_e32 v214, v128
	v_mov_b32_e32 v215, v124
	v_mul_f32_e32 v216, v216, v216
	v_mul_f32_e32 v217, v217, v217
	v_cmp_lt_i32_e32 vcc, v0, v170
	v_fma_f32 v214, v214, v214, v216
	v_fma_f32 v215, v215, v215, v217
	v_ashrrev_i32_e32 v211, 31, v210
	v_cndmask_b32_e32 v0, v225, v0, vcc
	v_add_f32_e32 v212, v212, v214
	v_add_f32_e32 v213, v213, v215
	v_lshlrev_b32_e32 v177, 2, v0
	v_add_f32_e32 v0, v212, v213
	v_lshlrev_b64 v[170:171], 9, v[210:211]
	ds_bpermute_b32 v211, v176, v0
	s_mov_b64 s[2:3], 0x1000
	v_lshl_add_u64 v[140:141], v[138:139], 0, s[2:3]
	s_mov_b64 s[2:3], 0x1800
	v_lshl_add_u64 v[138:139], v[138:139], 0, s[2:3]
	s_waitcnt lgkmcnt(0)
	v_add_f32_e32 v0, v0, v211
	ds_bpermute_b32 v211, v177, v0
	global_load_dwordx4 v[150:153], v[142:143], off
	global_load_dwordx4 v[146:149], v[140:141], off offset:16
	s_nop 0
	global_load_dwordx4 v[142:145], v[142:143], off offset:2048
	s_nop 0
	global_load_dwordx4 v[138:141], v[138:139], off offset:16
	v_lshl_add_u64 v[170:171], v[174:175], 0, v[170:171]
	s_waitcnt lgkmcnt(0)
	v_add_f32_e32 v0, v0, v211
	v_fmamk_f32 v0, v0, 0x3d000000, v219
	v_cmp_gt_f32_e32 vcc, s25, v0
	v_mul_f32_e32 v211, 0x4b800000, v0
	s_lshl_b32 s20, s87, 1
	v_cndmask_b32_e32 v0, v0, v211, vcc
	v_rsq_f32_e32 v0, v0
	v_lshl_add_u64 v[170:171], v[170:171], 0, s[20:21]
	v_lshlrev_b32_e32 v189, 4, v210
	s_mov_b32 s2, 0x10000
	v_mul_f32_e32 v211, 0x45800000, v0
	v_cndmask_b32_e32 v0, v0, v211, vcc
	v_mul_f32_e32 v0, 0x3e8293ee, v0
	s_waitcnt vmcnt(0)
	v_mul_f32_e32 v212, v128, v136
	v_mul_f32_e32 v213, v129, v137
	v_mul_f32_e32 v214, v126, v134
	v_mul_f32_e32 v215, v127, v135
	v_mul_f32_e32 v228, v122, v130
	v_mul_f32_e32 v229, v123, v131
	v_mul_f32_e32 v216, v212, v0
	v_mul_f32_e32 v217, v213, v0
	v_mul_f32_e32 v214, v214, v0
	v_mul_f32_e32 v215, v215, v0
	v_mul_f32_e32 v212, v124, v132
	v_mul_f32_e32 v213, v125, v133
	v_mul_f32_e32 v228, v228, v0
	v_mul_f32_e32 v229, v229, v0
	v_mul_f32_e32 v230, v212, v0
	v_mul_f32_e32 v231, v213, v0
	v_mov_b32_e32 v212, v214
	v_mov_b32_e32 v213, v228
	v_mul_f32_e32 v212, v166, v212
	v_mul_f32_e32 v213, v167, v213
	v_mov_b32_e32 v233, v214
	v_sub_f32_e32 v0, v212, v213
	v_mov_b32_e32 v212, v215
	v_mov_b32_e32 v213, v229
	v_mul_f32_e32 v212, v168, v212
	v_mul_f32_e32 v213, v169, v213
	v_mov_b32_e32 v214, v229
	v_sub_f32_e32 v211, v212, v213
	v_mov_b32_e32 v212, v216
	v_mov_b32_e32 v213, v230
	v_mul_f32_e32 v212, v162, v212
	v_mul_f32_e32 v213, v163, v213
	v_mul_f32_e32 v214, v168, v214
	v_mul_f32_e32 v215, v169, v215
	v_sub_f32_e32 v227, v212, v213
	v_mov_b32_e32 v212, v217
	v_mov_b32_e32 v213, v231
	v_mul_f32_e32 v212, v164, v212
	v_mul_f32_e32 v213, v165, v213
	v_mov_b32_e32 v232, v228
	v_sub_f32_e32 v213, v212, v213
	v_cvt_pk_bf16_f32 v212, v0, v211
	v_add_f32_e32 v211, v214, v215
	v_mov_b32_e32 v214, v230
	v_mov_b32_e32 v215, v216
	v_mul_f32_e32 v214, v162, v214
	v_mul_f32_e32 v215, v163, v215
	v_mov_b32_e32 v216, v231
	v_cvt_pk_bf16_f32 v213, v227, v213
	v_add_f32_e32 v227, v214, v215
	v_mul_f32_e32 v214, v164, v216
	v_mul_f32_e32 v215, v165, v217
	v_mul_f32_e32 v232, v166, v232
	v_mul_f32_e32 v233, v167, v233
	v_add_f32_e32 v215, v214, v215
	v_add_f32_e32 v0, v232, v233
	v_cvt_pk_bf16_f32 v214, v0, v211
	v_cvt_pk_bf16_f32 v215, v227, v215
	v_mov_b32_e32 v216, v121
	v_permlane16_swap_b32_e32 v212, v214
	v_permlane16_swap_b32_e32 v213, v215
	global_store_dwordx4 v[170:171], v[212:215], off
	v_mov_b32_e32 v217, v117
	v_mul_f32_e32 v216, v216, v216
	v_mul_f32_e32 v217, v217, v217
	v_mov_b32_e32 v214, v119
	v_mov_b32_e32 v215, v115
	v_mov_b32_e32 v212, v118
	v_mov_b32_e32 v213, v114
	v_mul_f32_e32 v214, v214, v214
	v_mul_f32_e32 v215, v215, v215
	v_mul_f32_e32 v228, v114, v130
	v_mul_f32_e32 v229, v115, v131
	v_fma_f32 v212, v212, v212, v214
	v_fma_f32 v213, v213, v213, v215
	v_mov_b32_e32 v214, v120
	v_mov_b32_e32 v215, v116
	v_fma_f32 v214, v214, v214, v216
	v_fma_f32 v215, v215, v215, v217
	s_nop 0
	v_add_f32_e32 v212, v212, v214
	v_add_f32_e32 v213, v213, v215
	v_mul_f32_e32 v214, v118, v134
	v_mul_f32_e32 v215, v119, v135
	v_add_f32_e32 v0, v212, v213
	ds_bpermute_b32 v211, v176, v0
	v_mul_f32_e32 v212, v120, v136
	v_mul_f32_e32 v213, v121, v137
	s_waitcnt lgkmcnt(0)
;     __device__ __forceinline__ static v2u pk4(float a, float b, float c, float d) { v2u o; o.x = pg8::cvt_pk_bf16(a, b); o.y = pg8::cvt_pk_bf16(c, d); return o; }
;     __device__ __forceinline__ void sub32(const pg8::f32x4 (&acc)[2][2][4][2], int row0, int wc, int fq, bf16r* dst, const float* gain, float scale, const float2* tseq) const {
;     ...
;             for (int m = 0; m < 4; ++m) { const int row = row0 + ai * 128 + m * 16;
;                 const pg8::f32x4 cs01 = cs[m][0], cs23 = cs[m][1];
;                 const float c0 = cs01[0], s0 = cs01[1], c1 = cs01[2], s1 = cs01[3], c2 = cs23[0], s2 = cs23[1], c3 = cs23[2], s3 = cs23[3];
; #pragma unroll
;                 for (int bj = 0; bj < 2; ++bj) { const pg8::f32x4 a = acc[ai][bj][m][0], b = acc[ai][bj][m][1];
;                     float ss = ((a[0] * a[0] + a[1] * a[1]) + (a[2] * a[2] + a[3] * a[3])) + ((b[0] * b[0] + b[1] * b[1]) + (b[2] * b[2] + b[3] * b[3]));
;                     ss += __shfl_xor(ss, 16); ss += __shfl_xor(ss, 32);
;                     const float rs = rsqrtf(ss * (1.f / 32.f) + EPS) * scale;
;                     const pg8::f32x4 x1 = a * g1 * rs, x2 = b * g2 * rs;
;                     store_pair16(dst + (size_t)row * 256 + (4 * bj + wc) * 32, fq, pk4(x1[0] * c0 - x2[0] * s0, x1[1] * c1 - x2[1] * s1, x1[2] * c2 - x2[2] * s2, x1[3] * c3 - x2[3] * s3),
;                                  pk4(x2[0] * c0 + x1[0] * s0, x2[1] * c1 + x1[1] * s1, x2[2] * c2 + x1[2] * s2, x2[3] * c3 + x1[3] * s3));
;                     } } }
	v_add_f32_e32 v0, v0, v211
	ds_bpermute_b32 v211, v177, v0
	s_waitcnt lgkmcnt(0)
	v_add_f32_e32 v0, v0, v211
	v_fmamk_f32 v0, v0, 0x3d000000, v219
	v_cmp_gt_f32_e32 vcc, s25, v0
	v_mul_f32_e32 v211, 0x4b800000, v0
	s_nop 0
	v_cndmask_b32_e32 v0, v0, v211, vcc
	v_rsq_f32_e32 v0, v0
	s_nop 0
	v_mul_f32_e32 v211, 0x45800000, v0
	v_cndmask_b32_e32 v0, v0, v211, vcc
	v_mul_f32_e32 v0, 0x3e8293ee, v0
	v_mul_f32_e32 v216, v212, v0
	v_mul_f32_e32 v217, v213, v0
	v_mul_f32_e32 v214, v214, v0
	v_mul_f32_e32 v215, v215, v0
	v_mul_f32_e32 v212, v116, v132
	v_mul_f32_e32 v213, v117, v133
	v_mul_f32_e32 v228, v228, v0
	v_mul_f32_e32 v229, v229, v0
	v_mul_f32_e32 v230, v212, v0
	v_mul_f32_e32 v231, v213, v0
	v_mov_b32_e32 v212, v214
	v_mov_b32_e32 v213, v228
	v_mul_f32_e32 v212, v166, v212
	v_mul_f32_e32 v213, v167, v213
	v_mov_b32_e32 v232, v228
	v_sub_f32_e32 v0, v212, v213
	v_mov_b32_e32 v212, v215
	v_mov_b32_e32 v213, v229
	v_mul_f32_e32 v212, v168, v212
	v_mul_f32_e32 v213, v169, v213
	v_mov_b32_e32 v233, v214
	v_sub_f32_e32 v211, v212, v213
	v_mov_b32_e32 v212, v216
	v_mov_b32_e32 v213, v230
	v_mul_f32_e32 v212, v162, v212
	v_mul_f32_e32 v213, v163, v213
	v_mul_f32_e32 v166, v166, v232
	v_mul_f32_e32 v167, v167, v233
	v_sub_f32_e32 v227, v212, v213
	v_mov_b32_e32 v212, v217
	v_mov_b32_e32 v213, v231
	v_mul_f32_e32 v212, v164, v212
	v_mul_f32_e32 v213, v165, v213
	v_mov_b32_e32 v214, v229
	v_sub_f32_e32 v213, v212, v213
	v_cvt_pk_bf16_f32 v212, v0, v211
	v_add_f32_e32 v0, v166, v167
	v_mul_f32_e32 v166, v168, v214
	v_mul_f32_e32 v167, v169, v215
	v_cvt_pk_bf16_f32 v213, v227, v213
	v_mov_b32_e32 v169, v93
	v_add_f32_e32 v168, v166, v167
	v_mov_b32_e32 v166, v230
	v_mov_b32_e32 v167, v216
	v_mul_f32_e32 v162, v162, v166
	v_mul_f32_e32 v163, v163, v167
	v_mov_b32_e32 v216, v231
	v_add_f32_e32 v166, v162, v163
	v_mul_f32_e32 v162, v164, v216
	v_mul_f32_e32 v163, v165, v217
	v_cvt_pk_bf16_f32 v214, v0, v168
	v_mov_b32_e32 v164, v95
	v_add_f32_e32 v162, v162, v163
	v_cvt_pk_bf16_f32 v215, v166, v162
	v_or_b32_e32 v162, 16, v210
	v_ashrrev_i32_e32 v163, 31, v162
	v_lshlrev_b64 v[162:163], 9, v[162:163]
	v_mov_b32_e32 v165, v91
	v_lshl_add_u64 v[166:167], v[174:175], 0, v[162:163]
	v_mov_b32_e32 v162, v94
	v_mov_b32_e32 v163, v90
	v_mul_f32_e32 v164, v164, v164
	v_mul_f32_e32 v165, v165, v165
	v_mov_b32_e32 v168, v97
	v_fma_f32 v162, v162, v162, v164
	v_fma_f32 v163, v163, v163, v165
	v_mov_b32_e32 v164, v96
	v_mov_b32_e32 v165, v92
	v_mul_f32_e32 v168, v168, v168
	v_mul_f32_e32 v169, v169, v169
	v_permlane16_swap_b32_e32 v212, v214
	v_fma_f32 v164, v164, v164, v168
	v_fma_f32 v165, v165, v165, v169
	v_permlane16_swap_b32_e32 v213, v215
	v_add_f32_e32 v162, v162, v164
	v_add_f32_e32 v163, v163, v165
	global_store_dwordx4 v[170:171], v[212:215], off offset:256
	v_add_f32_e32 v0, v162, v163
	ds_bpermute_b32 v162, v176, v0
	v_mul_f32_e32 v164, v94, v134
	v_mul_f32_e32 v165, v95, v135
	v_mul_f32_e32 v212, v90, v130
	v_mul_f32_e32 v213, v91, v131
	v_lshl_add_u64 v[166:167], v[166:167], 0, s[20:21]
	s_waitcnt lgkmcnt(0)
	v_add_f32_e32 v0, v0, v162
	ds_bpermute_b32 v162, v177, v0
	s_waitcnt lgkmcnt(0)
	v_add_f32_e32 v0, v0, v162
	v_fmamk_f32 v0, v0, 0x3d000000, v219
	v_cmp_gt_f32_e32 vcc, s25, v0
	v_mul_f32_e32 v162, 0x4b800000, v0
	s_nop 0
	v_cndmask_b32_e32 v0, v0, v162, vcc
	v_rsq_f32_e32 v0, v0
	s_nop 0
	v_mul_f32_e32 v162, 0x45800000, v0
	v_cndmask_b32_e32 v0, v0, v162, vcc
	v_mul_f32_e32 v0, 0x3e8293ee, v0
	v_mul_f32_e32 v162, v96, v136
	v_mul_f32_e32 v163, v97, v137
	v_mul_f32_e32 v164, v164, v0
	v_mul_f32_e32 v165, v165, v0
	v_mul_f32_e32 v168, v162, v0
	v_mul_f32_e32 v169, v163, v0
	v_mul_f32_e32 v162, v92, v132
	v_mul_f32_e32 v163, v93, v133
	v_mul_f32_e32 v212, v212, v0
	v_mul_f32_e32 v213, v213, v0
	v_mul_f32_e32 v214, v162, v0
	v_mul_f32_e32 v215, v163, v0
	v_mov_b32_e32 v162, v164
	v_mov_b32_e32 v163, v212
	v_mul_f32_e32 v162, v158, v162
	v_mul_f32_e32 v163, v159, v163
	v_mov_b32_e32 v217, v164
	v_sub_f32_e32 v0, v162, v163
	v_mov_b32_e32 v162, v165
	v_mov_b32_e32 v163, v213
	v_mul_f32_e32 v162, v160, v162
	v_mul_f32_e32 v163, v161, v163
	v_mov_b32_e32 v164, v213
	v_sub_f32_e32 v211, v162, v163
	v_mov_b32_e32 v162, v168
	v_mov_b32_e32 v163, v214
	v_mul_f32_e32 v162, v154, v162
	v_mul_f32_e32 v163, v155, v163
	v_mul_f32_e32 v164, v160, v164
	v_mul_f32_e32 v165, v161, v165
	v_sub_f32_e32 v216, v162, v163
	v_mov_b32_e32 v162, v169
	v_mov_b32_e32 v163, v215
	v_mul_f32_e32 v162, v156, v162
	v_mul_f32_e32 v163, v157, v163
	s_nop 0
	v_sub_f32_e32 v163, v162, v163
	v_cvt_pk_bf16_f32 v162, v0, v211
	v_add_f32_e32 v211, v164, v165
	v_mov_b32_e32 v164, v214
	v_mov_b32_e32 v165, v168
	v_mul_f32_e32 v164, v154, v164
	v_mul_f32_e32 v165, v155, v165
	v_mov_b32_e32 v168, v215
	v_cvt_pk_bf16_f32 v163, v216, v163
	v_mov_b32_e32 v216, v212
	v_add_f32_e32 v212, v164, v165
	v_mul_f32_e32 v164, v156, v168
	v_mul_f32_e32 v165, v157, v169
	v_mul_f32_e32 v216, v158, v216
	v_mul_f32_e32 v217, v159, v217
	v_add_f32_e32 v165, v164, v165
	v_add_f32_e32 v0, v216, v217
	v_cvt_pk_bf16_f32 v164, v0, v211
	v_cvt_pk_bf16_f32 v165, v212, v165
	v_mov_b32_e32 v168, v89
	v_permlane16_swap_b32_e32 v162, v164
	v_permlane16_swap_b32_e32 v163, v165
	global_store_dwordx4 v[166:167], v[162:165], off
	v_mov_b32_e32 v169, v85
	v_mul_f32_e32 v168, v168, v168
	v_mul_f32_e32 v169, v169, v169
	v_mov_b32_e32 v164, v87
	v_mov_b32_e32 v165, v83
	v_mov_b32_e32 v162, v86
	v_mov_b32_e32 v163, v82
	v_mul_f32_e32 v164, v164, v164
	v_mul_f32_e32 v165, v165, v165
	v_mul_f32_e32 v212, v82, v130
	v_mul_f32_e32 v213, v83, v131
	v_fma_f32 v162, v162, v162, v164
	v_fma_f32 v163, v163, v163, v165
	v_mov_b32_e32 v164, v88
	v_mov_b32_e32 v165, v84
	v_fma_f32 v164, v164, v164, v168
	v_fma_f32 v165, v165, v165, v169
	s_nop 0
	v_add_f32_e32 v162, v162, v164
	v_add_f32_e32 v163, v163, v165
	v_mul_f32_e32 v164, v86, v134
	v_mul_f32_e32 v165, v87, v135
	v_add_f32_e32 v0, v162, v163
	ds_bpermute_b32 v162, v176, v0
	s_waitcnt lgkmcnt(0)
;     __device__ __forceinline__ static v2u pk4(float a, float b, float c, float d) { v2u o; o.x = pg8::cvt_pk_bf16(a, b); o.y = pg8::cvt_pk_bf16(c, d); return o; }
;     __device__ __forceinline__ void sub32(const pg8::f32x4 (&acc)[2][2][4][2], int row0, int wc, int fq, bf16r* dst, const float* gain, float scale, const float2* tseq) const {
;     ...
;             for (int m = 0; m < 4; ++m) { const int row = row0 + ai * 128 + m * 16;
;                 const pg8::f32x4 cs01 = cs[m][0], cs23 = cs[m][1];
;                 const float c0 = cs01[0], s0 = cs01[1], c1 = cs01[2], s1 = cs01[3], c2 = cs23[0], s2 = cs23[1], c3 = cs23[2], s3 = cs23[3];
; #pragma unroll
;                 for (int bj = 0; bj < 2; ++bj) { const pg8::f32x4 a = acc[ai][bj][m][0], b = acc[ai][bj][m][1];
;                     float ss = ((a[0] * a[0] + a[1] * a[1]) + (a[2] * a[2] + a[3] * a[3])) + ((b[0] * b[0] + b[1] * b[1]) + (b[2] * b[2] + b[3] * b[3]));
;                     ss += __shfl_xor(ss, 16); ss += __shfl_xor(ss, 32);
;                     const float rs = rsqrtf(ss * (1.f / 32.f) + EPS) * scale;
;                     const pg8::f32x4 x1 = a * g1 * rs, x2 = b * g2 * rs;
;                     store_pair16(dst + (size_t)row * 256 + (4 * bj + wc) * 32, fq, pk4(x1[0] * c0 - x2[0] * s0, x1[1] * c1 - x2[1] * s1, x1[2] * c2 - x2[2] * s2, x1[3] * c3 - x2[3] * s3),
;                                  pk4(x2[0] * c0 + x1[0] * s0, x2[1] * c1 + x1[1] * s1, x2[2] * c2 + x1[2] * s2, x2[3] * c3 + x1[3] * s3));
;                     } } }
	v_add_f32_e32 v0, v0, v162
	ds_bpermute_b32 v162, v177, v0
	s_waitcnt lgkmcnt(0)
	v_add_f32_e32 v0, v0, v162
	v_fmamk_f32 v0, v0, 0x3d000000, v219
	v_cmp_gt_f32_e32 vcc, s25, v0
	v_mul_f32_e32 v162, 0x4b800000, v0
	s_nop 0
	v_cndmask_b32_e32 v0, v0, v162, vcc
	v_rsq_f32_e32 v0, v0
	s_nop 0
	v_mul_f32_e32 v162, 0x45800000, v0
	v_cndmask_b32_e32 v0, v0, v162, vcc
	v_mul_f32_e32 v0, 0x3e8293ee, v0
	v_mul_f32_e32 v162, v88, v136
	v_mul_f32_e32 v163, v89, v137
	v_mul_f32_e32 v164, v164, v0
	v_mul_f32_e32 v165, v165, v0
	v_mul_f32_e32 v168, v162, v0
	v_mul_f32_e32 v169, v163, v0
	v_mul_f32_e32 v162, v84, v132
	v_mul_f32_e32 v163, v85, v133
	v_mul_f32_e32 v212, v212, v0
	v_mul_f32_e32 v213, v213, v0
	v_mul_f32_e32 v214, v162, v0
	v_mul_f32_e32 v215, v163, v0
	v_mov_b32_e32 v162, v164
	v_mov_b32_e32 v163, v212
	v_mul_f32_e32 v162, v158, v162
	v_mul_f32_e32 v163, v159, v163
	v_mov_b32_e32 v217, v164
	v_sub_f32_e32 v0, v162, v163
	v_mov_b32_e32 v162, v165
	v_mov_b32_e32 v163, v213
	v_mul_f32_e32 v162, v160, v162
	v_mul_f32_e32 v163, v161, v163
	v_mov_b32_e32 v164, v213
	v_sub_f32_e32 v211, v162, v163
	v_mov_b32_e32 v162, v168
	v_mov_b32_e32 v163, v214
	v_mul_f32_e32 v162, v154, v162
	v_mul_f32_e32 v163, v155, v163
	v_mov_b32_e32 v213, v109
	v_sub_f32_e32 v216, v162, v163
	v_mov_b32_e32 v162, v169
	v_mov_b32_e32 v163, v215
	v_mul_f32_e32 v162, v156, v162
	v_mul_f32_e32 v163, v157, v163
	s_nop 0
	v_sub_f32_e32 v163, v162, v163
	v_cvt_pk_bf16_f32 v162, v0, v211
	v_cvt_pk_bf16_f32 v163, v216, v163
	v_mov_b32_e32 v216, v212
	v_mul_f32_e32 v158, v158, v216
	v_mul_f32_e32 v159, v159, v217
	v_mov_b32_e32 v212, v113
	v_add_f32_e32 v0, v158, v159
	v_mul_f32_e32 v158, v160, v164
	v_mul_f32_e32 v159, v161, v165
	v_mov_b32_e32 v161, v61
	v_add_f32_e32 v160, v158, v159
	v_mov_b32_e32 v158, v214
	v_mov_b32_e32 v159, v168
	v_mul_f32_e32 v154, v154, v158
	v_mul_f32_e32 v155, v155, v159
	v_mov_b32_e32 v168, v215
	v_add_f32_e32 v158, v154, v155
	v_mul_f32_e32 v154, v156, v168
	v_mul_f32_e32 v155, v157, v169
	v_cvt_pk_bf16_f32 v164, v0, v160
	v_mov_b32_e32 v156, v63
	v_add_f32_e32 v154, v154, v155
	v_cvt_pk_bf16_f32 v165, v158, v154
	v_or_b32_e32 v154, 32, v210
	v_ashrrev_i32_e32 v155, 31, v154
	v_lshlrev_b64 v[154:155], 9, v[154:155]
	v_mov_b32_e32 v157, v59
	v_lshl_add_u64 v[158:159], v[174:175], 0, v[154:155]
	v_mov_b32_e32 v154, v62
	v_mov_b32_e32 v155, v58
	v_mul_f32_e32 v156, v156, v156
	v_mul_f32_e32 v157, v157, v157
	v_mov_b32_e32 v160, v65
	v_fma_f32 v154, v154, v154, v156
	v_fma_f32 v155, v155, v155, v157
	v_mov_b32_e32 v156, v64
	v_mov_b32_e32 v157, v60
	v_mul_f32_e32 v160, v160, v160
	v_mul_f32_e32 v161, v161, v161
	v_permlane16_swap_b32_e32 v162, v164
	v_fma_f32 v156, v156, v156, v160
	v_fma_f32 v157, v157, v157, v161
	v_permlane16_swap_b32_e32 v163, v165
	v_add_f32_e32 v154, v154, v156
	v_add_f32_e32 v155, v155, v157
	global_store_dwordx4 v[166:167], v[162:165], off offset:256
	v_add_f32_e32 v0, v154, v155
	ds_bpermute_b32 v154, v176, v0
	v_mul_f32_e32 v156, v62, v134
	v_mul_f32_e32 v157, v63, v135
	v_mul_f32_e32 v162, v58, v130
	v_mul_f32_e32 v163, v59, v131
	v_lshl_add_u64 v[158:159], v[158:159], 0, s[20:21]
	v_mul_f32_e32 v212, v212, v212
	v_mul_f32_e32 v213, v213, v213
	s_waitcnt lgkmcnt(0)
	v_add_f32_e32 v0, v0, v154
	ds_bpermute_b32 v154, v177, v0
	v_mul_f32_e32 v214, v106, v130
	v_mul_f32_e32 v215, v107, v131
	s_waitcnt lgkmcnt(0)
	v_add_f32_e32 v0, v0, v154
	v_fmamk_f32 v0, v0, 0x3d000000, v219
	v_cmp_gt_f32_e32 vcc, s25, v0
	v_mul_f32_e32 v154, 0x4b800000, v0
	s_nop 0
	v_cndmask_b32_e32 v0, v0, v154, vcc
	v_rsq_f32_e32 v0, v0
	s_nop 0
	v_mul_f32_e32 v154, 0x45800000, v0
	v_cndmask_b32_e32 v0, v0, v154, vcc
	v_mul_f32_e32 v0, 0x3e8293ee, v0
	v_mul_f32_e32 v154, v64, v136
	v_mul_f32_e32 v155, v65, v137
	v_mul_f32_e32 v156, v156, v0
	v_mul_f32_e32 v157, v157, v0
	v_mul_f32_e32 v160, v154, v0
	v_mul_f32_e32 v161, v155, v0
	v_mul_f32_e32 v154, v60, v132
	v_mul_f32_e32 v155, v61, v133
	v_mul_f32_e32 v162, v162, v0
	v_mul_f32_e32 v163, v163, v0
	v_mul_f32_e32 v164, v154, v0
	v_mul_f32_e32 v165, v155, v0
	v_mov_b32_e32 v154, v156
	v_mov_b32_e32 v155, v162
	v_mul_f32_e32 v154, v150, v154
	v_mul_f32_e32 v155, v151, v155
	s_nop 0
	v_sub_f32_e32 v0, v154, v155
	v_mov_b32_e32 v154, v157
	v_mov_b32_e32 v155, v163
	v_mul_f32_e32 v154, v152, v154
	v_mul_f32_e32 v155, v153, v155
	s_nop 0
	v_sub_f32_e32 v166, v154, v155
	v_mov_b32_e32 v154, v160
	v_mov_b32_e32 v155, v164
	v_mul_f32_e32 v154, v146, v154
	v_mul_f32_e32 v155, v147, v155
	s_nop 0
	v_sub_f32_e32 v167, v154, v155
	v_mov_b32_e32 v154, v161
	v_mov_b32_e32 v155, v165
	v_mul_f32_e32 v154, v148, v154
	v_mul_f32_e32 v155, v149, v155
	s_nop 0
	v_sub_f32_e32 v155, v154, v155
	v_cvt_pk_bf16_f32 v154, v0, v166
	v_cvt_pk_bf16_f32 v155, v167, v155
	v_mov_b32_e32 v167, v156
	v_mov_b32_e32 v156, v163
	v_mul_f32_e32 v156, v152, v156
	v_mul_f32_e32 v157, v153, v157
	v_mov_b32_e32 v166, v162
	v_add_f32_e32 v162, v156, v157
	v_mov_b32_e32 v156, v164
	v_mov_b32_e32 v157, v160
	v_mul_f32_e32 v156, v146, v156
	v_mul_f32_e32 v157, v147, v157
	v_mov_b32_e32 v160, v165
	v_add_f32_e32 v163, v156, v157
	v_mul_f32_e32 v156, v148, v160
	v_mul_f32_e32 v157, v149, v161
	v_mul_f32_e32 v166, v150, v166
	v_mul_f32_e32 v167, v151, v167
	v_add_f32_e32 v157, v156, v157
	v_add_f32_e32 v0, v166, v167
	v_cvt_pk_bf16_f32 v156, v0, v162
	v_cvt_pk_bf16_f32 v157, v163, v157
	v_mov_b32_e32 v160, v57
	v_permlane16_swap_b32_e32 v154, v156
	v_permlane16_swap_b32_e32 v155, v157
	global_store_dwordx4 v[158:159], v[154:157], off
	v_mov_b32_e32 v161, v53
	v_mul_f32_e32 v160, v160, v160
	v_mul_f32_e32 v161, v161, v161
	v_mov_b32_e32 v156, v55
	v_mov_b32_e32 v157, v51
	v_mov_b32_e32 v154, v54
	v_mov_b32_e32 v155, v50
	v_mul_f32_e32 v156, v156, v156
	v_mul_f32_e32 v157, v157, v157
	v_mul_f32_e32 v162, v50, v130
	v_mul_f32_e32 v163, v51, v131
	v_fma_f32 v154, v154, v154, v156
	v_fma_f32 v155, v155, v155, v157
	v_mov_b32_e32 v156, v56
	v_mov_b32_e32 v157, v52
	v_fma_f32 v156, v156, v156, v160
	v_fma_f32 v157, v157, v157, v161
	s_nop 0
	v_add_f32_e32 v154, v154, v156
	v_add_f32_e32 v155, v155, v157
	v_mul_f32_e32 v156, v54, v134
	v_mul_f32_e32 v157, v55, v135
	v_add_f32_e32 v0, v154, v155
	ds_bpermute_b32 v154, v176, v0
	s_waitcnt lgkmcnt(0)
;     __device__ __forceinline__ static v2u pk4(float a, float b, float c, float d) { v2u o; o.x = pg8::cvt_pk_bf16(a, b); o.y = pg8::cvt_pk_bf16(c, d); return o; }
;     __device__ __forceinline__ void sub32(const pg8::f32x4 (&acc)[2][2][4][2], int row0, int wc, int fq, bf16r* dst, const float* gain, float scale, const float2* tseq) const {
;     ...
;             for (int m = 0; m < 4; ++m) { const int row = row0 + ai * 128 + m * 16;
;                 const pg8::f32x4 cs01 = cs[m][0], cs23 = cs[m][1];
;                 const float c0 = cs01[0], s0 = cs01[1], c1 = cs01[2], s1 = cs01[3], c2 = cs23[0], s2 = cs23[1], c3 = cs23[2], s3 = cs23[3];
; #pragma unroll
;                 for (int bj = 0; bj < 2; ++bj) { const pg8::f32x4 a = acc[ai][bj][m][0], b = acc[ai][bj][m][1];
;                     float ss = ((a[0] * a[0] + a[1] * a[1]) + (a[2] * a[2] + a[3] * a[3])) + ((b[0] * b[0] + b[1] * b[1]) + (b[2] * b[2] + b[3] * b[3]));
;                     ss += __shfl_xor(ss, 16); ss += __shfl_xor(ss, 32);
;                     const float rs = rsqrtf(ss * (1.f / 32.f) + EPS) * scale;
;                     const pg8::f32x4 x1 = a * g1 * rs, x2 = b * g2 * rs;
;                     store_pair16(dst + (size_t)row * 256 + (4 * bj + wc) * 32, fq, pk4(x1[0] * c0 - x2[0] * s0, x1[1] * c1 - x2[1] * s1, x1[2] * c2 - x2[2] * s2, x1[3] * c3 - x2[3] * s3),
;                                  pk4(x2[0] * c0 + x1[0] * s0, x2[1] * c1 + x1[1] * s1, x2[2] * c2 + x1[2] * s2, x2[3] * c3 + x1[3] * s3));
;                     } } }
	v_add_f32_e32 v0, v0, v154
	ds_bpermute_b32 v154, v177, v0
	s_waitcnt lgkmcnt(0)
	v_add_f32_e32 v0, v0, v154
	v_fmamk_f32 v0, v0, 0x3d000000, v219
	v_cmp_gt_f32_e32 vcc, s25, v0
	v_mul_f32_e32 v154, 0x4b800000, v0
	s_nop 0
	v_cndmask_b32_e32 v0, v0, v154, vcc
	v_rsq_f32_e32 v0, v0
	s_nop 0
	v_mul_f32_e32 v154, 0x45800000, v0
	v_cndmask_b32_e32 v0, v0, v154, vcc
	v_mul_f32_e32 v0, 0x3e8293ee, v0
	v_mul_f32_e32 v154, v56, v136
	v_mul_f32_e32 v155, v57, v137
	v_mul_f32_e32 v156, v156, v0
	v_mul_f32_e32 v157, v157, v0
	v_mul_f32_e32 v160, v154, v0
	v_mul_f32_e32 v161, v155, v0
	v_mul_f32_e32 v154, v52, v132
	v_mul_f32_e32 v155, v53, v133
	v_mul_f32_e32 v162, v162, v0
	v_mul_f32_e32 v163, v163, v0
	v_mul_f32_e32 v164, v154, v0
	v_mul_f32_e32 v165, v155, v0
	v_mov_b32_e32 v154, v156
	v_mov_b32_e32 v155, v162
	v_mul_f32_e32 v154, v150, v154
	v_mul_f32_e32 v155, v151, v155
	s_nop 0
	v_sub_f32_e32 v0, v154, v155
	v_mov_b32_e32 v154, v157
	v_mov_b32_e32 v155, v163
	v_mul_f32_e32 v154, v152, v154
	v_mul_f32_e32 v155, v153, v155
	s_nop 0
	v_sub_f32_e32 v166, v154, v155
	v_mov_b32_e32 v154, v160
	v_mov_b32_e32 v155, v164
	v_mul_f32_e32 v154, v146, v154
	v_mul_f32_e32 v155, v147, v155
	s_nop 0
	v_sub_f32_e32 v167, v154, v155
	v_mov_b32_e32 v154, v161
	v_mov_b32_e32 v155, v165
	v_mul_f32_e32 v154, v148, v154
	v_mul_f32_e32 v155, v149, v155
	s_nop 0
	v_sub_f32_e32 v155, v154, v155
	v_cvt_pk_bf16_f32 v154, v0, v166
	v_cvt_pk_bf16_f32 v155, v167, v155
	v_mov_b32_e32 v166, v162
	v_mov_b32_e32 v167, v156
	v_mul_f32_e32 v150, v150, v166
	v_mul_f32_e32 v151, v151, v167
	v_mov_b32_e32 v156, v163
	v_add_f32_e32 v0, v150, v151
	v_mul_f32_e32 v150, v152, v156
	v_mul_f32_e32 v151, v153, v157
	v_mov_b32_e32 v153, v29
	v_add_f32_e32 v152, v150, v151
	v_mov_b32_e32 v150, v164
	v_mov_b32_e32 v151, v160
	v_mul_f32_e32 v146, v146, v150
	v_mul_f32_e32 v147, v147, v151
	v_mov_b32_e32 v160, v165
	v_add_f32_e32 v150, v146, v147
	v_mul_f32_e32 v146, v148, v160
	v_mul_f32_e32 v147, v149, v161
	v_cvt_pk_bf16_f32 v156, v0, v152
	v_mov_b32_e32 v148, v31
	v_add_f32_e32 v146, v146, v147
	v_cvt_pk_bf16_f32 v157, v150, v146
	v_or_b32_e32 v146, 48, v210
	v_ashrrev_i32_e32 v147, 31, v146
	v_lshlrev_b64 v[146:147], 9, v[146:147]
	v_mov_b32_e32 v149, v27
	v_lshl_add_u64 v[150:151], v[174:175], 0, v[146:147]
	v_mov_b32_e32 v146, v30
	v_mov_b32_e32 v147, v26
	v_mul_f32_e32 v148, v148, v148
	v_mul_f32_e32 v149, v149, v149
	v_mov_b32_e32 v152, v33
	v_fma_f32 v146, v146, v146, v148
	v_fma_f32 v147, v147, v147, v149
	v_mov_b32_e32 v148, v32
	v_mov_b32_e32 v149, v28
	v_mul_f32_e32 v152, v152, v152
	v_mul_f32_e32 v153, v153, v153
	v_permlane16_swap_b32_e32 v154, v156
	v_fma_f32 v148, v148, v148, v152
	v_fma_f32 v149, v149, v149, v153
	v_permlane16_swap_b32_e32 v155, v157
	v_add_f32_e32 v146, v146, v148
	v_add_f32_e32 v147, v147, v149
	global_store_dwordx4 v[158:159], v[154:157], off offset:256
	v_add_f32_e32 v0, v146, v147
	ds_bpermute_b32 v146, v176, v0
	v_mul_f32_e32 v148, v30, v134
	v_mul_f32_e32 v149, v31, v135
	v_mul_f32_e32 v154, v26, v130
	v_mul_f32_e32 v155, v27, v131
	v_lshl_add_u64 v[150:151], v[150:151], 0, s[20:21]
	v_mov_b32_e32 v174, v111
	s_waitcnt lgkmcnt(0)
	v_add_f32_e32 v0, v0, v146
	ds_bpermute_b32 v146, v177, v0
	v_mov_b32_e32 v175, v107
	v_mul_f32_e32 v174, v174, v174
	v_mul_f32_e32 v175, v175, v175
	s_waitcnt lgkmcnt(0)
	v_add_f32_e32 v0, v0, v146
	v_fmamk_f32 v0, v0, 0x3d000000, v219
	v_cmp_gt_f32_e32 vcc, s25, v0
	v_mul_f32_e32 v146, 0x4b800000, v0
	s_nop 0
	v_cndmask_b32_e32 v0, v0, v146, vcc
	v_rsq_f32_e32 v0, v0
	s_nop 0
	v_mul_f32_e32 v146, 0x45800000, v0
	v_cndmask_b32_e32 v0, v0, v146, vcc
	v_mul_f32_e32 v0, 0x3e8293ee, v0
	v_mul_f32_e32 v146, v32, v136
	v_mul_f32_e32 v147, v33, v137
	v_mul_f32_e32 v148, v148, v0
	v_mul_f32_e32 v149, v149, v0
	v_mul_f32_e32 v152, v146, v0
	v_mul_f32_e32 v153, v147, v0
	v_mul_f32_e32 v146, v28, v132
	v_mul_f32_e32 v147, v29, v133
	v_mul_f32_e32 v154, v154, v0
	v_mul_f32_e32 v155, v155, v0
	v_mul_f32_e32 v156, v146, v0
	v_mul_f32_e32 v157, v147, v0
	v_mov_b32_e32 v146, v148
	v_mov_b32_e32 v147, v154
	v_mul_f32_e32 v146, v142, v146
	v_mul_f32_e32 v147, v143, v147
	s_nop 0
	v_sub_f32_e32 v0, v146, v147
	v_mov_b32_e32 v146, v149
	v_mov_b32_e32 v147, v155
	v_mul_f32_e32 v146, v144, v146
	v_mul_f32_e32 v147, v145, v147
	s_nop 0
	v_sub_f32_e32 v158, v146, v147
	v_mov_b32_e32 v146, v152
	v_mov_b32_e32 v147, v156
	v_mul_f32_e32 v146, v138, v146
	v_mul_f32_e32 v147, v139, v147
	s_nop 0
	v_sub_f32_e32 v159, v146, v147
	v_mov_b32_e32 v146, v153
	v_mov_b32_e32 v147, v157
	v_mul_f32_e32 v146, v140, v146
	v_mul_f32_e32 v147, v141, v147
	s_nop 0
	v_sub_f32_e32 v147, v146, v147
	v_cvt_pk_bf16_f32 v146, v0, v158
	v_cvt_pk_bf16_f32 v147, v159, v147
	v_mov_b32_e32 v159, v148
	v_mov_b32_e32 v148, v155
	v_mul_f32_e32 v148, v144, v148
	v_mul_f32_e32 v149, v145, v149
	v_mov_b32_e32 v158, v154
	v_add_f32_e32 v154, v148, v149
	v_mov_b32_e32 v148, v156
	v_mov_b32_e32 v149, v152
	v_mul_f32_e32 v148, v138, v148
	v_mul_f32_e32 v149, v139, v149
	v_mov_b32_e32 v152, v157
	v_add_f32_e32 v155, v148, v149
	v_mul_f32_e32 v148, v140, v152
	v_mul_f32_e32 v149, v141, v153
	v_mul_f32_e32 v158, v142, v158
	v_mul_f32_e32 v159, v143, v159
	v_add_f32_e32 v149, v148, v149
	v_add_f32_e32 v0, v158, v159
	v_cvt_pk_bf16_f32 v148, v0, v154
	v_cvt_pk_bf16_f32 v149, v155, v149
	v_mov_b32_e32 v152, v25
	v_permlane16_swap_b32_e32 v146, v148
	v_permlane16_swap_b32_e32 v147, v149
	global_store_dwordx4 v[150:151], v[146:149], off
	v_mov_b32_e32 v153, v21
	v_mul_f32_e32 v152, v152, v152
	v_mul_f32_e32 v153, v153, v153
	v_mov_b32_e32 v148, v23
	v_mov_b32_e32 v149, v19
	v_mov_b32_e32 v146, v22
	v_mov_b32_e32 v147, v18
	v_mul_f32_e32 v148, v148, v148
	v_mul_f32_e32 v149, v149, v149
	v_mul_f32_e32 v154, v18, v130
	v_mul_f32_e32 v155, v19, v131
	v_fma_f32 v146, v146, v146, v148
	v_fma_f32 v147, v147, v147, v149
	v_mov_b32_e32 v148, v24
	v_mov_b32_e32 v149, v20
	v_fma_f32 v148, v148, v148, v152
	v_fma_f32 v149, v149, v149, v153
	s_nop 0
	v_add_f32_e32 v146, v146, v148
	v_add_f32_e32 v147, v147, v149
	v_mul_f32_e32 v148, v22, v134
	v_mul_f32_e32 v149, v23, v135
	v_add_f32_e32 v0, v146, v147
	ds_bpermute_b32 v146, v176, v0
	s_waitcnt lgkmcnt(0)
;     __device__ __forceinline__ static v2u pk4(float a, float b, float c, float d) { v2u o; o.x = pg8::cvt_pk_bf16(a, b); o.y = pg8::cvt_pk_bf16(c, d); return o; }
;     __device__ __forceinline__ void sub32(const pg8::f32x4 (&acc)[2][2][4][2], int row0, int wc, int fq, bf16r* dst, const float* gain, float scale, const float2* tseq) const {
;     ...
;         for (int ai = 0; ai < 2; ++ai) {
;             pg8::f32x4 cs[4][2];
; #pragma unroll
;             for (int m = 0; m < 4; ++m) { const float2* tab = tseq + ((row0 + ai * 128 + m * 16) & (SEQ - 1)) * 16 + 4 * fq; cs[m][0] = *(const pg8::f32x4*)tab; cs[m][1] = *(const pg8::f32x4*)(tab + 2); }
;             asm volatile("" ::: "memory");
; #pragma unroll
;             for (int m = 0; m < 4; ++m) { const int row = row0 + ai * 128 + m * 16;
;                 const pg8::f32x4 cs01 = cs[m][0], cs23 = cs[m][1];
;                 const float c0 = cs01[0], s0 = cs01[1], c1 = cs01[2], s1 = cs01[3], c2 = cs23[0], s2 = cs23[1], c3 = cs23[2], s3 = cs23[3];
; #pragma unroll
;                 for (int bj = 0; bj < 2; ++bj) { const pg8::f32x4 a = acc[ai][bj][m][0], b = acc[ai][bj][m][1];
;                     float ss = ((a[0] * a[0] + a[1] * a[1]) + (a[2] * a[2] + a[3] * a[3])) + ((b[0] * b[0] + b[1] * b[1]) + (b[2] * b[2] + b[3] * b[3]));
;                     ss += __shfl_xor(ss, 16); ss += __shfl_xor(ss, 32);
;                     const float rs = rsqrtf(ss * (1.f / 32.f) + EPS) * scale;
;                     const pg8::f32x4 x1 = a * g1 * rs, x2 = b * g2 * rs;
;                     store_pair16(dst + (size_t)row * 256 + (4 * bj + wc) * 32, fq, pk4(x1[0] * c0 - x2[0] * s0, x1[1] * c1 - x2[1] * s1, x1[2] * c2 - x2[2] * s2, x1[3] * c3 - x2[3] * s3),
;                                  pk4(x2[0] * c0 + x1[0] * s0, x2[1] * c1 + x1[1] * s1, x2[2] * c2 + x1[2] * s2, x2[3] * c3 + x1[3] * s3));
;                     } } }
	v_add_f32_e32 v0, v0, v146
	ds_bpermute_b32 v146, v177, v0
	s_waitcnt lgkmcnt(0)
	v_add_f32_e32 v0, v0, v146
	v_fmamk_f32 v0, v0, 0x3d000000, v219
	v_cmp_gt_f32_e32 vcc, s25, v0
	v_mul_f32_e32 v146, 0x4b800000, v0
	s_nop 0
	v_cndmask_b32_e32 v0, v0, v146, vcc
	v_rsq_f32_e32 v0, v0
	s_nop 0
	v_mul_f32_e32 v146, 0x45800000, v0
	v_cndmask_b32_e32 v0, v0, v146, vcc
	v_mul_f32_e32 v0, 0x3e8293ee, v0
	v_mul_f32_e32 v146, v24, v136
	v_mul_f32_e32 v147, v25, v137
	v_mul_f32_e32 v148, v148, v0
	v_mul_f32_e32 v149, v149, v0
	v_mul_f32_e32 v152, v146, v0
	v_mul_f32_e32 v153, v147, v0
	v_mul_f32_e32 v146, v20, v132
	v_mul_f32_e32 v147, v21, v133
	v_mul_f32_e32 v154, v154, v0
	v_mul_f32_e32 v155, v155, v0
	v_mul_f32_e32 v156, v146, v0
	v_mul_f32_e32 v157, v147, v0
	v_mov_b32_e32 v146, v148
	v_mov_b32_e32 v147, v154
	v_mul_f32_e32 v146, v142, v146
	v_mul_f32_e32 v147, v143, v147
	s_nop 0
	v_sub_f32_e32 v0, v146, v147
	v_mov_b32_e32 v146, v149
	v_mov_b32_e32 v147, v155
	v_mul_f32_e32 v146, v144, v146
	v_mul_f32_e32 v147, v145, v147
	s_nop 0
	v_sub_f32_e32 v158, v146, v147
	v_mov_b32_e32 v146, v152
	v_mov_b32_e32 v147, v156
	v_mul_f32_e32 v146, v138, v146
	v_mul_f32_e32 v147, v139, v147
	s_nop 0
	v_sub_f32_e32 v159, v146, v147
	v_mov_b32_e32 v146, v153
	v_mov_b32_e32 v147, v157
	v_mul_f32_e32 v146, v140, v146
	v_mul_f32_e32 v147, v141, v147
	s_nop 0
	v_sub_f32_e32 v147, v146, v147
	v_cvt_pk_bf16_f32 v146, v0, v158
	v_cvt_pk_bf16_f32 v147, v159, v147
	v_mov_b32_e32 v158, v154
	v_mov_b32_e32 v159, v148
	v_mul_f32_e32 v142, v142, v158
	v_mul_f32_e32 v143, v143, v159
	v_mov_b32_e32 v148, v155
	v_add_f32_e32 v0, v142, v143
	v_mul_f32_e32 v142, v144, v148
	v_mul_f32_e32 v143, v145, v149
	s_nop 0
	v_add_f32_e32 v144, v142, v143
	v_mov_b32_e32 v142, v156
	v_mov_b32_e32 v143, v152
	v_mul_f32_e32 v138, v138, v142
	v_mul_f32_e32 v139, v139, v143
	v_mov_b32_e32 v152, v157
	v_add_f32_e32 v142, v138, v139
	v_mul_f32_e32 v138, v140, v152
	v_mul_f32_e32 v139, v141, v153
	v_cvt_pk_bf16_f32 v148, v0, v144
	v_add_u32_e32 v0, 0x800, v189
	v_add_f32_e32 v138, v138, v139
	v_cvt_pk_bf16_f32 v149, v142, v138
	v_and_b32_e32 v0, 0xfcf0, v0
	v_permlane16_swap_b32_e32 v146, v148
	v_permlane16_swap_b32_e32 v147, v149
	v_lshlrev_b32_e32 v0, 3, v0
	global_store_dwordx4 v[150:151], v[146:149], off offset:256
	v_lshl_add_u64 v[138:139], v[172:173], 0, v[0:1]
	global_load_dwordx4 v[162:165], v[138:139], off offset:16
	global_load_dwordx4 v[166:169], v[138:139], off
	v_add_u32_e32 v0, 0x900, v189
	v_and_b32_e32 v0, 0xfdf0, v0
	v_lshlrev_b32_e32 v0, 3, v0
	v_lshl_add_u64 v[138:139], v[172:173], 0, v[0:1]
	v_add_u32_e32 v0, 0xa00, v189
	v_and_b32_e32 v0, 0xfef0, v0
	v_lshlrev_b32_e32 v0, 3, v0
	global_load_dwordx4 v[154:157], v[138:139], off offset:16
	global_load_dwordx4 v[158:161], v[138:139], off
	v_lshl_add_u64 v[138:139], v[172:173], 0, v[0:1]
	v_add_u32_e32 v0, 0xb00, v189
	v_and_b32_e32 v0, 0xfff0, v0
	v_lshlrev_b32_e32 v0, 3, v0
	v_lshl_add_u64 v[142:143], v[172:173], 0, v[0:1]
	v_mov_b32_e32 v172, v110
	v_mov_b32_e32 v173, v106
	v_fma_f32 v172, v172, v172, v174
	v_fma_f32 v173, v173, v173, v175
	v_mov_b32_e32 v174, v112
	v_mov_b32_e32 v175, v108
	v_fma_f32 v174, v174, v174, v212
	v_fma_f32 v175, v175, v175, v213
	global_load_dwordx4 v[146:149], v[138:139], off offset:16
	global_load_dwordx4 v[150:153], v[138:139], off
	v_add_f32_e32 v172, v172, v174
	v_add_f32_e32 v173, v173, v175
	v_mul_f32_e32 v174, v110, v134
	v_mul_f32_e32 v175, v111, v135
	v_add_f32_e32 v0, v172, v173
	ds_bpermute_b32 v172, v176, v0
	global_load_dwordx4 v[138:141], v[142:143], off offset:16
	s_nop 0
	global_load_dwordx4 v[142:145], v[142:143], off
	s_waitcnt lgkmcnt(0)
	v_add_f32_e32 v0, v0, v172
	ds_bpermute_b32 v172, v177, v0
	s_waitcnt lgkmcnt(0)
	v_add_f32_e32 v0, v0, v172
	v_fmamk_f32 v0, v0, 0x3d000000, v219
	v_cmp_gt_f32_e32 vcc, s25, v0
	v_mul_f32_e32 v172, 0x4b800000, v0
	s_nop 0
	v_cndmask_b32_e32 v0, v0, v172, vcc
	v_rsq_f32_e32 v0, v0
	s_nop 0
	v_mul_f32_e32 v172, 0x45800000, v0
	v_cndmask_b32_e32 v0, v0, v172, vcc
	v_mul_f32_e32 v0, 0x3e8293ee, v0
	v_mul_f32_e32 v172, v112, v136
	v_mul_f32_e32 v173, v113, v137
	v_mul_f32_e32 v174, v174, v0
	v_mul_f32_e32 v175, v175, v0
	v_mul_f32_e32 v212, v172, v0
	v_mul_f32_e32 v213, v173, v0
	v_mul_f32_e32 v172, v108, v132
	v_mul_f32_e32 v173, v109, v133
	v_mul_f32_e32 v214, v214, v0
	v_mul_f32_e32 v215, v215, v0
	v_mul_f32_e32 v216, v172, v0
	v_mul_f32_e32 v217, v173, v0
	v_mov_b32_e32 v172, v174
	v_mov_b32_e32 v173, v214
	v_mov_b32_e32 v229, v174
	v_mov_b32_e32 v174, v215
	v_mov_b32_e32 v228, v214
	v_add_co_u32_e32 v214, vcc, s2, v170
	s_mov_b64 s[2:3], 0x12000
	s_waitcnt vmcnt(6)
;     __device__ __forceinline__ static v2u pk4(float a, float b, float c, float d) { v2u o; o.x = pg8::cvt_pk_bf16(a, b); o.y = pg8::cvt_pk_bf16(c, d); return o; }
;     __device__ __forceinline__ void sub32(const pg8::f32x4 (&acc)[2][2][4][2], int row0, int wc, int fq, bf16r* dst, const float* gain, float scale, const float2* tseq) const {
;     ...
;             for (int m = 0; m < 4; ++m) { const int row = row0 + ai * 128 + m * 16;
;                 const pg8::f32x4 cs01 = cs[m][0], cs23 = cs[m][1];
;                 const float c0 = cs01[0], s0 = cs01[1], c1 = cs01[2], s1 = cs01[3], c2 = cs23[0], s2 = cs23[1], c3 = cs23[2], s3 = cs23[3];
; #pragma unroll
;                 for (int bj = 0; bj < 2; ++bj) { const pg8::f32x4 a = acc[ai][bj][m][0], b = acc[ai][bj][m][1];
;                     float ss = ((a[0] * a[0] + a[1] * a[1]) + (a[2] * a[2] + a[3] * a[3])) + ((b[0] * b[0] + b[1] * b[1]) + (b[2] * b[2] + b[3] * b[3]));
;                     ss += __shfl_xor(ss, 16); ss += __shfl_xor(ss, 32);
;                     const float rs = rsqrtf(ss * (1.f / 32.f) + EPS) * scale;
;                     const pg8::f32x4 x1 = a * g1 * rs, x2 = b * g2 * rs;
;                     store_pair16(dst + (size_t)row * 256 + (4 * bj + wc) * 32, fq, pk4(x1[0] * c0 - x2[0] * s0, x1[1] * c1 - x2[1] * s1, x1[2] * c2 - x2[2] * s2, x1[3] * c3 - x2[3] * s3),
;                                  pk4(x2[0] * c0 + x1[0] * s0, x2[1] * c1 + x1[1] * s1, x2[2] * c2 + x1[2] * s2, x2[3] * c3 + x1[3] * s3));
;                     } } }
	v_mul_f32_e32 v172, v166, v172
	v_mul_f32_e32 v173, v167, v173
	s_nop 0
	v_sub_f32_e32 v0, v172, v173
	v_mov_b32_e32 v172, v175
	v_mov_b32_e32 v173, v215
	v_mul_f32_e32 v172, v168, v172
	v_mul_f32_e32 v173, v169, v173
	v_mul_f32_e32 v174, v168, v174
	v_mul_f32_e32 v175, v169, v175
	v_sub_f32_e32 v189, v172, v173
	v_mov_b32_e32 v172, v212
	v_mov_b32_e32 v173, v216
	v_mul_f32_e32 v172, v162, v172
	v_mul_f32_e32 v173, v163, v173
	v_mul_f32_e32 v228, v166, v228
	v_mul_f32_e32 v229, v167, v229
	v_sub_f32_e32 v211, v172, v173
	v_mov_b32_e32 v172, v213
	v_mov_b32_e32 v173, v217
	v_mul_f32_e32 v172, v164, v172
	v_mul_f32_e32 v173, v165, v173
	v_addc_co_u32_e32 v215, vcc, 0, v171, vcc
	v_sub_f32_e32 v173, v172, v173
	v_cvt_pk_bf16_f32 v172, v0, v189
	v_add_f32_e32 v189, v174, v175
	v_mov_b32_e32 v174, v216
	v_mov_b32_e32 v175, v212
	v_mul_f32_e32 v174, v162, v174
	v_mul_f32_e32 v175, v163, v175
	v_mov_b32_e32 v212, v217
	v_cvt_pk_bf16_f32 v173, v211, v173
	v_add_f32_e32 v211, v174, v175
	v_mul_f32_e32 v174, v164, v212
	v_mul_f32_e32 v175, v165, v213
	v_add_f32_e32 v0, v228, v229
	v_add_f32_e32 v175, v174, v175
	v_cvt_pk_bf16_f32 v174, v0, v189
	v_cvt_pk_bf16_f32 v175, v211, v175
	v_mul_f32_e32 v216, v98, v130
	v_mul_f32_e32 v217, v99, v131
	v_permlane16_swap_b32_e32 v172, v174
	v_permlane16_swap_b32_e32 v173, v175
	global_store_dwordx4 v[214:215], v[172:175], off
	v_mov_b32_e32 v214, v105
	v_mov_b32_e32 v215, v101
	v_mov_b32_e32 v174, v103
	v_mov_b32_e32 v175, v99
	v_mov_b32_e32 v172, v102
	v_mov_b32_e32 v173, v98
	v_mul_f32_e32 v174, v174, v174
	v_mul_f32_e32 v175, v175, v175
	v_mul_f32_e32 v214, v214, v214
	v_mul_f32_e32 v215, v215, v215
	v_fma_f32 v172, v172, v172, v174
	v_fma_f32 v173, v173, v173, v175
	v_mov_b32_e32 v174, v104
	v_mov_b32_e32 v175, v100
	v_fma_f32 v174, v174, v174, v214
	v_fma_f32 v175, v175, v175, v215
	v_lshl_add_u64 v[212:213], v[170:171], 0, s[92:93]
	v_add_f32_e32 v172, v172, v174
	v_add_f32_e32 v173, v173, v175
	v_mul_f32_e32 v174, v102, v134
	v_mul_f32_e32 v175, v103, v135
	v_add_f32_e32 v0, v172, v173
	ds_bpermute_b32 v172, v176, v0
	s_waitcnt lgkmcnt(0)
	v_add_f32_e32 v0, v0, v172
	ds_bpermute_b32 v172, v177, v0
	s_waitcnt lgkmcnt(0)
	v_add_f32_e32 v0, v0, v172
	v_fmamk_f32 v0, v0, 0x3d000000, v219
	v_cmp_gt_f32_e32 vcc, s25, v0
	v_mul_f32_e32 v172, 0x4b800000, v0
	s_nop 0
	v_cndmask_b32_e32 v0, v0, v172, vcc
	v_rsq_f32_e32 v0, v0
	s_nop 0
	v_mul_f32_e32 v172, 0x45800000, v0
	v_cndmask_b32_e32 v0, v0, v172, vcc
	v_mul_f32_e32 v0, 0x3e8293ee, v0
	v_mul_f32_e32 v172, v104, v136
	v_mul_f32_e32 v173, v105, v137
	v_mul_f32_e32 v174, v174, v0
	v_mul_f32_e32 v175, v175, v0
	v_mul_f32_e32 v214, v172, v0
	v_mul_f32_e32 v215, v173, v0
	v_mul_f32_e32 v172, v100, v132
	v_mul_f32_e32 v173, v101, v133
	v_mul_f32_e32 v216, v216, v0
	v_mul_f32_e32 v217, v217, v0
	v_mul_f32_e32 v228, v172, v0
	v_mul_f32_e32 v229, v173, v0
	v_mov_b32_e32 v172, v174
	v_mov_b32_e32 v173, v216
	v_mul_f32_e32 v172, v166, v172
	v_mul_f32_e32 v173, v167, v173
	v_mov_b32_e32 v230, v216
	v_sub_f32_e32 v0, v172, v173
	v_mov_b32_e32 v172, v175
	v_mov_b32_e32 v173, v217
	v_mul_f32_e32 v172, v168, v172
	v_mul_f32_e32 v173, v169, v173
	v_mov_b32_e32 v231, v174
	v_sub_f32_e32 v189, v172, v173
	v_mov_b32_e32 v172, v214
	v_mov_b32_e32 v173, v228
	v_mul_f32_e32 v172, v162, v172
	v_mul_f32_e32 v173, v163, v173
	v_mul_f32_e32 v166, v166, v230
	v_mul_f32_e32 v167, v167, v231
	v_sub_f32_e32 v211, v172, v173
	v_mov_b32_e32 v172, v215
	v_mov_b32_e32 v173, v229
	v_mul_f32_e32 v172, v164, v172
	v_mul_f32_e32 v173, v165, v173
	v_mov_b32_e32 v174, v217
	v_sub_f32_e32 v173, v172, v173
	v_cvt_pk_bf16_f32 v172, v0, v189
	v_add_f32_e32 v0, v166, v167
	v_mul_f32_e32 v166, v168, v174
	v_mul_f32_e32 v167, v169, v175
	v_cvt_pk_bf16_f32 v173, v211, v173
	s_nop 0
	v_add_f32_e32 v168, v166, v167
	v_mov_b32_e32 v166, v228
	v_mov_b32_e32 v167, v214
	v_mul_f32_e32 v162, v162, v166
	v_mul_f32_e32 v163, v163, v167
	v_mov_b32_e32 v214, v229
	v_add_f32_e32 v166, v162, v163
	v_mul_f32_e32 v162, v164, v214
	v_mul_f32_e32 v163, v165, v215
	v_mov_b32_e32 v164, v79
	v_add_f32_e32 v162, v162, v163
	v_mov_b32_e32 v165, v75
	v_cvt_pk_bf16_f32 v174, v0, v168
	v_cvt_pk_bf16_f32 v175, v166, v162
	v_mov_b32_e32 v162, v78
	v_mov_b32_e32 v163, v74
	v_mul_f32_e32 v164, v164, v164
	v_mul_f32_e32 v165, v165, v165
	v_mov_b32_e32 v166, v81
	v_mov_b32_e32 v167, v77
	v_fma_f32 v162, v162, v162, v164
	v_fma_f32 v163, v163, v163, v165
	v_mov_b32_e32 v164, v80
	v_mov_b32_e32 v165, v76
	v_mul_f32_e32 v166, v166, v166
	v_mul_f32_e32 v167, v167, v167
	v_mul_f32_e32 v168, v74, v130
	v_mul_f32_e32 v169, v75, v131
	v_fma_f32 v164, v164, v164, v166
	v_fma_f32 v165, v165, v165, v167
	v_permlane16_swap_b32_e32 v172, v174
	v_add_f32_e32 v162, v162, v164
	v_add_f32_e32 v163, v163, v165
	v_mul_f32_e32 v164, v78, v134
	v_mul_f32_e32 v165, v79, v135
	v_add_f32_e32 v0, v162, v163
	ds_bpermute_b32 v162, v176, v0
	v_permlane16_swap_b32_e32 v173, v175
	global_store_dwordx4 v[212:213], v[172:175], off offset:256
	s_waitcnt lgkmcnt(0)
	v_add_f32_e32 v0, v0, v162
	ds_bpermute_b32 v162, v177, v0
	s_waitcnt lgkmcnt(0)
	v_add_f32_e32 v0, v0, v162
	v_fmamk_f32 v0, v0, 0x3d000000, v219
	v_cmp_gt_f32_e32 vcc, s25, v0
	v_mul_f32_e32 v162, 0x4b800000, v0
	s_nop 0
	v_cndmask_b32_e32 v0, v0, v162, vcc
	v_rsq_f32_e32 v0, v0
	s_nop 0
	v_mul_f32_e32 v162, 0x45800000, v0
	v_cndmask_b32_e32 v0, v0, v162, vcc
	v_mul_f32_e32 v0, 0x3e8293ee, v0
	v_mul_f32_e32 v162, v80, v136
	v_mul_f32_e32 v163, v81, v137
	v_mul_f32_e32 v164, v164, v0
	v_mul_f32_e32 v165, v165, v0
	v_mul_f32_e32 v166, v162, v0
	v_mul_f32_e32 v167, v163, v0
	v_mul_f32_e32 v162, v76, v132
	v_mul_f32_e32 v163, v77, v133
	v_mul_f32_e32 v168, v168, v0
	v_mul_f32_e32 v169, v169, v0
	v_mul_f32_e32 v172, v162, v0
	v_mul_f32_e32 v173, v163, v0
	v_mov_b32_e32 v162, v164
	v_mov_b32_e32 v163, v168
	s_waitcnt vmcnt(6)
;     __device__ __forceinline__ static v2u pk4(float a, float b, float c, float d) { v2u o; o.x = pg8::cvt_pk_bf16(a, b); o.y = pg8::cvt_pk_bf16(c, d); return o; }
;     __device__ __forceinline__ void sub32(const pg8::f32x4 (&acc)[2][2][4][2], int row0, int wc, int fq, bf16r* dst, const float* gain, float scale, const float2* tseq) const {
;     ...
;             for (int m = 0; m < 4; ++m) { const int row = row0 + ai * 128 + m * 16;
;                 const pg8::f32x4 cs01 = cs[m][0], cs23 = cs[m][1];
;                 const float c0 = cs01[0], s0 = cs01[1], c1 = cs01[2], s1 = cs01[3], c2 = cs23[0], s2 = cs23[1], c3 = cs23[2], s3 = cs23[3];
; #pragma unroll
;                 for (int bj = 0; bj < 2; ++bj) { const pg8::f32x4 a = acc[ai][bj][m][0], b = acc[ai][bj][m][1];
;                     float ss = ((a[0] * a[0] + a[1] * a[1]) + (a[2] * a[2] + a[3] * a[3])) + ((b[0] * b[0] + b[1] * b[1]) + (b[2] * b[2] + b[3] * b[3]));
;                     ss += __shfl_xor(ss, 16); ss += __shfl_xor(ss, 32);
;                     const float rs = rsqrtf(ss * (1.f / 32.f) + EPS) * scale;
;                     const pg8::f32x4 x1 = a * g1 * rs, x2 = b * g2 * rs;
;                     store_pair16(dst + (size_t)row * 256 + (4 * bj + wc) * 32, fq, pk4(x1[0] * c0 - x2[0] * s0, x1[1] * c1 - x2[1] * s1, x1[2] * c2 - x2[2] * s2, x1[3] * c3 - x2[3] * s3),
;                                  pk4(x2[0] * c0 + x1[0] * s0, x2[1] * c1 + x1[1] * s1, x2[2] * c2 + x1[2] * s2, x2[3] * c3 + x1[3] * s3));
;                     } } }
	v_mul_f32_e32 v162, v158, v162
	v_mul_f32_e32 v163, v159, v163
	s_nop 0
	v_sub_f32_e32 v0, v162, v163
	v_mov_b32_e32 v162, v165
	v_mov_b32_e32 v163, v169
	v_mul_f32_e32 v162, v160, v162
	v_mul_f32_e32 v163, v161, v163
	s_nop 0
	v_sub_f32_e32 v174, v162, v163
	v_mov_b32_e32 v162, v166
	v_mov_b32_e32 v163, v172
	v_mul_f32_e32 v162, v154, v162
	v_mul_f32_e32 v163, v155, v163
	s_nop 0
	v_sub_f32_e32 v175, v162, v163
	v_mov_b32_e32 v162, v167
	v_mov_b32_e32 v163, v173
	v_mul_f32_e32 v162, v156, v162
	v_mul_f32_e32 v163, v157, v163
	s_nop 0
	v_sub_f32_e32 v163, v162, v163
	v_cvt_pk_bf16_f32 v162, v0, v174
	v_cvt_pk_bf16_f32 v163, v175, v163
	v_mov_b32_e32 v175, v164
	v_mov_b32_e32 v164, v169
	v_mul_f32_e32 v164, v160, v164
	v_mul_f32_e32 v165, v161, v165
	v_mov_b32_e32 v174, v168
	v_add_f32_e32 v168, v164, v165
	v_mov_b32_e32 v164, v172
	v_mov_b32_e32 v165, v166
	v_mul_f32_e32 v164, v154, v164
	v_mul_f32_e32 v165, v155, v165
	v_mov_b32_e32 v166, v173
	v_add_f32_e32 v169, v164, v165
	v_mul_f32_e32 v164, v156, v166
	v_mul_f32_e32 v165, v157, v167
	v_mul_f32_e32 v174, v158, v174
	v_mul_f32_e32 v175, v159, v175
	v_add_f32_e32 v165, v164, v165
	v_lshl_add_u64 v[166:167], v[170:171], 0, s[2:3]
	s_mov_b32 s2, 0x12000
	v_add_f32_e32 v0, v174, v175
	v_cvt_pk_bf16_f32 v164, v0, v168
	v_cvt_pk_bf16_f32 v165, v169, v165
	v_add_co_u32_e32 v168, vcc, s2, v170
	v_permlane16_swap_b32_e32 v162, v164
	v_permlane16_swap_b32_e32 v163, v165
	v_addc_co_u32_e32 v169, vcc, 0, v171, vcc
	global_store_dwordx4 v[168:169], v[162:165], off
	v_mov_b32_e32 v168, v73
	v_mov_b32_e32 v169, v69
	v_mov_b32_e32 v164, v71
	v_mov_b32_e32 v165, v67
	v_mov_b32_e32 v162, v70
	v_mov_b32_e32 v163, v66
	v_mul_f32_e32 v164, v164, v164
	v_mul_f32_e32 v165, v165, v165
	v_mul_f32_e32 v168, v168, v168
	v_mul_f32_e32 v169, v169, v169
	v_fma_f32 v162, v162, v162, v164
	v_fma_f32 v163, v163, v163, v165
	v_mov_b32_e32 v164, v72
	v_mov_b32_e32 v165, v68
	v_fma_f32 v164, v164, v164, v168
	v_fma_f32 v165, v165, v165, v169
	v_mul_f32_e32 v172, v66, v130
	v_mul_f32_e32 v173, v67, v131
	v_add_f32_e32 v162, v162, v164
	v_add_f32_e32 v163, v163, v165
	v_mul_f32_e32 v164, v70, v134
	v_mul_f32_e32 v165, v71, v135
	v_add_f32_e32 v0, v162, v163
	ds_bpermute_b32 v162, v176, v0
	s_mov_b64 s[2:3], 0x14000
	s_waitcnt lgkmcnt(0)
	v_add_f32_e32 v0, v0, v162
	ds_bpermute_b32 v162, v177, v0
	s_waitcnt lgkmcnt(0)
	v_add_f32_e32 v0, v0, v162
	v_fmamk_f32 v0, v0, 0x3d000000, v219
	v_cmp_gt_f32_e32 vcc, s25, v0
	v_mul_f32_e32 v162, 0x4b800000, v0
	s_nop 0
	v_cndmask_b32_e32 v0, v0, v162, vcc
	v_rsq_f32_e32 v0, v0
	s_nop 0
	v_mul_f32_e32 v162, 0x45800000, v0
	v_cndmask_b32_e32 v0, v0, v162, vcc
	v_mul_f32_e32 v0, 0x3e8293ee, v0
	v_mul_f32_e32 v162, v72, v136
	v_mul_f32_e32 v163, v73, v137
	v_mul_f32_e32 v164, v164, v0
	v_mul_f32_e32 v165, v165, v0
	v_mul_f32_e32 v168, v162, v0
	v_mul_f32_e32 v169, v163, v0
	v_mul_f32_e32 v162, v68, v132
	v_mul_f32_e32 v163, v69, v133
	v_mul_f32_e32 v172, v172, v0
	v_mul_f32_e32 v173, v173, v0
	v_mul_f32_e32 v174, v162, v0
	v_mul_f32_e32 v175, v163, v0
	v_mov_b32_e32 v162, v164
	v_mov_b32_e32 v163, v172
	v_mul_f32_e32 v162, v158, v162
	v_mul_f32_e32 v163, v159, v163
	v_mov_b32_e32 v212, v172
	v_sub_f32_e32 v0, v162, v163
	v_mov_b32_e32 v162, v165
	v_mov_b32_e32 v163, v173
	v_mul_f32_e32 v162, v160, v162
	v_mul_f32_e32 v163, v161, v163
	v_mov_b32_e32 v213, v164
	v_sub_f32_e32 v189, v162, v163
	v_mov_b32_e32 v162, v168
	v_mov_b32_e32 v163, v174
	v_mul_f32_e32 v162, v154, v162
	v_mul_f32_e32 v163, v155, v163
	v_mul_f32_e32 v158, v158, v212
	v_mul_f32_e32 v159, v159, v213
	v_sub_f32_e32 v211, v162, v163
	v_mov_b32_e32 v162, v169
	v_mov_b32_e32 v163, v175
	v_mul_f32_e32 v162, v156, v162
	v_mul_f32_e32 v163, v157, v163
	v_mov_b32_e32 v164, v173
	v_sub_f32_e32 v163, v162, v163
	v_cvt_pk_bf16_f32 v162, v0, v189
	v_add_f32_e32 v0, v158, v159
	v_mul_f32_e32 v158, v160, v164
	v_mul_f32_e32 v159, v161, v165
	v_cvt_pk_bf16_f32 v163, v211, v163
	s_nop 0
	v_add_f32_e32 v160, v158, v159
	v_mov_b32_e32 v158, v174
	v_mov_b32_e32 v159, v168
	v_mul_f32_e32 v154, v154, v158
	v_mul_f32_e32 v155, v155, v159
	v_mov_b32_e32 v168, v175
	v_add_f32_e32 v158, v154, v155
	v_mul_f32_e32 v154, v156, v168
	v_mul_f32_e32 v155, v157, v169
	v_mov_b32_e32 v156, v47
	v_add_f32_e32 v154, v154, v155
	v_mov_b32_e32 v157, v43
	v_cvt_pk_bf16_f32 v164, v0, v160
	v_cvt_pk_bf16_f32 v165, v158, v154
	v_mov_b32_e32 v154, v46
	v_mov_b32_e32 v155, v42
	v_mul_f32_e32 v156, v156, v156
	v_mul_f32_e32 v157, v157, v157
	v_mov_b32_e32 v158, v49
	v_mov_b32_e32 v159, v45
	v_fma_f32 v154, v154, v154, v156
	v_fma_f32 v155, v155, v155, v157
	v_mov_b32_e32 v156, v48
	v_mov_b32_e32 v157, v44
	v_mul_f32_e32 v158, v158, v158
	v_mul_f32_e32 v159, v159, v159
	v_mul_f32_e32 v160, v42, v130
	v_mul_f32_e32 v161, v43, v131
	v_fma_f32 v156, v156, v156, v158
	v_fma_f32 v157, v157, v157, v159
	v_permlane16_swap_b32_e32 v162, v164
	v_add_f32_e32 v154, v154, v156
	v_add_f32_e32 v155, v155, v157
	v_mul_f32_e32 v156, v46, v134
	v_mul_f32_e32 v157, v47, v135
	v_add_f32_e32 v0, v154, v155
	ds_bpermute_b32 v154, v176, v0
	v_permlane16_swap_b32_e32 v163, v165
	global_store_dwordx4 v[166:167], v[162:165], off offset:256
	s_waitcnt lgkmcnt(0)
	v_add_f32_e32 v0, v0, v154
	ds_bpermute_b32 v154, v177, v0
	s_waitcnt lgkmcnt(0)
;     __device__ __forceinline__ static v2u pk4(float a, float b, float c, float d) { v2u o; o.x = pg8::cvt_pk_bf16(a, b); o.y = pg8::cvt_pk_bf16(c, d); return o; }
;     __device__ __forceinline__ void sub32(const pg8::f32x4 (&acc)[2][2][4][2], int row0, int wc, int fq, bf16r* dst, const float* gain, float scale, const float2* tseq) const {
;     ...
;             for (int m = 0; m < 4; ++m) { const int row = row0 + ai * 128 + m * 16;
;                 const pg8::f32x4 cs01 = cs[m][0], cs23 = cs[m][1];
;                 const float c0 = cs01[0], s0 = cs01[1], c1 = cs01[2], s1 = cs01[3], c2 = cs23[0], s2 = cs23[1], c3 = cs23[2], s3 = cs23[3];
; #pragma unroll
;                 for (int bj = 0; bj < 2; ++bj) { const pg8::f32x4 a = acc[ai][bj][m][0], b = acc[ai][bj][m][1];
;                     float ss = ((a[0] * a[0] + a[1] * a[1]) + (a[2] * a[2] + a[3] * a[3])) + ((b[0] * b[0] + b[1] * b[1]) + (b[2] * b[2] + b[3] * b[3]));
;                     ss += __shfl_xor(ss, 16); ss += __shfl_xor(ss, 32);
;                     const float rs = rsqrtf(ss * (1.f / 32.f) + EPS) * scale;
;                     const pg8::f32x4 x1 = a * g1 * rs, x2 = b * g2 * rs;
;                     store_pair16(dst + (size_t)row * 256 + (4 * bj + wc) * 32, fq, pk4(x1[0] * c0 - x2[0] * s0, x1[1] * c1 - x2[1] * s1, x1[2] * c2 - x2[2] * s2, x1[3] * c3 - x2[3] * s3),
;                                  pk4(x2[0] * c0 + x1[0] * s0, x2[1] * c1 + x1[1] * s1, x2[2] * c2 + x1[2] * s2, x2[3] * c3 + x1[3] * s3));
;                     } } }
	v_add_f32_e32 v0, v0, v154
	v_fmamk_f32 v0, v0, 0x3d000000, v219
	v_cmp_gt_f32_e32 vcc, s25, v0
	v_mul_f32_e32 v154, 0x4b800000, v0
	s_nop 0
	v_cndmask_b32_e32 v0, v0, v154, vcc
	v_rsq_f32_e32 v0, v0
	s_nop 0
	v_mul_f32_e32 v154, 0x45800000, v0
	v_cndmask_b32_e32 v0, v0, v154, vcc
	v_mul_f32_e32 v0, 0x3e8293ee, v0
	v_mul_f32_e32 v154, v48, v136
	v_mul_f32_e32 v155, v49, v137
	v_mul_f32_e32 v156, v156, v0
	v_mul_f32_e32 v157, v157, v0
	v_mul_f32_e32 v158, v154, v0
	v_mul_f32_e32 v159, v155, v0
	v_mul_f32_e32 v154, v44, v132
	v_mul_f32_e32 v155, v45, v133
	v_mul_f32_e32 v160, v160, v0
	v_mul_f32_e32 v161, v161, v0
	v_mul_f32_e32 v162, v154, v0
	v_mul_f32_e32 v163, v155, v0
	v_mov_b32_e32 v154, v156
	v_mov_b32_e32 v155, v160
	s_waitcnt vmcnt(6)
	v_mul_f32_e32 v154, v150, v154
	v_mul_f32_e32 v155, v151, v155
	s_nop 0
	v_sub_f32_e32 v0, v154, v155
	v_mov_b32_e32 v154, v157
	v_mov_b32_e32 v155, v161
	v_mul_f32_e32 v154, v152, v154
	v_mul_f32_e32 v155, v153, v155
	s_nop 0
	v_sub_f32_e32 v164, v154, v155
	v_mov_b32_e32 v154, v158
	v_mov_b32_e32 v155, v162
	v_mul_f32_e32 v154, v146, v154
	v_mul_f32_e32 v155, v147, v155
	s_nop 0
	v_sub_f32_e32 v165, v154, v155
	v_mov_b32_e32 v154, v159
	v_mov_b32_e32 v155, v163
	v_mul_f32_e32 v154, v148, v154
	v_mul_f32_e32 v155, v149, v155
	s_nop 0
	v_sub_f32_e32 v155, v154, v155
	v_cvt_pk_bf16_f32 v154, v0, v164
	v_cvt_pk_bf16_f32 v155, v165, v155
	v_mov_b32_e32 v165, v156
	v_mov_b32_e32 v156, v161
	v_mul_f32_e32 v156, v152, v156
	v_mul_f32_e32 v157, v153, v157
	v_mov_b32_e32 v164, v160
	v_add_f32_e32 v160, v156, v157
	v_mov_b32_e32 v156, v162
	v_mov_b32_e32 v157, v158
	v_mul_f32_e32 v156, v146, v156
	v_mul_f32_e32 v157, v147, v157
	v_mov_b32_e32 v158, v163
	v_add_f32_e32 v161, v156, v157
	v_mul_f32_e32 v156, v148, v158
	v_mul_f32_e32 v157, v149, v159
	v_mul_f32_e32 v164, v150, v164
	v_mul_f32_e32 v165, v151, v165
	v_add_f32_e32 v157, v156, v157
	v_lshl_add_u64 v[158:159], v[170:171], 0, s[2:3]
	s_mov_b32 s2, 0x14000
	v_add_f32_e32 v0, v164, v165
	v_cvt_pk_bf16_f32 v156, v0, v160
	v_cvt_pk_bf16_f32 v157, v161, v157
	v_add_co_u32_e32 v160, vcc, s2, v170
	v_permlane16_swap_b32_e32 v154, v156
	v_permlane16_swap_b32_e32 v155, v157
	v_addc_co_u32_e32 v161, vcc, 0, v171, vcc
	global_store_dwordx4 v[160:161], v[154:157], off
	v_mov_b32_e32 v160, v41
	v_mov_b32_e32 v161, v37
	v_mov_b32_e32 v156, v39
	v_mov_b32_e32 v157, v35
	v_mov_b32_e32 v154, v38
	v_mov_b32_e32 v155, v34
	v_mul_f32_e32 v156, v156, v156
	v_mul_f32_e32 v157, v157, v157
	v_mul_f32_e32 v160, v160, v160
	v_mul_f32_e32 v161, v161, v161
	v_fma_f32 v154, v154, v154, v156
	v_fma_f32 v155, v155, v155, v157
	v_mov_b32_e32 v156, v40
	v_mov_b32_e32 v157, v36
	v_fma_f32 v156, v156, v156, v160
	v_fma_f32 v157, v157, v157, v161
	v_mul_f32_e32 v162, v34, v130
	v_mul_f32_e32 v163, v35, v131
	v_add_f32_e32 v154, v154, v156
	v_add_f32_e32 v155, v155, v157
	v_mul_f32_e32 v156, v38, v134
	v_mul_f32_e32 v157, v39, v135
	v_add_f32_e32 v0, v154, v155
	ds_bpermute_b32 v154, v176, v0
	s_mov_b64 s[2:3], 0x16000
	s_waitcnt lgkmcnt(0)
	v_add_f32_e32 v0, v0, v154
	ds_bpermute_b32 v154, v177, v0
	s_waitcnt lgkmcnt(0)
	v_add_f32_e32 v0, v0, v154
	v_fmamk_f32 v0, v0, 0x3d000000, v219
	v_cmp_gt_f32_e32 vcc, s25, v0
	v_mul_f32_e32 v154, 0x4b800000, v0
	s_nop 0
	v_cndmask_b32_e32 v0, v0, v154, vcc
	v_rsq_f32_e32 v0, v0
	s_nop 0
	v_mul_f32_e32 v154, 0x45800000, v0
	v_cndmask_b32_e32 v0, v0, v154, vcc
	v_mul_f32_e32 v0, 0x3e8293ee, v0
	v_mul_f32_e32 v154, v40, v136
	v_mul_f32_e32 v155, v41, v137
	v_mul_f32_e32 v156, v156, v0
	v_mul_f32_e32 v157, v157, v0
	v_mul_f32_e32 v160, v154, v0
	v_mul_f32_e32 v161, v155, v0
	v_mul_f32_e32 v154, v36, v132
	v_mul_f32_e32 v155, v37, v133
	v_mul_f32_e32 v162, v162, v0
	v_mul_f32_e32 v163, v163, v0
	v_mul_f32_e32 v164, v154, v0
	v_mul_f32_e32 v165, v155, v0
	v_mov_b32_e32 v154, v156
	v_mov_b32_e32 v155, v162
	v_mul_f32_e32 v154, v150, v154
	v_mul_f32_e32 v155, v151, v155
	s_nop 0
	v_sub_f32_e32 v0, v154, v155
	v_mov_b32_e32 v154, v157
	v_mov_b32_e32 v155, v163
	v_mul_f32_e32 v154, v152, v154
	v_mul_f32_e32 v155, v153, v155
	s_nop 0
	v_sub_f32_e32 v166, v154, v155
	v_mov_b32_e32 v154, v160
	v_mov_b32_e32 v155, v164
	v_mul_f32_e32 v154, v146, v154
	v_mul_f32_e32 v155, v147, v155
	s_nop 0
	v_sub_f32_e32 v167, v154, v155
	v_mov_b32_e32 v154, v161
	v_mov_b32_e32 v155, v165
	v_mul_f32_e32 v154, v148, v154
	v_mul_f32_e32 v155, v149, v155
	s_nop 0
	v_sub_f32_e32 v155, v154, v155
	v_cvt_pk_bf16_f32 v154, v0, v166
	v_cvt_pk_bf16_f32 v155, v167, v155
	v_mov_b32_e32 v166, v162
	v_mov_b32_e32 v167, v156
	v_mul_f32_e32 v150, v150, v166
	v_mul_f32_e32 v151, v151, v167
	v_mov_b32_e32 v156, v163
	v_add_f32_e32 v0, v150, v151
	v_mul_f32_e32 v150, v152, v156
	v_mul_f32_e32 v151, v153, v157
	s_nop 0
	v_add_f32_e32 v152, v150, v151
	v_mov_b32_e32 v150, v164
	v_mov_b32_e32 v151, v160
	v_mul_f32_e32 v146, v146, v150
	v_mul_f32_e32 v147, v147, v151
	v_mov_b32_e32 v160, v165
	v_add_f32_e32 v150, v146, v147
	v_mul_f32_e32 v146, v148, v160
	v_mul_f32_e32 v147, v149, v161
	v_mov_b32_e32 v148, v15
	v_add_f32_e32 v146, v146, v147
	v_mov_b32_e32 v149, v11
	v_cvt_pk_bf16_f32 v156, v0, v152
	v_cvt_pk_bf16_f32 v157, v150, v146
	v_mov_b32_e32 v146, v14
	v_mov_b32_e32 v147, v10
	v_mul_f32_e32 v148, v148, v148
	v_mul_f32_e32 v149, v149, v149
	v_mov_b32_e32 v150, v17
	v_mov_b32_e32 v151, v13
	v_fma_f32 v146, v146, v146, v148
	v_fma_f32 v147, v147, v147, v149
	v_mov_b32_e32 v148, v16
	v_mov_b32_e32 v149, v12
	v_mul_f32_e32 v150, v150, v150
	v_mul_f32_e32 v151, v151, v151
	v_mul_f32_e32 v152, v10, v130
	v_mul_f32_e32 v153, v11, v131
	v_fma_f32 v148, v148, v148, v150
	v_fma_f32 v149, v149, v149, v151
	v_permlane16_swap_b32_e32 v154, v156
	v_add_f32_e32 v146, v146, v148
	v_add_f32_e32 v147, v147, v149
	v_mul_f32_e32 v148, v14, v134
	v_mul_f32_e32 v149, v15, v135
	v_add_f32_e32 v0, v146, v147
	ds_bpermute_b32 v146, v176, v0
	v_permlane16_swap_b32_e32 v155, v157
	global_store_dwordx4 v[158:159], v[154:157], off offset:256
	v_mul_f32_e32 v134, v6, v134
	v_mul_f32_e32 v135, v7, v135
	s_waitcnt lgkmcnt(0)
;     __device__ __forceinline__ static v2u pk4(float a, float b, float c, float d) { v2u o; o.x = pg8::cvt_pk_bf16(a, b); o.y = pg8::cvt_pk_bf16(c, d); return o; }
;     __device__ __forceinline__ void sub32(const pg8::f32x4 (&acc)[2][2][4][2], int row0, int wc, int fq, bf16r* dst, const float* gain, float scale, const float2* tseq) const {
;     ...
;             for (int m = 0; m < 4; ++m) { const int row = row0 + ai * 128 + m * 16;
;                 const pg8::f32x4 cs01 = cs[m][0], cs23 = cs[m][1];
;                 const float c0 = cs01[0], s0 = cs01[1], c1 = cs01[2], s1 = cs01[3], c2 = cs23[0], s2 = cs23[1], c3 = cs23[2], s3 = cs23[3];
; #pragma unroll
;                 for (int bj = 0; bj < 2; ++bj) { const pg8::f32x4 a = acc[ai][bj][m][0], b = acc[ai][bj][m][1];
;                     float ss = ((a[0] * a[0] + a[1] * a[1]) + (a[2] * a[2] + a[3] * a[3])) + ((b[0] * b[0] + b[1] * b[1]) + (b[2] * b[2] + b[3] * b[3]));
;                     ss += __shfl_xor(ss, 16); ss += __shfl_xor(ss, 32);
;                     const float rs = rsqrtf(ss * (1.f / 32.f) + EPS) * scale;
;                     const pg8::f32x4 x1 = a * g1 * rs, x2 = b * g2 * rs;
;                     store_pair16(dst + (size_t)row * 256 + (4 * bj + wc) * 32, fq, pk4(x1[0] * c0 - x2[0] * s0, x1[1] * c1 - x2[1] * s1, x1[2] * c2 - x2[2] * s2, x1[3] * c3 - x2[3] * s3),
;                                  pk4(x2[0] * c0 + x1[0] * s0, x2[1] * c1 + x1[1] * s1, x2[2] * c2 + x1[2] * s2, x2[3] * c3 + x1[3] * s3));
;                     } } }
	v_add_f32_e32 v0, v0, v146
	ds_bpermute_b32 v146, v177, v0
	v_mul_f32_e32 v130, v2, v130
	v_mul_f32_e32 v131, v3, v131
	s_waitcnt lgkmcnt(0)
	v_add_f32_e32 v0, v0, v146
	v_fmamk_f32 v0, v0, 0x3d000000, v219
	v_cmp_gt_f32_e32 vcc, s25, v0
	v_mul_f32_e32 v146, 0x4b800000, v0
	s_nop 0
	v_cndmask_b32_e32 v0, v0, v146, vcc
	v_rsq_f32_e32 v0, v0
	s_nop 0
	v_mul_f32_e32 v146, 0x45800000, v0
	v_cndmask_b32_e32 v0, v0, v146, vcc
	v_mul_f32_e32 v0, 0x3e8293ee, v0
	v_mul_f32_e32 v146, v16, v136
	v_mul_f32_e32 v147, v17, v137
	v_mul_f32_e32 v148, v148, v0
	v_mul_f32_e32 v149, v149, v0
	v_mul_f32_e32 v150, v146, v0
	v_mul_f32_e32 v151, v147, v0
	v_mul_f32_e32 v146, v12, v132
	v_mul_f32_e32 v147, v13, v133
	v_mul_f32_e32 v152, v152, v0
	v_mul_f32_e32 v153, v153, v0
	v_mul_f32_e32 v154, v146, v0
	v_mul_f32_e32 v155, v147, v0
	v_mov_b32_e32 v146, v148
	v_mov_b32_e32 v147, v152
	s_waitcnt vmcnt(6)
	v_mul_f32_e32 v146, v142, v146
	v_mul_f32_e32 v147, v143, v147
	v_mul_f32_e32 v136, v8, v136
	v_mul_f32_e32 v137, v9, v137
	v_sub_f32_e32 v0, v146, v147
	v_mov_b32_e32 v146, v149
	v_mov_b32_e32 v147, v153
	v_mul_f32_e32 v146, v144, v146
	v_mul_f32_e32 v147, v145, v147
	v_mul_f32_e32 v132, v4, v132
	v_mul_f32_e32 v133, v5, v133
	v_sub_f32_e32 v156, v146, v147
	v_mov_b32_e32 v146, v150
	v_mov_b32_e32 v147, v154
	v_mul_f32_e32 v146, v138, v146
	v_mul_f32_e32 v147, v139, v147
	s_nop 0
	v_sub_f32_e32 v157, v146, v147
	v_mov_b32_e32 v146, v151
	v_mov_b32_e32 v147, v155
	v_mul_f32_e32 v146, v140, v146
	v_mul_f32_e32 v147, v141, v147
	s_nop 0
	v_sub_f32_e32 v147, v146, v147
	v_cvt_pk_bf16_f32 v146, v0, v156
	v_cvt_pk_bf16_f32 v147, v157, v147
	v_mov_b32_e32 v157, v148
	v_mov_b32_e32 v148, v153
	v_mul_f32_e32 v148, v144, v148
	v_mul_f32_e32 v149, v145, v149
	v_mov_b32_e32 v156, v152
	v_add_f32_e32 v152, v148, v149
	v_mov_b32_e32 v148, v154
	v_mov_b32_e32 v149, v150
	v_mul_f32_e32 v148, v138, v148
	v_mul_f32_e32 v149, v139, v149
	v_mov_b32_e32 v150, v155
	v_add_f32_e32 v153, v148, v149
	v_mul_f32_e32 v148, v140, v150
	v_mul_f32_e32 v149, v141, v151
	v_mul_f32_e32 v156, v142, v156
	v_mul_f32_e32 v157, v143, v157
	v_add_f32_e32 v149, v148, v149
	v_lshl_add_u64 v[150:151], v[170:171], 0, s[2:3]
	s_mov_b32 s2, 0x16000
	v_add_f32_e32 v0, v156, v157
	v_cvt_pk_bf16_f32 v148, v0, v152
	v_cvt_pk_bf16_f32 v149, v153, v149
	v_add_co_u32_e32 v152, vcc, s2, v170
	v_permlane16_swap_b32_e32 v146, v148
	v_permlane16_swap_b32_e32 v147, v149
	v_addc_co_u32_e32 v153, vcc, 0, v171, vcc
	global_store_dwordx4 v[152:153], v[146:149], off
	v_mov_b32_e32 v152, v9
	v_mov_b32_e32 v153, v5
	v_mov_b32_e32 v148, v7
	v_mov_b32_e32 v149, v3
	v_mov_b32_e32 v146, v6
	v_mov_b32_e32 v147, v2
	v_mul_f32_e32 v148, v148, v148
	v_mul_f32_e32 v149, v149, v149
	v_mul_f32_e32 v152, v152, v152
	v_mul_f32_e32 v153, v153, v153
	v_fma_f32 v146, v146, v146, v148
	v_fma_f32 v147, v147, v147, v149
	v_mov_b32_e32 v148, v8
	v_mov_b32_e32 v149, v4
	v_fma_f32 v148, v148, v148, v152
	v_fma_f32 v149, v149, v149, v153
	s_nop 0
	v_add_f32_e32 v146, v146, v148
	v_add_f32_e32 v147, v147, v149
	s_nop 0
	v_add_f32_e32 v0, v146, v147
	ds_bpermute_b32 v146, v176, v0
	s_waitcnt lgkmcnt(0)
	v_add_f32_e32 v0, v0, v146
	ds_bpermute_b32 v146, v177, v0
	s_waitcnt lgkmcnt(0)
	v_add_f32_e32 v0, v0, v146
	v_fmamk_f32 v0, v0, 0x3d000000, v219
	v_cmp_gt_f32_e32 vcc, s25, v0
	v_mul_f32_e32 v146, 0x4b800000, v0
	s_nop 0
	v_cndmask_b32_e32 v0, v0, v146, vcc
	v_rsq_f32_e32 v0, v0
	s_nop 0
	v_mul_f32_e32 v146, 0x45800000, v0
	v_cndmask_b32_e32 v0, v0, v146, vcc
	v_mul_f32_e32 v0, 0x3e8293ee, v0
	v_mul_f32_e32 v134, v134, v0
	v_mul_f32_e32 v135, v135, v0
	v_mul_f32_e32 v146, v130, v0
	v_mul_f32_e32 v147, v131, v0
	v_mov_b32_e32 v130, v134
	v_mov_b32_e32 v131, v146
	v_mul_f32_e32 v130, v142, v130
	v_mul_f32_e32 v131, v143, v131
	v_mul_f32_e32 v136, v136, v0
	v_mul_f32_e32 v137, v137, v0
	v_mul_f32_e32 v132, v132, v0
	v_mul_f32_e32 v133, v133, v0
	v_sub_f32_e32 v0, v130, v131
	v_mov_b32_e32 v130, v135
	v_mov_b32_e32 v131, v147
	v_mul_f32_e32 v130, v144, v130
	v_mul_f32_e32 v131, v145, v131
	s_nop 0
	v_sub_f32_e32 v148, v130, v131
	v_mov_b32_e32 v130, v136
	v_mov_b32_e32 v131, v132
	v_mul_f32_e32 v130, v138, v130
	v_mul_f32_e32 v131, v139, v131
	s_nop 0
	v_sub_f32_e32 v149, v130, v131
	v_mov_b32_e32 v130, v137
	v_mov_b32_e32 v131, v133
	v_mul_f32_e32 v130, v140, v130
	v_mul_f32_e32 v131, v141, v131
	s_nop 0
	v_sub_f32_e32 v131, v130, v131
	v_cvt_pk_bf16_f32 v130, v0, v148
	v_cvt_pk_bf16_f32 v131, v149, v131
	v_mov_b32_e32 v148, v146
	v_mov_b32_e32 v149, v134
	v_mov_b32_e32 v134, v147
	v_mul_f32_e32 v142, v142, v148
	v_mul_f32_e32 v143, v143, v149
	v_mul_f32_e32 v134, v144, v134
	v_mul_f32_e32 v135, v145, v135
	v_add_f32_e32 v0, v142, v143
	v_add_f32_e32 v142, v134, v135
	v_mov_b32_e32 v135, v136
	v_mov_b32_e32 v136, v133
	v_mov_b32_e32 v134, v132
	v_mul_f32_e32 v132, v140, v136
	v_mul_f32_e32 v133, v141, v137
	v_mul_f32_e32 v134, v138, v134
	v_mul_f32_e32 v135, v139, v135
	v_add_f32_e32 v133, v132, v133
	v_add_f32_e32 v134, v134, v135
	v_cvt_pk_bf16_f32 v132, v0, v142
	v_cvt_pk_bf16_f32 v133, v134, v133
	s_nop 0
	v_permlane16_swap_b32_e32 v130, v132
	v_permlane16_swap_b32_e32 v131, v133
	global_store_dwordx4 v[150:151], v[130:133], off offset:256

; __device__ __forceinline__ float silu_f(float v) { return v * __builtin_amdgcn_rcpf(1.f + __builtin_amdgcn_exp2f(-1.4426950408889634f * v)); }
; __device__ __forceinline__ v4u pack8(const float (&f)[8]) { v4u o; o.x = pk2(f[0], f[1]); o.y = pk2(f[2], f[3]); o.z = pk2(f[4], f[5]); o.w = pk2(f[6], f[7]); return o; }
; __device__ __forceinline__ unsigned f2bf(float f) { unsigned u = __builtin_bit_cast(unsigned, f); return (u + 0x7fffu + ((u >> 16) & 1u)) >> 16; }
; __device__ __forceinline__ unsigned pk2(float lo, float hi) { return f2bf(lo) | (f2bf(hi) << 16); }
;     template <bool SILU> __device__ __forceinline__ void pairmul(const pg8::f32x4 (&acc)[2][2][4][2], int row0, bf16r* dst0) const {
; #pragma unroll
;         for (int ai = 0; ai < 2; ++ai)
; #pragma unroll
;             for (int m = 0; m < 4; ++m) { float y[8];
; #pragma unroll
;                 for (int n = 0; n < 2; ++n)
; #pragma unroll
;                     for (int e = 0; e < 4; ++e) { const float p = acc[ai][0][m][n][e], q = acc[ai][1][m][n][e]; y[4 * n + e] = SILU ? silu_f(q) * p : p * q; }
;                 *(v4u*)(dst0 + (size_t)(row0 + ai * 128 + m * 16) * DIN) = pack8(y); }
.LBB0_259:
	s_and_b64 vcc, exec, s[68:69]
	s_cbranch_vccz .LBB0_261
	s_lshl_b32 s2, s35, 8
	s_waitcnt lgkmcnt(0)
	s_add_u32 s2, s62, s2
	s_addc_u32 s3, s63, 0
	s_lshl_b32 s14, s87, 1
	s_add_u32 s2, s2, s14
	s_addc_u32 s3, s3, 0
	v_lshlrev_b32_e32 v0, 1, v182
	v_mul_f32_e32 v132, v128, v120
	v_mul_f32_e32 v133, v129, v121
	v_mul_f32_e32 v134, v126, v118
	v_mul_f32_e32 v135, v127, v119
	v_mul_f32_e32 v136, v124, v116
	v_mul_f32_e32 v137, v125, v117
	v_mul_f32_e32 v138, v122, v114
	v_mul_f32_e32 v139, v123, v115
	v_lshl_add_u64 v[130:131], s[2:3], 0, v[0:1]
	v_bfe_u32 v0, v137, 16, 1
	v_bfe_u32 v140, v133, 16, 1
	v_bfe_u32 v141, v139, 16, 1
	v_bfe_u32 v142, v135, 16, 1
	v_add3_u32 v133, v133, v140, s72
	v_add3_u32 v0, v137, v0, s72
	v_add3_u32 v137, v135, v142, s72
	v_add3_u32 v139, v139, v141, s72
	v_bfe_u32 v135, v132, 16, 1
	v_bfe_u32 v140, v136, 16, 1
	v_bfe_u32 v141, v134, 16, 1
	v_bfe_u32 v142, v138, 16, 1
	s_mov_b64 s[2:3], 0x6000b00
	v_add3_u32 v136, v136, v140, s72
	v_add3_u32 v132, v132, v135, s72
	v_add3_u32 v135, v138, v142, s72
	v_add3_u32 v134, v134, v141, s72
	v_lshl_add_u64 v[130:131], v[130:131], 0, s[2:3]
	v_lshrrev_b32_e32 v132, 16, v132
	v_lshrrev_b32_e32 v136, 16, v136
	v_lshrrev_b32_e32 v138, 16, v134
	v_lshrrev_b32_e32 v134, 16, v135
	s_movk_i32 s14, 0x1e00
	v_and_or_b32 v135, v0, s55, v136
	v_and_or_b32 v133, v133, s55, v132
	v_and_or_b32 v134, v139, s55, v134
	v_and_or_b32 v132, v137, s55, v138
	v_mad_i64_i32 v[136:137], s[2:3], v210, s14, v[130:131]
	global_store_dwordx4 v[136:137], v[132:135], off
	v_mul_f32_e32 v136, v92, v84
	v_mul_f32_e32 v137, v93, v85
	v_mul_f32_e32 v138, v90, v82
	v_mul_f32_e32 v139, v91, v83
	v_mul_f32_e32 v132, v96, v88
	v_mul_f32_e32 v133, v97, v89
	v_mul_f32_e32 v134, v94, v86
	v_mul_f32_e32 v135, v95, v87
	v_bfe_u32 v140, v133, 16, 1
	v_bfe_u32 v0, v137, 16, 1
	v_bfe_u32 v141, v139, 16, 1
	v_bfe_u32 v142, v135, 16, 1
	v_add3_u32 v133, v133, v140, s72
	v_bfe_u32 v140, v136, 16, 1
	v_add3_u32 v0, v137, v0, s72
	v_add3_u32 v137, v135, v142, s72
	v_add3_u32 v139, v139, v141, s72
	v_bfe_u32 v135, v132, 16, 1
	v_bfe_u32 v141, v134, 16, 1
	v_bfe_u32 v142, v138, 16, 1
	v_add3_u32 v136, v136, v140, s72
	v_add3_u32 v132, v132, v135, s72
	v_add3_u32 v135, v138, v142, s72
	v_add3_u32 v134, v134, v141, s72
	v_lshrrev_b32_e32 v136, 16, v136
	v_lshrrev_b32_e32 v132, 16, v132
	v_lshrrev_b32_e32 v138, 16, v134
	v_lshrrev_b32_e32 v134, 16, v135
	v_and_or_b32 v135, v0, s55, v136
	v_or_b32_e32 v0, 16, v210
	v_and_or_b32 v133, v133, s55, v132
	v_and_or_b32 v134, v139, s55, v134
	v_and_or_b32 v132, v137, s55, v138
	v_mad_i64_i32 v[136:137], s[2:3], v0, s14, v[130:131]
	global_store_dwordx4 v[136:137], v[132:135], off
	v_mul_f32_e32 v136, v60, v52
	v_mul_f32_e32 v137, v61, v53
	v_mul_f32_e32 v138, v58, v50
	v_mul_f32_e32 v139, v59, v51
	v_mul_f32_e32 v132, v64, v56
	v_mul_f32_e32 v133, v65, v57
	v_mul_f32_e32 v134, v62, v54
	v_mul_f32_e32 v135, v63, v55
	v_bfe_u32 v140, v133, 16, 1
	v_bfe_u32 v0, v137, 16, 1
	v_bfe_u32 v141, v139, 16, 1
	v_bfe_u32 v142, v135, 16, 1
	v_add3_u32 v133, v133, v140, s72
	v_bfe_u32 v140, v136, 16, 1
	v_add3_u32 v0, v137, v0, s72
	v_add3_u32 v137, v135, v142, s72
	v_add3_u32 v139, v139, v141, s72
	v_bfe_u32 v135, v132, 16, 1
	v_bfe_u32 v141, v134, 16, 1
	v_bfe_u32 v142, v138, 16, 1
	v_add3_u32 v136, v136, v140, s72
	v_add3_u32 v132, v132, v135, s72
	v_add3_u32 v135, v138, v142, s72
	v_add3_u32 v134, v134, v141, s72
	v_lshrrev_b32_e32 v136, 16, v136
	v_lshrrev_b32_e32 v132, 16, v132
	v_lshrrev_b32_e32 v138, 16, v134
	v_lshrrev_b32_e32 v134, 16, v135
	v_and_or_b32 v135, v0, s55, v136
	v_or_b32_e32 v0, 32, v210
	v_and_or_b32 v133, v133, s55, v132
	v_and_or_b32 v134, v139, s55, v134
	v_and_or_b32 v132, v137, s55, v138
	v_mad_i64_i32 v[136:137], s[2:3], v0, s14, v[130:131]
	global_store_dwordx4 v[136:137], v[132:135], off
	v_mul_f32_e32 v136, v28, v20
	v_mul_f32_e32 v137, v29, v21
	v_mul_f32_e32 v138, v26, v18
	v_mul_f32_e32 v139, v27, v19
	v_mul_f32_e32 v132, v32, v24
	v_mul_f32_e32 v133, v33, v25
	v_mul_f32_e32 v134, v30, v22
	v_mul_f32_e32 v135, v31, v23
	v_bfe_u32 v140, v133, 16, 1
	v_bfe_u32 v0, v137, 16, 1
	v_bfe_u32 v141, v139, 16, 1
	v_bfe_u32 v142, v135, 16, 1
	v_add3_u32 v133, v133, v140, s72
	v_bfe_u32 v140, v136, 16, 1
	v_add3_u32 v0, v137, v0, s72
	v_add3_u32 v137, v135, v142, s72
	v_add3_u32 v139, v139, v141, s72
	v_bfe_u32 v135, v132, 16, 1
	v_bfe_u32 v141, v134, 16, 1
	v_bfe_u32 v142, v138, 16, 1
	v_add3_u32 v136, v136, v140, s72
	v_add3_u32 v132, v132, v135, s72
	v_add3_u32 v135, v138, v142, s72
	v_add3_u32 v134, v134, v141, s72
	v_lshrrev_b32_e32 v136, 16, v136
	v_lshrrev_b32_e32 v132, 16, v132
	v_lshrrev_b32_e32 v138, 16, v134
	v_lshrrev_b32_e32 v134, 16, v135
	v_and_or_b32 v135, v0, s55, v136
	v_or_b32_e32 v0, 48, v210
	v_and_or_b32 v133, v133, s55, v132
; __device__ __forceinline__ float silu_f(float v) { return v * __builtin_amdgcn_rcpf(1.f + __builtin_amdgcn_exp2f(-1.4426950408889634f * v)); }
; __device__ __forceinline__ v4u pack8(const float (&f)[8]) { v4u o; o.x = pk2(f[0], f[1]); o.y = pk2(f[2], f[3]); o.z = pk2(f[4], f[5]); o.w = pk2(f[6], f[7]); return o; }
; __device__ __forceinline__ unsigned f2bf(float f) { unsigned u = __builtin_bit_cast(unsigned, f); return (u + 0x7fffu + ((u >> 16) & 1u)) >> 16; }
; __device__ __forceinline__ unsigned pk2(float lo, float hi) { return f2bf(lo) | (f2bf(hi) << 16); }
;     template <bool SILU> __device__ __forceinline__ void pairmul(const pg8::f32x4 (&acc)[2][2][4][2], int row0, bf16r* dst0) const {
; #pragma unroll
;         for (int ai = 0; ai < 2; ++ai)
; #pragma unroll
;             for (int m = 0; m < 4; ++m) { float y[8];
; #pragma unroll
;                 for (int n = 0; n < 2; ++n)
; #pragma unroll
;                     for (int e = 0; e < 4; ++e) { const float p = acc[ai][0][m][n][e], q = acc[ai][1][m][n][e]; y[4 * n + e] = SILU ? silu_f(q) * p : p * q; }
;                 *(v4u*)(dst0 + (size_t)(row0 + ai * 128 + m * 16) * DIN) = pack8(y); }
	v_and_or_b32 v134, v139, s55, v134
	v_and_or_b32 v132, v137, s55, v138
	v_mad_i64_i32 v[136:137], s[2:3], v0, s14, v[130:131]
	global_store_dwordx4 v[136:137], v[132:135], off
	v_mul_f32_e32 v136, v108, v100
	v_mul_f32_e32 v137, v109, v101
	v_mul_f32_e32 v138, v106, v98
	v_mul_f32_e32 v139, v107, v99
	v_mul_f32_e32 v132, v112, v104
	v_mul_f32_e32 v133, v113, v105
	v_mul_f32_e32 v134, v110, v102
	v_mul_f32_e32 v135, v111, v103
	v_bfe_u32 v140, v137, 16, 1
	v_bfe_u32 v141, v133, 16, 1
	v_bfe_u32 v142, v139, 16, 1
	v_bfe_u32 v143, v135, 16, 1
	v_add3_u32 v133, v133, v141, s72
	v_add3_u32 v137, v137, v140, s72
	v_add3_u32 v140, v135, v143, s72
	v_add3_u32 v139, v139, v142, s72
	v_bfe_u32 v135, v132, 16, 1
	v_bfe_u32 v141, v136, 16, 1
	v_bfe_u32 v142, v134, 16, 1
	v_bfe_u32 v143, v138, 16, 1
	v_add3_u32 v136, v136, v141, s72
	v_add3_u32 v132, v132, v135, s72
	v_add3_u32 v135, v138, v143, s72
	v_add3_u32 v134, v134, v142, s72
	v_add_u32_e32 v0, 0x80, v210
	v_lshrrev_b32_e32 v132, 16, v132
	v_lshrrev_b32_e32 v136, 16, v136
	v_lshrrev_b32_e32 v138, 16, v134
	v_lshrrev_b32_e32 v134, 16, v135
	v_and_or_b32 v135, v137, s55, v136
	v_and_or_b32 v133, v133, s55, v132
	v_and_or_b32 v134, v139, s55, v134
	v_and_or_b32 v132, v140, s55, v138
	v_mad_i64_i32 v[136:137], s[2:3], v0, s14, v[130:131]
	global_store_dwordx4 v[136:137], v[132:135], off
	v_mul_f32_e32 v136, v76, v68
	v_mul_f32_e32 v137, v77, v69
	v_mul_f32_e32 v138, v74, v66
	v_mul_f32_e32 v139, v75, v67
	v_mul_f32_e32 v132, v80, v72
	v_mul_f32_e32 v133, v81, v73
	v_mul_f32_e32 v134, v78, v70
	v_mul_f32_e32 v135, v79, v71
	v_bfe_u32 v140, v133, 16, 1
	v_bfe_u32 v0, v137, 16, 1
	v_bfe_u32 v141, v139, 16, 1
	v_bfe_u32 v142, v135, 16, 1
	v_add3_u32 v133, v133, v140, s72
	v_bfe_u32 v140, v136, 16, 1
	v_add3_u32 v0, v137, v0, s72
	v_add3_u32 v137, v135, v142, s72
	v_add3_u32 v139, v139, v141, s72
	v_bfe_u32 v135, v132, 16, 1
	v_bfe_u32 v141, v134, 16, 1
	v_bfe_u32 v142, v138, 16, 1
	v_add3_u32 v136, v136, v140, s72
	v_add3_u32 v132, v132, v135, s72
	v_add3_u32 v135, v138, v142, s72
	v_add3_u32 v134, v134, v141, s72
	v_lshrrev_b32_e32 v136, 16, v136
	v_lshrrev_b32_e32 v132, 16, v132
	v_lshrrev_b32_e32 v138, 16, v134
	v_lshrrev_b32_e32 v134, 16, v135
	v_and_or_b32 v135, v0, s55, v136
	v_add_u32_e32 v0, 0x90, v210
	v_and_or_b32 v133, v133, s55, v132
	v_and_or_b32 v134, v139, s55, v134
	v_and_or_b32 v132, v137, s55, v138
	v_mad_i64_i32 v[136:137], s[2:3], v0, s14, v[130:131]
	global_store_dwordx4 v[136:137], v[132:135], off
	v_mul_f32_e32 v136, v44, v36
	v_mul_f32_e32 v137, v45, v37
	v_mul_f32_e32 v138, v42, v34
	v_mul_f32_e32 v139, v43, v35
	v_mul_f32_e32 v132, v48, v40
	v_mul_f32_e32 v133, v49, v41
	v_mul_f32_e32 v134, v46, v38
	v_mul_f32_e32 v135, v47, v39
	v_bfe_u32 v140, v133, 16, 1
	v_bfe_u32 v0, v137, 16, 1
	v_bfe_u32 v141, v139, 16, 1
	v_bfe_u32 v142, v135, 16, 1
	v_add3_u32 v133, v133, v140, s72
	v_bfe_u32 v140, v136, 16, 1
	v_add3_u32 v0, v137, v0, s72
	v_add3_u32 v137, v135, v142, s72
	v_add3_u32 v139, v139, v141, s72
	v_bfe_u32 v135, v132, 16, 1
	v_bfe_u32 v141, v134, 16, 1
	v_bfe_u32 v142, v138, 16, 1
	v_add3_u32 v136, v136, v140, s72
	v_add3_u32 v132, v132, v135, s72
	v_add3_u32 v135, v138, v142, s72
	v_add3_u32 v134, v134, v141, s72
	v_lshrrev_b32_e32 v136, 16, v136
	v_lshrrev_b32_e32 v132, 16, v132
	v_lshrrev_b32_e32 v138, 16, v134
	v_lshrrev_b32_e32 v134, 16, v135
	v_and_or_b32 v135, v0, s55, v136
	v_add_u32_e32 v0, 0xa0, v210
	v_and_or_b32 v133, v133, s55, v132
	v_and_or_b32 v134, v139, s55, v134
	v_and_or_b32 v132, v137, s55, v138
	v_mad_i64_i32 v[136:137], s[2:3], v0, s14, v[130:131]
	global_store_dwordx4 v[136:137], v[132:135], off
	v_mul_f32_e32 v136, v12, v4
	v_mul_f32_e32 v137, v13, v5
	v_mul_f32_e32 v138, v10, v2
	v_mul_f32_e32 v139, v11, v3
	v_mul_f32_e32 v132, v16, v8
	v_mul_f32_e32 v133, v17, v9
	v_mul_f32_e32 v134, v14, v6
	v_mul_f32_e32 v135, v15, v7
	v_bfe_u32 v140, v133, 16, 1
	v_bfe_u32 v0, v137, 16, 1
	v_bfe_u32 v141, v139, 16, 1
	v_bfe_u32 v142, v135, 16, 1
	v_add3_u32 v133, v133, v140, s72
	v_bfe_u32 v140, v136, 16, 1
	v_add3_u32 v0, v137, v0, s72
	v_add3_u32 v137, v135, v142, s72
	v_add3_u32 v139, v139, v141, s72
	v_bfe_u32 v135, v132, 16, 1
	v_bfe_u32 v141, v134, 16, 1
	v_bfe_u32 v142, v138, 16, 1
	v_add3_u32 v136, v136, v140, s72
	v_add3_u32 v132, v132, v135, s72
	v_add3_u32 v135, v138, v142, s72
	v_add3_u32 v134, v134, v141, s72
	v_lshrrev_b32_e32 v136, 16, v136
	v_lshrrev_b32_e32 v132, 16, v132
	v_lshrrev_b32_e32 v138, 16, v134
	v_lshrrev_b32_e32 v134, 16, v135
	v_and_or_b32 v135, v0, s55, v136
	v_add_u32_e32 v0, 0xb0, v210
	v_and_or_b32 v133, v133, s55, v132
	v_and_or_b32 v134, v139, s55, v134
	v_and_or_b32 v132, v137, s55, v138
	v_mad_i64_i32 v[130:131], s[2:3], v0, s14, v[130:131]
	global_store_dwordx4 v[130:131], v[132:135], off

; __device__ __forceinline__ v4u pack8(const float (&f)[8]) { v4u o; o.x = pk2(f[0], f[1]); o.y = pk2(f[2], f[3]); o.z = pk2(f[4], f[5]); o.w = pk2(f[6], f[7]); return o; }
; __device__ __forceinline__ float silu_f(float v) { return v * __builtin_amdgcn_rcpf(1.f + __builtin_amdgcn_exp2f(-1.4426950408889634f * v)); }
;     template <bool SILU> __device__ __forceinline__ void pairmul(const pg8::f32x4 (&acc)[2][2][4][2], int row0, bf16r* dst0) const {
; #pragma unroll
;         for (int ai = 0; ai < 2; ++ai)
; #pragma unroll
;             for (int m = 0; m < 4; ++m) { float y[8];
; #pragma unroll
;                 for (int n = 0; n < 2; ++n)
; #pragma unroll
;                     for (int e = 0; e < 4; ++e) { const float p = acc[ai][0][m][n][e], q = acc[ai][1][m][n][e]; y[4 * n + e] = SILU ? silu_f(q) * p : p * q; }
;                 *(v4u*)(dst0 + (size_t)(row0 + ai * 128 + m * 16) * DIN) = pack8(y); }
.LBB0_262:
	s_andn2_b64 vcc, exec, s[68:69]
	s_cbranch_vccnz .LBB0_264
	s_lshl_b32 s2, s35, 8
	s_waitcnt lgkmcnt(0)
	s_add_u32 s2, s62, s2
	s_addc_u32 s3, s63, 0
	s_lshl_b32 s14, s87, 1
	s_add_u32 s2, s2, s14
	s_addc_u32 s3, s3, 0
	v_lshlrev_b32_e32 v0, 1, v182
	v_lshl_add_u64 v[130:131], s[2:3], 0, v[0:1]
	v_mul_f32_e32 v0, 0xbfb8aa3b, v118
	v_exp_f32_e32 v0, v0
	v_mul_f32_e32 v132, 0xbfb8aa3b, v119
	v_exp_f32_e32 v133, v132
	v_mul_f32_e32 v134, 0xbfb8aa3b, v121
	v_add_f32_e32 v0, 1.0, v0
	v_rcp_f32_e32 v132, v0
	v_add_f32_e32 v0, 1.0, v133
	v_mul_f32_e32 v133, 0xbfb8aa3b, v120
	v_exp_f32_e32 v133, v133
	v_exp_f32_e32 v135, v134
	v_rcp_f32_e32 v134, v0
	v_mul_f32_e32 v138, 0xbfb8aa3b, v117
	v_add_f32_e32 v0, 1.0, v133
	v_rcp_f32_e32 v133, v0
	v_add_f32_e32 v0, 1.0, v135
	v_mul_f32_e32 v135, 0xbfb8aa3b, v114
	v_exp_f32_e32 v136, v135
	v_mul_f32_e32 v135, 0xbfb8aa3b, v115
	v_exp_f32_e32 v137, v135
	v_rcp_f32_e32 v135, v0
	v_add_f32_e32 v0, 1.0, v136
	v_rcp_f32_e32 v136, v0
	v_add_f32_e32 v0, 1.0, v137
	v_mul_f32_e32 v137, 0xbfb8aa3b, v116
	v_exp_f32_e32 v137, v137
	v_exp_f32_e32 v139, v138
	v_rcp_f32_e32 v138, v0
	v_mov_b32_e32 v140, v118
	v_add_f32_e32 v0, 1.0, v137
	v_mov_b32_e32 v141, v120
	v_rcp_f32_e32 v137, v0
	v_mul_f32_e32 v132, v140, v132
	v_mul_f32_e32 v133, v141, v133
	v_mov_b32_e32 v140, v126
	v_mov_b32_e32 v141, v128
	v_add_f32_e32 v0, 1.0, v139
	v_mul_f32_e32 v132, v140, v132
	v_mul_f32_e32 v133, v141, v133
	v_mov_b32_e32 v140, v119
	v_mov_b32_e32 v141, v121
	v_rcp_f32_e32 v139, v0
	v_mul_f32_e32 v134, v140, v134
	v_mul_f32_e32 v135, v141, v135
	v_mov_b32_e32 v140, v127
	v_mov_b32_e32 v141, v129
	v_mul_f32_e32 v134, v140, v134
	v_mul_f32_e32 v135, v141, v135
	v_mov_b32_e32 v140, v114
	v_mov_b32_e32 v141, v116
	v_mul_f32_e32 v136, v140, v136
	v_mul_f32_e32 v137, v141, v137
	v_mov_b32_e32 v140, v122
	v_mov_b32_e32 v141, v124
	v_mul_f32_e32 v136, v140, v136
	v_mul_f32_e32 v137, v141, v137
	v_mov_b32_e32 v140, v115
	v_mov_b32_e32 v141, v117
	v_mul_f32_e32 v138, v140, v138
	v_mul_f32_e32 v139, v141, v139
	v_mov_b32_e32 v140, v123
	v_mov_b32_e32 v141, v125
	v_mul_f32_e32 v138, v140, v138
	v_mul_f32_e32 v139, v141, v139
	v_bfe_u32 v142, v134, 16, 1
	v_bfe_u32 v140, v138, 16, 1
	v_bfe_u32 v0, v139, 16, 1
	v_bfe_u32 v141, v135, 16, 1
	v_add3_u32 v142, v134, v142, s72
	v_add3_u32 v134, v138, v140, s72
	v_bfe_u32 v140, v137, 16, 1
	v_add3_u32 v141, v135, v141, s72
	v_add3_u32 v0, v139, v0, s72
	v_bfe_u32 v135, v132, 16, 1
	v_bfe_u32 v138, v133, 16, 1
	v_bfe_u32 v139, v136, 16, 1
	v_add3_u32 v137, v137, v140, s72
	s_mov_b64 s[2:3], 0x6000b00
	v_add3_u32 v136, v136, v139, s72
	v_add3_u32 v133, v133, v138, s72
	v_add3_u32 v132, v132, v135, s72
	v_lshrrev_b32_e32 v135, 16, v137
	v_lshl_add_u64 v[130:131], v[130:131], 0, s[2:3]
	v_lshrrev_b32_e32 v132, 16, v132
	v_lshrrev_b32_e32 v133, 16, v133
	v_lshrrev_b32_e32 v136, 16, v136
	v_and_or_b32 v135, v0, s55, v135
	s_movk_i32 s14, 0x1e00
	v_mul_f32_e32 v0, 0xbfb8aa3b, v86
	v_and_or_b32 v134, v134, s55, v136
	v_and_or_b32 v133, v141, s55, v133
	v_and_or_b32 v132, v142, s55, v132
	v_mad_i64_i32 v[136:137], s[2:3], v210, s14, v[130:131]
	v_exp_f32_e32 v0, v0
	v_mul_f32_e32 v138, 0xbfb8aa3b, v87
	v_exp_f32_e32 v138, v138
	global_store_dwordx4 v[136:137], v[132:135], off
	v_add_f32_e32 v0, 1.0, v0
	v_mov_b32_e32 v140, v86
	v_mul_f32_e32 v133, 0xbfb8aa3b, v88
	v_exp_f32_e32 v133, v133
	v_mul_f32_e32 v134, 0xbfb8aa3b, v89
	v_exp_f32_e32 v135, v134
	v_rcp_f32_e32 v132, v0
	v_add_f32_e32 v0, 1.0, v138
	v_rcp_f32_e32 v134, v0
	v_add_f32_e32 v0, 1.0, v133
	v_rcp_f32_e32 v133, v0
	v_add_f32_e32 v0, 1.0, v135
	v_mul_f32_e32 v135, 0xbfb8aa3b, v82
	v_exp_f32_e32 v136, v135
	v_mul_f32_e32 v135, 0xbfb8aa3b, v83
	v_exp_f32_e32 v137, v135
	v_rcp_f32_e32 v135, v0
	v_add_f32_e32 v0, 1.0, v136
	v_rcp_f32_e32 v136, v0
	v_add_f32_e32 v0, 1.0, v137
	v_mul_f32_e32 v137, 0xbfb8aa3b, v84
	v_exp_f32_e32 v137, v137
	v_mul_f32_e32 v138, 0xbfb8aa3b, v85
	v_exp_f32_e32 v139, v138
	v_rcp_f32_e32 v138, v0
	v_add_f32_e32 v0, 1.0, v137
	v_mov_b32_e32 v141, v88
	v_rcp_f32_e32 v137, v0
	v_mul_f32_e32 v132, v140, v132
	v_mul_f32_e32 v133, v141, v133
	v_mov_b32_e32 v140, v94
	v_mov_b32_e32 v141, v96
	v_add_f32_e32 v0, 1.0, v139
	v_mul_f32_e32 v132, v140, v132
	v_mul_f32_e32 v133, v141, v133
	v_mov_b32_e32 v140, v87
	v_mov_b32_e32 v141, v89
	v_rcp_f32_e32 v139, v0
	v_mul_f32_e32 v134, v140, v134
	v_mul_f32_e32 v135, v141, v135
	v_mov_b32_e32 v140, v95
	v_mov_b32_e32 v141, v97
	v_mul_f32_e32 v134, v140, v134
	v_mul_f32_e32 v135, v141, v135
	v_mov_b32_e32 v140, v82
	v_mov_b32_e32 v141, v84
	v_mul_f32_e32 v136, v140, v136
	v_mul_f32_e32 v137, v141, v137
	v_mov_b32_e32 v140, v90
	v_mov_b32_e32 v141, v92
	v_mul_f32_e32 v136, v140, v136
	v_mul_f32_e32 v137, v141, v137
	v_mov_b32_e32 v140, v83
	v_mov_b32_e32 v141, v85
	v_mul_f32_e32 v138, v140, v138
	v_mul_f32_e32 v139, v141, v139
	v_mov_b32_e32 v140, v91
	v_mov_b32_e32 v141, v93
	v_mul_f32_e32 v138, v140, v138
	v_mul_f32_e32 v139, v141, v139
	v_bfe_u32 v142, v134, 16, 1
	v_bfe_u32 v140, v138, 16, 1
	v_bfe_u32 v0, v139, 16, 1
	v_bfe_u32 v141, v135, 16, 1
	v_add3_u32 v142, v134, v142, s72
	v_add3_u32 v134, v138, v140, s72
	v_bfe_u32 v140, v137, 16, 1
	v_add3_u32 v141, v135, v141, s72
	v_add3_u32 v0, v139, v0, s72
	v_bfe_u32 v135, v132, 16, 1
	v_bfe_u32 v139, v136, 16, 1
	v_add3_u32 v137, v137, v140, s72
	v_bfe_u32 v138, v133, 16, 1
	v_add3_u32 v136, v136, v139, s72
	v_add3_u32 v132, v132, v135, s72
	v_lshrrev_b32_e32 v135, 16, v137
	v_add3_u32 v133, v133, v138, s72
	v_lshrrev_b32_e32 v136, 16, v136
	v_and_or_b32 v135, v0, s55, v135
	v_or_b32_e32 v0, 16, v210
	v_lshrrev_b32_e32 v132, 16, v132
; __device__ __forceinline__ v4u pack8(const float (&f)[8]) { v4u o; o.x = pk2(f[0], f[1]); o.y = pk2(f[2], f[3]); o.z = pk2(f[4], f[5]); o.w = pk2(f[6], f[7]); return o; }
; __device__ __forceinline__ float silu_f(float v) { return v * __builtin_amdgcn_rcpf(1.f + __builtin_amdgcn_exp2f(-1.4426950408889634f * v)); }
;     template <bool SILU> __device__ __forceinline__ void pairmul(const pg8::f32x4 (&acc)[2][2][4][2], int row0, bf16r* dst0) const {
; #pragma unroll
;         for (int ai = 0; ai < 2; ++ai)
; #pragma unroll
;             for (int m = 0; m < 4; ++m) { float y[8];
; #pragma unroll
;                 for (int n = 0; n < 2; ++n)
; #pragma unroll
;                     for (int e = 0; e < 4; ++e) { const float p = acc[ai][0][m][n][e], q = acc[ai][1][m][n][e]; y[4 * n + e] = SILU ? silu_f(q) * p : p * q; }
;                 *(v4u*)(dst0 + (size_t)(row0 + ai * 128 + m * 16) * DIN) = pack8(y); }
	v_lshrrev_b32_e32 v133, 16, v133
	v_and_or_b32 v134, v134, s55, v136
	v_mad_i64_i32 v[136:137], s[2:3], v0, s14, v[130:131]
	v_mul_f32_e32 v0, 0xbfb8aa3b, v54
	v_and_or_b32 v133, v141, s55, v133
	v_and_or_b32 v132, v142, s55, v132
	v_exp_f32_e32 v0, v0
	v_mul_f32_e32 v138, 0xbfb8aa3b, v55
	v_exp_f32_e32 v138, v138
	global_store_dwordx4 v[136:137], v[132:135], off
	v_add_f32_e32 v0, 1.0, v0
	v_mov_b32_e32 v140, v54
	v_mul_f32_e32 v133, 0xbfb8aa3b, v56
	v_exp_f32_e32 v133, v133
	v_mul_f32_e32 v134, 0xbfb8aa3b, v57
	v_exp_f32_e32 v135, v134
	v_rcp_f32_e32 v132, v0
	v_add_f32_e32 v0, 1.0, v138
	v_rcp_f32_e32 v134, v0
	v_add_f32_e32 v0, 1.0, v133
	v_rcp_f32_e32 v133, v0
	v_add_f32_e32 v0, 1.0, v135
	v_mul_f32_e32 v135, 0xbfb8aa3b, v50
	v_exp_f32_e32 v136, v135
	v_mul_f32_e32 v135, 0xbfb8aa3b, v51
	v_exp_f32_e32 v137, v135
	v_rcp_f32_e32 v135, v0
	v_add_f32_e32 v0, 1.0, v136
	v_rcp_f32_e32 v136, v0
	v_add_f32_e32 v0, 1.0, v137
	v_mul_f32_e32 v137, 0xbfb8aa3b, v52
	v_exp_f32_e32 v137, v137
	v_mul_f32_e32 v138, 0xbfb8aa3b, v53
	v_exp_f32_e32 v139, v138
	v_rcp_f32_e32 v138, v0
	v_add_f32_e32 v0, 1.0, v137
	v_mov_b32_e32 v141, v56
	v_rcp_f32_e32 v137, v0
	v_mul_f32_e32 v132, v140, v132
	v_mul_f32_e32 v133, v141, v133
	v_mov_b32_e32 v140, v62
	v_mov_b32_e32 v141, v64
	v_add_f32_e32 v0, 1.0, v139
	v_mul_f32_e32 v132, v140, v132
	v_mul_f32_e32 v133, v141, v133
	v_mov_b32_e32 v140, v55
	v_mov_b32_e32 v141, v57
	v_rcp_f32_e32 v139, v0
	v_mul_f32_e32 v134, v140, v134
	v_mul_f32_e32 v135, v141, v135
	v_mov_b32_e32 v140, v63
	v_mov_b32_e32 v141, v65
	v_mul_f32_e32 v134, v140, v134
	v_mul_f32_e32 v135, v141, v135
	v_mov_b32_e32 v140, v50
	v_mov_b32_e32 v141, v52
	v_mul_f32_e32 v136, v140, v136
	v_mul_f32_e32 v137, v141, v137
	v_mov_b32_e32 v140, v58
	v_mov_b32_e32 v141, v60
	v_mul_f32_e32 v136, v140, v136
	v_mul_f32_e32 v137, v141, v137
	v_mov_b32_e32 v140, v51
	v_mov_b32_e32 v141, v53
	v_mul_f32_e32 v138, v140, v138
	v_mul_f32_e32 v139, v141, v139
	v_mov_b32_e32 v140, v59
	v_mov_b32_e32 v141, v61
	v_mul_f32_e32 v138, v140, v138
	v_mul_f32_e32 v139, v141, v139
	v_bfe_u32 v142, v134, 16, 1
	v_bfe_u32 v140, v138, 16, 1
	v_bfe_u32 v0, v139, 16, 1
	v_bfe_u32 v141, v135, 16, 1
	v_add3_u32 v142, v134, v142, s72
	v_add3_u32 v134, v138, v140, s72
	v_bfe_u32 v140, v137, 16, 1
	v_add3_u32 v141, v135, v141, s72
	v_add3_u32 v0, v139, v0, s72
	v_bfe_u32 v135, v132, 16, 1
	v_bfe_u32 v139, v136, 16, 1
	v_add3_u32 v137, v137, v140, s72
	v_bfe_u32 v138, v133, 16, 1
	v_add3_u32 v136, v136, v139, s72
	v_add3_u32 v132, v132, v135, s72
	v_lshrrev_b32_e32 v135, 16, v137
	v_add3_u32 v133, v133, v138, s72
	v_lshrrev_b32_e32 v136, 16, v136
	v_and_or_b32 v135, v0, s55, v135
	v_or_b32_e32 v0, 32, v210
	v_lshrrev_b32_e32 v132, 16, v132
	v_lshrrev_b32_e32 v133, 16, v133
	v_and_or_b32 v134, v134, s55, v136
	v_mad_i64_i32 v[136:137], s[2:3], v0, s14, v[130:131]
	v_mul_f32_e32 v0, 0xbfb8aa3b, v22
	v_and_or_b32 v133, v141, s55, v133
	v_and_or_b32 v132, v142, s55, v132
	v_exp_f32_e32 v0, v0
	v_mul_f32_e32 v138, 0xbfb8aa3b, v23
	v_exp_f32_e32 v138, v138
	global_store_dwordx4 v[136:137], v[132:135], off
	v_add_f32_e32 v0, 1.0, v0
	v_mov_b32_e32 v140, v22
	v_mul_f32_e32 v133, 0xbfb8aa3b, v24
	v_exp_f32_e32 v133, v133
	v_mul_f32_e32 v134, 0xbfb8aa3b, v25
	v_exp_f32_e32 v135, v134
	v_rcp_f32_e32 v132, v0
	v_add_f32_e32 v0, 1.0, v138
	v_rcp_f32_e32 v134, v0
	v_add_f32_e32 v0, 1.0, v133
	v_rcp_f32_e32 v133, v0
	v_add_f32_e32 v0, 1.0, v135
	v_mul_f32_e32 v135, 0xbfb8aa3b, v18
	v_exp_f32_e32 v136, v135
	v_mul_f32_e32 v135, 0xbfb8aa3b, v19
	v_exp_f32_e32 v137, v135
	v_rcp_f32_e32 v135, v0
	v_add_f32_e32 v0, 1.0, v136
	v_rcp_f32_e32 v136, v0
	v_add_f32_e32 v0, 1.0, v137
	v_mul_f32_e32 v137, 0xbfb8aa3b, v20
	v_exp_f32_e32 v137, v137
	v_mul_f32_e32 v138, 0xbfb8aa3b, v21
	v_exp_f32_e32 v139, v138
	v_rcp_f32_e32 v138, v0
	v_add_f32_e32 v0, 1.0, v137
	v_mov_b32_e32 v141, v24
	v_rcp_f32_e32 v137, v0
	v_mul_f32_e32 v132, v140, v132
	v_mul_f32_e32 v133, v141, v133
	v_mov_b32_e32 v140, v30
	v_mov_b32_e32 v141, v32
	v_add_f32_e32 v0, 1.0, v139
	v_mul_f32_e32 v132, v140, v132
	v_mul_f32_e32 v133, v141, v133
	v_mov_b32_e32 v140, v23
	v_mov_b32_e32 v141, v25
	v_rcp_f32_e32 v139, v0
	v_mul_f32_e32 v134, v140, v134
	v_mul_f32_e32 v135, v141, v135
	v_mov_b32_e32 v140, v31
	v_mov_b32_e32 v141, v33
	v_mul_f32_e32 v134, v140, v134
	v_mul_f32_e32 v135, v141, v135
	v_mov_b32_e32 v140, v18
	v_mov_b32_e32 v141, v20
	v_mul_f32_e32 v136, v140, v136
	v_mul_f32_e32 v137, v141, v137
	v_mov_b32_e32 v140, v26
	v_mov_b32_e32 v141, v28
	v_mul_f32_e32 v136, v140, v136
	v_mul_f32_e32 v137, v141, v137
	v_mov_b32_e32 v140, v19
	v_mov_b32_e32 v141, v21
	v_mul_f32_e32 v138, v140, v138
	v_mul_f32_e32 v139, v141, v139
	v_mov_b32_e32 v140, v27
	v_mov_b32_e32 v141, v29
	v_mul_f32_e32 v138, v140, v138
	v_mul_f32_e32 v139, v141, v139
	v_bfe_u32 v142, v134, 16, 1
	v_bfe_u32 v140, v138, 16, 1
	v_bfe_u32 v0, v139, 16, 1
	v_bfe_u32 v141, v135, 16, 1
	v_add3_u32 v142, v134, v142, s72
	v_add3_u32 v134, v138, v140, s72
	v_bfe_u32 v140, v137, 16, 1
	v_add3_u32 v141, v135, v141, s72
	v_add3_u32 v0, v139, v0, s72
	v_bfe_u32 v135, v132, 16, 1
	v_bfe_u32 v138, v133, 16, 1
	v_bfe_u32 v139, v136, 16, 1
	v_add3_u32 v137, v137, v140, s72
	v_add3_u32 v136, v136, v139, s72
	v_add3_u32 v133, v133, v138, s72
	v_add3_u32 v132, v132, v135, s72
	v_lshrrev_b32_e32 v135, 16, v137
	v_lshrrev_b32_e32 v132, 16, v132
	v_lshrrev_b32_e32 v133, 16, v133
	v_lshrrev_b32_e32 v136, 16, v136
	v_and_or_b32 v135, v0, s55, v135
	v_or_b32_e32 v0, 48, v210
	v_and_or_b32 v134, v134, s55, v136
	v_and_or_b32 v133, v141, s55, v133
	v_and_or_b32 v132, v142, s55, v132
; __device__ __forceinline__ v4u pack8(const float (&f)[8]) { v4u o; o.x = pk2(f[0], f[1]); o.y = pk2(f[2], f[3]); o.z = pk2(f[4], f[5]); o.w = pk2(f[6], f[7]); return o; }
; __device__ __forceinline__ float silu_f(float v) { return v * __builtin_amdgcn_rcpf(1.f + __builtin_amdgcn_exp2f(-1.4426950408889634f * v)); }
;     template <bool SILU> __device__ __forceinline__ void pairmul(const pg8::f32x4 (&acc)[2][2][4][2], int row0, bf16r* dst0) const {
; #pragma unroll
;         for (int ai = 0; ai < 2; ++ai)
; #pragma unroll
;             for (int m = 0; m < 4; ++m) { float y[8];
; #pragma unroll
;                 for (int n = 0; n < 2; ++n)
; #pragma unroll
;                     for (int e = 0; e < 4; ++e) { const float p = acc[ai][0][m][n][e], q = acc[ai][1][m][n][e]; y[4 * n + e] = SILU ? silu_f(q) * p : p * q; }
;                 *(v4u*)(dst0 + (size_t)(row0 + ai * 128 + m * 16) * DIN) = pack8(y); }
	v_mad_i64_i32 v[136:137], s[2:3], v0, s14, v[130:131]
	v_mul_f32_e32 v0, 0xbfb8aa3b, v102
	global_store_dwordx4 v[136:137], v[132:135], off
	v_exp_f32_e32 v0, v0
	v_mul_f32_e32 v138, 0xbfb8aa3b, v101
	v_mul_f32_e32 v132, 0xbfb8aa3b, v103
	v_exp_f32_e32 v133, v132
	v_add_f32_e32 v0, 1.0, v0
	v_rcp_f32_e32 v132, v0
	v_mul_f32_e32 v134, 0xbfb8aa3b, v105
	v_add_f32_e32 v0, 1.0, v133
	v_mul_f32_e32 v133, 0xbfb8aa3b, v104
	v_exp_f32_e32 v133, v133
	v_exp_f32_e32 v135, v134
	v_rcp_f32_e32 v134, v0
	v_exp_f32_e32 v139, v138
	v_add_f32_e32 v0, 1.0, v133
	v_rcp_f32_e32 v133, v0
	v_add_f32_e32 v0, 1.0, v135
	v_mul_f32_e32 v135, 0xbfb8aa3b, v98
	v_exp_f32_e32 v136, v135
	v_mul_f32_e32 v135, 0xbfb8aa3b, v99
	v_exp_f32_e32 v137, v135
	v_rcp_f32_e32 v135, v0
	v_add_f32_e32 v0, 1.0, v136
	v_rcp_f32_e32 v136, v0
	v_add_f32_e32 v0, 1.0, v137
	v_mul_f32_e32 v137, 0xbfb8aa3b, v100
	v_exp_f32_e32 v137, v137
	v_rcp_f32_e32 v138, v0
	v_mov_b32_e32 v140, v102
	v_mov_b32_e32 v141, v104
	v_add_f32_e32 v0, 1.0, v137
	v_rcp_f32_e32 v137, v0
	v_mul_f32_e32 v132, v140, v132
	v_mul_f32_e32 v133, v141, v133
	v_mov_b32_e32 v140, v110
	v_mov_b32_e32 v141, v112
	v_add_f32_e32 v0, 1.0, v139
	v_mul_f32_e32 v132, v140, v132
	v_mul_f32_e32 v133, v141, v133
	v_mov_b32_e32 v140, v103
	v_mov_b32_e32 v141, v105
	v_rcp_f32_e32 v139, v0
	v_mul_f32_e32 v134, v140, v134
	v_mul_f32_e32 v135, v141, v135
	v_mov_b32_e32 v140, v111
	v_mov_b32_e32 v141, v113
	v_mul_f32_e32 v134, v140, v134
	v_mul_f32_e32 v135, v141, v135
	v_mov_b32_e32 v140, v98
	v_mov_b32_e32 v141, v100
	v_mul_f32_e32 v136, v140, v136
	v_mul_f32_e32 v137, v141, v137
	v_mov_b32_e32 v140, v106
	v_mov_b32_e32 v141, v108
	v_mul_f32_e32 v136, v140, v136
	v_mul_f32_e32 v137, v141, v137
	v_mov_b32_e32 v140, v99
	v_mov_b32_e32 v141, v101
	v_mul_f32_e32 v138, v140, v138
	v_mul_f32_e32 v139, v141, v139
	v_mov_b32_e32 v140, v107
	v_mov_b32_e32 v141, v109
	v_mul_f32_e32 v138, v140, v138
	v_mul_f32_e32 v139, v141, v139
	v_bfe_u32 v143, v134, 16, 1
	v_bfe_u32 v140, v138, 16, 1
	v_bfe_u32 v0, v139, 16, 1
	v_bfe_u32 v141, v135, 16, 1
	v_add3_u32 v143, v134, v143, s72
	v_add3_u32 v134, v138, v140, s72
	v_bfe_u32 v140, v137, 16, 1
	v_add3_u32 v141, v135, v141, s72
	v_add3_u32 v0, v139, v0, s72
	v_bfe_u32 v135, v132, 16, 1
	v_bfe_u32 v138, v133, 16, 1
	v_bfe_u32 v139, v136, 16, 1
	v_add3_u32 v137, v137, v140, s72
	v_add3_u32 v136, v136, v139, s72
	v_add3_u32 v133, v133, v138, s72
	v_add3_u32 v132, v132, v135, s72
	v_lshrrev_b32_e32 v135, 16, v137
	v_add_u32_e32 v142, 0x80, v210
	v_lshrrev_b32_e32 v132, 16, v132
	v_lshrrev_b32_e32 v133, 16, v133
	v_lshrrev_b32_e32 v136, 16, v136
	v_and_or_b32 v135, v0, s55, v135
	v_mul_f32_e32 v0, 0xbfb8aa3b, v70
	v_and_or_b32 v134, v134, s55, v136
	v_and_or_b32 v133, v141, s55, v133
	v_and_or_b32 v132, v143, s55, v132
	v_mad_i64_i32 v[136:137], s[2:3], v142, s14, v[130:131]
	v_exp_f32_e32 v0, v0
	v_mul_f32_e32 v138, 0xbfb8aa3b, v71
	v_exp_f32_e32 v138, v138
	global_store_dwordx4 v[136:137], v[132:135], off
	v_add_f32_e32 v0, 1.0, v0
	v_mov_b32_e32 v140, v70
	v_mul_f32_e32 v133, 0xbfb8aa3b, v72
	v_exp_f32_e32 v133, v133
	v_mul_f32_e32 v134, 0xbfb8aa3b, v73
	v_exp_f32_e32 v135, v134
	v_rcp_f32_e32 v132, v0
	v_add_f32_e32 v0, 1.0, v138
	v_rcp_f32_e32 v134, v0
	v_add_f32_e32 v0, 1.0, v133
	v_rcp_f32_e32 v133, v0
	v_add_f32_e32 v0, 1.0, v135
	v_mul_f32_e32 v135, 0xbfb8aa3b, v66
	v_exp_f32_e32 v136, v135
	v_mul_f32_e32 v135, 0xbfb8aa3b, v67
	v_exp_f32_e32 v137, v135
	v_rcp_f32_e32 v135, v0
	v_add_f32_e32 v0, 1.0, v136
	v_rcp_f32_e32 v136, v0
	v_add_f32_e32 v0, 1.0, v137
	v_mul_f32_e32 v137, 0xbfb8aa3b, v68
	v_exp_f32_e32 v137, v137
	v_mul_f32_e32 v138, 0xbfb8aa3b, v69
	v_exp_f32_e32 v139, v138
	v_rcp_f32_e32 v138, v0
	v_add_f32_e32 v0, 1.0, v137
	v_mov_b32_e32 v141, v72
	v_rcp_f32_e32 v137, v0
	v_mul_f32_e32 v132, v140, v132
	v_mul_f32_e32 v133, v141, v133
	v_mov_b32_e32 v140, v78
	v_mov_b32_e32 v141, v80
	v_add_f32_e32 v0, 1.0, v139
	v_mul_f32_e32 v132, v140, v132
	v_mul_f32_e32 v133, v141, v133
	v_mov_b32_e32 v140, v71
	v_mov_b32_e32 v141, v73
	v_rcp_f32_e32 v139, v0
	v_mul_f32_e32 v134, v140, v134
	v_mul_f32_e32 v135, v141, v135
	v_mov_b32_e32 v140, v79
	v_mov_b32_e32 v141, v81
	v_mul_f32_e32 v134, v140, v134
	v_mul_f32_e32 v135, v141, v135
	v_mov_b32_e32 v140, v66
	v_mov_b32_e32 v141, v68
	v_mul_f32_e32 v136, v140, v136
	v_mul_f32_e32 v137, v141, v137
	v_mov_b32_e32 v140, v74
	v_mov_b32_e32 v141, v76
	v_mul_f32_e32 v136, v140, v136
	v_mul_f32_e32 v137, v141, v137
	v_mov_b32_e32 v140, v67
	v_mov_b32_e32 v141, v69
	v_mul_f32_e32 v138, v140, v138
	v_mul_f32_e32 v139, v141, v139
	v_mov_b32_e32 v140, v75
	v_mov_b32_e32 v141, v77
	v_mul_f32_e32 v138, v140, v138
	v_mul_f32_e32 v139, v141, v139
	v_bfe_u32 v142, v134, 16, 1
	v_bfe_u32 v140, v138, 16, 1
	v_bfe_u32 v0, v139, 16, 1
	v_bfe_u32 v141, v135, 16, 1
	v_add3_u32 v142, v134, v142, s72
	v_add3_u32 v134, v138, v140, s72
	v_bfe_u32 v140, v137, 16, 1
	v_add3_u32 v141, v135, v141, s72
	v_add3_u32 v0, v139, v0, s72
	v_bfe_u32 v135, v132, 16, 1
	v_bfe_u32 v139, v136, 16, 1
	v_add3_u32 v137, v137, v140, s72
	v_bfe_u32 v138, v133, 16, 1
	v_add3_u32 v136, v136, v139, s72
	v_add3_u32 v132, v132, v135, s72
	v_lshrrev_b32_e32 v135, 16, v137
	v_add3_u32 v133, v133, v138, s72
	v_lshrrev_b32_e32 v136, 16, v136
	v_and_or_b32 v135, v0, s55, v135
	v_add_u32_e32 v0, 0x90, v210
	v_lshrrev_b32_e32 v132, 16, v132
	v_lshrrev_b32_e32 v133, 16, v133
	v_and_or_b32 v134, v134, s55, v136
	v_mad_i64_i32 v[136:137], s[2:3], v0, s14, v[130:131]
	v_mul_f32_e32 v0, 0xbfb8aa3b, v38
; __device__ __forceinline__ v4u pack8(const float (&f)[8]) { v4u o; o.x = pk2(f[0], f[1]); o.y = pk2(f[2], f[3]); o.z = pk2(f[4], f[5]); o.w = pk2(f[6], f[7]); return o; }
; __device__ __forceinline__ float silu_f(float v) { return v * __builtin_amdgcn_rcpf(1.f + __builtin_amdgcn_exp2f(-1.4426950408889634f * v)); }
;     template <bool SILU> __device__ __forceinline__ void pairmul(const pg8::f32x4 (&acc)[2][2][4][2], int row0, bf16r* dst0) const {
; #pragma unroll
;         for (int ai = 0; ai < 2; ++ai)
; #pragma unroll
;             for (int m = 0; m < 4; ++m) { float y[8];
; #pragma unroll
;                 for (int n = 0; n < 2; ++n)
; #pragma unroll
;                     for (int e = 0; e < 4; ++e) { const float p = acc[ai][0][m][n][e], q = acc[ai][1][m][n][e]; y[4 * n + e] = SILU ? silu_f(q) * p : p * q; }
;                 *(v4u*)(dst0 + (size_t)(row0 + ai * 128 + m * 16) * DIN) = pack8(y); }
	v_and_or_b32 v133, v141, s55, v133
	v_and_or_b32 v132, v142, s55, v132
	v_exp_f32_e32 v0, v0
	v_mul_f32_e32 v138, 0xbfb8aa3b, v39
	v_exp_f32_e32 v138, v138
	global_store_dwordx4 v[136:137], v[132:135], off
	v_add_f32_e32 v0, 1.0, v0
	v_mov_b32_e32 v140, v38
	v_mul_f32_e32 v133, 0xbfb8aa3b, v40
	v_exp_f32_e32 v133, v133
	v_mul_f32_e32 v134, 0xbfb8aa3b, v41
	v_exp_f32_e32 v135, v134
	v_rcp_f32_e32 v132, v0
	v_add_f32_e32 v0, 1.0, v138
	v_rcp_f32_e32 v134, v0
	v_add_f32_e32 v0, 1.0, v133
	v_rcp_f32_e32 v133, v0
	v_add_f32_e32 v0, 1.0, v135
	v_mul_f32_e32 v135, 0xbfb8aa3b, v34
	v_exp_f32_e32 v136, v135
	v_mul_f32_e32 v135, 0xbfb8aa3b, v35
	v_exp_f32_e32 v137, v135
	v_rcp_f32_e32 v135, v0
	v_add_f32_e32 v0, 1.0, v136
	v_rcp_f32_e32 v136, v0
	v_add_f32_e32 v0, 1.0, v137
	v_mul_f32_e32 v137, 0xbfb8aa3b, v36
	v_exp_f32_e32 v137, v137
	v_mul_f32_e32 v138, 0xbfb8aa3b, v37
	v_exp_f32_e32 v139, v138
	v_rcp_f32_e32 v138, v0
	v_add_f32_e32 v0, 1.0, v137
	v_mov_b32_e32 v141, v40
	v_rcp_f32_e32 v137, v0
	v_mul_f32_e32 v132, v140, v132
	v_mul_f32_e32 v133, v141, v133
	v_mov_b32_e32 v140, v46
	v_mov_b32_e32 v141, v48
	v_add_f32_e32 v0, 1.0, v139
	v_mul_f32_e32 v132, v140, v132
	v_mul_f32_e32 v133, v141, v133
	v_mov_b32_e32 v140, v39
	v_mov_b32_e32 v141, v41
	v_rcp_f32_e32 v139, v0
	v_mul_f32_e32 v134, v140, v134
	v_mul_f32_e32 v135, v141, v135
	v_mov_b32_e32 v140, v47
	v_mov_b32_e32 v141, v49
	v_mul_f32_e32 v134, v140, v134
	v_mul_f32_e32 v135, v141, v135
	v_mov_b32_e32 v140, v34
	v_mov_b32_e32 v141, v36
	v_mul_f32_e32 v136, v140, v136
	v_mul_f32_e32 v137, v141, v137
	v_mov_b32_e32 v140, v42
	v_mov_b32_e32 v141, v44
	v_mul_f32_e32 v136, v140, v136
	v_mul_f32_e32 v137, v141, v137
	v_mov_b32_e32 v140, v35
	v_mov_b32_e32 v141, v37
	v_mul_f32_e32 v138, v140, v138
	v_mul_f32_e32 v139, v141, v139
	v_mov_b32_e32 v140, v43
	v_mov_b32_e32 v141, v45
	v_mul_f32_e32 v138, v140, v138
	v_mul_f32_e32 v139, v141, v139
	v_bfe_u32 v142, v134, 16, 1
	v_bfe_u32 v140, v138, 16, 1
	v_bfe_u32 v0, v139, 16, 1
	v_bfe_u32 v141, v135, 16, 1
	v_add3_u32 v142, v134, v142, s72
	v_add3_u32 v134, v138, v140, s72
	v_bfe_u32 v140, v137, 16, 1
	v_add3_u32 v141, v135, v141, s72
	v_add3_u32 v0, v139, v0, s72
	v_bfe_u32 v135, v132, 16, 1
	v_bfe_u32 v139, v136, 16, 1
	v_add3_u32 v137, v137, v140, s72
	v_bfe_u32 v138, v133, 16, 1
	v_add3_u32 v136, v136, v139, s72
	v_add3_u32 v132, v132, v135, s72
	v_lshrrev_b32_e32 v135, 16, v137
	v_add3_u32 v133, v133, v138, s72
	v_lshrrev_b32_e32 v136, 16, v136
	v_and_or_b32 v135, v0, s55, v135
	v_add_u32_e32 v0, 0xa0, v210
	v_lshrrev_b32_e32 v132, 16, v132
	v_lshrrev_b32_e32 v133, 16, v133
	v_and_or_b32 v134, v134, s55, v136
	v_mad_i64_i32 v[136:137], s[2:3], v0, s14, v[130:131]
	v_mul_f32_e32 v0, 0xbfb8aa3b, v6
	v_and_or_b32 v133, v141, s55, v133
	v_and_or_b32 v132, v142, s55, v132
	v_exp_f32_e32 v0, v0
	v_mul_f32_e32 v138, 0xbfb8aa3b, v7
	v_exp_f32_e32 v138, v138
	global_store_dwordx4 v[136:137], v[132:135], off
	v_add_f32_e32 v0, 1.0, v0
	v_mov_b32_e32 v140, v6
	v_mul_f32_e32 v133, 0xbfb8aa3b, v8
	v_exp_f32_e32 v133, v133
	v_mul_f32_e32 v134, 0xbfb8aa3b, v9
	v_exp_f32_e32 v135, v134
	v_rcp_f32_e32 v132, v0
	v_add_f32_e32 v0, 1.0, v138
	v_rcp_f32_e32 v134, v0
	v_add_f32_e32 v0, 1.0, v133
	v_rcp_f32_e32 v133, v0
	v_add_f32_e32 v0, 1.0, v135
	v_mul_f32_e32 v135, 0xbfb8aa3b, v2
	v_exp_f32_e32 v136, v135
	v_mul_f32_e32 v135, 0xbfb8aa3b, v3
	v_exp_f32_e32 v137, v135
	v_rcp_f32_e32 v135, v0
	v_add_f32_e32 v0, 1.0, v136
	v_rcp_f32_e32 v136, v0
	v_add_f32_e32 v0, 1.0, v137
	v_mul_f32_e32 v137, 0xbfb8aa3b, v4
	v_exp_f32_e32 v137, v137
	v_mul_f32_e32 v138, 0xbfb8aa3b, v5
	v_exp_f32_e32 v139, v138
	v_rcp_f32_e32 v138, v0
	v_add_f32_e32 v0, 1.0, v137
	v_mov_b32_e32 v141, v8
	v_rcp_f32_e32 v137, v0
	v_mul_f32_e32 v132, v140, v132
	v_mul_f32_e32 v133, v141, v133
	v_mov_b32_e32 v140, v14
	v_mov_b32_e32 v141, v16
	v_add_f32_e32 v0, 1.0, v139
	v_mul_f32_e32 v132, v140, v132
	v_mul_f32_e32 v133, v141, v133
	v_mov_b32_e32 v140, v7
	v_mov_b32_e32 v141, v9
	v_rcp_f32_e32 v139, v0
	v_mul_f32_e32 v134, v140, v134
	v_mul_f32_e32 v135, v141, v135
	v_mov_b32_e32 v140, v15
	v_mov_b32_e32 v141, v17
	v_mul_f32_e32 v134, v140, v134
	v_mul_f32_e32 v135, v141, v135
	v_mov_b32_e32 v140, v2
	v_mov_b32_e32 v141, v4
	v_mul_f32_e32 v136, v140, v136
	v_mul_f32_e32 v137, v141, v137
	v_mov_b32_e32 v140, v10
	v_mov_b32_e32 v141, v12
	v_mul_f32_e32 v136, v140, v136
	v_mul_f32_e32 v137, v141, v137
	v_mov_b32_e32 v140, v3
	v_mov_b32_e32 v141, v5
	v_mul_f32_e32 v138, v140, v138
	v_mul_f32_e32 v139, v141, v139
	v_mov_b32_e32 v140, v11
	v_mov_b32_e32 v141, v13
	v_mul_f32_e32 v138, v140, v138
	v_mul_f32_e32 v139, v141, v139
	v_bfe_u32 v142, v134, 16, 1
	v_bfe_u32 v140, v138, 16, 1
	v_bfe_u32 v0, v139, 16, 1
	v_bfe_u32 v141, v135, 16, 1
	v_add3_u32 v142, v134, v142, s72
	v_add3_u32 v134, v138, v140, s72
	v_bfe_u32 v140, v137, 16, 1
	v_add3_u32 v141, v135, v141, s72
	v_add3_u32 v0, v139, v0, s72
	v_bfe_u32 v135, v132, 16, 1
	v_bfe_u32 v138, v133, 16, 1
	v_bfe_u32 v139, v136, 16, 1
	v_add3_u32 v137, v137, v140, s72
	v_add3_u32 v136, v136, v139, s72
	v_add3_u32 v133, v133, v138, s72
	v_add3_u32 v132, v132, v135, s72
	v_lshrrev_b32_e32 v135, 16, v137
	v_lshrrev_b32_e32 v132, 16, v132
	v_lshrrev_b32_e32 v133, 16, v133
	v_lshrrev_b32_e32 v136, 16, v136
	v_and_or_b32 v135, v0, s55, v135
	v_add_u32_e32 v0, 0xb0, v210
	v_and_or_b32 v134, v134, s55, v136
	v_and_or_b32 v133, v141, s55, v133
	v_and_or_b32 v132, v142, s55, v132
	v_mad_i64_i32 v[130:131], s[2:3], v0, s14, v[130:131]
	global_store_dwordx4 v[130:131], v[132:135], off

;     __device__ __forceinline__ void head64(const pg8::f32x4 (&acc)[2][2][4][2], int row0, int fq, bf16r* dst, int pitch, int colbase, const float* gain, float scale, const float2* trc) const {
;         pg8::f32x4 g[2][2], rcs[2][2];
; #pragma unroll
;         for (int bj = 0; bj < 2; ++bj) { g[bj][0] = *(const pg8::f32x4*)(gain + 32 * bj + 4 * fq); g[bj][1] = *(const pg8::f32x4*)(gain + 32 * bj + 16 + 4 * fq); }
; #pragma unroll
;         for (int ai = 0; ai < 2; ++ai) { const float2* tab = trc + (((row0 + ai * 128) & (SEQ - 1)) >> 6) * 16 + 4 * fq; rcs[ai][0] = *(const pg8::f32x4*)tab; rcs[ai][1] = *(const pg8::f32x4*)(tab + 2); }
; #pragma unroll
;         for (int mh = 0; mh < 2; ++mh) {
;             pg8::f32x4 ccs[2][2];
; #pragma unroll
;             for (int mm = 0; mm < 2; ++mm) { const float2* tab = trc + ((row0 + (2 * mh + mm) * 16) & 63) * 16 + 4 * fq; ccs[mm][0] = *(const pg8::f32x4*)tab; ccs[mm][1] = *(const pg8::f32x4*)(tab + 2); }
;             asm volatile("" ::: "memory");
; #pragma unroll
;         for (int mm = 0; mm < 2; ++mm)
; #pragma unroll
;             for (int ai = 0; ai < 2; ++ai) { const int m = 2 * mh + mm; const int row = row0 + ai * 128 + m * 16;
;                 float ss = 0.f;
; #pragma unroll
;                 for (int bj = 0; bj < 2; ++bj)
; #pragma unroll
;                     for (int n = 0; n < 2; ++n) { const pg8::f32x4 v = acc[ai][bj][m][n]; ss += (v[0] * v[0] + v[1] * v[1]) + (v[2] * v[2] + v[3] * v[3]); }
;                 ss += __shfl_xor(ss, 16); ss += __shfl_xor(ss, 32);
;                 const float rstd = rsqrtf(ss * (1.f / 64.f) + EPS);
; #pragma unroll
;                 for (int bj = 0; bj < 2; ++bj) { const pg8::f32x4 cs01 = bj == 0 ? rcs[ai][0] : ccs[mm][0], cs23 = bj == 0 ? rcs[ai][1] : ccs[mm][1];
;                     const pg8::f32x4 x1 = acc[ai][bj][m][0] * g[bj][0] * (rstd * scale), x2 = acc[ai][bj][m][1] * g[bj][1] * (rstd * scale);
;                     const float c0 = cs01[0], s0 = cs01[1], c1 = cs01[2], s1 = cs01[3], c2 = cs23[0], s2 = cs23[1], c3 = cs23[2], s3 = cs23[3];
;                     store_pair16(dst + (size_t)row * pitch + colbase + 32 * bj, fq, pk4(x1[0] * c0 - x2[0] * s0, x1[1] * c1 - x2[1] * s1, x1[2] * c2 - x2[2] * s2, x1[3] * c3 - x2[3] * s3),
.LBB0_268:
	s_andn2_b64 vcc, exec, s[68:69]
	s_cbranch_vccnz .LBB0_270
	s_load_dwordx2 s[2:3], s[64:65], 0x40
	s_lshl_b64 s[14:15], s[16:17], 2
	v_lshlrev_b32_e32 v0, 2, v184
	v_add_u32_e32 v216, 0x80, v210
	v_and_b32_e32 v189, 64, v225
	s_waitcnt lgkmcnt(0)
	s_add_u32 s2, s2, s14
	s_addc_u32 s3, s3, s15
	global_load_dwordx4 v[142:145], v0, s[2:3]
	global_load_dwordx4 v[138:141], v0, s[2:3] offset:64
	global_load_dwordx4 v[134:137], v0, s[2:3] offset:128
	global_load_dwordx4 v[130:133], v0, s[2:3] offset:192
	v_readlane_b32 s2, v246, 7
	v_lshlrev_b32_e32 v0, 3, v184
	v_readlane_b32 s3, v246, 8
	v_add_u32_e32 v189, 64, v189
	v_mul_f32_e32 v228, v128, v128
	v_mul_f32_e32 v229, v129, v129
	v_lshl_add_u64 v[162:163], s[2:3], 0, v[0:1]
	s_lshl_b32 s2, s1, 1
	s_and_b32 s20, s2, 0x1f80
	v_lshl_add_u64 v[146:147], v[162:163], 0, s[20:21]
	global_load_dwordx4 v[154:157], v[146:147], off offset:16
	global_load_dwordx4 v[158:161], v[146:147], off
	v_lshlrev_b32_e32 v0, 1, v216
	s_lshl_b32 s2, s91, 1
	v_and_b32_e32 v0, 0x1f80, v0
	s_add_u32 s2, s62, s2
	v_lshl_add_u64 v[150:151], v[162:163], 0, v[0:1]
	s_addc_u32 s3, s63, 0
	v_lshlrev_b32_e32 v0, 1, v186
	v_lshl_add_u64 v[164:165], s[2:3], 0, v[0:1]
	v_lshlrev_b32_e32 v0, 3, v188
	s_mov_b64 s[2:3], 0x16000000
	v_lshl_add_u64 v[214:215], v[162:163], 0, v[0:1]
	global_load_dwordx4 v[146:149], v[150:151], off offset:16
	s_nop 0
	global_load_dwordx4 v[150:153], v[150:151], off
	v_lshl_add_u64 v[212:213], v[164:165], 0, s[2:3]
	global_load_dwordx4 v[170:173], v[214:215], off offset:16
	global_load_dwordx4 v[174:177], v[214:215], off
	global_load_dwordx4 v[162:165], v[214:215], off offset:2064
	global_load_dwordx4 v[166:169], v[214:215], off offset:2048
	v_xor_b32_e32 v0, 16, v225
	v_cmp_lt_i32_e32 vcc, v0, v189
	v_mul_f32_e32 v230, v126, v126
	v_mul_f32_e32 v231, v127, v127
	v_mul_f32_e32 v211, v115, v115
	v_cndmask_b32_e32 v0, v225, v0, vcc
	v_pk_mov_b32 v[232:233], v[230:231], v[228:229] op_sel:[1,0]
	v_mov_b32_e32 v231, v229
	v_lshlrev_b32_e32 v227, 2, v0
	v_xor_b32_e32 v0, 32, v225
	v_add_f32_e32 v228, v232, v230
	v_add_f32_e32 v229, v233, v231
	v_mul_f32_e32 v230, v124, v124
	v_mul_f32_e32 v231, v125, v125
	v_mul_f32_e32 v232, v122, v122
	v_mul_f32_e32 v233, v123, v123
	v_cmp_lt_i32_e32 vcc, v0, v189
	v_pk_mov_b32 v[234:235], v[232:233], v[230:231] op_sel:[1,0]
	v_mov_b32_e32 v233, v231
	v_cndmask_b32_e32 v0, v225, v0, vcc
	v_add_f32_e32 v230, v234, v232
	v_add_f32_e32 v231, v235, v233
	v_lshlrev_b32_e32 v189, 2, v0
	v_mul_f32_e32 v0, v114, v114
	v_pk_add_f32 v[228:229], v[228:229], v[228:229] op_sel:[0,1] op_sel_hi:[1,0]
	v_pk_add_f32 v[230:231], v[230:231], v[230:231] op_sel:[0,1] op_sel_hi:[1,0]
	v_mov_b32_e32 v229, v0
	v_mov_b32_e32 v231, v211
	v_mul_f32_e32 v0, v119, v119
	v_add_f32_e32 v228, v228, v230
	v_add_f32_e32 v229, v229, v231
	v_fma_f32 v230, v118, v118, v0
	v_fma_f32 v231, v119, v119, v0
	v_mul_f32_e32 v0, v121, v121
	v_mul_f32_e32 v217, v116, v116
	v_mul_f32_e32 v234, v117, v117
	v_fma_f32 v232, v120, v120, v0
	v_fma_f32 v233, v121, v121, v0
	v_mov_b32_e32 v231, v217
	v_mov_b32_e32 v233, v234
	v_add_f32_e32 v230, v230, v232
	v_add_f32_e32 v231, v231, v233
	s_mov_b64 s[2:3], 0x1000
	v_add_f32_e32 v228, v228, v230
	v_add_f32_e32 v229, v229, v231
	s_waitcnt vmcnt(0)
	v_mul_f32_e32 v230, v126, v142
	v_mul_f32_e32 v231, v127, v143
	v_add_f32_e32 v0, v228, v229
	ds_bpermute_b32 v211, v227, v0
	v_mul_f32_e32 v236, v122, v138
	v_mul_f32_e32 v237, v123, v139
	s_waitcnt lgkmcnt(0)
	v_add_f32_e32 v0, v0, v211
	ds_bpermute_b32 v211, v189, v0
	s_waitcnt lgkmcnt(0)
	v_add_f32_e32 v0, v0, v211
	v_fmamk_f32 v0, v0, 0x3c800000, v219
	v_cmp_gt_f32_e32 vcc, s25, v0
	v_mul_f32_e32 v211, 0x4b800000, v0
	s_nop 0
	v_cndmask_b32_e32 v0, v0, v211, vcc
	v_rsq_f32_e32 v0, v0
	s_nop 0
	v_mul_f32_e32 v211, 0x45800000, v0
	v_cndmask_b32_e32 v0, v0, v211, vcc
	v_ashrrev_i32_e32 v211, 31, v210
	v_lshlrev_b64 v[228:229], 8, v[210:211]
	v_lshl_add_u64 v[232:233], v[212:213], 0, v[228:229]
	v_mul_f32_e32 v228, v128, v144
	v_mul_f32_e32 v229, v129, v145
	v_mul_f32_e32 v230, v230, v0
	v_mul_f32_e32 v231, v231, v0
	v_mul_f32_e32 v234, v228, v0
	v_mul_f32_e32 v235, v229, v0
	v_mul_f32_e32 v228, v124, v140
	v_mul_f32_e32 v229, v125, v141
	v_mul_f32_e32 v236, v236, v0
	v_mul_f32_e32 v237, v237, v0
	v_mul_f32_e32 v238, v228, v0
	v_mul_f32_e32 v239, v229, v0
	v_mov_b32_e32 v228, v230
	v_mov_b32_e32 v229, v236
	v_mul_f32_e32 v228, v158, v228
	v_mul_f32_e32 v229, v159, v229
	v_mov_b32_e32 v241, v230
	v_sub_f32_e32 v211, v228, v229
	v_mov_b32_e32 v228, v231
	v_mov_b32_e32 v229, v237
	v_mul_f32_e32 v228, v160, v228
	v_mul_f32_e32 v229, v161, v229
	v_mov_b32_e32 v230, v237
	v_sub_f32_e32 v217, v228, v229
	v_mov_b32_e32 v228, v234
	v_mov_b32_e32 v229, v238
	v_mul_f32_e32 v228, v154, v228
	v_mul_f32_e32 v229, v155, v229
	v_mul_f32_e32 v230, v160, v230
	v_mul_f32_e32 v231, v161, v231
	v_sub_f32_e32 v240, v228, v229
	v_mov_b32_e32 v228, v235
	v_mov_b32_e32 v229, v239
	v_mul_f32_e32 v228, v156, v228
	v_mul_f32_e32 v229, v157, v229
	s_nop 0
	v_sub_f32_e32 v229, v228, v229
	v_cvt_pk_bf16_f32 v228, v211, v217
	v_add_f32_e32 v217, v231, v230
	v_mov_b32_e32 v230, v238
	v_mov_b32_e32 v231, v234
	v_mul_f32_e32 v230, v154, v230
	v_mul_f32_e32 v231, v155, v231
	v_mov_b32_e32 v234, v239
	v_cvt_pk_bf16_f32 v229, v240, v229
	v_mov_b32_e32 v240, v236
	v_add_f32_e32 v236, v231, v230
	v_mul_f32_e32 v230, v156, v234
	v_mul_f32_e32 v231, v157, v235
	v_mul_f32_e32 v240, v158, v240
	v_mul_f32_e32 v241, v159, v241
	v_add_f32_e32 v231, v231, v230
	v_add_f32_e32 v211, v241, v240
	v_cvt_pk_bf16_f32 v230, v211, v217
	v_cvt_pk_bf16_f32 v231, v236, v231
;     __device__ __forceinline__ static v2u pk4(float a, float b, float c, float d) { v2u o; o.x = pg8::cvt_pk_bf16(a, b); o.y = pg8::cvt_pk_bf16(c, d); return o; }
;     __device__ __forceinline__ void head64(const pg8::f32x4 (&acc)[2][2][4][2], int row0, int fq, bf16r* dst, int pitch, int colbase, const float* gain, float scale, const float2* trc) const {
;     ...
;             for (int ai = 0; ai < 2; ++ai) { const int m = 2 * mh + mm; const int row = row0 + ai * 128 + m * 16;
;                 float ss = 0.f;
; #pragma unroll
;                 for (int bj = 0; bj < 2; ++bj)
; #pragma unroll
;                     for (int n = 0; n < 2; ++n) { const pg8::f32x4 v = acc[ai][bj][m][n]; ss += (v[0] * v[0] + v[1] * v[1]) + (v[2] * v[2] + v[3] * v[3]); }
;                 ss += __shfl_xor(ss, 16); ss += __shfl_xor(ss, 32);
;                 const float rstd = rsqrtf(ss * (1.f / 64.f) + EPS);
; #pragma unroll
;                 for (int bj = 0; bj < 2; ++bj) { const pg8::f32x4 cs01 = bj == 0 ? rcs[ai][0] : ccs[mm][0], cs23 = bj == 0 ? rcs[ai][1] : ccs[mm][1];
;                     const pg8::f32x4 x1 = acc[ai][bj][m][0] * g[bj][0] * (rstd * scale), x2 = acc[ai][bj][m][1] * g[bj][1] * (rstd * scale);
;                     const float c0 = cs01[0], s0 = cs01[1], c1 = cs01[2], s1 = cs01[3], c2 = cs23[0], s2 = cs23[1], c3 = cs23[2], s3 = cs23[3];
;                     store_pair16(dst + (size_t)row * pitch + colbase + 32 * bj, fq, pk4(x1[0] * c0 - x2[0] * s0, x1[1] * c1 - x2[1] * s1, x1[2] * c2 - x2[2] * s2, x1[3] * c3 - x2[3] * s3),
;                                  pk4(x2[0] * c0 + x1[0] * s0, x2[1] * c1 + x1[1] * s1, x2[2] * c2 + x1[2] * s2, x2[3] * c3 + x1[3] * s3)); } } }
	v_mul_f32_e32 v236, v114, v130
	v_mul_f32_e32 v237, v115, v131
	v_permlane16_swap_b32_e32 v228, v230
	v_permlane16_swap_b32_e32 v229, v231
	global_store_dwordx4 v[232:233], v[228:231], off
	v_mul_f32_e32 v236, v236, v0
	v_mul_f32_e32 v237, v237, v0
	s_nop 0
	v_mul_f32_e32 v228, v120, v136
	v_mul_f32_e32 v229, v121, v137
	v_mul_f32_e32 v230, v118, v134
	v_mul_f32_e32 v231, v119, v135
	v_mul_f32_e32 v234, v228, v0
	v_mul_f32_e32 v235, v229, v0
	v_mul_f32_e32 v230, v230, v0
	v_mul_f32_e32 v231, v231, v0
	v_mul_f32_e32 v228, v116, v132
	v_mul_f32_e32 v229, v117, v133
	v_mov_b32_e32 v241, v230
	v_mul_f32_e32 v238, v228, v0
	v_mul_f32_e32 v239, v229, v0
	v_mov_b32_e32 v228, v230
	v_mov_b32_e32 v229, v236
	v_mul_f32_e32 v228, v174, v228
	v_mul_f32_e32 v229, v175, v229
	v_mov_b32_e32 v230, v237
	v_sub_f32_e32 v0, v228, v229
	v_mov_b32_e32 v228, v231
	v_mov_b32_e32 v229, v237
	v_mul_f32_e32 v228, v176, v228
	v_mul_f32_e32 v229, v177, v229
	v_mul_f32_e32 v230, v176, v230
	v_mul_f32_e32 v231, v177, v231
	v_sub_f32_e32 v211, v228, v229
	v_mov_b32_e32 v228, v234
	v_mov_b32_e32 v229, v238
	v_mul_f32_e32 v228, v170, v228
	v_mul_f32_e32 v229, v171, v229
	v_mov_b32_e32 v240, v236
	v_sub_f32_e32 v217, v228, v229
	v_mov_b32_e32 v228, v235
	v_mov_b32_e32 v229, v239
	v_mul_f32_e32 v228, v172, v228
	v_mul_f32_e32 v229, v173, v229
	v_mul_f32_e32 v240, v174, v240
	v_mul_f32_e32 v241, v175, v241
	v_sub_f32_e32 v229, v228, v229
	v_cvt_pk_bf16_f32 v228, v0, v211
	v_add_f32_e32 v211, v231, v230
	v_mov_b32_e32 v230, v238
	v_mov_b32_e32 v231, v234
	v_mul_f32_e32 v230, v170, v230
	v_mul_f32_e32 v231, v171, v231
	v_mov_b32_e32 v234, v239
	v_cvt_pk_bf16_f32 v229, v217, v229
	v_add_f32_e32 v217, v231, v230
	v_mul_f32_e32 v230, v172, v234
	v_mul_f32_e32 v231, v173, v235
	v_add_f32_e32 v0, v241, v240
	v_add_f32_e32 v231, v231, v230
	v_cvt_pk_bf16_f32 v230, v0, v211
	v_cvt_pk_bf16_f32 v231, v217, v231
	v_mul_f32_e32 v0, v98, v98
	v_permlane16_swap_b32_e32 v228, v230
	v_permlane16_swap_b32_e32 v229, v231
	global_store_dwordx4 v[232:233], v[228:231], off offset:64
	v_mul_f32_e32 v211, v99, v99
	v_mul_f32_e32 v217, v100, v100
	v_mul_f32_e32 v228, v112, v112
	v_mul_f32_e32 v229, v113, v113
	v_mul_f32_e32 v230, v110, v110
	v_mul_f32_e32 v231, v111, v111
	s_nop 0
	v_pk_mov_b32 v[232:233], v[230:231], v[228:229] op_sel:[1,0]
	v_mov_b32_e32 v231, v229
	v_add_f32_e32 v228, v232, v230
	v_add_f32_e32 v229, v233, v231
	v_mul_f32_e32 v230, v108, v108
	v_mul_f32_e32 v231, v109, v109
	v_mul_f32_e32 v232, v106, v106
	v_mul_f32_e32 v233, v107, v107
	v_pk_add_f32 v[228:229], v[228:229], v[228:229] op_sel:[0,1] op_sel_hi:[1,0]
	v_pk_mov_b32 v[234:235], v[232:233], v[230:231] op_sel:[1,0]
	v_mov_b32_e32 v233, v231
	v_add_f32_e32 v230, v234, v232
	v_add_f32_e32 v231, v235, v233
	v_mov_b32_e32 v229, v0
	v_pk_add_f32 v[230:231], v[230:231], v[230:231] op_sel:[0,1] op_sel_hi:[1,0]
	v_mul_f32_e32 v0, v103, v103
	v_mov_b32_e32 v231, v211
	v_add_f32_e32 v228, v228, v230
	v_add_f32_e32 v229, v229, v231
	v_fma_f32 v230, v102, v102, v0
	v_fma_f32 v231, v103, v103, v0
	v_mul_f32_e32 v0, v105, v105
	v_mul_f32_e32 v234, v101, v101
	v_fma_f32 v232, v104, v104, v0
	v_fma_f32 v233, v105, v105, v0
	v_mov_b32_e32 v231, v217
	v_mov_b32_e32 v233, v234
	v_add_f32_e32 v230, v230, v232
	v_add_f32_e32 v231, v231, v233
	v_mul_f32_e32 v234, v106, v138
	v_mul_f32_e32 v235, v107, v139
	v_add_f32_e32 v228, v228, v230
	v_add_f32_e32 v229, v229, v231
	v_mul_f32_e32 v230, v110, v142
	v_mul_f32_e32 v231, v111, v143
	v_add_f32_e32 v0, v228, v229
	ds_bpermute_b32 v211, v227, v0
	v_mul_f32_e32 v228, v112, v144
	v_mul_f32_e32 v229, v113, v145
	v_ashrrev_i32_e32 v217, 31, v216
	v_lshlrev_b64 v[216:217], 8, v[216:217]
	v_lshl_add_u64 v[216:217], v[212:213], 0, v[216:217]
	s_waitcnt lgkmcnt(0)
	v_add_f32_e32 v0, v0, v211
	ds_bpermute_b32 v211, v189, v0
	s_waitcnt lgkmcnt(0)
	v_add_f32_e32 v0, v0, v211
	v_fmamk_f32 v0, v0, 0x3c800000, v219
	v_cmp_gt_f32_e32 vcc, s25, v0
	v_mul_f32_e32 v211, 0x4b800000, v0
	s_nop 0
	v_cndmask_b32_e32 v0, v0, v211, vcc
	v_rsq_f32_e32 v0, v0
	s_nop 0
	v_mul_f32_e32 v211, 0x45800000, v0
	v_cndmask_b32_e32 v0, v0, v211, vcc
	v_mul_f32_e32 v232, v228, v0
	v_mul_f32_e32 v233, v229, v0
	v_mul_f32_e32 v230, v230, v0
	v_mul_f32_e32 v231, v231, v0
	v_mul_f32_e32 v228, v108, v140
	v_mul_f32_e32 v229, v109, v141
	v_mul_f32_e32 v234, v234, v0
	v_mul_f32_e32 v235, v235, v0
	v_mul_f32_e32 v236, v228, v0
	v_mul_f32_e32 v237, v229, v0
	v_mov_b32_e32 v228, v230
	v_mov_b32_e32 v229, v234
	v_mul_f32_e32 v228, v150, v228
	v_mul_f32_e32 v229, v151, v229
	s_nop 0
	v_sub_f32_e32 v211, v228, v229
	v_mov_b32_e32 v228, v231
	v_mov_b32_e32 v229, v235
	v_mul_f32_e32 v228, v152, v228
	v_mul_f32_e32 v229, v153, v229
	s_nop 0
	v_sub_f32_e32 v238, v228, v229
	v_mov_b32_e32 v228, v232
	v_mov_b32_e32 v229, v236
	v_mul_f32_e32 v228, v146, v228
	v_mul_f32_e32 v229, v147, v229
	s_nop 0
	v_sub_f32_e32 v239, v228, v229
	v_mov_b32_e32 v228, v233
	v_mov_b32_e32 v229, v237
	v_mul_f32_e32 v228, v148, v228
	v_mul_f32_e32 v229, v149, v229
	s_nop 0
	v_sub_f32_e32 v229, v228, v229
	v_cvt_pk_bf16_f32 v228, v211, v238
	v_cvt_pk_bf16_f32 v229, v239, v229
	v_mov_b32_e32 v239, v230
	v_mov_b32_e32 v230, v235
	v_mul_f32_e32 v230, v152, v230
	v_mul_f32_e32 v231, v153, v231
	v_mov_b32_e32 v238, v234
	v_add_f32_e32 v234, v231, v230
	v_mov_b32_e32 v230, v236
	v_mov_b32_e32 v231, v232
	v_mul_f32_e32 v230, v146, v230
	v_mul_f32_e32 v231, v147, v231
	v_mov_b32_e32 v232, v237
	v_add_f32_e32 v235, v231, v230
	v_mul_f32_e32 v230, v148, v232
	v_mul_f32_e32 v231, v149, v233
	v_mul_f32_e32 v238, v150, v238
	v_mul_f32_e32 v239, v151, v239
	v_add_f32_e32 v231, v231, v230
;     __device__ __forceinline__ static v2u pk4(float a, float b, float c, float d) { v2u o; o.x = pg8::cvt_pk_bf16(a, b); o.y = pg8::cvt_pk_bf16(c, d); return o; }
;     __device__ __forceinline__ void head64(const pg8::f32x4 (&acc)[2][2][4][2], int row0, int fq, bf16r* dst, int pitch, int colbase, const float* gain, float scale, const float2* trc) const {
;     ...
;             for (int ai = 0; ai < 2; ++ai) { const int m = 2 * mh + mm; const int row = row0 + ai * 128 + m * 16;
;                 float ss = 0.f;
; #pragma unroll
;                 for (int bj = 0; bj < 2; ++bj)
; #pragma unroll
;                     for (int n = 0; n < 2; ++n) { const pg8::f32x4 v = acc[ai][bj][m][n]; ss += (v[0] * v[0] + v[1] * v[1]) + (v[2] * v[2] + v[3] * v[3]); }
;                 ss += __shfl_xor(ss, 16); ss += __shfl_xor(ss, 32);
;                 const float rstd = rsqrtf(ss * (1.f / 64.f) + EPS);
; #pragma unroll
;                 for (int bj = 0; bj < 2; ++bj) { const pg8::f32x4 cs01 = bj == 0 ? rcs[ai][0] : ccs[mm][0], cs23 = bj == 0 ? rcs[ai][1] : ccs[mm][1];
;                     const pg8::f32x4 x1 = acc[ai][bj][m][0] * g[bj][0] * (rstd * scale), x2 = acc[ai][bj][m][1] * g[bj][1] * (rstd * scale);
;                     const float c0 = cs01[0], s0 = cs01[1], c1 = cs01[2], s1 = cs01[3], c2 = cs23[0], s2 = cs23[1], c3 = cs23[2], s3 = cs23[3];
;                     store_pair16(dst + (size_t)row * pitch + colbase + 32 * bj, fq, pk4(x1[0] * c0 - x2[0] * s0, x1[1] * c1 - x2[1] * s1, x1[2] * c2 - x2[2] * s2, x1[3] * c3 - x2[3] * s3),
;                                  pk4(x2[0] * c0 + x1[0] * s0, x2[1] * c1 + x1[1] * s1, x2[2] * c2 + x1[2] * s2, x2[3] * c3 + x1[3] * s3)); } } }
	v_add_f32_e32 v211, v239, v238
	v_cvt_pk_bf16_f32 v230, v211, v234
	v_cvt_pk_bf16_f32 v231, v235, v231
	v_mul_f32_e32 v234, v98, v130
	v_mul_f32_e32 v235, v99, v131
	v_permlane16_swap_b32_e32 v228, v230
	v_permlane16_swap_b32_e32 v229, v231
	global_store_dwordx4 v[216:217], v[228:231], off
	v_mul_f32_e32 v234, v234, v0
	v_mul_f32_e32 v235, v235, v0
	s_nop 0
	v_mul_f32_e32 v228, v104, v136
	v_mul_f32_e32 v229, v105, v137
	v_mul_f32_e32 v230, v102, v134
	v_mul_f32_e32 v231, v103, v135
	v_mul_f32_e32 v232, v228, v0
	v_mul_f32_e32 v233, v229, v0
	v_mul_f32_e32 v230, v230, v0
	v_mul_f32_e32 v231, v231, v0
	v_mul_f32_e32 v228, v100, v132
	v_mul_f32_e32 v229, v101, v133
	v_mov_b32_e32 v239, v230
	v_mul_f32_e32 v236, v228, v0
	v_mul_f32_e32 v237, v229, v0
	v_mov_b32_e32 v228, v230
	v_mov_b32_e32 v229, v234
	v_mul_f32_e32 v228, v174, v228
	v_mul_f32_e32 v229, v175, v229
	v_mov_b32_e32 v230, v235
	v_sub_f32_e32 v0, v228, v229
	v_mov_b32_e32 v228, v231
	v_mov_b32_e32 v229, v235
	v_mul_f32_e32 v228, v176, v228
	v_mul_f32_e32 v229, v177, v229
	s_nop 0
	v_sub_f32_e32 v211, v228, v229
	v_mov_b32_e32 v228, v232
	v_mov_b32_e32 v229, v236
	v_mul_f32_e32 v228, v170, v228
	v_mul_f32_e32 v229, v171, v229
	s_nop 0
	v_sub_f32_e32 v238, v228, v229
	v_mov_b32_e32 v228, v233
	v_mov_b32_e32 v229, v237
	v_mul_f32_e32 v228, v172, v228
	v_mul_f32_e32 v229, v173, v229
	s_nop 0
	v_sub_f32_e32 v229, v228, v229
	v_cvt_pk_bf16_f32 v228, v0, v211
	v_cvt_pk_bf16_f32 v229, v238, v229
	v_mov_b32_e32 v238, v234
	v_mul_f32_e32 v174, v174, v238
	v_mul_f32_e32 v175, v175, v239
	v_mul_f32_e32 v211, v85, v85
	v_add_f32_e32 v0, v175, v174
	v_mul_f32_e32 v174, v176, v230
	v_mul_f32_e32 v175, v177, v231
	s_nop 0
	v_add_f32_e32 v176, v175, v174
	v_mov_b32_e32 v174, v236
	v_mov_b32_e32 v175, v232
	v_mul_f32_e32 v170, v170, v174
	v_mul_f32_e32 v171, v171, v175
	v_mov_b32_e32 v232, v237
	v_add_f32_e32 v174, v171, v170
	v_mul_f32_e32 v170, v172, v232
	v_mul_f32_e32 v171, v173, v233
	v_cvt_pk_bf16_f32 v230, v0, v176
	v_mul_f32_e32 v172, v96, v96
	v_mul_f32_e32 v173, v97, v97
	v_add_f32_e32 v170, v171, v170
	v_cvt_pk_bf16_f32 v231, v174, v170
	v_mul_f32_e32 v174, v94, v94
	v_mul_f32_e32 v175, v95, v95
	v_permlane16_swap_b32_e32 v228, v230
	v_pk_mov_b32 v[176:177], v[174:175], v[172:173] op_sel:[1,0]
	v_mov_b32_e32 v175, v173
	v_permlane16_swap_b32_e32 v229, v231
	v_add_f32_e32 v172, v176, v174
	v_add_f32_e32 v173, v177, v175
	v_mul_f32_e32 v174, v92, v92
	v_mul_f32_e32 v175, v93, v93
	v_mul_f32_e32 v176, v90, v90
	v_mul_f32_e32 v177, v91, v91
	global_store_dwordx4 v[216:217], v[228:231], off offset:64
	v_pk_mov_b32 v[216:217], v[176:177], v[174:175] op_sel:[1,0]
	v_mov_b32_e32 v177, v175
	v_add_f32_e32 v174, v216, v176
	v_add_f32_e32 v175, v217, v177
	v_mul_f32_e32 v0, v82, v82
	v_mul_f32_e32 v171, v83, v83
	v_pk_add_f32 v[172:173], v[172:173], v[172:173] op_sel:[0,1] op_sel_hi:[1,0]
	v_pk_add_f32 v[174:175], v[174:175], v[174:175] op_sel:[0,1] op_sel_hi:[1,0]
	v_mov_b32_e32 v173, v0
	v_mov_b32_e32 v175, v171
	v_mul_f32_e32 v0, v87, v87
	v_mul_f32_e32 v176, v84, v84
	v_add_f32_e32 v172, v172, v174
	v_add_f32_e32 v173, v173, v175
	v_fma_f32 v174, v86, v86, v0
	v_fma_f32 v175, v87, v87, v0
	v_mul_f32_e32 v0, v89, v89
	v_mov_b32_e32 v175, v176
	v_fma_f32 v176, v88, v88, v0
	v_fma_f32 v177, v89, v89, v0
	v_or_b32_e32 v170, 16, v210
	v_mov_b32_e32 v177, v211
	v_add_f32_e32 v174, v174, v176
	v_add_f32_e32 v175, v175, v177
	v_mul_f32_e32 v216, v90, v138
	v_mul_f32_e32 v217, v91, v139
	v_add_f32_e32 v172, v172, v174
	v_add_f32_e32 v173, v173, v175
	s_nop 0
	v_add_f32_e32 v0, v172, v173
	ds_bpermute_b32 v171, v227, v0
	v_mul_f32_e32 v172, v94, v142
	v_mul_f32_e32 v173, v95, v143
	s_waitcnt lgkmcnt(0)
	v_add_f32_e32 v0, v0, v171
	ds_bpermute_b32 v171, v189, v0
	s_waitcnt lgkmcnt(0)
	v_add_f32_e32 v0, v0, v171
	v_fmamk_f32 v0, v0, 0x3c800000, v219
	v_cmp_gt_f32_e32 vcc, s25, v0
	v_mul_f32_e32 v171, 0x4b800000, v0
	s_nop 0
	v_cndmask_b32_e32 v0, v0, v171, vcc
	v_rsq_f32_e32 v0, v0
	s_nop 0
	v_mul_f32_e32 v171, 0x45800000, v0
	v_cndmask_b32_e32 v0, v0, v171, vcc
	v_ashrrev_i32_e32 v171, 31, v170
	v_lshlrev_b64 v[170:171], 8, v[170:171]
	v_lshl_add_u64 v[174:175], v[212:213], 0, v[170:171]
	v_mul_f32_e32 v170, v96, v144
	v_mul_f32_e32 v171, v97, v145
	v_mul_f32_e32 v172, v172, v0
	v_mul_f32_e32 v173, v173, v0
	v_mul_f32_e32 v176, v170, v0
	v_mul_f32_e32 v177, v171, v0
	v_mul_f32_e32 v170, v92, v140
	v_mul_f32_e32 v171, v93, v141
	v_mul_f32_e32 v216, v216, v0
	v_mul_f32_e32 v217, v217, v0
	v_mul_f32_e32 v228, v170, v0
	v_mul_f32_e32 v229, v171, v0
	v_mov_b32_e32 v170, v172
	v_mov_b32_e32 v171, v216
	v_mul_f32_e32 v170, v158, v170
	v_mul_f32_e32 v171, v159, v171
	s_nop 0
	v_sub_f32_e32 v211, v170, v171
	v_mov_b32_e32 v170, v173
	v_mov_b32_e32 v171, v217
	v_mul_f32_e32 v170, v160, v170
	v_mul_f32_e32 v171, v161, v171
	s_nop 0
	v_sub_f32_e32 v230, v170, v171
	v_mov_b32_e32 v170, v176
	v_mov_b32_e32 v171, v228
	v_mul_f32_e32 v170, v154, v170
	v_mul_f32_e32 v171, v155, v171
	s_nop 0
	v_sub_f32_e32 v231, v170, v171
	v_mov_b32_e32 v170, v177
	v_mov_b32_e32 v171, v229
	v_mul_f32_e32 v170, v156, v170
	v_mul_f32_e32 v171, v157, v171
	s_nop 0
	v_sub_f32_e32 v171, v170, v171
	v_cvt_pk_bf16_f32 v170, v211, v230
	v_cvt_pk_bf16_f32 v171, v231, v171
	v_mov_b32_e32 v231, v172
	v_mov_b32_e32 v172, v217
	v_mul_f32_e32 v172, v160, v172
	v_mul_f32_e32 v173, v161, v173
	v_mov_b32_e32 v230, v216
	v_add_f32_e32 v216, v173, v172
	v_mov_b32_e32 v172, v228
	v_mov_b32_e32 v173, v176
	v_mul_f32_e32 v172, v154, v172
	v_mul_f32_e32 v173, v155, v173
	v_mov_b32_e32 v176, v229
	v_add_f32_e32 v217, v173, v172
	v_mul_f32_e32 v172, v156, v176
;     __device__ __forceinline__ static v2u pk4(float a, float b, float c, float d) { v2u o; o.x = pg8::cvt_pk_bf16(a, b); o.y = pg8::cvt_pk_bf16(c, d); return o; }
;     __device__ __forceinline__ void head64(const pg8::f32x4 (&acc)[2][2][4][2], int row0, int fq, bf16r* dst, int pitch, int colbase, const float* gain, float scale, const float2* trc) const {
;     ...
;             for (int ai = 0; ai < 2; ++ai) { const int m = 2 * mh + mm; const int row = row0 + ai * 128 + m * 16;
;                 float ss = 0.f;
; #pragma unroll
;                 for (int bj = 0; bj < 2; ++bj)
; #pragma unroll
;                     for (int n = 0; n < 2; ++n) { const pg8::f32x4 v = acc[ai][bj][m][n]; ss += (v[0] * v[0] + v[1] * v[1]) + (v[2] * v[2] + v[3] * v[3]); }
;                 ss += __shfl_xor(ss, 16); ss += __shfl_xor(ss, 32);
;                 const float rstd = rsqrtf(ss * (1.f / 64.f) + EPS);
; #pragma unroll
;                 for (int bj = 0; bj < 2; ++bj) { const pg8::f32x4 cs01 = bj == 0 ? rcs[ai][0] : ccs[mm][0], cs23 = bj == 0 ? rcs[ai][1] : ccs[mm][1];
;                     const pg8::f32x4 x1 = acc[ai][bj][m][0] * g[bj][0] * (rstd * scale), x2 = acc[ai][bj][m][1] * g[bj][1] * (rstd * scale);
;                     const float c0 = cs01[0], s0 = cs01[1], c1 = cs01[2], s1 = cs01[3], c2 = cs23[0], s2 = cs23[1], c3 = cs23[2], s3 = cs23[3];
;                     store_pair16(dst + (size_t)row * pitch + colbase + 32 * bj, fq, pk4(x1[0] * c0 - x2[0] * s0, x1[1] * c1 - x2[1] * s1, x1[2] * c2 - x2[2] * s2, x1[3] * c3 - x2[3] * s3),
;                                  pk4(x2[0] * c0 + x1[0] * s0, x2[1] * c1 + x1[1] * s1, x2[2] * c2 + x1[2] * s2, x2[3] * c3 + x1[3] * s3)); } } }
	v_mul_f32_e32 v173, v157, v177
	v_mul_f32_e32 v230, v158, v230
	v_mul_f32_e32 v231, v159, v231
	v_add_f32_e32 v173, v173, v172
	v_add_f32_e32 v211, v231, v230
	v_cvt_pk_bf16_f32 v172, v211, v216
	v_cvt_pk_bf16_f32 v173, v217, v173
	v_mul_f32_e32 v216, v82, v130
	v_mul_f32_e32 v217, v83, v131
	v_permlane16_swap_b32_e32 v170, v172
	v_permlane16_swap_b32_e32 v171, v173
	global_store_dwordx4 v[174:175], v[170:173], off
	v_mul_f32_e32 v216, v216, v0
	v_mul_f32_e32 v217, v217, v0
	s_nop 0
	v_mul_f32_e32 v170, v88, v136
	v_mul_f32_e32 v171, v89, v137
	v_mul_f32_e32 v172, v86, v134
	v_mul_f32_e32 v173, v87, v135
	v_mul_f32_e32 v176, v170, v0
	v_mul_f32_e32 v177, v171, v0
	v_mul_f32_e32 v172, v172, v0
	v_mul_f32_e32 v173, v173, v0
	v_mul_f32_e32 v170, v84, v132
	v_mul_f32_e32 v171, v85, v133
	v_mov_b32_e32 v231, v172
	v_mul_f32_e32 v228, v170, v0
	v_mul_f32_e32 v229, v171, v0
	v_mov_b32_e32 v170, v172
	v_mov_b32_e32 v171, v216
	v_mul_f32_e32 v170, v166, v170
	v_mul_f32_e32 v171, v167, v171
	v_mov_b32_e32 v172, v217
	v_sub_f32_e32 v0, v170, v171
	v_mov_b32_e32 v170, v173
	v_mov_b32_e32 v171, v217
	v_mul_f32_e32 v170, v168, v170
	v_mul_f32_e32 v171, v169, v171
	v_mul_f32_e32 v172, v168, v172
	v_mul_f32_e32 v173, v169, v173
	v_sub_f32_e32 v211, v170, v171
	v_mov_b32_e32 v170, v176
	v_mov_b32_e32 v171, v228
	v_mul_f32_e32 v170, v162, v170
	v_mul_f32_e32 v171, v163, v171
	s_nop 0
	v_sub_f32_e32 v230, v170, v171
	v_mov_b32_e32 v170, v177
	v_mov_b32_e32 v171, v229
	v_mul_f32_e32 v170, v164, v170
	v_mul_f32_e32 v171, v165, v171
	s_nop 0
	v_sub_f32_e32 v171, v170, v171
	v_cvt_pk_bf16_f32 v170, v0, v211
	v_add_f32_e32 v211, v173, v172
	v_mov_b32_e32 v172, v228
	v_mov_b32_e32 v173, v176
	v_mul_f32_e32 v172, v162, v172
	v_mul_f32_e32 v173, v163, v173
	v_mov_b32_e32 v176, v229
	v_cvt_pk_bf16_f32 v171, v230, v171
	v_mov_b32_e32 v230, v216
	v_add_f32_e32 v216, v173, v172
	v_mul_f32_e32 v172, v164, v176
	v_mul_f32_e32 v173, v165, v177
	v_mul_f32_e32 v230, v166, v230
	v_mul_f32_e32 v231, v167, v231
	v_add_f32_e32 v173, v173, v172
	v_add_f32_e32 v0, v231, v230
	v_cvt_pk_bf16_f32 v172, v0, v211
	v_cvt_pk_bf16_f32 v173, v216, v173
	v_mul_f32_e32 v0, v66, v66
	v_permlane16_swap_b32_e32 v170, v172
	v_permlane16_swap_b32_e32 v171, v173
	global_store_dwordx4 v[174:175], v[170:173], off offset:64
	v_mul_f32_e32 v216, v74, v138
	v_mul_f32_e32 v217, v75, v139
	s_nop 0
	v_mul_f32_e32 v170, v80, v80
	v_mul_f32_e32 v171, v81, v81
	v_mul_f32_e32 v172, v78, v78
	v_mul_f32_e32 v173, v79, v79
	s_nop 0
	v_pk_mov_b32 v[174:175], v[172:173], v[170:171] op_sel:[1,0]
	v_mov_b32_e32 v173, v171
	v_add_f32_e32 v170, v174, v172
	v_add_f32_e32 v171, v175, v173
	v_mul_f32_e32 v172, v76, v76
	v_mul_f32_e32 v173, v77, v77
	v_mul_f32_e32 v174, v74, v74
	v_mul_f32_e32 v175, v75, v75
	v_pk_add_f32 v[170:171], v[170:171], v[170:171] op_sel:[0,1] op_sel_hi:[1,0]
	v_pk_mov_b32 v[176:177], v[174:175], v[172:173] op_sel:[1,0]
	v_mov_b32_e32 v175, v173
	v_add_f32_e32 v172, v176, v174
	v_add_f32_e32 v173, v177, v175
	v_mul_f32_e32 v174, v67, v67
	v_pk_add_f32 v[172:173], v[172:173], v[172:173] op_sel:[0,1] op_sel_hi:[1,0]
	v_mov_b32_e32 v171, v0
	v_mov_b32_e32 v173, v174
	v_mul_f32_e32 v0, v71, v71
	v_mul_f32_e32 v175, v68, v68
	v_add_f32_e32 v170, v170, v172
	v_add_f32_e32 v171, v171, v173
	v_fma_f32 v172, v70, v70, v0
	v_fma_f32 v173, v71, v71, v0
	v_mul_f32_e32 v0, v73, v73
	v_mul_f32_e32 v176, v69, v69
	v_mov_b32_e32 v173, v175
	v_fma_f32 v174, v72, v72, v0
	v_fma_f32 v175, v73, v73, v0
	s_nop 0
	v_mov_b32_e32 v175, v176
	v_add_f32_e32 v172, v172, v174
	v_add_f32_e32 v173, v173, v175
	s_nop 0
	v_add_f32_e32 v170, v170, v172
	v_add_f32_e32 v171, v171, v173
	v_mul_f32_e32 v172, v78, v142
	v_mul_f32_e32 v173, v79, v143
	v_add_f32_e32 v0, v170, v171
	ds_bpermute_b32 v171, v227, v0
	v_add_u32_e32 v170, 0x90, v210
	s_waitcnt lgkmcnt(0)
	v_add_f32_e32 v0, v0, v171
	ds_bpermute_b32 v171, v189, v0
	s_waitcnt lgkmcnt(0)
	v_add_f32_e32 v0, v0, v171
	v_fmamk_f32 v0, v0, 0x3c800000, v219
	v_cmp_gt_f32_e32 vcc, s25, v0
	v_mul_f32_e32 v171, 0x4b800000, v0
	s_nop 0
	v_cndmask_b32_e32 v0, v0, v171, vcc
	v_rsq_f32_e32 v0, v0
	s_nop 0
	v_mul_f32_e32 v171, 0x45800000, v0
	v_cndmask_b32_e32 v0, v0, v171, vcc
	v_ashrrev_i32_e32 v171, 31, v170
	v_lshlrev_b64 v[170:171], 8, v[170:171]
	v_lshl_add_u64 v[174:175], v[212:213], 0, v[170:171]
	v_mul_f32_e32 v170, v80, v144
	v_mul_f32_e32 v171, v81, v145
	v_mul_f32_e32 v172, v172, v0
	v_mul_f32_e32 v173, v173, v0
	v_mul_f32_e32 v176, v170, v0
	v_mul_f32_e32 v177, v171, v0
	v_mul_f32_e32 v170, v76, v140
	v_mul_f32_e32 v171, v77, v141
	v_mul_f32_e32 v216, v216, v0
	v_mul_f32_e32 v217, v217, v0
	v_mul_f32_e32 v228, v170, v0
	v_mul_f32_e32 v229, v171, v0
	v_mov_b32_e32 v170, v172
	v_mov_b32_e32 v171, v216
	v_mul_f32_e32 v170, v150, v170
	v_mul_f32_e32 v171, v151, v171
	s_nop 0
	v_sub_f32_e32 v211, v170, v171
	v_mov_b32_e32 v170, v173
	v_mov_b32_e32 v171, v217
	v_mul_f32_e32 v170, v152, v170
	v_mul_f32_e32 v171, v153, v171
	s_nop 0
	v_sub_f32_e32 v230, v170, v171
	v_mov_b32_e32 v170, v176
	v_mov_b32_e32 v171, v228
	v_mul_f32_e32 v170, v146, v170
	v_mul_f32_e32 v171, v147, v171
	s_nop 0
	v_sub_f32_e32 v231, v170, v171
	v_mov_b32_e32 v170, v177
	v_mov_b32_e32 v171, v229
	v_mul_f32_e32 v170, v148, v170
	v_mul_f32_e32 v171, v149, v171
	s_nop 0
	v_sub_f32_e32 v171, v170, v171
	v_cvt_pk_bf16_f32 v170, v211, v230
	v_cvt_pk_bf16_f32 v171, v231, v171
	v_mov_b32_e32 v231, v172
	v_mov_b32_e32 v172, v217
	v_mul_f32_e32 v172, v152, v172
	v_mul_f32_e32 v173, v153, v173
	v_mov_b32_e32 v230, v216
	v_add_f32_e32 v216, v173, v172
	v_mov_b32_e32 v172, v228
	v_mov_b32_e32 v173, v176
;     __device__ __forceinline__ static v2u pk4(float a, float b, float c, float d) { v2u o; o.x = pg8::cvt_pk_bf16(a, b); o.y = pg8::cvt_pk_bf16(c, d); return o; }
;     __device__ __forceinline__ void head64(const pg8::f32x4 (&acc)[2][2][4][2], int row0, int fq, bf16r* dst, int pitch, int colbase, const float* gain, float scale, const float2* trc) const {
;     ...
;             for (int mm = 0; mm < 2; ++mm) { const float2* tab = trc + ((row0 + (2 * mh + mm) * 16) & 63) * 16 + 4 * fq; ccs[mm][0] = *(const pg8::f32x4*)tab; ccs[mm][1] = *(const pg8::f32x4*)(tab + 2); }
;     ...
;             for (int ai = 0; ai < 2; ++ai) { const int m = 2 * mh + mm; const int row = row0 + ai * 128 + m * 16;
;                 float ss = 0.f;
; #pragma unroll
;                 for (int bj = 0; bj < 2; ++bj)
; #pragma unroll
;                     for (int n = 0; n < 2; ++n) { const pg8::f32x4 v = acc[ai][bj][m][n]; ss += (v[0] * v[0] + v[1] * v[1]) + (v[2] * v[2] + v[3] * v[3]); }
;                 ss += __shfl_xor(ss, 16); ss += __shfl_xor(ss, 32);
;                 const float rstd = rsqrtf(ss * (1.f / 64.f) + EPS);
; #pragma unroll
;                 for (int bj = 0; bj < 2; ++bj) { const pg8::f32x4 cs01 = bj == 0 ? rcs[ai][0] : ccs[mm][0], cs23 = bj == 0 ? rcs[ai][1] : ccs[mm][1];
;                     const pg8::f32x4 x1 = acc[ai][bj][m][0] * g[bj][0] * (rstd * scale), x2 = acc[ai][bj][m][1] * g[bj][1] * (rstd * scale);
;                     const float c0 = cs01[0], s0 = cs01[1], c1 = cs01[2], s1 = cs01[3], c2 = cs23[0], s2 = cs23[1], c3 = cs23[2], s3 = cs23[3];
;                     store_pair16(dst + (size_t)row * pitch + colbase + 32 * bj, fq, pk4(x1[0] * c0 - x2[0] * s0, x1[1] * c1 - x2[1] * s1, x1[2] * c2 - x2[2] * s2, x1[3] * c3 - x2[3] * s3),
;                                  pk4(x2[0] * c0 + x1[0] * s0, x2[1] * c1 + x1[1] * s1, x2[2] * c2 + x1[2] * s2, x2[3] * c3 + x1[3] * s3)); } } }
	v_mul_f32_e32 v172, v146, v172
	v_mul_f32_e32 v173, v147, v173
	v_mov_b32_e32 v176, v229
	v_add_f32_e32 v217, v173, v172
	v_mul_f32_e32 v172, v148, v176
	v_mul_f32_e32 v173, v149, v177
	v_mul_f32_e32 v230, v150, v230
	v_mul_f32_e32 v231, v151, v231
	v_add_f32_e32 v173, v173, v172
	v_add_f32_e32 v211, v231, v230
	v_cvt_pk_bf16_f32 v172, v211, v216
	v_cvt_pk_bf16_f32 v173, v217, v173
	v_mul_f32_e32 v216, v66, v130
	v_mul_f32_e32 v217, v67, v131
	v_permlane16_swap_b32_e32 v170, v172
	v_permlane16_swap_b32_e32 v171, v173
	global_store_dwordx4 v[174:175], v[170:173], off
	v_mul_f32_e32 v216, v216, v0
	v_mul_f32_e32 v217, v217, v0
	s_nop 0
	v_mul_f32_e32 v170, v72, v136
	v_mul_f32_e32 v171, v73, v137
	v_mul_f32_e32 v172, v70, v134
	v_mul_f32_e32 v173, v71, v135
	v_mul_f32_e32 v176, v170, v0
	v_mul_f32_e32 v177, v171, v0
	v_mul_f32_e32 v172, v172, v0
	v_mul_f32_e32 v173, v173, v0
	v_mul_f32_e32 v170, v68, v132
	v_mul_f32_e32 v171, v69, v133
	v_mov_b32_e32 v231, v172
	v_mul_f32_e32 v228, v170, v0
	v_mul_f32_e32 v229, v171, v0
	v_mov_b32_e32 v170, v172
	v_mov_b32_e32 v171, v216
	v_mul_f32_e32 v170, v166, v170
	v_mul_f32_e32 v171, v167, v171
	v_mov_b32_e32 v172, v217
	v_sub_f32_e32 v0, v170, v171
	v_mov_b32_e32 v170, v173
	v_mov_b32_e32 v171, v217
	v_mul_f32_e32 v170, v168, v170
	v_mul_f32_e32 v171, v169, v171
	s_nop 0
	v_sub_f32_e32 v211, v170, v171
	v_mov_b32_e32 v170, v176
	v_mov_b32_e32 v171, v228
	v_mul_f32_e32 v170, v162, v170
	v_mul_f32_e32 v171, v163, v171
	s_nop 0
	v_sub_f32_e32 v230, v170, v171
	v_mov_b32_e32 v170, v177
	v_mov_b32_e32 v171, v229
	v_mul_f32_e32 v170, v164, v170
	v_mul_f32_e32 v171, v165, v171
	s_nop 0
	v_sub_f32_e32 v171, v170, v171
	v_cvt_pk_bf16_f32 v170, v0, v211
	v_cvt_pk_bf16_f32 v171, v230, v171
	v_mov_b32_e32 v230, v216
	v_mul_f32_e32 v166, v166, v230
	v_mul_f32_e32 v167, v167, v231
	v_mul_f32_e32 v216, v64, v64
	v_mul_f32_e32 v217, v65, v65
	v_add_f32_e32 v0, v167, v166
	v_mul_f32_e32 v166, v168, v172
	v_mul_f32_e32 v167, v169, v173
	v_mul_f32_e32 v211, v51, v51
	v_add_f32_e32 v168, v167, v166
	v_mov_b32_e32 v166, v228
	v_mov_b32_e32 v167, v176
	v_mul_f32_e32 v162, v162, v166
	v_mul_f32_e32 v163, v163, v167
	v_mov_b32_e32 v176, v229
	v_add_f32_e32 v166, v163, v162
	v_mul_f32_e32 v162, v164, v176
	v_mul_f32_e32 v163, v165, v177
	v_cvt_pk_bf16_f32 v172, v0, v168
	v_add_co_u32_e32 v164, vcc, s75, v214
	v_add_f32_e32 v162, v163, v162
	v_cvt_pk_bf16_f32 v173, v166, v162
	v_permlane16_swap_b32_e32 v170, v172
	v_permlane16_swap_b32_e32 v171, v173
	global_store_dwordx4 v[174:175], v[170:173], off offset:64
	v_addc_co_u32_e32 v165, vcc, 0, v215, vcc
	v_lshl_add_u64 v[162:163], v[214:215], 0, s[2:3]
	global_load_dwordx4 v[174:177], v[164:165], off
	global_load_dwordx4 v[170:173], v[162:163], off offset:16
	v_mul_f32_e32 v228, v62, v62
	v_mul_f32_e32 v229, v63, v63
	v_mul_f32_e32 v0, v50, v50
	v_pk_mov_b32 v[230:231], v[228:229], v[216:217] op_sel:[1,0]
	v_mov_b32_e32 v229, v217
	v_add_f32_e32 v216, v230, v228
	v_add_f32_e32 v217, v231, v229
	v_mul_f32_e32 v228, v60, v60
	v_mul_f32_e32 v229, v61, v61
	v_mul_f32_e32 v230, v58, v58
	v_mul_f32_e32 v231, v59, v59
	v_pk_add_f32 v[216:217], v[216:217], v[216:217] op_sel:[0,1] op_sel_hi:[1,0]
	v_pk_mov_b32 v[232:233], v[230:231], v[228:229] op_sel:[1,0]
	v_mov_b32_e32 v231, v229
	v_add_f32_e32 v228, v232, v230
	v_add_f32_e32 v229, v233, v231
	v_mov_b32_e32 v217, v0
	v_pk_add_f32 v[228:229], v[228:229], v[228:229] op_sel:[0,1] op_sel_hi:[1,0]
	v_mul_f32_e32 v0, v55, v55
	v_mov_b32_e32 v229, v211
	s_mov_b64 s[2:3], 0x1800
	v_add_f32_e32 v216, v216, v228
	v_add_f32_e32 v217, v217, v229
	v_fma_f32 v228, v54, v54, v0
	v_fma_f32 v229, v55, v55, v0
	v_mul_f32_e32 v0, v57, v57
	v_lshl_add_u64 v[162:163], v[214:215], 0, s[2:3]
	v_mul_f32_e32 v215, v52, v52
	v_mul_f32_e32 v232, v53, v53
	v_fma_f32 v230, v56, v56, v0
	v_fma_f32 v231, v57, v57, v0
	v_mov_b32_e32 v229, v215
	v_mov_b32_e32 v231, v232
	v_add_f32_e32 v228, v228, v230
	v_add_f32_e32 v229, v229, v231
	v_or_b32_e32 v214, 32, v210
	v_add_f32_e32 v216, v216, v228
	v_add_f32_e32 v217, v217, v229
	v_ashrrev_i32_e32 v215, 31, v214
	v_add_f32_e32 v0, v216, v217
	ds_bpermute_b32 v211, v227, v0
	v_lshlrev_b64 v[214:215], 8, v[214:215]
	v_lshl_add_u64 v[228:229], v[212:213], 0, v[214:215]
	v_mul_f32_e32 v214, v64, v144
	v_mul_f32_e32 v215, v65, v145
	v_mul_f32_e32 v216, v62, v142
	v_mul_f32_e32 v217, v63, v143
	s_waitcnt lgkmcnt(0)
	v_add_f32_e32 v0, v0, v211
	ds_bpermute_b32 v211, v189, v0
	v_mul_f32_e32 v232, v58, v138
	v_mul_f32_e32 v233, v59, v139
	global_load_dwordx4 v[166:169], v[164:165], off offset:2048
	s_nop 0
	global_load_dwordx4 v[162:165], v[162:163], off offset:16
	s_waitcnt lgkmcnt(0)
;     __device__ __forceinline__ static v2u pk4(float a, float b, float c, float d) { v2u o; o.x = pg8::cvt_pk_bf16(a, b); o.y = pg8::cvt_pk_bf16(c, d); return o; }
;     __device__ __forceinline__ void head64(const pg8::f32x4 (&acc)[2][2][4][2], int row0, int fq, bf16r* dst, int pitch, int colbase, const float* gain, float scale, const float2* trc) const {
;     ...
;             for (int ai = 0; ai < 2; ++ai) { const int m = 2 * mh + mm; const int row = row0 + ai * 128 + m * 16;
;                 float ss = 0.f;
; #pragma unroll
;                 for (int bj = 0; bj < 2; ++bj)
; #pragma unroll
;                     for (int n = 0; n < 2; ++n) { const pg8::f32x4 v = acc[ai][bj][m][n]; ss += (v[0] * v[0] + v[1] * v[1]) + (v[2] * v[2] + v[3] * v[3]); }
;                 ss += __shfl_xor(ss, 16); ss += __shfl_xor(ss, 32);
;                 const float rstd = rsqrtf(ss * (1.f / 64.f) + EPS);
; #pragma unroll
;                 for (int bj = 0; bj < 2; ++bj) { const pg8::f32x4 cs01 = bj == 0 ? rcs[ai][0] : ccs[mm][0], cs23 = bj == 0 ? rcs[ai][1] : ccs[mm][1];
;                     const pg8::f32x4 x1 = acc[ai][bj][m][0] * g[bj][0] * (rstd * scale), x2 = acc[ai][bj][m][1] * g[bj][1] * (rstd * scale);
;                     const float c0 = cs01[0], s0 = cs01[1], c1 = cs01[2], s1 = cs01[3], c2 = cs23[0], s2 = cs23[1], c3 = cs23[2], s3 = cs23[3];
;                     store_pair16(dst + (size_t)row * pitch + colbase + 32 * bj, fq, pk4(x1[0] * c0 - x2[0] * s0, x1[1] * c1 - x2[1] * s1, x1[2] * c2 - x2[2] * s2, x1[3] * c3 - x2[3] * s3),
;                                  pk4(x2[0] * c0 + x1[0] * s0, x2[1] * c1 + x1[1] * s1, x2[2] * c2 + x1[2] * s2, x2[3] * c3 + x1[3] * s3)); } } }
	v_add_f32_e32 v0, v0, v211
	v_fmamk_f32 v0, v0, 0x3c800000, v219
	v_cmp_gt_f32_e32 vcc, s25, v0
	v_mul_f32_e32 v211, 0x4b800000, v0
	s_nop 0
	v_cndmask_b32_e32 v0, v0, v211, vcc
	v_rsq_f32_e32 v0, v0
	s_nop 0
	v_mul_f32_e32 v211, 0x45800000, v0
	v_cndmask_b32_e32 v0, v0, v211, vcc
	v_mul_f32_e32 v230, v214, v0
	v_mul_f32_e32 v231, v215, v0
	v_mul_f32_e32 v216, v216, v0
	v_mul_f32_e32 v217, v217, v0
	v_mul_f32_e32 v214, v60, v140
	v_mul_f32_e32 v215, v61, v141
	v_mul_f32_e32 v232, v232, v0
	v_mul_f32_e32 v233, v233, v0
	v_mul_f32_e32 v234, v214, v0
	v_mul_f32_e32 v235, v215, v0
	v_mov_b32_e32 v214, v216
	v_mov_b32_e32 v215, v232
	v_mul_f32_e32 v214, v158, v214
	v_mul_f32_e32 v215, v159, v215
	s_nop 0
	v_sub_f32_e32 v211, v214, v215
	v_mov_b32_e32 v214, v217
	v_mov_b32_e32 v215, v233
	v_mul_f32_e32 v214, v160, v214
	v_mul_f32_e32 v215, v161, v215
	s_nop 0
	v_sub_f32_e32 v236, v214, v215
	v_mov_b32_e32 v214, v230
	v_mov_b32_e32 v215, v234
	v_mul_f32_e32 v214, v154, v214
	v_mul_f32_e32 v215, v155, v215
	s_nop 0
	v_sub_f32_e32 v237, v214, v215
	v_mov_b32_e32 v214, v231
	v_mov_b32_e32 v215, v235
	v_mul_f32_e32 v214, v156, v214
	v_mul_f32_e32 v215, v157, v215
	s_nop 0
	v_sub_f32_e32 v215, v214, v215
	v_cvt_pk_bf16_f32 v214, v211, v236
	v_cvt_pk_bf16_f32 v215, v237, v215
	v_mov_b32_e32 v237, v216
	v_mov_b32_e32 v216, v233
	v_mul_f32_e32 v216, v160, v216
	v_mul_f32_e32 v217, v161, v217
	v_mov_b32_e32 v236, v232
	v_add_f32_e32 v232, v217, v216
	v_mov_b32_e32 v216, v234
	v_mov_b32_e32 v217, v230
	v_mul_f32_e32 v216, v154, v216
	v_mul_f32_e32 v217, v155, v217
	v_mov_b32_e32 v230, v235
	v_add_f32_e32 v233, v217, v216
	v_mul_f32_e32 v216, v156, v230
	v_mul_f32_e32 v217, v157, v231
	v_mul_f32_e32 v236, v158, v236
	v_mul_f32_e32 v237, v159, v237
	v_add_f32_e32 v217, v217, v216
	v_add_f32_e32 v211, v237, v236
	v_cvt_pk_bf16_f32 v216, v211, v232
	v_cvt_pk_bf16_f32 v217, v233, v217
	v_mul_f32_e32 v232, v50, v130
	v_mul_f32_e32 v233, v51, v131
	v_permlane16_swap_b32_e32 v214, v216
	v_permlane16_swap_b32_e32 v215, v217
	global_store_dwordx4 v[228:229], v[214:217], off
	v_mul_f32_e32 v232, v232, v0
	v_mul_f32_e32 v233, v233, v0
	s_nop 0
	v_mul_f32_e32 v214, v56, v136
	v_mul_f32_e32 v215, v57, v137
	v_mul_f32_e32 v216, v54, v134
	v_mul_f32_e32 v217, v55, v135
	v_mul_f32_e32 v230, v214, v0
	v_mul_f32_e32 v231, v215, v0
	v_mul_f32_e32 v216, v216, v0
	v_mul_f32_e32 v217, v217, v0
	v_mul_f32_e32 v214, v52, v132
	v_mul_f32_e32 v215, v53, v133
	v_mov_b32_e32 v237, v216
	v_mul_f32_e32 v234, v214, v0
	v_mul_f32_e32 v235, v215, v0
	v_mov_b32_e32 v214, v216
	v_mov_b32_e32 v215, v232
	s_waitcnt vmcnt(4)
	v_mul_f32_e32 v214, v174, v214
	v_mul_f32_e32 v215, v175, v215
	v_mov_b32_e32 v216, v233
	v_sub_f32_e32 v0, v214, v215
	v_mov_b32_e32 v214, v217
	v_mov_b32_e32 v215, v233
	v_mul_f32_e32 v214, v176, v214
	v_mul_f32_e32 v215, v177, v215
	v_mul_f32_e32 v216, v176, v216
	v_mul_f32_e32 v217, v177, v217
	v_sub_f32_e32 v211, v214, v215
	v_mov_b32_e32 v214, v230
	v_mov_b32_e32 v215, v234
	s_waitcnt vmcnt(3)
	v_mul_f32_e32 v214, v170, v214
	v_mul_f32_e32 v215, v171, v215
	s_nop 0
	v_sub_f32_e32 v236, v214, v215
	v_mov_b32_e32 v214, v231
	v_mov_b32_e32 v215, v235
	v_mul_f32_e32 v214, v172, v214
	v_mul_f32_e32 v215, v173, v215
	s_nop 0
	v_sub_f32_e32 v215, v214, v215
	v_cvt_pk_bf16_f32 v214, v0, v211
	v_add_f32_e32 v211, v217, v216
	v_mov_b32_e32 v216, v234
	v_mov_b32_e32 v217, v230
	v_mul_f32_e32 v216, v170, v216
	v_mul_f32_e32 v217, v171, v217
	v_mov_b32_e32 v230, v235
	v_cvt_pk_bf16_f32 v215, v236, v215
	v_mov_b32_e32 v236, v232
	v_add_f32_e32 v232, v217, v216
	v_mul_f32_e32 v216, v172, v230
	v_mul_f32_e32 v217, v173, v231
	v_mul_f32_e32 v236, v174, v236
	v_mul_f32_e32 v237, v175, v237
	v_add_f32_e32 v217, v217, v216
	v_add_f32_e32 v0, v237, v236
	v_cvt_pk_bf16_f32 v216, v0, v211
	v_cvt_pk_bf16_f32 v217, v232, v217
	v_mul_f32_e32 v0, v34, v34
	v_permlane16_swap_b32_e32 v214, v216
	v_permlane16_swap_b32_e32 v215, v217
	global_store_dwordx4 v[228:229], v[214:217], off offset:64
	v_mul_f32_e32 v211, v35, v35
	v_mul_f32_e32 v232, v42, v138
	v_mul_f32_e32 v233, v43, v139
	v_mul_f32_e32 v214, v48, v48
	v_mul_f32_e32 v215, v49, v49
	v_mul_f32_e32 v216, v46, v46
	v_mul_f32_e32 v217, v47, v47
	s_nop 0
	v_pk_mov_b32 v[228:229], v[216:217], v[214:215] op_sel:[1,0]
	v_mov_b32_e32 v217, v215
	v_add_f32_e32 v214, v228, v216
	v_add_f32_e32 v215, v229, v217
	v_mul_f32_e32 v216, v44, v44
	v_mul_f32_e32 v217, v45, v45
	v_mul_f32_e32 v228, v42, v42
	v_mul_f32_e32 v229, v43, v43
	v_pk_add_f32 v[214:215], v[214:215], v[214:215] op_sel:[0,1] op_sel_hi:[1,0]
	v_pk_mov_b32 v[230:231], v[228:229], v[216:217] op_sel:[1,0]
	v_mov_b32_e32 v229, v217
	v_add_f32_e32 v216, v230, v228
	v_add_f32_e32 v217, v231, v229
	v_mov_b32_e32 v215, v0
	v_pk_add_f32 v[216:217], v[216:217], v[216:217] op_sel:[0,1] op_sel_hi:[1,0]
	v_mul_f32_e32 v0, v39, v39
	v_mov_b32_e32 v217, v211
	v_mul_f32_e32 v228, v36, v36
	v_add_f32_e32 v214, v214, v216
	v_add_f32_e32 v215, v215, v217
	v_fma_f32 v216, v38, v38, v0
	v_fma_f32 v217, v39, v39, v0
	v_mul_f32_e32 v0, v41, v41
	v_mul_f32_e32 v230, v37, v37
	v_mov_b32_e32 v217, v228
	v_fma_f32 v228, v40, v40, v0
	v_fma_f32 v229, v41, v41, v0
	s_nop 0
	v_mov_b32_e32 v229, v230
	v_add_f32_e32 v216, v216, v228
	v_add_f32_e32 v217, v217, v229
	s_nop 0
	v_add_f32_e32 v214, v214, v216
	v_add_f32_e32 v215, v215, v217
	v_mul_f32_e32 v216, v46, v142
	v_mul_f32_e32 v217, v47, v143
	v_add_f32_e32 v0, v214, v215
	ds_bpermute_b32 v211, v227, v0
	v_add_u32_e32 v214, 0xa0, v210
	v_ashrrev_i32_e32 v215, 31, v214
	v_lshlrev_b64 v[214:215], 8, v[214:215]
	v_lshl_add_u64 v[228:229], v[212:213], 0, v[214:215]
	s_waitcnt lgkmcnt(0)
;     __device__ __forceinline__ static v2u pk4(float a, float b, float c, float d) { v2u o; o.x = pg8::cvt_pk_bf16(a, b); o.y = pg8::cvt_pk_bf16(c, d); return o; }
;     __device__ __forceinline__ void head64(const pg8::f32x4 (&acc)[2][2][4][2], int row0, int fq, bf16r* dst, int pitch, int colbase, const float* gain, float scale, const float2* trc) const {
;     ...
;             for (int ai = 0; ai < 2; ++ai) { const int m = 2 * mh + mm; const int row = row0 + ai * 128 + m * 16;
;                 float ss = 0.f;
; #pragma unroll
;                 for (int bj = 0; bj < 2; ++bj)
; #pragma unroll
;                     for (int n = 0; n < 2; ++n) { const pg8::f32x4 v = acc[ai][bj][m][n]; ss += (v[0] * v[0] + v[1] * v[1]) + (v[2] * v[2] + v[3] * v[3]); }
;                 ss += __shfl_xor(ss, 16); ss += __shfl_xor(ss, 32);
;                 const float rstd = rsqrtf(ss * (1.f / 64.f) + EPS);
; #pragma unroll
;                 for (int bj = 0; bj < 2; ++bj) { const pg8::f32x4 cs01 = bj == 0 ? rcs[ai][0] : ccs[mm][0], cs23 = bj == 0 ? rcs[ai][1] : ccs[mm][1];
;                     const pg8::f32x4 x1 = acc[ai][bj][m][0] * g[bj][0] * (rstd * scale), x2 = acc[ai][bj][m][1] * g[bj][1] * (rstd * scale);
;                     const float c0 = cs01[0], s0 = cs01[1], c1 = cs01[2], s1 = cs01[3], c2 = cs23[0], s2 = cs23[1], c3 = cs23[2], s3 = cs23[3];
;                     store_pair16(dst + (size_t)row * pitch + colbase + 32 * bj, fq, pk4(x1[0] * c0 - x2[0] * s0, x1[1] * c1 - x2[1] * s1, x1[2] * c2 - x2[2] * s2, x1[3] * c3 - x2[3] * s3),
;                                  pk4(x2[0] * c0 + x1[0] * s0, x2[1] * c1 + x1[1] * s1, x2[2] * c2 + x1[2] * s2, x2[3] * c3 + x1[3] * s3)); } } }
	v_add_f32_e32 v0, v0, v211
	ds_bpermute_b32 v211, v189, v0
	v_mul_f32_e32 v214, v48, v144
	v_mul_f32_e32 v215, v49, v145
	s_waitcnt lgkmcnt(0)
	v_add_f32_e32 v0, v0, v211
	v_fmamk_f32 v0, v0, 0x3c800000, v219
	v_cmp_gt_f32_e32 vcc, s25, v0
	v_mul_f32_e32 v211, 0x4b800000, v0
	s_nop 0
	v_cndmask_b32_e32 v0, v0, v211, vcc
	v_rsq_f32_e32 v0, v0
	s_nop 0
	v_mul_f32_e32 v211, 0x45800000, v0
	v_cndmask_b32_e32 v0, v0, v211, vcc
	v_mul_f32_e32 v230, v214, v0
	v_mul_f32_e32 v231, v215, v0
	v_mul_f32_e32 v216, v216, v0
	v_mul_f32_e32 v217, v217, v0
	v_mul_f32_e32 v214, v44, v140
	v_mul_f32_e32 v215, v45, v141
	v_mul_f32_e32 v232, v232, v0
	v_mul_f32_e32 v233, v233, v0
	v_mul_f32_e32 v234, v214, v0
	v_mul_f32_e32 v235, v215, v0
	v_mov_b32_e32 v214, v216
	v_mov_b32_e32 v215, v232
	v_mul_f32_e32 v214, v150, v214
	v_mul_f32_e32 v215, v151, v215
	s_nop 0
	v_sub_f32_e32 v211, v214, v215
	v_mov_b32_e32 v214, v217
	v_mov_b32_e32 v215, v233
	v_mul_f32_e32 v214, v152, v214
	v_mul_f32_e32 v215, v153, v215
	s_nop 0
	v_sub_f32_e32 v236, v214, v215
	v_mov_b32_e32 v214, v230
	v_mov_b32_e32 v215, v234
	v_mul_f32_e32 v214, v146, v214
	v_mul_f32_e32 v215, v147, v215
	s_nop 0
	v_sub_f32_e32 v237, v214, v215
	v_mov_b32_e32 v214, v231
	v_mov_b32_e32 v215, v235
	v_mul_f32_e32 v214, v148, v214
	v_mul_f32_e32 v215, v149, v215
	s_nop 0
	v_sub_f32_e32 v215, v214, v215
	v_cvt_pk_bf16_f32 v214, v211, v236
	v_cvt_pk_bf16_f32 v215, v237, v215
	v_mov_b32_e32 v237, v216
	v_mov_b32_e32 v216, v233
	v_mul_f32_e32 v216, v152, v216
	v_mul_f32_e32 v217, v153, v217
	v_mov_b32_e32 v236, v232
	v_add_f32_e32 v232, v217, v216
	v_mov_b32_e32 v216, v234
	v_mov_b32_e32 v217, v230
	v_mul_f32_e32 v216, v146, v216
	v_mul_f32_e32 v217, v147, v217
	v_mov_b32_e32 v230, v235
	v_add_f32_e32 v233, v217, v216
	v_mul_f32_e32 v216, v148, v230
	v_mul_f32_e32 v217, v149, v231
	v_mul_f32_e32 v236, v150, v236
	v_mul_f32_e32 v237, v151, v237
	v_add_f32_e32 v217, v217, v216
	v_add_f32_e32 v211, v237, v236
	v_cvt_pk_bf16_f32 v216, v211, v232
	v_cvt_pk_bf16_f32 v217, v233, v217
	v_mul_f32_e32 v232, v34, v130
	v_mul_f32_e32 v233, v35, v131
	v_permlane16_swap_b32_e32 v214, v216
	v_permlane16_swap_b32_e32 v215, v217
	global_store_dwordx4 v[228:229], v[214:217], off
	v_mul_f32_e32 v232, v232, v0
	v_mul_f32_e32 v233, v233, v0
	s_nop 0
	v_mul_f32_e32 v214, v40, v136
	v_mul_f32_e32 v215, v41, v137
	v_mul_f32_e32 v216, v38, v134
	v_mul_f32_e32 v217, v39, v135
	v_mul_f32_e32 v230, v214, v0
	v_mul_f32_e32 v231, v215, v0
	v_mul_f32_e32 v216, v216, v0
	v_mul_f32_e32 v217, v217, v0
	v_mul_f32_e32 v214, v36, v132
	v_mul_f32_e32 v215, v37, v133
	v_mov_b32_e32 v237, v216
	v_mul_f32_e32 v234, v214, v0
	v_mul_f32_e32 v235, v215, v0
	v_mov_b32_e32 v214, v216
	v_mov_b32_e32 v215, v232
	v_mul_f32_e32 v214, v174, v214
	v_mul_f32_e32 v215, v175, v215
	v_mov_b32_e32 v216, v233
	v_sub_f32_e32 v0, v214, v215
	v_mov_b32_e32 v214, v217
	v_mov_b32_e32 v215, v233
	v_mul_f32_e32 v214, v176, v214
	v_mul_f32_e32 v215, v177, v215
	s_nop 0
	v_sub_f32_e32 v211, v214, v215
	v_mov_b32_e32 v214, v230
	v_mov_b32_e32 v215, v234
	v_mul_f32_e32 v214, v170, v214
	v_mul_f32_e32 v215, v171, v215
	s_nop 0
	v_sub_f32_e32 v236, v214, v215
	v_mov_b32_e32 v214, v231
	v_mov_b32_e32 v215, v235
	v_mul_f32_e32 v214, v172, v214
	v_mul_f32_e32 v215, v173, v215
	s_nop 0
	v_sub_f32_e32 v215, v214, v215
	v_cvt_pk_bf16_f32 v214, v0, v211
	v_cvt_pk_bf16_f32 v215, v236, v215
	v_mov_b32_e32 v236, v232
	v_mul_f32_e32 v174, v174, v236
	v_mul_f32_e32 v175, v175, v237
	v_mul_f32_e32 v211, v21, v21
	v_add_f32_e32 v0, v175, v174
	v_mul_f32_e32 v174, v176, v216
	v_mul_f32_e32 v175, v177, v217
	s_nop 0
	v_add_f32_e32 v176, v175, v174
	v_mov_b32_e32 v174, v234
	v_mov_b32_e32 v175, v230
	v_mul_f32_e32 v170, v170, v174
	v_mul_f32_e32 v171, v171, v175
	v_mov_b32_e32 v230, v235
	v_add_f32_e32 v174, v171, v170
	v_mul_f32_e32 v170, v172, v230
	v_mul_f32_e32 v171, v173, v231
	v_cvt_pk_bf16_f32 v216, v0, v176
	v_mul_f32_e32 v172, v32, v32
	v_mul_f32_e32 v173, v33, v33
	v_add_f32_e32 v170, v171, v170
	v_cvt_pk_bf16_f32 v217, v174, v170
	v_mul_f32_e32 v174, v30, v30
	v_mul_f32_e32 v175, v31, v31
	v_permlane16_swap_b32_e32 v214, v216
	v_pk_mov_b32 v[176:177], v[174:175], v[172:173] op_sel:[1,0]
	v_mov_b32_e32 v175, v173
	v_permlane16_swap_b32_e32 v215, v217
	v_add_f32_e32 v172, v176, v174
	v_add_f32_e32 v173, v177, v175
	v_mul_f32_e32 v174, v28, v28
	v_mul_f32_e32 v175, v29, v29
	v_mul_f32_e32 v176, v26, v26
	v_mul_f32_e32 v177, v27, v27
	global_store_dwordx4 v[228:229], v[214:217], off offset:64
	v_mul_f32_e32 v0, v18, v18
	v_mul_f32_e32 v171, v19, v19
	v_pk_mov_b32 v[214:215], v[176:177], v[174:175] op_sel:[1,0]
	v_mov_b32_e32 v177, v175
	v_add_f32_e32 v174, v214, v176
	v_add_f32_e32 v175, v215, v177
	v_pk_add_f32 v[172:173], v[172:173], v[172:173] op_sel:[0,1] op_sel_hi:[1,0]
	v_pk_add_f32 v[174:175], v[174:175], v[174:175] op_sel:[0,1] op_sel_hi:[1,0]
	v_mov_b32_e32 v173, v0
	v_mov_b32_e32 v175, v171
	v_mul_f32_e32 v0, v23, v23
	v_mul_f32_e32 v176, v20, v20
	v_add_f32_e32 v172, v172, v174
	v_add_f32_e32 v173, v173, v175
	v_fma_f32 v174, v22, v22, v0
	v_fma_f32 v175, v23, v23, v0
	v_mul_f32_e32 v0, v25, v25
	v_mov_b32_e32 v175, v176
	v_fma_f32 v176, v24, v24, v0
	v_fma_f32 v177, v25, v25, v0
	v_or_b32_e32 v170, 48, v210
	v_mov_b32_e32 v177, v211
	v_add_f32_e32 v174, v174, v176
	v_add_f32_e32 v175, v175, v177
	v_mul_f32_e32 v214, v26, v138
	v_mul_f32_e32 v215, v27, v139
	v_add_f32_e32 v172, v172, v174
	v_add_f32_e32 v173, v173, v175
	v_mul_f32_e32 v138, v10, v138
	v_mul_f32_e32 v139, v11, v139
	v_add_f32_e32 v0, v172, v173
	ds_bpermute_b32 v171, v227, v0
	v_mul_f32_e32 v172, v30, v142
	v_mul_f32_e32 v173, v31, v143
	v_mul_f32_e32 v142, v14, v142
	v_mul_f32_e32 v143, v15, v143
	s_waitcnt lgkmcnt(0)
;     __device__ __forceinline__ static v2u pk4(float a, float b, float c, float d) { v2u o; o.x = pg8::cvt_pk_bf16(a, b); o.y = pg8::cvt_pk_bf16(c, d); return o; }
;     __device__ __forceinline__ void head64(const pg8::f32x4 (&acc)[2][2][4][2], int row0, int fq, bf16r* dst, int pitch, int colbase, const float* gain, float scale, const float2* trc) const {
;     ...
;             for (int ai = 0; ai < 2; ++ai) { const int m = 2 * mh + mm; const int row = row0 + ai * 128 + m * 16;
;                 float ss = 0.f;
; #pragma unroll
;                 for (int bj = 0; bj < 2; ++bj)
; #pragma unroll
;                     for (int n = 0; n < 2; ++n) { const pg8::f32x4 v = acc[ai][bj][m][n]; ss += (v[0] * v[0] + v[1] * v[1]) + (v[2] * v[2] + v[3] * v[3]); }
;                 ss += __shfl_xor(ss, 16); ss += __shfl_xor(ss, 32);
;                 const float rstd = rsqrtf(ss * (1.f / 64.f) + EPS);
; #pragma unroll
;                 for (int bj = 0; bj < 2; ++bj) { const pg8::f32x4 cs01 = bj == 0 ? rcs[ai][0] : ccs[mm][0], cs23 = bj == 0 ? rcs[ai][1] : ccs[mm][1];
;                     const pg8::f32x4 x1 = acc[ai][bj][m][0] * g[bj][0] * (rstd * scale), x2 = acc[ai][bj][m][1] * g[bj][1] * (rstd * scale);
;                     const float c0 = cs01[0], s0 = cs01[1], c1 = cs01[2], s1 = cs01[3], c2 = cs23[0], s2 = cs23[1], c3 = cs23[2], s3 = cs23[3];
;                     store_pair16(dst + (size_t)row * pitch + colbase + 32 * bj, fq, pk4(x1[0] * c0 - x2[0] * s0, x1[1] * c1 - x2[1] * s1, x1[2] * c2 - x2[2] * s2, x1[3] * c3 - x2[3] * s3),
;                                  pk4(x2[0] * c0 + x1[0] * s0, x2[1] * c1 + x1[1] * s1, x2[2] * c2 + x1[2] * s2, x2[3] * c3 + x1[3] * s3)); } } }
	v_add_f32_e32 v0, v0, v171
	ds_bpermute_b32 v171, v189, v0
	s_waitcnt lgkmcnt(0)
	v_add_f32_e32 v0, v0, v171
	v_fmamk_f32 v0, v0, 0x3c800000, v219
	v_cmp_gt_f32_e32 vcc, s25, v0
	v_mul_f32_e32 v171, 0x4b800000, v0
	s_nop 0
	v_cndmask_b32_e32 v0, v0, v171, vcc
	v_rsq_f32_e32 v0, v0
	s_nop 0
	v_mul_f32_e32 v171, 0x45800000, v0
	v_cndmask_b32_e32 v0, v0, v171, vcc
	v_ashrrev_i32_e32 v171, 31, v170
	v_lshlrev_b64 v[170:171], 8, v[170:171]
	v_lshl_add_u64 v[174:175], v[212:213], 0, v[170:171]
	v_mul_f32_e32 v170, v32, v144
	v_mul_f32_e32 v171, v33, v145
	v_mul_f32_e32 v172, v172, v0
	v_mul_f32_e32 v173, v173, v0
	v_mul_f32_e32 v176, v170, v0
	v_mul_f32_e32 v177, v171, v0
	v_mul_f32_e32 v170, v28, v140
	v_mul_f32_e32 v171, v29, v141
	v_mul_f32_e32 v214, v214, v0
	v_mul_f32_e32 v215, v215, v0
	v_mul_f32_e32 v216, v170, v0
	v_mul_f32_e32 v217, v171, v0
	v_mov_b32_e32 v170, v172
	v_mov_b32_e32 v171, v214
	v_mul_f32_e32 v170, v158, v170
	v_mul_f32_e32 v171, v159, v171
	v_mul_f32_e32 v144, v16, v144
	v_mul_f32_e32 v145, v17, v145
	v_sub_f32_e32 v211, v170, v171
	v_mov_b32_e32 v170, v173
	v_mov_b32_e32 v171, v215
	v_mul_f32_e32 v170, v160, v170
	v_mul_f32_e32 v171, v161, v171
	v_mul_f32_e32 v140, v12, v140
	v_mul_f32_e32 v141, v13, v141
	v_sub_f32_e32 v228, v170, v171
	v_mov_b32_e32 v170, v176
	v_mov_b32_e32 v171, v216
	v_mul_f32_e32 v170, v154, v170
	v_mul_f32_e32 v171, v155, v171
	s_nop 0
	v_sub_f32_e32 v229, v170, v171
	v_mov_b32_e32 v170, v177
	v_mov_b32_e32 v171, v217
	v_mul_f32_e32 v170, v156, v170
	v_mul_f32_e32 v171, v157, v171
	s_nop 0
	v_sub_f32_e32 v171, v170, v171
	v_cvt_pk_bf16_f32 v170, v211, v228
	v_cvt_pk_bf16_f32 v171, v229, v171
	v_mov_b32_e32 v228, v214
	v_mov_b32_e32 v229, v172
	v_mul_f32_e32 v158, v158, v228
	v_mul_f32_e32 v159, v159, v229
	v_mov_b32_e32 v172, v215
	v_add_f32_e32 v211, v159, v158
	v_mul_f32_e32 v158, v160, v172
	v_mul_f32_e32 v159, v161, v173
	s_nop 0
	v_add_f32_e32 v160, v159, v158
	v_mov_b32_e32 v158, v216
	v_mov_b32_e32 v159, v176
	v_mul_f32_e32 v154, v154, v158
	v_mul_f32_e32 v155, v155, v159
	v_mov_b32_e32 v176, v217
	v_add_f32_e32 v158, v155, v154
	v_mul_f32_e32 v154, v156, v176
	v_mul_f32_e32 v155, v157, v177
	v_cvt_pk_bf16_f32 v172, v211, v160
	v_mul_f32_e32 v156, v22, v134
	v_mul_f32_e32 v157, v23, v135
	v_add_f32_e32 v154, v155, v154
	v_cvt_pk_bf16_f32 v173, v158, v154
	v_mul_f32_e32 v154, v24, v136
	v_mul_f32_e32 v155, v25, v137
	v_mul_f32_e32 v160, v18, v130
	v_mul_f32_e32 v161, v19, v131
	v_permlane16_swap_b32_e32 v170, v172
	v_permlane16_swap_b32_e32 v171, v173
	v_mul_f32_e32 v158, v154, v0
	v_mul_f32_e32 v159, v155, v0
	v_mul_f32_e32 v156, v156, v0
	v_mul_f32_e32 v157, v157, v0
	v_mul_f32_e32 v154, v20, v132
	v_mul_f32_e32 v155, v21, v133
	v_mul_f32_e32 v160, v160, v0
	v_mul_f32_e32 v161, v161, v0
	global_store_dwordx4 v[174:175], v[170:173], off
	v_mul_f32_e32 v134, v6, v134
	v_mul_f32_e32 v135, v7, v135
	v_mul_f32_e32 v130, v2, v130
	v_mul_f32_e32 v131, v3, v131
	v_mul_f32_e32 v170, v154, v0
	v_mul_f32_e32 v171, v155, v0
	v_mov_b32_e32 v154, v156
	v_mov_b32_e32 v155, v160
	s_waitcnt vmcnt(6)
	v_mul_f32_e32 v154, v166, v154
	v_mul_f32_e32 v155, v167, v155
	v_mul_f32_e32 v136, v8, v136
	v_mul_f32_e32 v137, v9, v137
	v_sub_f32_e32 v0, v154, v155
	v_mov_b32_e32 v154, v157
	v_mov_b32_e32 v155, v161
	v_mul_f32_e32 v154, v168, v154
	v_mul_f32_e32 v155, v169, v155
	v_mul_f32_e32 v132, v4, v132
	v_mul_f32_e32 v133, v5, v133
	v_sub_f32_e32 v172, v154, v155
	v_mov_b32_e32 v154, v158
	v_mov_b32_e32 v155, v170
	s_waitcnt vmcnt(5)
	v_mul_f32_e32 v154, v162, v154
	v_mul_f32_e32 v155, v163, v155
	s_nop 0
	v_sub_f32_e32 v173, v154, v155
	v_mov_b32_e32 v154, v159
	v_mov_b32_e32 v155, v171
	v_mul_f32_e32 v154, v164, v154
	v_mul_f32_e32 v155, v165, v155
	s_nop 0
	v_sub_f32_e32 v155, v154, v155
	v_cvt_pk_bf16_f32 v154, v0, v172
	v_cvt_pk_bf16_f32 v155, v173, v155
	v_mov_b32_e32 v173, v156
	v_mov_b32_e32 v156, v161
	v_mul_f32_e32 v156, v168, v156
	v_mul_f32_e32 v157, v169, v157
	v_mov_b32_e32 v172, v160
	v_add_f32_e32 v160, v157, v156
	v_mov_b32_e32 v156, v170
	v_mov_b32_e32 v157, v158
	v_mul_f32_e32 v156, v162, v156
	v_mul_f32_e32 v157, v163, v157
	v_mov_b32_e32 v158, v171
	v_add_f32_e32 v161, v157, v156
	v_mul_f32_e32 v156, v164, v158
	v_mul_f32_e32 v157, v165, v159
	v_mul_f32_e32 v172, v166, v172
	v_mul_f32_e32 v173, v167, v173
	v_add_f32_e32 v157, v157, v156
	v_add_f32_e32 v0, v173, v172
	v_cvt_pk_bf16_f32 v156, v0, v160
	v_cvt_pk_bf16_f32 v157, v161, v157
	v_mul_f32_e32 v0, v2, v2
	v_permlane16_swap_b32_e32 v154, v156
	v_permlane16_swap_b32_e32 v155, v157
	global_store_dwordx4 v[174:175], v[154:157], off offset:64
	s_nop 1
	v_mul_f32_e32 v154, v16, v16
	v_mul_f32_e32 v155, v17, v17
	v_mul_f32_e32 v156, v14, v14
	v_mul_f32_e32 v157, v15, v15
	s_nop 0
	v_pk_mov_b32 v[158:159], v[156:157], v[154:155] op_sel:[1,0]
	v_mov_b32_e32 v157, v155
	v_add_f32_e32 v154, v158, v156
	v_add_f32_e32 v155, v159, v157
	v_mul_f32_e32 v156, v12, v12
	v_mul_f32_e32 v157, v13, v13
	v_mul_f32_e32 v158, v10, v10
	v_mul_f32_e32 v159, v11, v11
	v_pk_add_f32 v[154:155], v[154:155], v[154:155] op_sel:[0,1] op_sel_hi:[1,0]
	v_pk_mov_b32 v[160:161], v[158:159], v[156:157] op_sel:[1,0]
	v_mov_b32_e32 v159, v157
	v_add_f32_e32 v156, v160, v158
	v_add_f32_e32 v157, v161, v159
	v_mul_f32_e32 v158, v3, v3
	v_pk_add_f32 v[156:157], v[156:157], v[156:157] op_sel:[0,1] op_sel_hi:[1,0]
	v_mov_b32_e32 v155, v0
	v_mov_b32_e32 v157, v158
	v_mul_f32_e32 v0, v7, v7
	v_mul_f32_e32 v159, v4, v4
	v_add_f32_e32 v154, v154, v156
	v_add_f32_e32 v155, v155, v157
	v_fma_f32 v156, v6, v6, v0
	v_fma_f32 v157, v7, v7, v0
	v_mul_f32_e32 v0, v9, v9
	v_mul_f32_e32 v160, v5, v5
	v_mov_b32_e32 v157, v159
	v_fma_f32 v158, v8, v8, v0
	v_fma_f32 v159, v9, v9, v0
	s_nop 0
	v_mov_b32_e32 v159, v160
	v_add_f32_e32 v156, v156, v158
	v_add_f32_e32 v157, v157, v159
	s_nop 0
	v_add_f32_e32 v154, v154, v156
	v_add_f32_e32 v155, v155, v157
	s_nop 0
	v_add_f32_e32 v0, v154, v155
	ds_bpermute_b32 v155, v227, v0
	v_add_u32_e32 v154, 0xb0, v210
	s_waitcnt lgkmcnt(0)
;     __device__ __forceinline__ void head64(const pg8::f32x4 (&acc)[2][2][4][2], int row0, int fq, bf16r* dst, int pitch, int colbase, const float* gain, float scale, const float2* trc) const {
;         pg8::f32x4 g[2][2], rcs[2][2];
; #pragma unroll
;         for (int bj = 0; bj < 2; ++bj) { g[bj][0] = *(const pg8::f32x4*)(gain + 32 * bj + 4 * fq); g[bj][1] = *(const pg8::f32x4*)(gain + 32 * bj + 16 + 4 * fq); }
; #pragma unroll
;         for (int ai = 0; ai < 2; ++ai) { const float2* tab = trc + (((row0 + ai * 128) & (SEQ - 1)) >> 6) * 16 + 4 * fq; rcs[ai][0] = *(const pg8::f32x4*)tab; rcs[ai][1] = *(const pg8::f32x4*)(tab + 2); }
; #pragma unroll
;         for (int mh = 0; mh < 2; ++mh) {
;             pg8::f32x4 ccs[2][2];
; #pragma unroll
;             for (int mm = 0; mm < 2; ++mm) { const float2* tab = trc + ((row0 + (2 * mh + mm) * 16) & 63) * 16 + 4 * fq; ccs[mm][0] = *(const pg8::f32x4*)tab; ccs[mm][1] = *(const pg8::f32x4*)(tab + 2); }
;             asm volatile("" ::: "memory");
; #pragma unroll
;         for (int mm = 0; mm < 2; ++mm)
; #pragma unroll
;             for (int ai = 0; ai < 2; ++ai) { const int m = 2 * mh + mm; const int row = row0 + ai * 128 + m * 16;
;                 float ss = 0.f;
; #pragma unroll
;                 for (int bj = 0; bj < 2; ++bj)
; #pragma unroll
;                     for (int n = 0; n < 2; ++n) { const pg8::f32x4 v = acc[ai][bj][m][n]; ss += (v[0] * v[0] + v[1] * v[1]) + (v[2] * v[2] + v[3] * v[3]); }
;                 ss += __shfl_xor(ss, 16); ss += __shfl_xor(ss, 32);
;     ...
;                 for (int bj = 0; bj < 2; ++bj) { const pg8::f32x4 cs01 = bj == 0 ? rcs[ai][0] : ccs[mm][0], cs23 = bj == 0 ? rcs[ai][1] : ccs[mm][1];
;                     const pg8::f32x4 x1 = acc[ai][bj][m][0] * g[bj][0] * (rstd * scale), x2 = acc[ai][bj][m][1] * g[bj][1] * (rstd * scale);
;                     const float c0 = cs01[0], s0 = cs01[1], c1 = cs01[2], s1 = cs01[3], c2 = cs23[0], s2 = cs23[1], c3 = cs23[2], s3 = cs23[3];
;                     store_pair16(dst + (size_t)row * pitch + colbase + 32 * bj, fq, pk4(x1[0] * c0 - x2[0] * s0, x1[1] * c1 - x2[1] * s1, x1[2] * c2 - x2[2] * s2, x1[3] * c3 - x2[3] * s3),
;                                  pk4(x2[0] * c0 + x1[0] * s0, x2[1] * c1 + x1[1] * s1, x2[2] * c2 + x1[2] * s2, x2[3] * c3 + x1[3] * s3)); } } }
	v_add_f32_e32 v0, v0, v155
	ds_bpermute_b32 v155, v189, v0
	s_waitcnt lgkmcnt(0)
	v_add_f32_e32 v0, v0, v155
	v_fmamk_f32 v0, v0, 0x3c800000, v219
	v_cmp_gt_f32_e32 vcc, s25, v0
	v_mul_f32_e32 v155, 0x4b800000, v0
	s_nop 0
	v_cndmask_b32_e32 v0, v0, v155, vcc
	v_rsq_f32_e32 v0, v0
	s_nop 0
	v_mul_f32_e32 v155, 0x45800000, v0
	v_cndmask_b32_e32 v0, v0, v155, vcc
	v_mul_f32_e32 v142, v142, v0
	v_mul_f32_e32 v143, v143, v0
	v_mul_f32_e32 v156, v138, v0
	v_mul_f32_e32 v157, v139, v0
	v_mov_b32_e32 v138, v142
	v_mov_b32_e32 v139, v156
	v_mul_f32_e32 v138, v150, v138
	v_mul_f32_e32 v139, v151, v139
	v_mul_f32_e32 v144, v144, v0
	v_mul_f32_e32 v145, v145, v0
	v_sub_f32_e32 v158, v138, v139
	v_mov_b32_e32 v138, v143
	v_mov_b32_e32 v139, v157
	v_mul_f32_e32 v140, v140, v0
	v_mul_f32_e32 v141, v141, v0
	v_mul_f32_e32 v138, v152, v138
	v_mul_f32_e32 v139, v153, v139
	v_ashrrev_i32_e32 v155, 31, v154
	v_sub_f32_e32 v159, v138, v139
	v_mov_b32_e32 v138, v144
	v_mov_b32_e32 v139, v140
	v_mul_f32_e32 v138, v146, v138
	v_mul_f32_e32 v139, v147, v139
	v_lshlrev_b64 v[154:155], 8, v[154:155]
	v_sub_f32_e32 v160, v138, v139
	v_mov_b32_e32 v138, v145
	v_mov_b32_e32 v139, v141
	v_mul_f32_e32 v138, v148, v138
	v_mul_f32_e32 v139, v149, v139
	v_lshl_add_u64 v[154:155], v[212:213], 0, v[154:155]
	v_sub_f32_e32 v139, v138, v139
	v_cvt_pk_bf16_f32 v138, v158, v159
	v_mov_b32_e32 v158, v156
	v_mov_b32_e32 v159, v142
	v_mov_b32_e32 v142, v157
	v_mul_f32_e32 v150, v150, v158
	v_mul_f32_e32 v151, v151, v159
	v_mul_f32_e32 v142, v152, v142
	v_mul_f32_e32 v143, v153, v143
	v_add_f32_e32 v150, v151, v150
	v_add_f32_e32 v151, v143, v142
	v_mov_b32_e32 v143, v144
	v_mov_b32_e32 v144, v141
	v_mov_b32_e32 v142, v140
	v_mul_f32_e32 v140, v148, v144
	v_mul_f32_e32 v141, v149, v145
	v_mul_f32_e32 v142, v146, v142
	v_mul_f32_e32 v143, v147, v143
	v_add_f32_e32 v141, v141, v140
	v_cvt_pk_bf16_f32 v139, v160, v139
	v_add_f32_e32 v142, v143, v142
	v_cvt_pk_bf16_f32 v140, v150, v151
	v_cvt_pk_bf16_f32 v141, v142, v141
	v_mul_f32_e32 v134, v134, v0
	v_mul_f32_e32 v135, v135, v0
	v_permlane16_swap_b32_e32 v138, v140
	v_permlane16_swap_b32_e32 v139, v141
	global_store_dwordx4 v[154:155], v[138:141], off
	v_mul_f32_e32 v136, v136, v0
	v_mul_f32_e32 v137, v137, v0
	v_mul_f32_e32 v132, v132, v0
	v_mul_f32_e32 v133, v133, v0
	v_mul_f32_e32 v138, v130, v0
	v_mul_f32_e32 v139, v131, v0
	v_mov_b32_e32 v130, v134
	v_mov_b32_e32 v131, v138
	v_mul_f32_e32 v130, v166, v130
	v_mul_f32_e32 v131, v167, v131
	s_nop 0
	v_sub_f32_e32 v0, v130, v131
	v_mov_b32_e32 v130, v135
	v_mov_b32_e32 v131, v139
	v_mul_f32_e32 v130, v168, v130
	v_mul_f32_e32 v131, v169, v131
	s_nop 0
	v_sub_f32_e32 v140, v130, v131
	v_mov_b32_e32 v130, v136
	v_mov_b32_e32 v131, v132
	v_mul_f32_e32 v130, v162, v130
	v_mul_f32_e32 v131, v163, v131
	s_nop 0
	v_sub_f32_e32 v141, v130, v131
	v_mov_b32_e32 v130, v137
	v_mov_b32_e32 v131, v133
	v_mul_f32_e32 v130, v164, v130
	v_mul_f32_e32 v131, v165, v131
	s_nop 0
	v_sub_f32_e32 v131, v130, v131
	v_cvt_pk_bf16_f32 v130, v0, v140
	v_cvt_pk_bf16_f32 v131, v141, v131
	v_mov_b32_e32 v141, v134
	v_mov_b32_e32 v134, v139
	v_mul_f32_e32 v134, v168, v134
	v_mul_f32_e32 v135, v169, v135
	v_mov_b32_e32 v140, v138
	v_add_f32_e32 v138, v135, v134
	v_mov_b32_e32 v135, v136
	v_mov_b32_e32 v136, v133
	v_mov_b32_e32 v134, v132
	v_mul_f32_e32 v132, v164, v136
	v_mul_f32_e32 v133, v165, v137
	v_mul_f32_e32 v140, v166, v140
	v_mul_f32_e32 v141, v167, v141
	v_mul_f32_e32 v134, v162, v134
	v_mul_f32_e32 v135, v163, v135
	v_add_f32_e32 v133, v133, v132
	v_add_f32_e32 v0, v141, v140
	v_add_f32_e32 v134, v135, v134
	v_cvt_pk_bf16_f32 v132, v0, v138
	v_cvt_pk_bf16_f32 v133, v134, v133
	s_nop 0
	v_permlane16_swap_b32_e32 v130, v132
	v_permlane16_swap_b32_e32 v131, v133
	global_store_dwordx4 v[154:155], v[130:133], off offset:64
.LBB0_270:
	s_andn2_b64 vcc, exec, s[66:67]
	s_cbranch_vccnz .LBB0_273
	s_load_dwordx2 s[2:3], s[64:65], 0x38
	s_lshl_b64 s[14:15], s[16:17], 2
	v_lshlrev_b32_e32 v0, 2, v184
	v_add_u32_e32 v216, 0x80, v210
	s_waitcnt lgkmcnt(0)
	s_add_u32 s2, s2, s14
	s_addc_u32 s3, s3, s15
	global_load_dwordx4 v[142:145], v0, s[2:3]
	global_load_dwordx4 v[138:141], v0, s[2:3] offset:64
	global_load_dwordx4 v[134:137], v0, s[2:3] offset:128
	global_load_dwordx4 v[130:133], v0, s[2:3] offset:192
	v_readlane_b32 s2, v246, 7
	v_lshlrev_b32_e32 v0, 3, v184
	v_readlane_b32 s3, v246, 8
	s_lshl_b32 s1, s1, 1
	s_and_b32 s20, s1, 0x1f80
	v_lshl_add_u64 v[146:147], s[2:3], 0, v[0:1]
	v_lshlrev_b32_e32 v0, 1, v216
	s_lshl_b32 s1, s91, 1
	v_and_b32_e32 v0, 0x1f80, v0
	s_add_u32 s2, s62, s1
	v_lshl_add_u64 v[148:149], v[146:147], 0, s[20:21]
	v_lshl_add_u64 v[150:151], v[146:147], 0, v[0:1]
	s_addc_u32 s3, s63, 0
	v_lshlrev_b32_e32 v0, 1, v186
	global_load_dwordx4 v[154:157], v[148:149], off offset:16
	global_load_dwordx4 v[158:161], v[148:149], off
	v_lshl_add_u64 v[162:163], s[2:3], 0, v[0:1]
	v_lshlrev_b32_e32 v0, 3, v188
	v_lshl_add_u64 v[214:215], v[146:147], 0, v[0:1]
	v_and_b32_e32 v146, 64, v225
	v_add_u32_e32 v166, 64, v146
	v_mul_f32_e32 v146, v128, v128
	v_mul_f32_e32 v147, v129, v129
	v_mul_f32_e32 v148, v126, v126
	v_mul_f32_e32 v149, v127, v127
	v_xor_b32_e32 v0, 16, v225
	v_pk_mov_b32 v[152:153], v[148:149], v[146:147] op_sel:[1,0]
	v_mov_b32_e32 v149, v147
	v_add_f32_e32 v146, v152, v148
	v_add_f32_e32 v147, v153, v149
	v_mul_f32_e32 v148, v124, v124
	v_mul_f32_e32 v149, v125, v125
	v_mul_f32_e32 v152, v122, v122
	v_mul_f32_e32 v153, v123, v123
	v_pk_add_f32 v[146:147], v[146:147], v[146:147] op_sel:[0,1] op_sel_hi:[1,0]
	v_pk_mov_b32 v[164:165], v[152:153], v[148:149] op_sel:[1,0]
	v_mov_b32_e32 v153, v149
	v_add_f32_e32 v148, v164, v152
	v_add_f32_e32 v149, v165, v153
	v_mul_f32_e32 v152, v114, v114
	v_mul_f32_e32 v153, v115, v115
	v_pk_add_f32 v[148:149], v[148:149], v[148:149] op_sel:[0,1] op_sel_hi:[1,0]
	v_mov_b32_e32 v147, v152
	v_mov_b32_e32 v149, v153
	v_add_f32_e32 v146, v146, v148
	v_add_f32_e32 v147, v147, v149
	v_mul_f32_e32 v148, v119, v119
	v_mul_f32_e32 v152, v121, v121
	v_mul_f32_e32 v164, v116, v116
	v_mul_f32_e32 v165, v117, v117
	v_fma_f32 v149, v119, v119, v148
	v_fma_f32 v148, v118, v118, v148
	v_fma_f32 v153, v121, v121, v152
	v_fma_f32 v152, v120, v120, v152
	v_mov_b32_e32 v149, v164
	v_mov_b32_e32 v153, v165
	v_cmp_lt_i32_e32 vcc, v0, v166
	v_add_f32_e32 v148, v148, v152
	v_add_f32_e32 v149, v149, v153
	global_load_dwordx4 v[174:177], v[214:215], off
	v_cndmask_b32_e32 v0, v225, v0, vcc
	v_add_f32_e32 v146, v146, v148
	v_add_f32_e32 v147, v147, v149
	v_lshlrev_b32_e32 v0, 2, v0
	v_add_f32_e32 v146, v146, v147
	ds_bpermute_b32 v147, v0, v146
	v_xor_b32_e32 v148, 32, v225
	v_cmp_lt_i32_e32 vcc, v148, v166
	s_mov_b64 s[2:3], 0x15000000
	v_lshl_add_u64 v[212:213], v[162:163], 0, s[2:3]
	v_cndmask_b32_e32 v148, v225, v148, vcc
	v_lshlrev_b32_e32 v189, 2, v148
	s_waitcnt lgkmcnt(0)
;     __device__ __forceinline__ static v2u pk4(float a, float b, float c, float d) { v2u o; o.x = pg8::cvt_pk_bf16(a, b); o.y = pg8::cvt_pk_bf16(c, d); return o; }
;     __device__ __forceinline__ void head64(const pg8::f32x4 (&acc)[2][2][4][2], int row0, int fq, bf16r* dst, int pitch, int colbase, const float* gain, float scale, const float2* trc) const {
;     ...
;             for (int ai = 0; ai < 2; ++ai) { const int m = 2 * mh + mm; const int row = row0 + ai * 128 + m * 16;
;                 float ss = 0.f;
; #pragma unroll
;                 for (int bj = 0; bj < 2; ++bj)
; #pragma unroll
;                     for (int n = 0; n < 2; ++n) { const pg8::f32x4 v = acc[ai][bj][m][n]; ss += (v[0] * v[0] + v[1] * v[1]) + (v[2] * v[2] + v[3] * v[3]); }
;                 ss += __shfl_xor(ss, 16); ss += __shfl_xor(ss, 32);
;                 const float rstd = rsqrtf(ss * (1.f / 64.f) + EPS);
; #pragma unroll
;                 for (int bj = 0; bj < 2; ++bj) { const pg8::f32x4 cs01 = bj == 0 ? rcs[ai][0] : ccs[mm][0], cs23 = bj == 0 ? rcs[ai][1] : ccs[mm][1];
;                     const pg8::f32x4 x1 = acc[ai][bj][m][0] * g[bj][0] * (rstd * scale), x2 = acc[ai][bj][m][1] * g[bj][1] * (rstd * scale);
;                     const float c0 = cs01[0], s0 = cs01[1], c1 = cs01[2], s1 = cs01[3], c2 = cs23[0], s2 = cs23[1], c3 = cs23[2], s3 = cs23[3];
;                     store_pair16(dst + (size_t)row * pitch + colbase + 32 * bj, fq, pk4(x1[0] * c0 - x2[0] * s0, x1[1] * c1 - x2[1] * s1, x1[2] * c2 - x2[2] * s2, x1[3] * c3 - x2[3] * s3),
;                                  pk4(x2[0] * c0 + x1[0] * s0, x2[1] * c1 + x1[1] * s1, x2[2] * c2 + x1[2] * s2, x2[3] * c3 + x1[3] * s3)); } } }
	v_add_f32_e32 v164, v146, v147
	global_load_dwordx4 v[170:173], v[214:215], off offset:16
	global_load_dwordx4 v[146:149], v[150:151], off offset:16
	s_nop 0
	global_load_dwordx4 v[150:153], v[150:151], off
	ds_bpermute_b32 v165, v189, v164
	s_mov_b64 s[2:3], 0x1000
	s_waitcnt lgkmcnt(0)
	v_add_f32_e32 v162, v164, v165
	v_fmamk_f32 v162, v162, 0x3c800000, v219
	v_mul_f32_e32 v163, 0x4b800000, v162
	v_cmp_gt_f32_e32 vcc, s25, v162
	s_waitcnt vmcnt(0)
	v_mul_f32_e32 v126, v126, v142
	v_mul_f32_e32 v127, v127, v143
	v_cndmask_b32_e32 v162, v162, v163, vcc
	v_rsq_f32_e32 v211, v162
	v_mul_f32_e32 v122, v122, v138
	v_mul_f32_e32 v123, v123, v139
	v_mul_f32_e32 v128, v128, v144
	v_mul_f32_e32 v129, v129, v145
	v_mul_f32_e32 v124, v124, v140
	v_mul_f32_e32 v125, v125, v141
	v_mul_f32_e32 v217, 0x45800000, v211
	v_cndmask_b32_e32 v211, v211, v217, vcc
	v_mul_f32_e32 v228, 0x3e38aa3b, v211
	v_mul_f32_e32 v126, v126, v228
	v_mul_f32_e32 v127, v127, v228
	v_mul_f32_e32 v232, v122, v228
	v_mul_f32_e32 v233, v123, v228
	v_mov_b32_e32 v122, v126
	v_mov_b32_e32 v123, v232
	v_ashrrev_i32_e32 v211, 31, v210
	v_lshlrev_b64 v[230:231], 9, v[210:211]
	v_mul_f32_e32 v128, v128, v228
	v_mul_f32_e32 v129, v129, v228
	v_mul_f32_e32 v124, v124, v228
	v_mul_f32_e32 v125, v125, v228
	v_mov_b32_e32 v235, v126
	v_mul_f32_e32 v122, v158, v122
	v_mul_f32_e32 v123, v159, v123
	v_mov_b32_e32 v126, v233
	v_sub_f32_e32 v211, v122, v123
	v_mov_b32_e32 v122, v127
	v_mov_b32_e32 v123, v233
	v_mul_f32_e32 v122, v160, v122
	v_mul_f32_e32 v123, v161, v123
	v_mul_f32_e32 v126, v160, v126
	v_mul_f32_e32 v127, v161, v127
	v_sub_f32_e32 v217, v122, v123
	v_mov_b32_e32 v122, v128
	v_mov_b32_e32 v123, v124
	v_mul_f32_e32 v122, v154, v122
	v_mul_f32_e32 v123, v155, v123
	global_load_dwordx4 v[162:165], v[214:215], off offset:2064
	global_load_dwordx4 v[166:169], v[214:215], off offset:2048
	v_sub_f32_e32 v227, v122, v123
	v_mov_b32_e32 v122, v129
	v_mov_b32_e32 v123, v125
	v_mul_f32_e32 v122, v156, v122
	v_mul_f32_e32 v123, v157, v123
	v_mov_b32_e32 v234, v232
	v_sub_f32_e32 v123, v122, v123
	v_cvt_pk_bf16_f32 v122, v211, v217
	v_add_f32_e32 v217, v127, v126
	v_mov_b32_e32 v127, v128
	v_mov_b32_e32 v128, v125
	v_mov_b32_e32 v126, v124
	v_mul_f32_e32 v124, v156, v128
	v_mul_f32_e32 v125, v157, v129
	v_mul_f32_e32 v234, v158, v234
	v_mul_f32_e32 v235, v159, v235
	v_mul_f32_e32 v126, v154, v126
	v_mul_f32_e32 v127, v155, v127
	v_add_f32_e32 v125, v125, v124
	v_cvt_pk_bf16_f32 v123, v227, v123
	v_add_f32_e32 v211, v235, v234
	v_add_f32_e32 v126, v127, v126
	v_cvt_pk_bf16_f32 v124, v211, v217
	v_cvt_pk_bf16_f32 v125, v126, v125
	v_lshl_add_u64 v[230:231], v[212:213], 0, v[230:231]
	v_permlane16_swap_b32_e32 v122, v124
	v_permlane16_swap_b32_e32 v123, v125
	v_mul_f32_e32 v118, v118, v134
	v_mul_f32_e32 v119, v119, v135
	v_mul_f32_e32 v114, v114, v130
	v_mul_f32_e32 v115, v115, v131
	global_store_dwordx4 v[230:231], v[122:125], off
	v_mul_f32_e32 v118, v118, v228
	v_mul_f32_e32 v119, v119, v228
	v_mul_f32_e32 v120, v120, v136
	v_mul_f32_e32 v121, v121, v137
	v_mul_f32_e32 v122, v114, v228
	v_mul_f32_e32 v123, v115, v228
	v_mov_b32_e32 v114, v118
	v_mov_b32_e32 v115, v122
	v_mul_f32_e32 v114, v174, v114
	v_mul_f32_e32 v115, v175, v115
	v_mul_f32_e32 v116, v116, v132
	v_mul_f32_e32 v117, v117, v133
	v_sub_f32_e32 v124, v114, v115
	v_mov_b32_e32 v114, v119
	v_mov_b32_e32 v115, v123
	v_mul_f32_e32 v120, v120, v228
	v_mul_f32_e32 v121, v121, v228
	v_mul_f32_e32 v116, v116, v228
	v_mul_f32_e32 v117, v117, v228
	v_mul_f32_e32 v114, v176, v114
	v_mul_f32_e32 v115, v177, v115
	s_nop 0
	v_sub_f32_e32 v125, v114, v115
	v_mov_b32_e32 v114, v120
	v_mov_b32_e32 v115, v116
	v_mul_f32_e32 v114, v170, v114
	v_mul_f32_e32 v115, v171, v115
	s_nop 0
	v_sub_f32_e32 v126, v114, v115
	v_mov_b32_e32 v114, v121
	v_mov_b32_e32 v115, v117
	v_mul_f32_e32 v114, v172, v114
	v_mul_f32_e32 v115, v173, v115
	s_nop 0
	v_sub_f32_e32 v115, v114, v115
	v_cvt_pk_bf16_f32 v114, v124, v125
	v_mov_b32_e32 v124, v122
	v_mov_b32_e32 v125, v118
	v_mul_f32_e32 v124, v174, v124
	v_mul_f32_e32 v125, v175, v125
	v_mov_b32_e32 v118, v123
	v_add_f32_e32 v211, v125, v124
	v_mul_f32_e32 v122, v112, v112
	v_mul_f32_e32 v123, v113, v113
	v_mul_f32_e32 v124, v110, v110
	v_mul_f32_e32 v125, v111, v111
	v_cvt_pk_bf16_f32 v115, v126, v115
	v_mul_f32_e32 v118, v176, v118
	v_mul_f32_e32 v119, v177, v119
	v_pk_mov_b32 v[126:127], v[124:125], v[122:123] op_sel:[1,0]
	v_mov_b32_e32 v125, v123
	v_add_f32_e32 v122, v126, v124
	v_add_f32_e32 v123, v127, v125
	v_mul_f32_e32 v124, v108, v108
	v_mul_f32_e32 v125, v109, v109
	v_mul_f32_e32 v126, v106, v106
	v_mul_f32_e32 v127, v107, v107
	v_add_f32_e32 v217, v119, v118
	v_pk_mov_b32 v[128:129], v[126:127], v[124:125] op_sel:[1,0]
	v_mov_b32_e32 v127, v125
	v_add_f32_e32 v124, v128, v126
	v_add_f32_e32 v125, v129, v127
	v_mov_b32_e32 v118, v116
	v_mov_b32_e32 v119, v120
	v_mul_f32_e32 v116, v98, v98
	v_mul_f32_e32 v120, v99, v99
	v_pk_add_f32 v[122:123], v[122:123], v[122:123] op_sel:[0,1] op_sel_hi:[1,0]
	v_pk_add_f32 v[124:125], v[124:125], v[124:125] op_sel:[0,1] op_sel_hi:[1,0]
	v_mov_b32_e32 v123, v116
	v_mov_b32_e32 v125, v120
	v_mul_f32_e32 v116, v103, v103
	v_mul_f32_e32 v126, v100, v100
	v_add_f32_e32 v122, v122, v124
	v_add_f32_e32 v123, v123, v125
	v_fma_f32 v124, v102, v102, v116
	v_fma_f32 v125, v103, v103, v116
	v_mul_f32_e32 v116, v105, v105
	v_mul_f32_e32 v128, v101, v101
	v_mov_b32_e32 v125, v126
	v_fma_f32 v126, v104, v104, v116
	v_fma_f32 v127, v105, v105, v116
	v_mul_f32_e32 v118, v170, v118
	v_mul_f32_e32 v119, v171, v119
	v_mov_b32_e32 v127, v128
	v_add_f32_e32 v124, v124, v126
	v_add_f32_e32 v125, v125, v127
	v_add_f32_e32 v118, v119, v118
	v_add_f32_e32 v122, v122, v124
	v_add_f32_e32 v123, v123, v125
	v_mov_b32_e32 v120, v117
	v_add_f32_e32 v122, v122, v123
	ds_bpermute_b32 v123, v0, v122
	v_mul_f32_e32 v116, v172, v120
	v_mul_f32_e32 v117, v173, v121
	v_mul_f32_e32 v110, v110, v142
	v_mul_f32_e32 v111, v111, v143
	v_add_f32_e32 v117, v117, v116
	v_cvt_pk_bf16_f32 v116, v211, v217
	s_waitcnt lgkmcnt(0)
;     __device__ __forceinline__ static v2u pk4(float a, float b, float c, float d) { v2u o; o.x = pg8::cvt_pk_bf16(a, b); o.y = pg8::cvt_pk_bf16(c, d); return o; }
;     __device__ __forceinline__ void head64(const pg8::f32x4 (&acc)[2][2][4][2], int row0, int fq, bf16r* dst, int pitch, int colbase, const float* gain, float scale, const float2* trc) const {
;     ...
;             for (int ai = 0; ai < 2; ++ai) { const int m = 2 * mh + mm; const int row = row0 + ai * 128 + m * 16;
;                 float ss = 0.f;
; #pragma unroll
;                 for (int bj = 0; bj < 2; ++bj)
; #pragma unroll
;                     for (int n = 0; n < 2; ++n) { const pg8::f32x4 v = acc[ai][bj][m][n]; ss += (v[0] * v[0] + v[1] * v[1]) + (v[2] * v[2] + v[3] * v[3]); }
;                 ss += __shfl_xor(ss, 16); ss += __shfl_xor(ss, 32);
;                 const float rstd = rsqrtf(ss * (1.f / 64.f) + EPS);
; #pragma unroll
;                 for (int bj = 0; bj < 2; ++bj) { const pg8::f32x4 cs01 = bj == 0 ? rcs[ai][0] : ccs[mm][0], cs23 = bj == 0 ? rcs[ai][1] : ccs[mm][1];
;                     const pg8::f32x4 x1 = acc[ai][bj][m][0] * g[bj][0] * (rstd * scale), x2 = acc[ai][bj][m][1] * g[bj][1] * (rstd * scale);
;                     const float c0 = cs01[0], s0 = cs01[1], c1 = cs01[2], s1 = cs01[3], c2 = cs23[0], s2 = cs23[1], c3 = cs23[2], s3 = cs23[3];
;                     store_pair16(dst + (size_t)row * pitch + colbase + 32 * bj, fq, pk4(x1[0] * c0 - x2[0] * s0, x1[1] * c1 - x2[1] * s1, x1[2] * c2 - x2[2] * s2, x1[3] * c3 - x2[3] * s3),
;                                  pk4(x2[0] * c0 + x1[0] * s0, x2[1] * c1 + x1[1] * s1, x2[2] * c2 + x1[2] * s2, x2[3] * c3 + x1[3] * s3)); } } }
	v_add_f32_e32 v119, v122, v123
	ds_bpermute_b32 v120, v189, v119
	v_cvt_pk_bf16_f32 v117, v118, v117
	v_permlane16_swap_b32_e32 v114, v116
	v_permlane16_swap_b32_e32 v115, v117
	s_waitcnt lgkmcnt(0)
	v_add_f32_e32 v118, v119, v120
	v_fmamk_f32 v118, v118, 0x3c800000, v219
	v_mul_f32_e32 v119, 0x4b800000, v118
	v_cmp_gt_f32_e32 vcc, s25, v118
	global_store_dwordx4 v[230:231], v[114:117], off offset:64
	v_mul_f32_e32 v106, v106, v138
	v_mul_f32_e32 v107, v107, v139
	v_cndmask_b32_e32 v118, v118, v119, vcc
	v_rsq_f32_e32 v118, v118
	v_mul_f32_e32 v112, v112, v144
	v_mul_f32_e32 v113, v113, v145
	v_mul_f32_e32 v108, v108, v140
	v_mul_f32_e32 v109, v109, v141
	v_ashrrev_i32_e32 v217, 31, v216
	v_mul_f32_e32 v114, 0x45800000, v118
	v_cndmask_b32_e32 v114, v118, v114, vcc
	v_mul_f32_e32 v114, 0x3e38aa3b, v114
	v_mul_f32_e32 v110, v110, v114
	v_mul_f32_e32 v111, v111, v114
	v_mul_f32_e32 v118, v106, v114
	v_mul_f32_e32 v119, v107, v114
	v_mov_b32_e32 v106, v110
	v_mov_b32_e32 v107, v118
	v_mul_f32_e32 v106, v150, v106
	v_mul_f32_e32 v107, v151, v107
	v_mul_f32_e32 v112, v112, v114
	v_mul_f32_e32 v113, v113, v114
	v_mul_f32_e32 v108, v108, v114
	v_mul_f32_e32 v109, v109, v114
	v_sub_f32_e32 v115, v106, v107
	v_mov_b32_e32 v106, v111
	v_mov_b32_e32 v107, v119
	v_mul_f32_e32 v106, v152, v106
	v_mul_f32_e32 v107, v153, v107
	v_lshlrev_b64 v[116:117], 9, v[216:217]
	v_sub_f32_e32 v120, v106, v107
	v_mov_b32_e32 v106, v112
	v_mov_b32_e32 v107, v108
	v_mul_f32_e32 v106, v146, v106
	v_mul_f32_e32 v107, v147, v107
	v_lshl_add_u64 v[116:117], v[212:213], 0, v[116:117]
	v_sub_f32_e32 v121, v106, v107
	v_mov_b32_e32 v106, v113
	v_mov_b32_e32 v107, v109
	v_mul_f32_e32 v106, v148, v106
	v_mul_f32_e32 v107, v149, v107
	v_mul_f32_e32 v102, v102, v134
	v_mul_f32_e32 v103, v103, v135
	v_sub_f32_e32 v107, v106, v107
	v_cvt_pk_bf16_f32 v106, v115, v120
	v_cvt_pk_bf16_f32 v107, v121, v107
	v_mov_b32_e32 v121, v110
	v_mov_b32_e32 v110, v119
	v_mul_f32_e32 v110, v152, v110
	v_mul_f32_e32 v111, v153, v111
	v_mov_b32_e32 v120, v118
	v_add_f32_e32 v118, v111, v110
	v_mov_b32_e32 v111, v112
	v_mov_b32_e32 v112, v109
	v_mov_b32_e32 v110, v108
	v_mul_f32_e32 v108, v148, v112
	v_mul_f32_e32 v109, v149, v113
	v_mul_f32_e32 v120, v150, v120
	v_mul_f32_e32 v121, v151, v121
	v_mul_f32_e32 v110, v146, v110
	v_mul_f32_e32 v111, v147, v111
	v_add_f32_e32 v109, v109, v108
	v_add_f32_e32 v115, v121, v120
	v_add_f32_e32 v110, v111, v110
	v_cvt_pk_bf16_f32 v108, v115, v118
	v_cvt_pk_bf16_f32 v109, v110, v109
	v_mul_f32_e32 v98, v98, v130
	v_mul_f32_e32 v99, v99, v131
	v_permlane16_swap_b32_e32 v106, v108
	v_permlane16_swap_b32_e32 v107, v109
	global_store_dwordx4 v[116:117], v[106:109], off
	v_mul_f32_e32 v102, v102, v114
	v_mul_f32_e32 v103, v103, v114
	v_mul_f32_e32 v104, v104, v136
	v_mul_f32_e32 v105, v105, v137
	v_mul_f32_e32 v106, v98, v114
	v_mul_f32_e32 v107, v99, v114
	v_mov_b32_e32 v98, v102
	v_mov_b32_e32 v99, v106
	v_mul_f32_e32 v98, v174, v98
	v_mul_f32_e32 v99, v175, v99
	v_mul_f32_e32 v100, v100, v132
	v_mul_f32_e32 v101, v101, v133
	v_sub_f32_e32 v108, v98, v99
	v_mov_b32_e32 v98, v103
	v_mov_b32_e32 v99, v107
	v_mul_f32_e32 v104, v104, v114
	v_mul_f32_e32 v105, v105, v114
	v_mul_f32_e32 v100, v100, v114
	v_mul_f32_e32 v101, v101, v114
	v_mul_f32_e32 v98, v176, v98
	v_mul_f32_e32 v99, v177, v99
	s_nop 0
	v_sub_f32_e32 v109, v98, v99
	v_mov_b32_e32 v98, v104
	v_mov_b32_e32 v99, v100
	v_mul_f32_e32 v98, v170, v98
	v_mul_f32_e32 v99, v171, v99
	s_nop 0
	v_sub_f32_e32 v110, v98, v99
	v_mov_b32_e32 v98, v105
	v_mov_b32_e32 v99, v101
	v_mul_f32_e32 v98, v172, v98
	v_mul_f32_e32 v99, v173, v99
	s_nop 0
	v_sub_f32_e32 v99, v98, v99
	v_cvt_pk_bf16_f32 v98, v108, v109
	v_mov_b32_e32 v108, v106
	v_mov_b32_e32 v109, v102
	v_mul_f32_e32 v108, v174, v108
	v_mul_f32_e32 v109, v175, v109
	v_mov_b32_e32 v102, v107
	v_add_f32_e32 v114, v109, v108
	v_mul_f32_e32 v106, v96, v96
	v_mul_f32_e32 v107, v97, v97
	v_mul_f32_e32 v108, v94, v94
	v_mul_f32_e32 v109, v95, v95
	v_cvt_pk_bf16_f32 v99, v110, v99
	v_mul_f32_e32 v102, v176, v102
	v_mul_f32_e32 v103, v177, v103
	v_pk_mov_b32 v[110:111], v[108:109], v[106:107] op_sel:[1,0]
	v_mov_b32_e32 v109, v107
	v_add_f32_e32 v106, v110, v108
	v_add_f32_e32 v107, v111, v109
	v_mul_f32_e32 v108, v92, v92
	v_mul_f32_e32 v109, v93, v93
	v_mul_f32_e32 v110, v90, v90
	v_mul_f32_e32 v111, v91, v91
	v_add_f32_e32 v115, v103, v102
	v_pk_mov_b32 v[112:113], v[110:111], v[108:109] op_sel:[1,0]
	v_mov_b32_e32 v111, v109
	v_add_f32_e32 v108, v112, v110
	v_add_f32_e32 v109, v113, v111
	v_mov_b32_e32 v102, v100
	v_mov_b32_e32 v103, v104
	v_mul_f32_e32 v100, v82, v82
	v_mul_f32_e32 v104, v83, v83
	v_pk_add_f32 v[106:107], v[106:107], v[106:107] op_sel:[0,1] op_sel_hi:[1,0]
	v_pk_add_f32 v[108:109], v[108:109], v[108:109] op_sel:[0,1] op_sel_hi:[1,0]
	v_mov_b32_e32 v107, v100
	v_mov_b32_e32 v109, v104
	v_mul_f32_e32 v100, v87, v87
	v_mul_f32_e32 v110, v84, v84
	v_add_f32_e32 v106, v106, v108
	v_add_f32_e32 v107, v107, v109
	v_fma_f32 v108, v86, v86, v100
	v_fma_f32 v109, v87, v87, v100
	v_mul_f32_e32 v100, v89, v89
	v_mul_f32_e32 v112, v85, v85
	v_mov_b32_e32 v109, v110
	v_fma_f32 v110, v88, v88, v100
	v_fma_f32 v111, v89, v89, v100
	v_mul_f32_e32 v102, v170, v102
	v_mul_f32_e32 v103, v171, v103
	v_mov_b32_e32 v111, v112
	v_add_f32_e32 v108, v108, v110
	v_add_f32_e32 v109, v109, v111
	v_add_f32_e32 v102, v103, v102
	v_add_f32_e32 v106, v106, v108
	v_add_f32_e32 v107, v107, v109
	v_mov_b32_e32 v104, v101
	v_add_f32_e32 v106, v106, v107
	ds_bpermute_b32 v107, v0, v106
	v_mul_f32_e32 v100, v172, v104
	v_mul_f32_e32 v101, v173, v105
	v_mul_f32_e32 v94, v94, v142
	v_mul_f32_e32 v95, v95, v143
	v_add_f32_e32 v101, v101, v100
	v_cvt_pk_bf16_f32 v100, v114, v115
	s_waitcnt lgkmcnt(0)
;     __device__ __forceinline__ static v2u pk4(float a, float b, float c, float d) { v2u o; o.x = pg8::cvt_pk_bf16(a, b); o.y = pg8::cvt_pk_bf16(c, d); return o; }
;     __device__ __forceinline__ void head64(const pg8::f32x4 (&acc)[2][2][4][2], int row0, int fq, bf16r* dst, int pitch, int colbase, const float* gain, float scale, const float2* trc) const {
;     ...
;             for (int ai = 0; ai < 2; ++ai) { const int m = 2 * mh + mm; const int row = row0 + ai * 128 + m * 16;
;                 float ss = 0.f;
; #pragma unroll
;                 for (int bj = 0; bj < 2; ++bj)
; #pragma unroll
;                     for (int n = 0; n < 2; ++n) { const pg8::f32x4 v = acc[ai][bj][m][n]; ss += (v[0] * v[0] + v[1] * v[1]) + (v[2] * v[2] + v[3] * v[3]); }
;                 ss += __shfl_xor(ss, 16); ss += __shfl_xor(ss, 32);
;                 const float rstd = rsqrtf(ss * (1.f / 64.f) + EPS);
; #pragma unroll
;                 for (int bj = 0; bj < 2; ++bj) { const pg8::f32x4 cs01 = bj == 0 ? rcs[ai][0] : ccs[mm][0], cs23 = bj == 0 ? rcs[ai][1] : ccs[mm][1];
;                     const pg8::f32x4 x1 = acc[ai][bj][m][0] * g[bj][0] * (rstd * scale), x2 = acc[ai][bj][m][1] * g[bj][1] * (rstd * scale);
;                     const float c0 = cs01[0], s0 = cs01[1], c1 = cs01[2], s1 = cs01[3], c2 = cs23[0], s2 = cs23[1], c3 = cs23[2], s3 = cs23[3];
;                     store_pair16(dst + (size_t)row * pitch + colbase + 32 * bj, fq, pk4(x1[0] * c0 - x2[0] * s0, x1[1] * c1 - x2[1] * s1, x1[2] * c2 - x2[2] * s2, x1[3] * c3 - x2[3] * s3),
;                                  pk4(x2[0] * c0 + x1[0] * s0, x2[1] * c1 + x1[1] * s1, x2[2] * c2 + x1[2] * s2, x2[3] * c3 + x1[3] * s3)); } } }
	v_add_f32_e32 v103, v106, v107
	ds_bpermute_b32 v104, v189, v103
	v_cvt_pk_bf16_f32 v101, v102, v101
	v_permlane16_swap_b32_e32 v98, v100
	v_permlane16_swap_b32_e32 v99, v101
	s_waitcnt lgkmcnt(0)
	v_add_f32_e32 v102, v103, v104
	v_fmamk_f32 v102, v102, 0x3c800000, v219
	v_mul_f32_e32 v103, 0x4b800000, v102
	v_cmp_gt_f32_e32 vcc, s25, v102
	global_store_dwordx4 v[116:117], v[98:101], off offset:64
	v_mul_f32_e32 v90, v90, v138
	v_mul_f32_e32 v91, v91, v139
	v_cndmask_b32_e32 v102, v102, v103, vcc
	v_rsq_f32_e32 v102, v102
	v_mul_f32_e32 v96, v96, v144
	v_mul_f32_e32 v97, v97, v145
	v_mul_f32_e32 v92, v92, v140
	v_mul_f32_e32 v93, v93, v141
	v_or_b32_e32 v98, 16, v210
	v_mul_f32_e32 v99, 0x45800000, v102
	v_cndmask_b32_e32 v99, v102, v99, vcc
	v_mul_f32_e32 v100, 0x3e38aa3b, v99
	v_mul_f32_e32 v94, v94, v100
	v_mul_f32_e32 v95, v95, v100
	v_mul_f32_e32 v102, v90, v100
	v_mul_f32_e32 v103, v91, v100
	v_mov_b32_e32 v90, v94
	v_mov_b32_e32 v91, v102
	v_mul_f32_e32 v90, v158, v90
	v_mul_f32_e32 v91, v159, v91
	v_mul_f32_e32 v96, v96, v100
	v_mul_f32_e32 v97, v97, v100
	v_mul_f32_e32 v92, v92, v100
	v_mul_f32_e32 v93, v93, v100
	v_sub_f32_e32 v101, v90, v91
	v_mov_b32_e32 v90, v95
	v_mov_b32_e32 v91, v103
	v_mul_f32_e32 v90, v160, v90
	v_mul_f32_e32 v91, v161, v91
	v_ashrrev_i32_e32 v99, 31, v98
	v_sub_f32_e32 v104, v90, v91
	v_mov_b32_e32 v90, v96
	v_mov_b32_e32 v91, v92
	v_mul_f32_e32 v90, v154, v90
	v_mul_f32_e32 v91, v155, v91
	v_lshlrev_b64 v[98:99], 9, v[98:99]
	v_sub_f32_e32 v105, v90, v91
	v_mov_b32_e32 v90, v97
	v_mov_b32_e32 v91, v93
	v_mul_f32_e32 v90, v156, v90
	v_mul_f32_e32 v91, v157, v91
	v_lshl_add_u64 v[98:99], v[212:213], 0, v[98:99]
	v_sub_f32_e32 v91, v90, v91
	v_cvt_pk_bf16_f32 v90, v101, v104
	v_cvt_pk_bf16_f32 v91, v105, v91
	v_mov_b32_e32 v105, v94
	v_mov_b32_e32 v94, v103
	v_mul_f32_e32 v94, v160, v94
	v_mul_f32_e32 v95, v161, v95
	v_mov_b32_e32 v104, v102
	v_add_f32_e32 v102, v95, v94
	v_mov_b32_e32 v95, v96
	v_mov_b32_e32 v96, v93
	v_mov_b32_e32 v94, v92
	v_mul_f32_e32 v92, v156, v96
	v_mul_f32_e32 v93, v157, v97
	v_mul_f32_e32 v104, v158, v104
	v_mul_f32_e32 v105, v159, v105
	v_mul_f32_e32 v94, v154, v94
	v_mul_f32_e32 v95, v155, v95
	v_add_f32_e32 v93, v93, v92
	v_add_f32_e32 v101, v105, v104
	v_add_f32_e32 v94, v95, v94
	v_cvt_pk_bf16_f32 v92, v101, v102
	v_cvt_pk_bf16_f32 v93, v94, v93
	v_mul_f32_e32 v86, v86, v134
	v_mul_f32_e32 v87, v87, v135
	v_permlane16_swap_b32_e32 v90, v92
	v_permlane16_swap_b32_e32 v91, v93
	v_mul_f32_e32 v82, v82, v130
	v_mul_f32_e32 v83, v83, v131
	global_store_dwordx4 v[98:99], v[90:93], off
	v_mul_f32_e32 v86, v86, v100
	v_mul_f32_e32 v87, v87, v100
	v_mul_f32_e32 v88, v88, v136
	v_mul_f32_e32 v89, v89, v137
	v_mul_f32_e32 v90, v82, v100
	v_mul_f32_e32 v91, v83, v100
	v_mov_b32_e32 v82, v86
	v_mov_b32_e32 v83, v90
	s_waitcnt vmcnt(5)
	v_mul_f32_e32 v82, v166, v82
	v_mul_f32_e32 v83, v167, v83
	v_mul_f32_e32 v84, v84, v132
	v_mul_f32_e32 v85, v85, v133
	v_sub_f32_e32 v92, v82, v83
	v_mov_b32_e32 v82, v87
	v_mov_b32_e32 v83, v91
	v_mul_f32_e32 v88, v88, v100
	v_mul_f32_e32 v89, v89, v100
	v_mul_f32_e32 v84, v84, v100
	v_mul_f32_e32 v85, v85, v100
	v_mul_f32_e32 v82, v168, v82
	v_mul_f32_e32 v83, v169, v83
	s_nop 0
	v_sub_f32_e32 v93, v82, v83
	v_mov_b32_e32 v82, v88
	v_mov_b32_e32 v83, v84
	v_mul_f32_e32 v82, v162, v82
	v_mul_f32_e32 v83, v163, v83
	s_nop 0
	v_sub_f32_e32 v94, v82, v83
	v_mov_b32_e32 v82, v89
	v_mov_b32_e32 v83, v85
	v_mul_f32_e32 v82, v164, v82
	v_mul_f32_e32 v83, v165, v83
	s_nop 0
	v_sub_f32_e32 v83, v82, v83
	v_cvt_pk_bf16_f32 v82, v92, v93
	v_mov_b32_e32 v92, v90
	v_mov_b32_e32 v93, v86
	v_mul_f32_e32 v92, v166, v92
	v_mul_f32_e32 v93, v167, v93
	v_mov_b32_e32 v86, v91
	v_add_f32_e32 v100, v93, v92
	v_mul_f32_e32 v90, v80, v80
	v_mul_f32_e32 v91, v81, v81
	v_mul_f32_e32 v92, v78, v78
	v_mul_f32_e32 v93, v79, v79
	v_cvt_pk_bf16_f32 v83, v94, v83
	v_mul_f32_e32 v86, v168, v86
	v_mul_f32_e32 v87, v169, v87
	v_pk_mov_b32 v[94:95], v[92:93], v[90:91] op_sel:[1,0]
	v_mov_b32_e32 v93, v91
	v_add_f32_e32 v90, v94, v92
	v_add_f32_e32 v91, v95, v93
	v_mul_f32_e32 v92, v76, v76
	v_mul_f32_e32 v93, v77, v77
	v_mul_f32_e32 v94, v74, v74
	v_mul_f32_e32 v95, v75, v75
	v_add_f32_e32 v101, v87, v86
	v_pk_mov_b32 v[96:97], v[94:95], v[92:93] op_sel:[1,0]
	v_mov_b32_e32 v95, v93
	v_add_f32_e32 v92, v96, v94
	v_add_f32_e32 v93, v97, v95
	v_mov_b32_e32 v86, v84
	v_mov_b32_e32 v87, v88
	v_mul_f32_e32 v84, v66, v66
	v_mul_f32_e32 v88, v67, v67
	v_pk_add_f32 v[90:91], v[90:91], v[90:91] op_sel:[0,1] op_sel_hi:[1,0]
	v_pk_add_f32 v[92:93], v[92:93], v[92:93] op_sel:[0,1] op_sel_hi:[1,0]
	v_mov_b32_e32 v91, v84
	v_mov_b32_e32 v93, v88
	v_mul_f32_e32 v84, v71, v71
	v_mul_f32_e32 v94, v68, v68
	v_add_f32_e32 v90, v90, v92
	v_add_f32_e32 v91, v91, v93
	v_fma_f32 v92, v70, v70, v84
	v_fma_f32 v93, v71, v71, v84
	v_mul_f32_e32 v84, v73, v73
	v_mul_f32_e32 v96, v69, v69
	v_mov_b32_e32 v93, v94
	v_fma_f32 v94, v72, v72, v84
	v_fma_f32 v95, v73, v73, v84
	v_mul_f32_e32 v86, v162, v86
	v_mul_f32_e32 v87, v163, v87
	v_mov_b32_e32 v95, v96
	v_add_f32_e32 v92, v92, v94
	v_add_f32_e32 v93, v93, v95
	v_add_f32_e32 v86, v87, v86
	v_add_f32_e32 v90, v90, v92
	v_add_f32_e32 v91, v91, v93
	v_mov_b32_e32 v88, v85
	v_add_f32_e32 v90, v90, v91
	ds_bpermute_b32 v91, v0, v90
	v_mul_f32_e32 v84, v164, v88
	v_mul_f32_e32 v85, v165, v89
	v_mul_f32_e32 v78, v78, v142
	v_mul_f32_e32 v79, v79, v143
	v_add_f32_e32 v85, v85, v84
	v_cvt_pk_bf16_f32 v84, v100, v101
	s_waitcnt lgkmcnt(0)
	v_add_f32_e32 v87, v90, v91
	ds_bpermute_b32 v88, v189, v87
	v_cvt_pk_bf16_f32 v85, v86, v85
	v_permlane16_swap_b32_e32 v82, v84
	v_permlane16_swap_b32_e32 v83, v85
	s_waitcnt lgkmcnt(0)
;     __device__ __forceinline__ static v2u pk4(float a, float b, float c, float d) { v2u o; o.x = pg8::cvt_pk_bf16(a, b); o.y = pg8::cvt_pk_bf16(c, d); return o; }
;     __device__ __forceinline__ void head64(const pg8::f32x4 (&acc)[2][2][4][2], int row0, int fq, bf16r* dst, int pitch, int colbase, const float* gain, float scale, const float2* trc) const {
;     ...
;             for (int ai = 0; ai < 2; ++ai) { const int m = 2 * mh + mm; const int row = row0 + ai * 128 + m * 16;
;                 float ss = 0.f;
; #pragma unroll
;                 for (int bj = 0; bj < 2; ++bj)
; #pragma unroll
;                     for (int n = 0; n < 2; ++n) { const pg8::f32x4 v = acc[ai][bj][m][n]; ss += (v[0] * v[0] + v[1] * v[1]) + (v[2] * v[2] + v[3] * v[3]); }
;                 ss += __shfl_xor(ss, 16); ss += __shfl_xor(ss, 32);
;                 const float rstd = rsqrtf(ss * (1.f / 64.f) + EPS);
; #pragma unroll
;                 for (int bj = 0; bj < 2; ++bj) { const pg8::f32x4 cs01 = bj == 0 ? rcs[ai][0] : ccs[mm][0], cs23 = bj == 0 ? rcs[ai][1] : ccs[mm][1];
;                     const pg8::f32x4 x1 = acc[ai][bj][m][0] * g[bj][0] * (rstd * scale), x2 = acc[ai][bj][m][1] * g[bj][1] * (rstd * scale);
;                     const float c0 = cs01[0], s0 = cs01[1], c1 = cs01[2], s1 = cs01[3], c2 = cs23[0], s2 = cs23[1], c3 = cs23[2], s3 = cs23[3];
;                     store_pair16(dst + (size_t)row * pitch + colbase + 32 * bj, fq, pk4(x1[0] * c0 - x2[0] * s0, x1[1] * c1 - x2[1] * s1, x1[2] * c2 - x2[2] * s2, x1[3] * c3 - x2[3] * s3),
;                                  pk4(x2[0] * c0 + x1[0] * s0, x2[1] * c1 + x1[1] * s1, x2[2] * c2 + x1[2] * s2, x2[3] * c3 + x1[3] * s3)); } } }
	v_add_f32_e32 v86, v87, v88
	v_fmamk_f32 v86, v86, 0x3c800000, v219
	v_mul_f32_e32 v87, 0x4b800000, v86
	v_cmp_gt_f32_e32 vcc, s25, v86
	global_store_dwordx4 v[98:99], v[82:85], off offset:64
	v_mul_f32_e32 v74, v74, v138
	v_mul_f32_e32 v75, v75, v139
	v_cndmask_b32_e32 v86, v86, v87, vcc
	v_rsq_f32_e32 v86, v86
	v_mul_f32_e32 v80, v80, v144
	v_mul_f32_e32 v81, v81, v145
	v_mul_f32_e32 v76, v76, v140
	v_mul_f32_e32 v77, v77, v141
	v_add_u32_e32 v82, 0x90, v210
	v_mul_f32_e32 v83, 0x45800000, v86
	v_cndmask_b32_e32 v83, v86, v83, vcc
	v_mul_f32_e32 v84, 0x3e38aa3b, v83
	v_mul_f32_e32 v78, v78, v84
	v_mul_f32_e32 v79, v79, v84
	v_mul_f32_e32 v86, v74, v84
	v_mul_f32_e32 v87, v75, v84
	v_mov_b32_e32 v74, v78
	v_mov_b32_e32 v75, v86
	v_mul_f32_e32 v74, v150, v74
	v_mul_f32_e32 v75, v151, v75
	v_mul_f32_e32 v80, v80, v84
	v_mul_f32_e32 v81, v81, v84
	v_mul_f32_e32 v76, v76, v84
	v_mul_f32_e32 v77, v77, v84
	v_sub_f32_e32 v85, v74, v75
	v_mov_b32_e32 v74, v79
	v_mov_b32_e32 v75, v87
	v_mul_f32_e32 v74, v152, v74
	v_mul_f32_e32 v75, v153, v75
	v_ashrrev_i32_e32 v83, 31, v82
	v_sub_f32_e32 v88, v74, v75
	v_mov_b32_e32 v74, v80
	v_mov_b32_e32 v75, v76
	v_mul_f32_e32 v74, v146, v74
	v_mul_f32_e32 v75, v147, v75
	v_lshlrev_b64 v[82:83], 9, v[82:83]
	v_sub_f32_e32 v89, v74, v75
	v_mov_b32_e32 v74, v81
	v_mov_b32_e32 v75, v77
	v_mul_f32_e32 v74, v148, v74
	v_mul_f32_e32 v75, v149, v75
	v_lshl_add_u64 v[82:83], v[212:213], 0, v[82:83]
	v_sub_f32_e32 v75, v74, v75
	v_cvt_pk_bf16_f32 v74, v85, v88
	v_cvt_pk_bf16_f32 v75, v89, v75
	v_mov_b32_e32 v89, v78
	v_mov_b32_e32 v78, v87
	v_mul_f32_e32 v78, v152, v78
	v_mul_f32_e32 v79, v153, v79
	v_mov_b32_e32 v88, v86
	v_add_f32_e32 v86, v79, v78
	v_mov_b32_e32 v79, v80
	v_mov_b32_e32 v80, v77
	v_mov_b32_e32 v78, v76
	v_mul_f32_e32 v76, v148, v80
	v_mul_f32_e32 v77, v149, v81
	v_mul_f32_e32 v88, v150, v88
	v_mul_f32_e32 v89, v151, v89
	v_mul_f32_e32 v78, v146, v78
	v_mul_f32_e32 v79, v147, v79
	v_add_f32_e32 v77, v77, v76
	v_add_f32_e32 v85, v89, v88
	v_add_f32_e32 v78, v79, v78
	v_cvt_pk_bf16_f32 v76, v85, v86
	v_cvt_pk_bf16_f32 v77, v78, v77
	v_mul_f32_e32 v70, v70, v134
	v_mul_f32_e32 v71, v71, v135
	v_permlane16_swap_b32_e32 v74, v76
	v_permlane16_swap_b32_e32 v75, v77
	v_mul_f32_e32 v66, v66, v130
	v_mul_f32_e32 v67, v67, v131
	global_store_dwordx4 v[82:83], v[74:77], off
	v_mul_f32_e32 v70, v70, v84
	v_mul_f32_e32 v71, v71, v84
	v_mul_f32_e32 v72, v72, v136
	v_mul_f32_e32 v73, v73, v137
	v_mul_f32_e32 v74, v66, v84
	v_mul_f32_e32 v75, v67, v84
	v_mov_b32_e32 v66, v70
	v_mov_b32_e32 v67, v74
	v_mul_f32_e32 v66, v166, v66
	v_mul_f32_e32 v67, v167, v67
	v_mul_f32_e32 v68, v68, v132
	v_mul_f32_e32 v69, v69, v133
	v_sub_f32_e32 v76, v66, v67
	v_mov_b32_e32 v66, v71
	v_mov_b32_e32 v67, v75
	v_mul_f32_e32 v72, v72, v84
	v_mul_f32_e32 v73, v73, v84
	v_mul_f32_e32 v68, v68, v84
	v_mul_f32_e32 v69, v69, v84
	v_mul_f32_e32 v66, v168, v66
	v_mul_f32_e32 v67, v169, v67
	s_nop 0
	v_sub_f32_e32 v77, v66, v67
	v_mov_b32_e32 v66, v72
	v_mov_b32_e32 v67, v68
	v_mul_f32_e32 v66, v162, v66
	v_mul_f32_e32 v67, v163, v67
	s_nop 0
	v_sub_f32_e32 v78, v66, v67
	v_mov_b32_e32 v66, v73
	v_mov_b32_e32 v67, v69
	v_mul_f32_e32 v66, v164, v66
	v_mul_f32_e32 v67, v165, v67
	s_nop 0
	v_sub_f32_e32 v67, v66, v67
	v_cvt_pk_bf16_f32 v66, v76, v77
	v_mov_b32_e32 v77, v70
	v_mov_b32_e32 v70, v75
	v_mul_f32_e32 v70, v168, v70
	v_mul_f32_e32 v71, v169, v71
	v_mov_b32_e32 v76, v74
	v_add_f32_e32 v75, v71, v70
	v_mov_b32_e32 v71, v72
	v_mov_b32_e32 v72, v69
	v_mov_b32_e32 v70, v68
	v_mul_f32_e32 v68, v164, v72
	v_mul_f32_e32 v69, v165, v73
	v_mul_f32_e32 v76, v166, v76
	v_mul_f32_e32 v77, v167, v77
	v_mul_f32_e32 v70, v162, v70
	v_mul_f32_e32 v71, v163, v71
	v_add_f32_e32 v69, v69, v68
	v_cvt_pk_bf16_f32 v67, v78, v67
	v_add_f32_e32 v74, v77, v76
	v_add_f32_e32 v70, v71, v70
	v_cvt_pk_bf16_f32 v68, v74, v75
	v_cvt_pk_bf16_f32 v69, v70, v69
	s_nop 0
	v_permlane16_swap_b32_e32 v66, v68
	v_permlane16_swap_b32_e32 v67, v69
	global_store_dwordx4 v[82:83], v[66:69], off offset:64
	v_or_b32_e32 v82, 32, v210
	s_nop 0
	v_mul_f32_e32 v66, v64, v64
	v_mul_f32_e32 v67, v65, v65
	v_mul_f32_e32 v68, v62, v62
	v_mul_f32_e32 v69, v63, v63
	v_mul_f32_e32 v62, v62, v142
	v_mul_f32_e32 v63, v63, v143
	v_pk_mov_b32 v[70:71], v[68:69], v[66:67] op_sel:[1,0]
	v_mov_b32_e32 v69, v67
	v_add_f32_e32 v66, v70, v68
	v_add_f32_e32 v67, v71, v69
	v_mul_f32_e32 v68, v60, v60
	v_mul_f32_e32 v69, v61, v61
	v_mul_f32_e32 v70, v58, v58
	v_mul_f32_e32 v71, v59, v59
	v_pk_add_f32 v[66:67], v[66:67], v[66:67] op_sel:[0,1] op_sel_hi:[1,0]
	v_pk_mov_b32 v[72:73], v[70:71], v[68:69] op_sel:[1,0]
	v_mov_b32_e32 v71, v69
	v_add_f32_e32 v68, v72, v70
	v_add_f32_e32 v69, v73, v71
	v_mul_f32_e32 v70, v50, v50
	v_mul_f32_e32 v71, v51, v51
	v_pk_add_f32 v[68:69], v[68:69], v[68:69] op_sel:[0,1] op_sel_hi:[1,0]
	v_mov_b32_e32 v67, v70
	v_mov_b32_e32 v69, v71
	v_add_f32_e32 v66, v66, v68
	v_add_f32_e32 v67, v67, v69
	v_mul_f32_e32 v68, v55, v55
	v_mul_f32_e32 v70, v57, v57
	v_mul_f32_e32 v72, v52, v52
	v_mul_f32_e32 v73, v53, v53
	v_fma_f32 v69, v55, v55, v68
	v_fma_f32 v68, v54, v54, v68
	v_fma_f32 v71, v57, v57, v70
	v_fma_f32 v70, v56, v56, v70
	v_mov_b32_e32 v69, v72
	v_mov_b32_e32 v71, v73
	v_add_f32_e32 v68, v68, v70
	v_add_f32_e32 v69, v69, v71
	v_mul_f32_e32 v58, v58, v138
	v_mul_f32_e32 v59, v59, v139
	v_add_f32_e32 v66, v66, v68
	v_add_f32_e32 v67, v67, v69
	v_mul_f32_e32 v64, v64, v144
	v_mul_f32_e32 v65, v65, v145
	v_add_f32_e32 v68, v66, v67
	ds_bpermute_b32 v69, v0, v68
	v_add_co_u32_e32 v66, vcc, s75, v214
	v_mul_f32_e32 v60, v60, v140
	v_mul_f32_e32 v61, v61, v141
	s_nop 0
	v_addc_co_u32_e32 v67, vcc, 0, v215, vcc
	global_load_dwordx4 v[78:81], v[66:67], off
	s_waitcnt lgkmcnt(0)
;     __device__ __forceinline__ static v2u pk4(float a, float b, float c, float d) { v2u o; o.x = pg8::cvt_pk_bf16(a, b); o.y = pg8::cvt_pk_bf16(c, d); return o; }
;     __device__ __forceinline__ void head64(const pg8::f32x4 (&acc)[2][2][4][2], int row0, int fq, bf16r* dst, int pitch, int colbase, const float* gain, float scale, const float2* trc) const {
;     ...
;             for (int ai = 0; ai < 2; ++ai) { const int m = 2 * mh + mm; const int row = row0 + ai * 128 + m * 16;
;                 float ss = 0.f;
; #pragma unroll
;                 for (int bj = 0; bj < 2; ++bj)
; #pragma unroll
;                     for (int n = 0; n < 2; ++n) { const pg8::f32x4 v = acc[ai][bj][m][n]; ss += (v[0] * v[0] + v[1] * v[1]) + (v[2] * v[2] + v[3] * v[3]); }
;                 ss += __shfl_xor(ss, 16); ss += __shfl_xor(ss, 32);
;                 const float rstd = rsqrtf(ss * (1.f / 64.f) + EPS);
; #pragma unroll
;                 for (int bj = 0; bj < 2; ++bj) { const pg8::f32x4 cs01 = bj == 0 ? rcs[ai][0] : ccs[mm][0], cs23 = bj == 0 ? rcs[ai][1] : ccs[mm][1];
;                     const pg8::f32x4 x1 = acc[ai][bj][m][0] * g[bj][0] * (rstd * scale), x2 = acc[ai][bj][m][1] * g[bj][1] * (rstd * scale);
;                     const float c0 = cs01[0], s0 = cs01[1], c1 = cs01[2], s1 = cs01[3], c2 = cs23[0], s2 = cs23[1], c3 = cs23[2], s3 = cs23[3];
;                     store_pair16(dst + (size_t)row * pitch + colbase + 32 * bj, fq, pk4(x1[0] * c0 - x2[0] * s0, x1[1] * c1 - x2[1] * s1, x1[2] * c2 - x2[2] * s2, x1[3] * c3 - x2[3] * s3),
;                                  pk4(x2[0] * c0 + x1[0] * s0, x2[1] * c1 + x1[1] * s1, x2[2] * c2 + x1[2] * s2, x2[3] * c3 + x1[3] * s3)); } } }
	v_add_f32_e32 v70, v68, v69
	v_lshl_add_u64 v[68:69], v[214:215], 0, s[2:3]
	global_load_dwordx4 v[74:77], v[68:69], off offset:16
	ds_bpermute_b32 v71, v189, v70
	s_mov_b64 s[2:3], 0x1800
	v_lshl_add_u64 v[68:69], v[214:215], 0, s[2:3]
	v_mul_f32_e32 v54, v54, v134
	v_mul_f32_e32 v55, v55, v135
	v_mul_f32_e32 v50, v50, v130
	v_mul_f32_e32 v51, v51, v131
	s_waitcnt lgkmcnt(0)
	v_add_f32_e32 v70, v70, v71
	v_fmamk_f32 v70, v70, 0x3c800000, v219
	v_mul_f32_e32 v71, 0x4b800000, v70
	v_cmp_gt_f32_e32 vcc, s25, v70
	v_mul_f32_e32 v56, v56, v136
	v_mul_f32_e32 v57, v57, v137
	v_mul_f32_e32 v52, v52, v132
	v_mul_f32_e32 v53, v53, v133
	v_cndmask_b32_e32 v70, v70, v71, vcc
	v_rsq_f32_e32 v83, v70
	global_load_dwordx4 v[70:73], v[66:67], off offset:2048
	s_nop 0
	global_load_dwordx4 v[66:69], v[68:69], off offset:16
	v_mul_f32_e32 v84, 0x45800000, v83
	v_cndmask_b32_e32 v83, v83, v84, vcc
	v_mul_f32_e32 v84, 0x3e38aa3b, v83
	v_mul_f32_e32 v62, v62, v84
	v_mul_f32_e32 v63, v63, v84
	v_mul_f32_e32 v86, v58, v84
	v_mul_f32_e32 v87, v59, v84
	v_mov_b32_e32 v58, v62
	v_mov_b32_e32 v59, v86
	v_mul_f32_e32 v58, v158, v58
	v_mul_f32_e32 v59, v159, v59
	v_mul_f32_e32 v64, v64, v84
	v_mul_f32_e32 v65, v65, v84
	v_mul_f32_e32 v60, v60, v84
	v_mul_f32_e32 v61, v61, v84
	v_sub_f32_e32 v85, v58, v59
	v_mov_b32_e32 v58, v63
	v_mov_b32_e32 v59, v87
	v_mul_f32_e32 v58, v160, v58
	v_mul_f32_e32 v59, v161, v59
	v_ashrrev_i32_e32 v83, 31, v82
	v_sub_f32_e32 v88, v58, v59
	v_mov_b32_e32 v58, v64
	v_mov_b32_e32 v59, v60
	v_mul_f32_e32 v58, v154, v58
	v_mul_f32_e32 v59, v155, v59
	v_lshlrev_b64 v[82:83], 9, v[82:83]
	v_sub_f32_e32 v89, v58, v59
	v_mov_b32_e32 v58, v65
	v_mov_b32_e32 v59, v61
	v_mul_f32_e32 v58, v156, v58
	v_mul_f32_e32 v59, v157, v59
	v_lshl_add_u64 v[82:83], v[212:213], 0, v[82:83]
	v_sub_f32_e32 v59, v58, v59
	v_cvt_pk_bf16_f32 v58, v85, v88
	v_cvt_pk_bf16_f32 v59, v89, v59
	v_mov_b32_e32 v89, v62
	v_mov_b32_e32 v62, v87
	v_mul_f32_e32 v62, v160, v62
	v_mul_f32_e32 v63, v161, v63
	v_mov_b32_e32 v88, v86
	v_add_f32_e32 v86, v63, v62
	v_mov_b32_e32 v63, v64
	v_mov_b32_e32 v64, v61
	v_mov_b32_e32 v62, v60
	v_mul_f32_e32 v60, v156, v64
	v_mul_f32_e32 v61, v157, v65
	v_mul_f32_e32 v88, v158, v88
	v_mul_f32_e32 v89, v159, v89
	v_mul_f32_e32 v62, v154, v62
	v_mul_f32_e32 v63, v155, v63
	v_add_f32_e32 v61, v61, v60
	v_add_f32_e32 v85, v89, v88
	v_add_f32_e32 v62, v63, v62
	v_cvt_pk_bf16_f32 v60, v85, v86
	v_cvt_pk_bf16_f32 v61, v62, v61
	v_mul_f32_e32 v54, v54, v84
	v_mul_f32_e32 v55, v55, v84
	v_permlane16_swap_b32_e32 v58, v60
	v_permlane16_swap_b32_e32 v59, v61
	global_store_dwordx4 v[82:83], v[58:61], off
	v_mul_f32_e32 v56, v56, v84
	v_mul_f32_e32 v57, v57, v84
	v_mul_f32_e32 v52, v52, v84
	v_mul_f32_e32 v53, v53, v84
	v_mul_f32_e32 v58, v50, v84
	v_mul_f32_e32 v59, v51, v84
	v_mov_b32_e32 v50, v54
	v_mov_b32_e32 v51, v58
	s_waitcnt vmcnt(4)
	v_mul_f32_e32 v50, v78, v50
	v_mul_f32_e32 v51, v79, v51
	s_nop 0
	v_sub_f32_e32 v60, v50, v51
	v_mov_b32_e32 v50, v55
	v_mov_b32_e32 v51, v59
	v_mul_f32_e32 v50, v80, v50
	v_mul_f32_e32 v51, v81, v51
	s_nop 0
	v_sub_f32_e32 v61, v50, v51
	v_mov_b32_e32 v50, v56
	v_mov_b32_e32 v51, v52
	s_waitcnt vmcnt(3)
	v_mul_f32_e32 v50, v74, v50
	v_mul_f32_e32 v51, v75, v51
	s_nop 0
	v_sub_f32_e32 v62, v50, v51
	v_mov_b32_e32 v50, v57
	v_mov_b32_e32 v51, v53
	v_mul_f32_e32 v50, v76, v50
	v_mul_f32_e32 v51, v77, v51
	s_nop 0
	v_sub_f32_e32 v51, v50, v51
	v_cvt_pk_bf16_f32 v50, v60, v61
	v_mov_b32_e32 v60, v58
	v_mov_b32_e32 v61, v54
	v_mul_f32_e32 v60, v78, v60
	v_mul_f32_e32 v61, v79, v61
	v_mov_b32_e32 v54, v59
	v_add_f32_e32 v84, v61, v60
	v_mul_f32_e32 v58, v48, v48
	v_mul_f32_e32 v59, v49, v49
	v_mul_f32_e32 v60, v46, v46
	v_mul_f32_e32 v61, v47, v47
	v_cvt_pk_bf16_f32 v51, v62, v51
	v_mul_f32_e32 v54, v80, v54
	v_mul_f32_e32 v55, v81, v55
	v_pk_mov_b32 v[62:63], v[60:61], v[58:59] op_sel:[1,0]
	v_mov_b32_e32 v61, v59
	v_add_f32_e32 v58, v62, v60
	v_add_f32_e32 v59, v63, v61
	v_mul_f32_e32 v60, v44, v44
	v_mul_f32_e32 v61, v45, v45
	v_mul_f32_e32 v62, v42, v42
	v_mul_f32_e32 v63, v43, v43
	v_add_f32_e32 v85, v55, v54
	v_pk_mov_b32 v[64:65], v[62:63], v[60:61] op_sel:[1,0]
	v_mov_b32_e32 v63, v61
	v_add_f32_e32 v60, v64, v62
	v_add_f32_e32 v61, v65, v63
	v_mov_b32_e32 v54, v52
	v_mov_b32_e32 v55, v56
	v_mul_f32_e32 v52, v34, v34
	v_mul_f32_e32 v56, v35, v35
	v_pk_add_f32 v[58:59], v[58:59], v[58:59] op_sel:[0,1] op_sel_hi:[1,0]
	v_pk_add_f32 v[60:61], v[60:61], v[60:61] op_sel:[0,1] op_sel_hi:[1,0]
	v_mov_b32_e32 v59, v52
	v_mov_b32_e32 v61, v56
	v_mul_f32_e32 v52, v39, v39
	v_mul_f32_e32 v62, v36, v36
	v_add_f32_e32 v58, v58, v60
	v_add_f32_e32 v59, v59, v61
	v_fma_f32 v60, v38, v38, v52
	v_fma_f32 v61, v39, v39, v52
	v_mul_f32_e32 v52, v41, v41
	v_mul_f32_e32 v64, v37, v37
	v_mov_b32_e32 v61, v62
	v_fma_f32 v62, v40, v40, v52
	v_fma_f32 v63, v41, v41, v52
	v_mul_f32_e32 v54, v74, v54
	v_mul_f32_e32 v55, v75, v55
	v_mov_b32_e32 v63, v64
	v_add_f32_e32 v60, v60, v62
	v_add_f32_e32 v61, v61, v63
	v_add_f32_e32 v54, v55, v54
	v_add_f32_e32 v58, v58, v60
	v_add_f32_e32 v59, v59, v61
	v_mov_b32_e32 v56, v53
	v_add_f32_e32 v58, v58, v59
	ds_bpermute_b32 v59, v0, v58
	v_mul_f32_e32 v52, v76, v56
	v_mul_f32_e32 v53, v77, v57
	v_mul_f32_e32 v46, v46, v142
	v_mul_f32_e32 v47, v47, v143
	v_add_f32_e32 v53, v53, v52
	v_cvt_pk_bf16_f32 v52, v84, v85
	s_waitcnt lgkmcnt(0)
	v_add_f32_e32 v55, v58, v59
	ds_bpermute_b32 v56, v189, v55
	v_cvt_pk_bf16_f32 v53, v54, v53
	v_permlane16_swap_b32_e32 v50, v52
	v_permlane16_swap_b32_e32 v51, v53
	s_waitcnt lgkmcnt(0)
;     __device__ __forceinline__ static v2u pk4(float a, float b, float c, float d) { v2u o; o.x = pg8::cvt_pk_bf16(a, b); o.y = pg8::cvt_pk_bf16(c, d); return o; }
;     __device__ __forceinline__ void head64(const pg8::f32x4 (&acc)[2][2][4][2], int row0, int fq, bf16r* dst, int pitch, int colbase, const float* gain, float scale, const float2* trc) const {
;     ...
;             for (int ai = 0; ai < 2; ++ai) { const int m = 2 * mh + mm; const int row = row0 + ai * 128 + m * 16;
;                 float ss = 0.f;
; #pragma unroll
;                 for (int bj = 0; bj < 2; ++bj)
; #pragma unroll
;                     for (int n = 0; n < 2; ++n) { const pg8::f32x4 v = acc[ai][bj][m][n]; ss += (v[0] * v[0] + v[1] * v[1]) + (v[2] * v[2] + v[3] * v[3]); }
;                 ss += __shfl_xor(ss, 16); ss += __shfl_xor(ss, 32);
;                 const float rstd = rsqrtf(ss * (1.f / 64.f) + EPS);
; #pragma unroll
;                 for (int bj = 0; bj < 2; ++bj) { const pg8::f32x4 cs01 = bj == 0 ? rcs[ai][0] : ccs[mm][0], cs23 = bj == 0 ? rcs[ai][1] : ccs[mm][1];
;                     const pg8::f32x4 x1 = acc[ai][bj][m][0] * g[bj][0] * (rstd * scale), x2 = acc[ai][bj][m][1] * g[bj][1] * (rstd * scale);
;                     const float c0 = cs01[0], s0 = cs01[1], c1 = cs01[2], s1 = cs01[3], c2 = cs23[0], s2 = cs23[1], c3 = cs23[2], s3 = cs23[3];
;                     store_pair16(dst + (size_t)row * pitch + colbase + 32 * bj, fq, pk4(x1[0] * c0 - x2[0] * s0, x1[1] * c1 - x2[1] * s1, x1[2] * c2 - x2[2] * s2, x1[3] * c3 - x2[3] * s3),
;                                  pk4(x2[0] * c0 + x1[0] * s0, x2[1] * c1 + x1[1] * s1, x2[2] * c2 + x1[2] * s2, x2[3] * c3 + x1[3] * s3)); } } }
	v_add_f32_e32 v54, v55, v56
	v_fmamk_f32 v54, v54, 0x3c800000, v219
	v_mul_f32_e32 v55, 0x4b800000, v54
	v_cmp_gt_f32_e32 vcc, s25, v54
	global_store_dwordx4 v[82:83], v[50:53], off offset:64
	v_mul_f32_e32 v42, v42, v138
	v_mul_f32_e32 v43, v43, v139
	v_cndmask_b32_e32 v54, v54, v55, vcc
	v_rsq_f32_e32 v54, v54
	v_mul_f32_e32 v48, v48, v144
	v_mul_f32_e32 v49, v49, v145
	v_mul_f32_e32 v44, v44, v140
	v_mul_f32_e32 v45, v45, v141
	v_add_u32_e32 v50, 0xa0, v210
	v_mul_f32_e32 v51, 0x45800000, v54
	v_cndmask_b32_e32 v51, v54, v51, vcc
	v_mul_f32_e32 v52, 0x3e38aa3b, v51
	v_mul_f32_e32 v46, v46, v52
	v_mul_f32_e32 v47, v47, v52
	v_mul_f32_e32 v54, v42, v52
	v_mul_f32_e32 v55, v43, v52
	v_mov_b32_e32 v42, v46
	v_mov_b32_e32 v43, v54
	v_mul_f32_e32 v42, v150, v42
	v_mul_f32_e32 v43, v151, v43
	v_mul_f32_e32 v48, v48, v52
	v_mul_f32_e32 v49, v49, v52
	v_mul_f32_e32 v44, v44, v52
	v_mul_f32_e32 v45, v45, v52
	v_sub_f32_e32 v53, v42, v43
	v_mov_b32_e32 v42, v47
	v_mov_b32_e32 v43, v55
	v_mul_f32_e32 v42, v152, v42
	v_mul_f32_e32 v43, v153, v43
	v_ashrrev_i32_e32 v51, 31, v50
	v_sub_f32_e32 v56, v42, v43
	v_mov_b32_e32 v42, v48
	v_mov_b32_e32 v43, v44
	v_mul_f32_e32 v42, v146, v42
	v_mul_f32_e32 v43, v147, v43
	v_lshlrev_b64 v[50:51], 9, v[50:51]
	v_sub_f32_e32 v57, v42, v43
	v_mov_b32_e32 v42, v49
	v_mov_b32_e32 v43, v45
	v_mul_f32_e32 v42, v148, v42
	v_mul_f32_e32 v43, v149, v43
	v_lshl_add_u64 v[50:51], v[212:213], 0, v[50:51]
	v_sub_f32_e32 v43, v42, v43
	v_cvt_pk_bf16_f32 v42, v53, v56
	v_cvt_pk_bf16_f32 v43, v57, v43
	v_mov_b32_e32 v57, v46
	v_mov_b32_e32 v46, v55
	v_mul_f32_e32 v46, v152, v46
	v_mul_f32_e32 v47, v153, v47
	v_mov_b32_e32 v56, v54
	v_add_f32_e32 v54, v47, v46
	v_mov_b32_e32 v47, v48
	v_mov_b32_e32 v48, v45
	v_mov_b32_e32 v46, v44
	v_mul_f32_e32 v44, v148, v48
	v_mul_f32_e32 v45, v149, v49
	v_mul_f32_e32 v56, v150, v56
	v_mul_f32_e32 v57, v151, v57
	v_mul_f32_e32 v46, v146, v46
	v_mul_f32_e32 v47, v147, v47
	v_add_f32_e32 v45, v45, v44
	v_add_f32_e32 v53, v57, v56
	v_add_f32_e32 v46, v47, v46
	v_cvt_pk_bf16_f32 v44, v53, v54
	v_cvt_pk_bf16_f32 v45, v46, v45
	v_mul_f32_e32 v38, v38, v134
	v_mul_f32_e32 v39, v39, v135
	v_permlane16_swap_b32_e32 v42, v44
	v_permlane16_swap_b32_e32 v43, v45
	v_mul_f32_e32 v34, v34, v130
	v_mul_f32_e32 v35, v35, v131
	global_store_dwordx4 v[50:51], v[42:45], off
	v_mul_f32_e32 v38, v38, v52
	v_mul_f32_e32 v39, v39, v52
	v_mul_f32_e32 v40, v40, v136
	v_mul_f32_e32 v41, v41, v137
	v_mul_f32_e32 v42, v34, v52
	v_mul_f32_e32 v43, v35, v52
	v_mov_b32_e32 v34, v38
	v_mov_b32_e32 v35, v42
	v_mul_f32_e32 v34, v78, v34
	v_mul_f32_e32 v35, v79, v35
	v_mul_f32_e32 v36, v36, v132
	v_mul_f32_e32 v37, v37, v133
	v_sub_f32_e32 v44, v34, v35
	v_mov_b32_e32 v34, v39
	v_mov_b32_e32 v35, v43
	v_mul_f32_e32 v40, v40, v52
	v_mul_f32_e32 v41, v41, v52
	v_mul_f32_e32 v36, v36, v52
	v_mul_f32_e32 v37, v37, v52
	v_mul_f32_e32 v34, v80, v34
	v_mul_f32_e32 v35, v81, v35
	s_nop 0
	v_sub_f32_e32 v45, v34, v35
	v_mov_b32_e32 v34, v40
	v_mov_b32_e32 v35, v36
	v_mul_f32_e32 v34, v74, v34
	v_mul_f32_e32 v35, v75, v35
	s_nop 0
	v_sub_f32_e32 v46, v34, v35
	v_mov_b32_e32 v34, v41
	v_mov_b32_e32 v35, v37
	v_mul_f32_e32 v34, v76, v34
	v_mul_f32_e32 v35, v77, v35
	s_nop 0
	v_sub_f32_e32 v35, v34, v35
	v_cvt_pk_bf16_f32 v34, v44, v45
	v_mov_b32_e32 v44, v42
	v_mov_b32_e32 v45, v38
	v_mul_f32_e32 v44, v78, v44
	v_mul_f32_e32 v45, v79, v45
	v_mov_b32_e32 v38, v43
	v_add_f32_e32 v52, v45, v44
	v_mul_f32_e32 v42, v32, v32
	v_mul_f32_e32 v43, v33, v33
	v_mul_f32_e32 v44, v30, v30
	v_mul_f32_e32 v45, v31, v31
	v_cvt_pk_bf16_f32 v35, v46, v35
	v_mul_f32_e32 v38, v80, v38
	v_mul_f32_e32 v39, v81, v39
	v_pk_mov_b32 v[46:47], v[44:45], v[42:43] op_sel:[1,0]
	v_mov_b32_e32 v45, v43
	v_add_f32_e32 v42, v46, v44
	v_add_f32_e32 v43, v47, v45
	v_mul_f32_e32 v44, v28, v28
	v_mul_f32_e32 v45, v29, v29
	v_mul_f32_e32 v46, v26, v26
	v_mul_f32_e32 v47, v27, v27
	v_add_f32_e32 v53, v39, v38
	v_pk_mov_b32 v[48:49], v[46:47], v[44:45] op_sel:[1,0]
	v_mov_b32_e32 v47, v45
	v_add_f32_e32 v44, v48, v46
	v_add_f32_e32 v45, v49, v47
	v_mov_b32_e32 v38, v36
	v_mov_b32_e32 v39, v40
	v_mul_f32_e32 v36, v18, v18
	v_mul_f32_e32 v40, v19, v19
	v_pk_add_f32 v[42:43], v[42:43], v[42:43] op_sel:[0,1] op_sel_hi:[1,0]
	v_pk_add_f32 v[44:45], v[44:45], v[44:45] op_sel:[0,1] op_sel_hi:[1,0]
	v_mov_b32_e32 v43, v36
	v_mov_b32_e32 v45, v40
	v_mul_f32_e32 v36, v23, v23
	v_mul_f32_e32 v46, v20, v20
	v_add_f32_e32 v42, v42, v44
	v_add_f32_e32 v43, v43, v45
	v_fma_f32 v44, v22, v22, v36
	v_fma_f32 v45, v23, v23, v36
	v_mul_f32_e32 v36, v25, v25
	v_mul_f32_e32 v48, v21, v21
	v_mov_b32_e32 v45, v46
	v_fma_f32 v46, v24, v24, v36
	v_fma_f32 v47, v25, v25, v36
	v_mul_f32_e32 v38, v74, v38
	v_mul_f32_e32 v39, v75, v39
	v_mov_b32_e32 v47, v48
	v_add_f32_e32 v44, v44, v46
	v_add_f32_e32 v45, v45, v47
	v_add_f32_e32 v38, v39, v38
	v_add_f32_e32 v42, v42, v44
	v_add_f32_e32 v43, v43, v45
	v_mov_b32_e32 v40, v37
	v_add_f32_e32 v42, v42, v43
	ds_bpermute_b32 v43, v0, v42
	v_mul_f32_e32 v36, v76, v40
	v_mul_f32_e32 v37, v77, v41
	v_mul_f32_e32 v30, v30, v142
	v_mul_f32_e32 v31, v31, v143
	v_add_f32_e32 v37, v37, v36
	v_cvt_pk_bf16_f32 v36, v52, v53
	s_waitcnt lgkmcnt(0)
	v_add_f32_e32 v39, v42, v43
	ds_bpermute_b32 v40, v189, v39
	v_cvt_pk_bf16_f32 v37, v38, v37
	v_permlane16_swap_b32_e32 v34, v36
	v_permlane16_swap_b32_e32 v35, v37
	s_waitcnt lgkmcnt(0)
;     __device__ __forceinline__ static v2u pk4(float a, float b, float c, float d) { v2u o; o.x = pg8::cvt_pk_bf16(a, b); o.y = pg8::cvt_pk_bf16(c, d); return o; }
;     __device__ __forceinline__ void head64(const pg8::f32x4 (&acc)[2][2][4][2], int row0, int fq, bf16r* dst, int pitch, int colbase, const float* gain, float scale, const float2* trc) const {
;     ...
;             for (int ai = 0; ai < 2; ++ai) { const int m = 2 * mh + mm; const int row = row0 + ai * 128 + m * 16;
;                 float ss = 0.f;
; #pragma unroll
;                 for (int bj = 0; bj < 2; ++bj)
; #pragma unroll
;                     for (int n = 0; n < 2; ++n) { const pg8::f32x4 v = acc[ai][bj][m][n]; ss += (v[0] * v[0] + v[1] * v[1]) + (v[2] * v[2] + v[3] * v[3]); }
;                 ss += __shfl_xor(ss, 16); ss += __shfl_xor(ss, 32);
;                 const float rstd = rsqrtf(ss * (1.f / 64.f) + EPS);
; #pragma unroll
;                 for (int bj = 0; bj < 2; ++bj) { const pg8::f32x4 cs01 = bj == 0 ? rcs[ai][0] : ccs[mm][0], cs23 = bj == 0 ? rcs[ai][1] : ccs[mm][1];
;                     const pg8::f32x4 x1 = acc[ai][bj][m][0] * g[bj][0] * (rstd * scale), x2 = acc[ai][bj][m][1] * g[bj][1] * (rstd * scale);
;                     const float c0 = cs01[0], s0 = cs01[1], c1 = cs01[2], s1 = cs01[3], c2 = cs23[0], s2 = cs23[1], c3 = cs23[2], s3 = cs23[3];
;                     store_pair16(dst + (size_t)row * pitch + colbase + 32 * bj, fq, pk4(x1[0] * c0 - x2[0] * s0, x1[1] * c1 - x2[1] * s1, x1[2] * c2 - x2[2] * s2, x1[3] * c3 - x2[3] * s3),
;                                  pk4(x2[0] * c0 + x1[0] * s0, x2[1] * c1 + x1[1] * s1, x2[2] * c2 + x1[2] * s2, x2[3] * c3 + x1[3] * s3)); } } }
	v_add_f32_e32 v38, v39, v40
	v_fmamk_f32 v38, v38, 0x3c800000, v219
	v_mul_f32_e32 v39, 0x4b800000, v38
	v_cmp_gt_f32_e32 vcc, s25, v38
	global_store_dwordx4 v[50:51], v[34:37], off offset:64
	v_mul_f32_e32 v26, v26, v138
	v_mul_f32_e32 v27, v27, v139
	v_cndmask_b32_e32 v38, v38, v39, vcc
	v_rsq_f32_e32 v38, v38
	v_mul_f32_e32 v32, v32, v144
	v_mul_f32_e32 v33, v33, v145
	v_mul_f32_e32 v28, v28, v140
	v_mul_f32_e32 v29, v29, v141
	v_or_b32_e32 v34, 48, v210
	v_mul_f32_e32 v35, 0x45800000, v38
	v_cndmask_b32_e32 v35, v38, v35, vcc
	v_mul_f32_e32 v36, 0x3e38aa3b, v35
	v_mul_f32_e32 v30, v30, v36
	v_mul_f32_e32 v31, v31, v36
	v_mul_f32_e32 v38, v26, v36
	v_mul_f32_e32 v39, v27, v36
	v_mov_b32_e32 v26, v30
	v_mov_b32_e32 v27, v38
	v_mul_f32_e32 v26, v158, v26
	v_mul_f32_e32 v27, v159, v27
	v_mul_f32_e32 v32, v32, v36
	v_mul_f32_e32 v33, v33, v36
	v_mul_f32_e32 v28, v28, v36
	v_mul_f32_e32 v29, v29, v36
	v_sub_f32_e32 v37, v26, v27
	v_mov_b32_e32 v26, v31
	v_mov_b32_e32 v27, v39
	v_mul_f32_e32 v26, v160, v26
	v_mul_f32_e32 v27, v161, v27
	v_ashrrev_i32_e32 v35, 31, v34
	v_sub_f32_e32 v40, v26, v27
	v_mov_b32_e32 v26, v32
	v_mov_b32_e32 v27, v28
	v_mul_f32_e32 v26, v154, v26
	v_mul_f32_e32 v27, v155, v27
	v_lshlrev_b64 v[34:35], 9, v[34:35]
	v_sub_f32_e32 v41, v26, v27
	v_mov_b32_e32 v26, v33
	v_mov_b32_e32 v27, v29
	v_mul_f32_e32 v26, v156, v26
	v_mul_f32_e32 v27, v157, v27
	v_lshl_add_u64 v[34:35], v[212:213], 0, v[34:35]
	v_sub_f32_e32 v27, v26, v27
	v_cvt_pk_bf16_f32 v26, v37, v40
	v_cvt_pk_bf16_f32 v27, v41, v27
	v_mov_b32_e32 v41, v30
	v_mov_b32_e32 v30, v39
	v_mul_f32_e32 v30, v160, v30
	v_mul_f32_e32 v31, v161, v31
	v_mov_b32_e32 v40, v38
	v_add_f32_e32 v38, v31, v30
	v_mov_b32_e32 v31, v32
	v_mov_b32_e32 v32, v29
	v_mov_b32_e32 v30, v28
	v_mul_f32_e32 v28, v156, v32
	v_mul_f32_e32 v29, v157, v33
	v_mul_f32_e32 v40, v158, v40
	v_mul_f32_e32 v41, v159, v41
	v_mul_f32_e32 v30, v154, v30
	v_mul_f32_e32 v31, v155, v31
	v_add_f32_e32 v29, v29, v28
	v_add_f32_e32 v37, v41, v40
	v_add_f32_e32 v30, v31, v30
	v_cvt_pk_bf16_f32 v28, v37, v38
	v_cvt_pk_bf16_f32 v29, v30, v29
	v_mul_f32_e32 v22, v22, v134
	v_mul_f32_e32 v23, v23, v135
	v_permlane16_swap_b32_e32 v26, v28
	v_permlane16_swap_b32_e32 v27, v29
	v_mul_f32_e32 v18, v18, v130
	v_mul_f32_e32 v19, v19, v131
	global_store_dwordx4 v[34:35], v[26:29], off
	v_mul_f32_e32 v22, v22, v36
	v_mul_f32_e32 v23, v23, v36
	v_mul_f32_e32 v24, v24, v136
	v_mul_f32_e32 v25, v25, v137
	v_mul_f32_e32 v26, v18, v36
	v_mul_f32_e32 v27, v19, v36
	v_mov_b32_e32 v18, v22
	v_mov_b32_e32 v19, v26
	s_waitcnt vmcnt(6)
	v_mul_f32_e32 v18, v70, v18
	v_mul_f32_e32 v19, v71, v19
	v_mul_f32_e32 v20, v20, v132
	v_mul_f32_e32 v21, v21, v133
	v_sub_f32_e32 v28, v18, v19
	v_mov_b32_e32 v18, v23
	v_mov_b32_e32 v19, v27
	v_mul_f32_e32 v24, v24, v36
	v_mul_f32_e32 v25, v25, v36
	v_mul_f32_e32 v20, v20, v36
	v_mul_f32_e32 v21, v21, v36
	v_mul_f32_e32 v18, v72, v18
	v_mul_f32_e32 v19, v73, v19
	s_nop 0
	v_sub_f32_e32 v29, v18, v19
	v_mov_b32_e32 v18, v24
	v_mov_b32_e32 v19, v20
	s_waitcnt vmcnt(5)
	v_mul_f32_e32 v18, v66, v18
	v_mul_f32_e32 v19, v67, v19
	s_nop 0
	v_sub_f32_e32 v30, v18, v19
	v_mov_b32_e32 v18, v25
	v_mov_b32_e32 v19, v21
	v_mul_f32_e32 v18, v68, v18
	v_mul_f32_e32 v19, v69, v19
	s_nop 0
	v_sub_f32_e32 v19, v18, v19
	v_cvt_pk_bf16_f32 v18, v28, v29
	v_mov_b32_e32 v28, v26
	v_mov_b32_e32 v29, v22
	v_mul_f32_e32 v28, v70, v28
	v_mul_f32_e32 v29, v71, v29
	v_mov_b32_e32 v22, v27
	v_add_f32_e32 v36, v29, v28
	v_mul_f32_e32 v26, v16, v16
	v_mul_f32_e32 v27, v17, v17
	v_mul_f32_e32 v28, v14, v14
	v_mul_f32_e32 v29, v15, v15
	v_cvt_pk_bf16_f32 v19, v30, v19
	v_mul_f32_e32 v22, v72, v22
	v_mul_f32_e32 v23, v73, v23
	v_pk_mov_b32 v[30:31], v[28:29], v[26:27] op_sel:[1,0]
	v_mov_b32_e32 v29, v27
	v_add_f32_e32 v26, v30, v28
	v_add_f32_e32 v27, v31, v29
	v_mul_f32_e32 v28, v12, v12
	v_mul_f32_e32 v29, v13, v13
	v_mul_f32_e32 v30, v10, v10
	v_mul_f32_e32 v31, v11, v11
	v_add_f32_e32 v37, v23, v22
	v_pk_mov_b32 v[32:33], v[30:31], v[28:29] op_sel:[1,0]
	v_mov_b32_e32 v31, v29
	v_add_f32_e32 v28, v32, v30
	v_add_f32_e32 v29, v33, v31
	v_mov_b32_e32 v22, v20
	v_mov_b32_e32 v23, v24
	v_mul_f32_e32 v20, v2, v2
	v_mul_f32_e32 v24, v3, v3
	v_pk_add_f32 v[26:27], v[26:27], v[26:27] op_sel:[0,1] op_sel_hi:[1,0]
	v_pk_add_f32 v[28:29], v[28:29], v[28:29] op_sel:[0,1] op_sel_hi:[1,0]
	v_mov_b32_e32 v27, v20
	v_mov_b32_e32 v29, v24
	v_mul_f32_e32 v20, v7, v7
	v_mul_f32_e32 v30, v4, v4
	v_add_f32_e32 v26, v26, v28
	v_add_f32_e32 v27, v27, v29
	v_fma_f32 v28, v6, v6, v20
	v_fma_f32 v29, v7, v7, v20
	v_mul_f32_e32 v20, v9, v9
	v_mul_f32_e32 v32, v5, v5
	v_mov_b32_e32 v29, v30
	v_fma_f32 v30, v8, v8, v20
	v_fma_f32 v31, v9, v9, v20
	v_mul_f32_e32 v22, v66, v22
	v_mul_f32_e32 v23, v67, v23
	v_mov_b32_e32 v31, v32
	v_add_f32_e32 v28, v28, v30
	v_add_f32_e32 v29, v29, v31
	v_add_f32_e32 v22, v23, v22
	v_add_f32_e32 v26, v26, v28
	v_add_f32_e32 v27, v27, v29
	v_mov_b32_e32 v24, v21
	v_add_f32_e32 v26, v26, v27
	ds_bpermute_b32 v0, v0, v26
	v_mul_f32_e32 v20, v68, v24
	v_mul_f32_e32 v21, v69, v25
	v_mul_f32_e32 v14, v14, v142
	v_mul_f32_e32 v15, v15, v143
	v_add_f32_e32 v21, v21, v20
	v_cvt_pk_bf16_f32 v20, v36, v37
	s_waitcnt lgkmcnt(0)
;     __device__ __forceinline__ static v2u pk4(float a, float b, float c, float d) { v2u o; o.x = pg8::cvt_pk_bf16(a, b); o.y = pg8::cvt_pk_bf16(c, d); return o; }
;     __device__ __forceinline__ void head64(const pg8::f32x4 (&acc)[2][2][4][2], int row0, int fq, bf16r* dst, int pitch, int colbase, const float* gain, float scale, const float2* trc) const {
;     ...
;             for (int ai = 0; ai < 2; ++ai) { const int m = 2 * mh + mm; const int row = row0 + ai * 128 + m * 16;
;                 float ss = 0.f;
; #pragma unroll
;                 for (int bj = 0; bj < 2; ++bj)
; #pragma unroll
;                     for (int n = 0; n < 2; ++n) { const pg8::f32x4 v = acc[ai][bj][m][n]; ss += (v[0] * v[0] + v[1] * v[1]) + (v[2] * v[2] + v[3] * v[3]); }
;                 ss += __shfl_xor(ss, 16); ss += __shfl_xor(ss, 32);
;                 const float rstd = rsqrtf(ss * (1.f / 64.f) + EPS);
; #pragma unroll
;                 for (int bj = 0; bj < 2; ++bj) { const pg8::f32x4 cs01 = bj == 0 ? rcs[ai][0] : ccs[mm][0], cs23 = bj == 0 ? rcs[ai][1] : ccs[mm][1];
;                     const pg8::f32x4 x1 = acc[ai][bj][m][0] * g[bj][0] * (rstd * scale), x2 = acc[ai][bj][m][1] * g[bj][1] * (rstd * scale);
;                     const float c0 = cs01[0], s0 = cs01[1], c1 = cs01[2], s1 = cs01[3], c2 = cs23[0], s2 = cs23[1], c3 = cs23[2], s3 = cs23[3];
;                     store_pair16(dst + (size_t)row * pitch + colbase + 32 * bj, fq, pk4(x1[0] * c0 - x2[0] * s0, x1[1] * c1 - x2[1] * s1, x1[2] * c2 - x2[2] * s2, x1[3] * c3 - x2[3] * s3),
;                                  pk4(x2[0] * c0 + x1[0] * s0, x2[1] * c1 + x1[1] * s1, x2[2] * c2 + x1[2] * s2, x2[3] * c3 + x1[3] * s3)); } } }
	v_add_f32_e32 v0, v26, v0
	ds_bpermute_b32 v23, v189, v0
	v_cvt_pk_bf16_f32 v21, v22, v21
	v_permlane16_swap_b32_e32 v18, v20
	v_permlane16_swap_b32_e32 v19, v21
	s_waitcnt lgkmcnt(0)
	v_add_f32_e32 v0, v0, v23
	v_fmamk_f32 v0, v0, 0x3c800000, v219
	v_mul_f32_e32 v22, 0x4b800000, v0
	v_cmp_gt_f32_e32 vcc, s25, v0
	global_store_dwordx4 v[34:35], v[18:21], off offset:64
	v_mul_f32_e32 v10, v10, v138
	v_mul_f32_e32 v11, v11, v139
	v_cndmask_b32_e32 v0, v0, v22, vcc
	v_rsq_f32_e32 v0, v0
	v_mul_f32_e32 v16, v16, v144
	v_mul_f32_e32 v17, v17, v145
	v_mul_f32_e32 v12, v12, v140
	v_mul_f32_e32 v13, v13, v141
	v_add_u32_e32 v18, 0xb0, v210
	v_mul_f32_e32 v19, 0x45800000, v0
	v_cndmask_b32_e32 v0, v0, v19, vcc
	v_mul_f32_e32 v0, 0x3e38aa3b, v0
	v_mul_f32_e32 v14, v14, v0
	v_mul_f32_e32 v15, v15, v0
	v_mul_f32_e32 v20, v10, v0
	v_mul_f32_e32 v21, v11, v0
	v_mov_b32_e32 v10, v14
	v_mov_b32_e32 v11, v20
	v_mul_f32_e32 v10, v150, v10
	v_mul_f32_e32 v11, v151, v11
	v_mul_f32_e32 v16, v16, v0
	v_mul_f32_e32 v17, v17, v0
	v_sub_f32_e32 v22, v10, v11
	v_mov_b32_e32 v10, v15
	v_mov_b32_e32 v11, v21
	v_mul_f32_e32 v12, v12, v0
	v_mul_f32_e32 v13, v13, v0
	v_mul_f32_e32 v10, v152, v10
	v_mul_f32_e32 v11, v153, v11
	v_ashrrev_i32_e32 v19, 31, v18
	v_sub_f32_e32 v23, v10, v11
	v_mov_b32_e32 v10, v16
	v_mov_b32_e32 v11, v12
	v_mul_f32_e32 v10, v146, v10
	v_mul_f32_e32 v11, v147, v11
	v_lshlrev_b64 v[18:19], 9, v[18:19]
	v_sub_f32_e32 v24, v10, v11
	v_mov_b32_e32 v10, v17
	v_mov_b32_e32 v11, v13
	v_mul_f32_e32 v10, v148, v10
	v_mul_f32_e32 v11, v149, v11
	v_lshl_add_u64 v[18:19], v[212:213], 0, v[18:19]
	v_sub_f32_e32 v11, v10, v11
	v_cvt_pk_bf16_f32 v10, v22, v23
	v_mov_b32_e32 v23, v14
	v_mov_b32_e32 v14, v21
	v_mul_f32_e32 v14, v152, v14
	v_mul_f32_e32 v15, v153, v15
	v_mov_b32_e32 v22, v20
	v_add_f32_e32 v21, v15, v14
	v_mov_b32_e32 v15, v16
	v_mov_b32_e32 v16, v13
	v_mov_b32_e32 v14, v12
	v_mul_f32_e32 v12, v148, v16
	v_mul_f32_e32 v13, v149, v17
	v_mul_f32_e32 v22, v150, v22
	v_mul_f32_e32 v23, v151, v23
	v_mul_f32_e32 v14, v146, v14
	v_mul_f32_e32 v15, v147, v15
	v_add_f32_e32 v13, v13, v12
	v_cvt_pk_bf16_f32 v11, v24, v11
	v_add_f32_e32 v20, v23, v22
	v_add_f32_e32 v14, v15, v14
	v_cvt_pk_bf16_f32 v12, v20, v21
	v_cvt_pk_bf16_f32 v13, v14, v13
	v_mul_f32_e32 v6, v6, v134
	v_mul_f32_e32 v7, v7, v135
	v_permlane16_swap_b32_e32 v10, v12
	v_permlane16_swap_b32_e32 v11, v13
	v_mul_f32_e32 v2, v2, v130
	v_mul_f32_e32 v3, v3, v131
	global_store_dwordx4 v[18:19], v[10:13], off
	v_mul_f32_e32 v6, v6, v0
	v_mul_f32_e32 v7, v7, v0
	v_mul_f32_e32 v8, v8, v136
	v_mul_f32_e32 v9, v9, v137
	v_mul_f32_e32 v10, v2, v0
	v_mul_f32_e32 v11, v3, v0
	v_mov_b32_e32 v2, v6
	v_mov_b32_e32 v3, v10
	v_mul_f32_e32 v4, v4, v132
	v_mul_f32_e32 v5, v5, v133
	v_mul_f32_e32 v2, v70, v2
	v_mul_f32_e32 v3, v71, v3
	v_mul_f32_e32 v8, v8, v0
	v_mul_f32_e32 v9, v9, v0
	v_mul_f32_e32 v4, v4, v0
	v_mul_f32_e32 v5, v5, v0
	v_sub_f32_e32 v0, v2, v3
	v_mov_b32_e32 v2, v7
	v_mov_b32_e32 v3, v11
	v_mul_f32_e32 v2, v72, v2
	v_mul_f32_e32 v3, v73, v3
	s_nop 0
	v_sub_f32_e32 v12, v2, v3
	v_mov_b32_e32 v2, v8
	v_mov_b32_e32 v3, v4
	v_mul_f32_e32 v2, v66, v2
	v_mul_f32_e32 v3, v67, v3
	s_nop 0
	v_sub_f32_e32 v13, v2, v3
	v_mov_b32_e32 v2, v9
	v_mov_b32_e32 v3, v5
	v_mul_f32_e32 v2, v68, v2
	v_mul_f32_e32 v3, v69, v3
	s_nop 0
	v_sub_f32_e32 v3, v2, v3
	v_cvt_pk_bf16_f32 v2, v0, v12
	v_cvt_pk_bf16_f32 v3, v13, v3
	v_mov_b32_e32 v13, v6
	v_mov_b32_e32 v6, v11
	v_mul_f32_e32 v6, v72, v6
	v_mul_f32_e32 v7, v73, v7
	v_mov_b32_e32 v12, v10
	v_add_f32_e32 v10, v7, v6
	v_mov_b32_e32 v7, v8
	v_mov_b32_e32 v8, v5
	v_mov_b32_e32 v6, v4
	v_mul_f32_e32 v4, v68, v8
	v_mul_f32_e32 v5, v69, v9
	v_mul_f32_e32 v12, v70, v12
	v_mul_f32_e32 v13, v71, v13
	v_mul_f32_e32 v6, v66, v6
	v_mul_f32_e32 v7, v67, v7
	v_add_f32_e32 v5, v5, v4
	v_add_f32_e32 v0, v13, v12
	v_add_f32_e32 v6, v7, v6
	v_cvt_pk_bf16_f32 v4, v0, v10
	v_cvt_pk_bf16_f32 v5, v6, v5
	s_nop 0
	v_permlane16_swap_b32_e32 v2, v4
	v_permlane16_swap_b32_e32 v3, v5
	global_store_dwordx4 v[18:19], v[2:5], off offset:64
	s_andn2_b64 vcc, exec, s[46:47]
	s_mov_b64 s[46:47], -1
	s_cbranch_vccz .LBB0_274
